# software-pipelined K-loops without per-group s_setprio toggles (priority flips removed from the 7 pipelined GEMM loops)
# speedup vs baseline: 1.0434x; 1.0084x over previous
; DI f32x16 mfma(bf16x8 a, bf16x8 b, f32x16 c) { return __builtin_amdgcn_mfma_f32_32x32x16_bf16(a, b, c, 0, 0, 0); }
; template <int BK> DI int swz(int row) { constexpr int CPR = BK / 8; return (row / (16 / CPR)) % CPR; }
;     ...
;     bf16x8 fa[2][2], fb[2][NTW];
; #pragma unroll
;     for (int mt = 0; mt < 2; ++mt) { int row = wm * 64 + mt * 32 + l31; fa[0][mt] = *(const bf16x8*)(cur + row * (BK * 2) + ((hh ^ swz<BK>(row)) << 4)); }
; #pragma unroll
;     for (int nt = 0; nt < NTW; ++nt) { int row = wn * (32 * NTW) + nt * 32 + l31; fb[0][nt] = *(const bf16x8*)(cur + ABYTES + row * (BK * 2) + ((hh ^ swz<BK>(row)) << 4)); }
; #pragma unroll
;     for (int kk = 0; kk < NKK; ++kk) {
;       if (kk + 1 < NKK) {
;         const int ch = (kk + 1) * 2 + hh;
; #pragma unroll
;         for (int mt = 0; mt < 2; ++mt) { int row = wm * 64 + mt * 32 + l31; fa[(kk + 1) & 1][mt] = *(const bf16x8*)(cur + row * (BK * 2) + ((ch ^ swz<BK>(row)) << 4)); }
; #pragma unroll
;         for (int nt = 0; nt < NTW; ++nt) { int row = wn * (32 * NTW) + nt * 32 + l31; fb[(kk + 1) & 1][nt] = *(const bf16x8*)(cur + ABYTES + row * (BK * 2) + ((ch ^ swz<BK>(row)) << 4)); }
;       }
;       if (more) {
; #pragma unroll
;         for (int q = 0; q < PPK; ++q) {
;           const int pi = kk * PPK + q;
;           if (pi < NPA) stage_piece<BM, BK>(An, lda, nxt, tid, pi, wv);
;           else if (pi < NP) stage_piece<BN, BK>(Bn, ldb, nxt + ABYTES, tid, pi - NPA, wv);
;         }
;       }
;       __builtin_amdgcn_s_setprio(1);
; #pragma unroll
;       for (int mt = 0; mt < 2; ++mt)
; #pragma unroll
;         for (int nt = 0; nt < NTW; ++nt) acc[mt][nt] = mfma(fa[kk & 1][mt], fb[kk & 1][nt], acc[mt][nt]);
;       __builtin_amdgcn_s_setprio(0);
;       __builtin_amdgcn_sched_barrier(0);
;     }
.LBB0_173:
	s_and_b32 s30, s3, 0x10000
	s_xor_b32 s100, s30, 0x10000
	s_add_i32 s31, s30, s2
	v_add3_u32 v194, s100, v136, v166
	v_add3_u32 v198, s100, v144, v167
	ds_read_b128 v[194:197], v194
	v_add3_u32 v202, s100, v145, v161
	ds_read_b128 v[198:201], v198
	v_add3_u32 v206, s100, v152, v163
	ds_read_b128 v[202:205], v202 offset:32768
	v_add3_u32 v210, s100, v155, v159
	ds_read_b128 v[206:209], v206 offset:32768
	v_add3_u32 v226, s100, v158, v160
	ds_read_b128 v[210:213], v210 offset:32768
	ds_read_b128 v[226:229], v226 offset:32768
	v_lshl_add_u64 v[214:215], v[132:133], 0, s[6:7]
	v_lshl_add_u64 v[230:231], v[130:131], 0, s[6:7]
	s_mov_b32 m0, s31
	v_lshl_add_u64 v[232:233], v[214:215], 0, s[28:29]
	s_waitcnt lgkmcnt(6)
	v_mfma_f32_32x32x16_bf16 v[114:129], v[170:173], v[178:181], v[114:129]
	global_load_lds_dwordx4 v[232:233], off
	v_lshl_add_u64 v[232:233], v[214:215], 0, s[24:25]
	s_add_i32 m0, s31, 0x2000
	v_mfma_f32_32x32x16_bf16 v[98:113], v[170:173], v[182:185], v[98:113]
	global_load_lds_dwordx4 v[232:233], off
	v_lshl_add_u64 v[232:233], v[214:215], 0, s[26:27]
	s_add_i32 m0, s31, 0x4000
	v_mfma_f32_32x32x16_bf16 v[82:97], v[170:173], v[186:189], v[82:97]
	global_load_lds_dwordx4 v[232:233], off
	v_lshl_add_u64 v[232:233], v[214:215], 0, s[38:39]
	s_add_i32 m0, s31, 0x6000
	v_mfma_f32_32x32x16_bf16 v[66:81], v[170:173], v[190:193], v[66:81]
	global_load_lds_dwordx4 v[232:233], off
	v_lshl_add_u64 v[232:233], v[230:231], 0, s[28:29]
	s_add_i32 m0, s31, 0x8000
	v_mfma_f32_32x32x16_bf16 v[50:65], v[174:177], v[178:181], v[50:65]
	global_load_lds_dwordx4 v[232:233], off
	v_lshl_add_u64 v[232:233], v[230:231], 0, s[24:25]
	s_add_i32 m0, s31, 0xa000
	v_mfma_f32_32x32x16_bf16 v[34:49], v[174:177], v[182:185], v[34:49]
	global_load_lds_dwordx4 v[232:233], off
	v_lshl_add_u64 v[232:233], v[230:231], 0, s[26:27]
	s_add_i32 m0, s31, 0xc000
	v_mfma_f32_32x32x16_bf16 v[18:33], v[174:177], v[186:189], v[18:33]
	global_load_lds_dwordx4 v[232:233], off
	v_lshl_add_u64 v[232:233], v[230:231], 0, s[38:39]
	s_add_i32 m0, s31, 0xe000
	v_mfma_f32_32x32x16_bf16 v[2:17], v[174:177], v[190:193], v[2:17]
	global_load_lds_dwordx4 v[232:233], off
	v_add3_u32 v170, s100, v136, v153
	v_add3_u32 v174, s100, v144, v154
	ds_read_b128 v[170:173], v170
	v_add3_u32 v178, s100, v145, v149
	ds_read_b128 v[174:177], v174
	v_add3_u32 v182, s100, v152, v150
	ds_read_b128 v[178:181], v178 offset:32768
	v_add3_u32 v186, s100, v155, v147
	ds_read_b128 v[182:185], v182 offset:32768
	v_add3_u32 v190, s100, v158, v148
	ds_read_b128 v[186:189], v186 offset:32768
	ds_read_b128 v[190:193], v190 offset:32768
	s_waitcnt lgkmcnt(6)
	v_mfma_f32_32x32x16_bf16 v[114:129], v[194:197], v[202:205], v[114:129]
	v_mfma_f32_32x32x16_bf16 v[98:113], v[194:197], v[206:209], v[98:113]
	v_mfma_f32_32x32x16_bf16 v[82:97], v[194:197], v[210:213], v[82:97]
	v_mfma_f32_32x32x16_bf16 v[66:81], v[194:197], v[226:229], v[66:81]
	v_mfma_f32_32x32x16_bf16 v[50:65], v[198:201], v[202:205], v[50:65]
	v_mfma_f32_32x32x16_bf16 v[34:49], v[198:201], v[206:209], v[34:49]
	v_mfma_f32_32x32x16_bf16 v[18:33], v[198:201], v[210:213], v[18:33]
	v_mfma_f32_32x32x16_bf16 v[2:17], v[198:201], v[226:229], v[2:17]
	v_add3_u32 v194, s100, v136, v141
	v_add3_u32 v198, s100, v144, v142
	ds_read_b128 v[194:197], v194
	v_add3_u32 v202, s100, v145, v139
	ds_read_b128 v[198:201], v198
	v_add3_u32 v206, s100, v152, v140
	ds_read_b128 v[202:205], v202 offset:32768
	v_add3_u32 v210, s100, v155, v137
	ds_read_b128 v[206:209], v206 offset:32768
	v_add3_u32 v226, s100, v158, v138
	ds_read_b128 v[210:213], v210 offset:32768
	ds_read_b128 v[226:229], v226 offset:32768
	s_waitcnt lgkmcnt(6)
	v_mfma_f32_32x32x16_bf16 v[114:129], v[170:173], v[178:181], v[114:129]
	v_mfma_f32_32x32x16_bf16 v[98:113], v[170:173], v[182:185], v[98:113]
	v_mfma_f32_32x32x16_bf16 v[82:97], v[170:173], v[186:189], v[82:97]
	v_mfma_f32_32x32x16_bf16 v[66:81], v[170:173], v[190:193], v[66:81]
	v_mfma_f32_32x32x16_bf16 v[50:65], v[174:177], v[178:181], v[50:65]
	v_mfma_f32_32x32x16_bf16 v[34:49], v[174:177], v[182:185], v[34:49]
	v_mfma_f32_32x32x16_bf16 v[18:33], v[174:177], v[186:189], v[18:33]
	v_mfma_f32_32x32x16_bf16 v[2:17], v[174:177], v[190:193], v[2:17]
	s_add_u32 s6, s6, 0x80
	s_addc_u32 s7, s7, 0
	s_add_i32 s3, s3, 0x10000
	s_waitcnt vmcnt(0) lgkmcnt(0)
	s_barrier
	v_add3_u32 v170, s30, v136, v143
	v_add3_u32 v174, s30, v144, v146
	ds_read_b128 v[170:173], v170
	v_add3_u32 v178, s30, v145, v151
	ds_read_b128 v[174:177], v174
	v_add3_u32 v182, s30, v152, v156
	ds_read_b128 v[178:181], v178 offset:32768
	v_add3_u32 v186, s30, v155, v157
	ds_read_b128 v[182:185], v182 offset:32768
	v_add3_u32 v190, s30, v158, v168
	ds_read_b128 v[186:189], v186 offset:32768
	ds_read_b128 v[190:193], v190 offset:32768
	v_mfma_f32_32x32x16_bf16 v[114:129], v[194:197], v[202:205], v[114:129]
	v_mfma_f32_32x32x16_bf16 v[98:113], v[194:197], v[206:209], v[98:113]
	v_mfma_f32_32x32x16_bf16 v[82:97], v[194:197], v[210:213], v[82:97]
	v_mfma_f32_32x32x16_bf16 v[66:81], v[194:197], v[226:229], v[66:81]
	v_mfma_f32_32x32x16_bf16 v[50:65], v[198:201], v[202:205], v[50:65]
	v_mfma_f32_32x32x16_bf16 v[34:49], v[198:201], v[206:209], v[34:49]
	v_mfma_f32_32x32x16_bf16 v[18:33], v[198:201], v[210:213], v[18:33]
	v_mfma_f32_32x32x16_bf16 v[2:17], v[198:201], v[226:229], v[2:17]
	s_cmpk_lg_i32 s6, 0x780
	s_cbranch_scc1 .LBB0_173
; DI f32x16 mfma(bf16x8 a, bf16x8 b, f32x16 c) { return __builtin_amdgcn_mfma_f32_32x32x16_bf16(a, b, c, 0, 0, 0); }
; DI void wait_vm0() { asm volatile("s_waitcnt vmcnt(0)" ::: "memory"); }
;     ...
;     if (!more) epi.pre(row0 + wm * 64, col0 + wn * (32 * NTW), lane, w, lds);
;     bf16x8 fa[2][2], fb[2][NTW];
; #pragma unroll
;     for (int mt = 0; mt < 2; ++mt) { int row = wm * 64 + mt * 32 + l31; fa[0][mt] = *(const bf16x8*)(cur + row * (BK * 2) + ((hh ^ swz<BK>(row)) << 4)); }
; #pragma unroll
;     for (int nt = 0; nt < NTW; ++nt) { int row = wn * (32 * NTW) + nt * 32 + l31; fb[0][nt] = *(const bf16x8*)(cur + ABYTES + row * (BK * 2) + ((hh ^ swz<BK>(row)) << 4)); }
; #pragma unroll
;     for (int kk = 0; kk < NKK; ++kk) {
;       if (kk + 1 < NKK) {
;         const int ch = (kk + 1) * 2 + hh;
; #pragma unroll
;         for (int mt = 0; mt < 2; ++mt) { int row = wm * 64 + mt * 32 + l31; fa[(kk + 1) & 1][mt] = *(const bf16x8*)(cur + row * (BK * 2) + ((ch ^ swz<BK>(row)) << 4)); }
; #pragma unroll
;         for (int nt = 0; nt < NTW; ++nt) { int row = wn * (32 * NTW) + nt * 32 + l31; fb[(kk + 1) & 1][nt] = *(const bf16x8*)(cur + ABYTES + row * (BK * 2) + ((ch ^ swz<BK>(row)) << 4)); }
;       }
;       if (more) {
; #pragma unroll
;         for (int q = 0; q < PPK; ++q) {
;           const int pi = kk * PPK + q;
;           if (pi < NPA) stage_piece<BM, BK>(An, lda, nxt, tid, pi, wv);
;           else if (pi < NP) stage_piece<BN, BK>(Bn, ldb, nxt + ABYTES, tid, pi - NPA, wv);
;         }
;       }
;       __builtin_amdgcn_s_setprio(1);
; #pragma unroll
;       for (int mt = 0; mt < 2; ++mt)
; #pragma unroll
;         for (int nt = 0; nt < NTW; ++nt) acc[mt][nt] = mfma(fa[kk & 1][mt], fb[kk & 1][nt], acc[mt][nt]);
;       __builtin_amdgcn_s_setprio(0);
;       __builtin_amdgcn_sched_barrier(0);
;     }
;     wait_vm0();
;     __syncthreads();
;   DI void xpass(int ps, int grow0, int gcol0, int lane, int w, char* lds) const {
;     char* xs = lds + (ps & 1) * 65536 + __builtin_amdgcn_readfirstlane(w) * 8192;
;     const float* xsrc = Xin + (size_t)(grow0 + (ps >> 1) * 32 + (ps & 1) * 16 + (lane >> 5)) * D_ + gcol0 + (lane & 31) * 4;
; #pragma unroll
;     for (int pc = 0; pc < 8; ++pc)
;       __builtin_amdgcn_global_load_lds((const unsigned*)(xsrc + (size_t)(2 * pc) * D_), (__attribute__((address_space(3))) unsigned*)(xs + pc * 1024), 16, 0, 0);
;   }
	s_waitcnt lgkmcnt(0)
	v_readlane_b32 s3, v253, 9
	v_readlane_b32 s6, v253, 27
	v_readfirstlane_b32 s2, v134
	v_or_b32_e32 v130, s3, v135
	v_add_u32_e32 v130, v130, v169
	v_ashrrev_i32_e32 v131, 31, v130
	v_lshlrev_b64 v[130:131], 12, v[130:131]
	v_add_u32_e32 v132, s6, v164
	v_ashrrev_i32_e32 v133, 31, v132
	v_lshl_add_u64 v[130:131], s[10:11], 0, v[130:131]
	v_lshlrev_b32_e32 v0, 4, v0
	s_lshl_b32 s2, s2, 13
	v_lshl_add_u64 v[130:131], v[132:133], 2, v[130:131]
	v_and_b32_e32 v132, 0x1f0, v0
	v_mov_b32_e32 v133, v1
	v_lshl_add_u64 v[130:131], v[130:131], 0, v[132:133]
	s_mov_b32 m0, s2
	s_mov_b64 s[34:35], 0x2000
	global_load_lds_dwordx4 v[130:131], off
	v_lshl_add_u64 v[132:133], v[130:131], 0, s[34:35]
	s_or_b32 m0, s2, 0x400
	s_mov_b64 s[36:37], 0x4000
	global_load_lds_dwordx4 v[132:133], off
	v_lshl_add_u64 v[132:133], v[130:131], 0, s[36:37]
	s_or_b32 m0, s2, 0x800
	s_mov_b64 s[40:41], 0x6000
	global_load_lds_dwordx4 v[132:133], off
	v_lshl_add_u64 v[132:133], v[130:131], 0, s[40:41]
	s_or_b32 m0, s2, 0xc00
	s_mov_b64 s[44:45], 0x8000
	global_load_lds_dwordx4 v[132:133], off
	v_lshl_add_u64 v[132:133], v[130:131], 0, s[44:45]
	s_or_b32 m0, s2, 0x1000
	s_mov_b64 s[46:47], 0xa000
	global_load_lds_dwordx4 v[132:133], off
	v_lshl_add_u64 v[132:133], v[130:131], 0, s[46:47]
	s_or_b32 m0, s2, 0x1400
	s_mov_b64 s[52:53], 0xc000
	global_load_lds_dwordx4 v[132:133], off
	v_lshl_add_u64 v[132:133], v[130:131], 0, s[52:53]
	s_or_b32 m0, s2, 0x1800
	s_mov_b64 s[54:55], 0xe000
	global_load_lds_dwordx4 v[132:133], off
	v_lshl_add_u64 v[130:131], v[130:131], 0, s[54:55]
	s_or_b32 m0, s2, 0x1c00
	v_add_u32_e32 v0, s30, v136
	global_load_lds_dwordx4 v[130:131], off
	v_add_u32_e32 v134, s30, v144
	v_add_u32_e32 v130, v0, v143
	v_add_u32_e32 v135, v134, v146
	s_waitcnt vmcnt(0)
	ds_read_b128 v[130:133], v130
	ds_read_b128 v[170:173], v135
	v_add_u32_e32 v135, s30, v145
	v_add_u32_e32 v136, v135, v151
	v_add_u32_e32 v143, s30, v152
	v_add_u32_e32 v144, v143, v156
	ds_read_b128 v[174:177], v136 offset:32768
	ds_read_b128 v[178:181], v144 offset:32768
	v_add_u32_e32 v136, s30, v155
	v_add_u32_e32 v144, v136, v157
	v_add_u32_e32 v164, s30, v158
	v_add_u32_e32 v145, v164, v168
	ds_read_b128 v[182:185], v144 offset:32768
	ds_read_b128 v[186:189], v145 offset:32768
	v_add_u32_e32 v144, v0, v166
	v_add_u32_e32 v145, v134, v167
	ds_read_b128 v[166:169], v144
	ds_read_b128 v[190:193], v145
	v_add_u32_e32 v144, v135, v161
	v_add_u32_e32 v145, v143, v163
	ds_read_b128 v[194:197], v144 offset:32768
	ds_read_b128 v[198:201], v145 offset:32768
	v_add_u32_e32 v144, v136, v159
	v_add_u32_e32 v145, v164, v160
	ds_read_b128 v[156:159], v144 offset:32768
	ds_read_b128 v[202:205], v145 offset:32768
	v_readlane_b32 s7, v253, 28
	s_setprio 1
	s_waitcnt lgkmcnt(0)
	v_mfma_f32_32x32x16_bf16 v[114:129], v[130:133], v[174:177], v[114:129]
	v_mfma_f32_32x32x16_bf16 v[98:113], v[130:133], v[178:181], v[98:113]
	v_mfma_f32_32x32x16_bf16 v[82:97], v[130:133], v[182:185], v[82:97]
	v_mfma_f32_32x32x16_bf16 v[66:81], v[130:133], v[186:189], v[66:81]
	v_mfma_f32_32x32x16_bf16 v[50:65], v[170:173], v[174:177], v[50:65]
	v_mfma_f32_32x32x16_bf16 v[34:49], v[170:173], v[178:181], v[34:49]
	v_mfma_f32_32x32x16_bf16 v[18:33], v[170:173], v[182:185], v[18:33]
	v_mfma_f32_32x32x16_bf16 v[2:17], v[170:173], v[186:189], v[2:17]
	s_setprio 0
	v_add_u32_e32 v130, v0, v153
	v_add_u32_e32 v144, v134, v154
	ds_read_b128 v[130:133], v130
	ds_read_b128 v[152:155], v144
	v_add_u32_e32 v144, v135, v149
	v_add_u32_e32 v145, v143, v150
	ds_read_b128 v[170:173], v144 offset:32768
	ds_read_b128 v[174:177], v145 offset:32768
	v_add_u32_e32 v144, v136, v147
	v_add_u32_e32 v148, v164, v148
	ds_read_b128 v[144:147], v144 offset:32768
	ds_read_b128 v[148:151], v148 offset:32768
	s_setprio 1
	v_mfma_f32_32x32x16_bf16 v[114:129], v[166:169], v[194:197], v[114:129]
	v_mfma_f32_32x32x16_bf16 v[98:113], v[166:169], v[198:201], v[98:113]
	v_mfma_f32_32x32x16_bf16 v[82:97], v[166:169], v[156:159], v[82:97]
	v_mfma_f32_32x32x16_bf16 v[66:81], v[166:169], v[202:205], v[66:81]
	v_mfma_f32_32x32x16_bf16 v[50:65], v[190:193], v[194:197], v[50:65]
	v_mfma_f32_32x32x16_bf16 v[34:49], v[190:193], v[198:201], v[34:49]
	v_mfma_f32_32x32x16_bf16 v[18:33], v[190:193], v[156:159], v[18:33]
	v_mfma_f32_32x32x16_bf16 v[2:17], v[190:193], v[202:205], v[2:17]
	s_setprio 0
	v_add_u32_e32 v0, v0, v141
	v_add_u32_e32 v134, v134, v142
	ds_read_b128 v[156:159], v0
	ds_read_b128 v[166:169], v134
	v_add_u32_e32 v0, v135, v139
	v_add_u32_e32 v134, v143, v140
	ds_read_b128 v[140:143], v0 offset:32768
	ds_read_b128 v[178:181], v134 offset:32768
	v_add_u32_e32 v0, v136, v137
	v_add_u32_e32 v138, v164, v138
	ds_read_b128 v[134:137], v0 offset:32768
	ds_read_b128 v[182:185], v138 offset:32768
	s_setprio 1
	s_waitcnt lgkmcnt(9)
	v_mfma_f32_32x32x16_bf16 v[114:129], v[130:133], v[170:173], v[114:129]
	s_waitcnt lgkmcnt(8)
	v_mfma_f32_32x32x16_bf16 v[98:113], v[130:133], v[174:177], v[98:113]
	s_waitcnt lgkmcnt(7)
	v_mfma_f32_32x32x16_bf16 v[82:97], v[130:133], v[144:147], v[82:97]
	s_waitcnt lgkmcnt(6)
	v_mfma_f32_32x32x16_bf16 v[66:81], v[130:133], v[148:151], v[66:81]
	v_mfma_f32_32x32x16_bf16 v[50:65], v[152:155], v[170:173], v[50:65]
	v_mfma_f32_32x32x16_bf16 v[34:49], v[152:155], v[174:177], v[34:49]
	v_mfma_f32_32x32x16_bf16 v[18:33], v[152:155], v[144:147], v[18:33]
	v_mfma_f32_32x32x16_bf16 v[2:17], v[152:155], v[148:151], v[2:17]
	s_setprio 0
	s_setprio 1
	s_waitcnt lgkmcnt(3)
	v_mfma_f32_32x32x16_bf16 v[114:129], v[156:159], v[140:143], v[114:129]
	s_waitcnt lgkmcnt(2)
	v_mfma_f32_32x32x16_bf16 v[98:113], v[156:159], v[178:181], v[98:113]
	s_waitcnt lgkmcnt(1)
	v_mfma_f32_32x32x16_bf16 v[82:97], v[156:159], v[134:137], v[82:97]
	s_waitcnt lgkmcnt(0)
	v_mfma_f32_32x32x16_bf16 v[66:81], v[156:159], v[182:185], v[66:81]
	v_mfma_f32_32x32x16_bf16 v[50:65], v[166:169], v[140:143], v[50:65]
	v_mfma_f32_32x32x16_bf16 v[34:49], v[166:169], v[178:181], v[34:49]
	v_mfma_f32_32x32x16_bf16 v[18:33], v[166:169], v[134:137], v[18:33]
	v_mfma_f32_32x32x16_bf16 v[2:17], v[166:169], v[182:185], v[2:17]
	s_setprio 0
	v_mov_b32_e32 v164, v216
	s_waitcnt vmcnt(0)
	s_barrier
;   DI void xpass(int ps, int grow0, int gcol0, int lane, int w, char* lds) const {
;     char* xs = lds + (ps & 1) * 65536 + __builtin_amdgcn_readfirstlane(w) * 8192;
;     const float* xsrc = Xin + (size_t)(grow0 + (ps >> 1) * 32 + (ps & 1) * 16 + (lane >> 5)) * D_ + gcol0 + (lane & 31) * 4;
; #pragma unroll
;     for (int pc = 0; pc < 8; ++pc)
;       __builtin_amdgcn_global_load_lds((const unsigned*)(xsrc + (size_t)(2 * pc) * D_), (__attribute__((address_space(3))) unsigned*)(xs + pc * 1024), 16, 0, 0);
;   }
;   DI void operator()(f32x16 (&acc)[2][4], int grow0, int gcol0, int lane, int w, char* lds) {
;     ...
;     for (int ps = 0; ps < 4; ++ps) {
;       const int mt = ps >> 1;
;       if (ps + 1 < 4) {
;         if (ps >= 1) asm volatile("s_waitcnt lgkmcnt(0)" ::: "memory");
;         xpass(ps + 1, grow0, gcol0, lane, w, lds);
;         if (ps >= 1) asm volatile("s_waitcnt vmcnt(8)" ::: "memory");
;       } else asm volatile("s_waitcnt vmcnt(0)" ::: "memory");
;       const char* xs = lds + (ps & 1) * 65536 + w * 8192;
; #pragma unroll
;       for (int qq = 0; qq < 2; ++qq)
; #pragma unroll
;         for (int e = 0; e < 4; ++e) {
;           const int i = 4 * (2 * (ps & 1) + qq) + e;
;           const float* xr = (const float*)(xs + (8 * qq + 4 * hh + e) * 512) + l31;
;           float s1 = 0.f, s2 = 0.f;
; #pragma unroll
;           for (int nt = 0; nt < 4; ++nt) {
;             float v = (acc[mt][nt][i] + bia[nt]) * csc[nt];
;             float z = ALPHA * xr[nt * 32] + hs * v;
;             acc[mt][nt][i] = z; s1 += z; s2 += z * z;
;           }
;           s1 = row16_sum(s1); s2 = row16_sum(s2);
;           if ((lane & 15) == 0) { f32x2 sv = {s1, s2}; *(f32x2*)(redw + (mt * 32 + (i & 3) + 8 * (i >> 2)) * 2) = sv; }
;         }
	v_mov_b32_e32 v133, v1
	v_ashrrev_i32_e32 v158, 6, v164
	v_lshrrev_b32_e32 v0, 30, v158
	v_add_u32_e32 v0, v158, v0
	v_ashrrev_i32_e32 v134, 2, v0
	v_mul_i32_i24_e32 v0, 4, v134
	v_sub_u32_e32 v0, v158, v0
	v_lshlrev_b32_e32 v135, 6, v0
	v_add_u32_e32 v163, s3, v135
	v_bfe_u32 v0, v164, 5, 1
	v_or_b32_e32 v159, v163, v0
	v_or_b32_e32 v130, 16, v159
	v_lshlrev_b32_e32 v200, 2, v164
	v_ashrrev_i32_e32 v131, 31, v130
	v_lshl_add_u32 v184, v134, 7, s6
	v_and_b32_e32 v0, 0x7c, v200
	v_lshlrev_b64 v[130:131], 12, v[130:131]
	v_ashrrev_i32_e32 v185, 31, v184
	v_readfirstlane_b32 s2, v158
	v_lshl_add_u64 v[130:131], s[10:11], 0, v[130:131]
	v_lshlrev_b32_e32 v0, 2, v0
	s_lshl_b32 s2, s2, 13
	v_lshl_add_u64 v[130:131], v[184:185], 2, v[130:131]
	v_mov_b32_e32 v132, v0
	s_add_i32 m0, s2, 0x10000
	v_lshl_add_u64 v[130:131], v[130:131], 0, v[132:133]
	global_load_lds_dwordx4 v[130:131], off
	v_lshl_add_u64 v[132:133], v[130:131], 0, s[34:35]
	s_add_i32 m0, s2, 0x10400
	v_and_b32_e32 v210, 0xc0, v135
	global_load_lds_dwordx4 v[132:133], off
	v_lshl_add_u64 v[132:133], v[130:131], 0, s[36:37]
	s_add_i32 m0, s2, 0x10800
	v_mov_b32_e32 v136, v114
	global_load_lds_dwordx4 v[132:133], off
	v_lshl_add_u64 v[132:133], v[130:131], 0, s[40:41]
	s_add_i32 m0, s2, 0x10c00
	v_mov_b32_e32 v137, v82
	global_load_lds_dwordx4 v[132:133], off
	v_lshl_add_u64 v[132:133], v[130:131], 0, s[44:45]
	s_add_i32 m0, s2, 0x11000
	v_mov_b32_e32 v140, v98
	global_load_lds_dwordx4 v[132:133], off
	v_lshl_add_u64 v[132:133], v[130:131], 0, s[46:47]
	s_add_i32 m0, s2, 0x11400
	v_mov_b32_e32 v141, v82
	global_load_lds_dwordx4 v[132:133], off
	v_lshl_add_u64 v[132:133], v[130:131], 0, s[52:53]
	s_add_i32 m0, s2, 0x11800
	v_lshl_add_u64 v[130:131], v[130:131], 0, s[54:55]
	global_load_lds_dwordx4 v[132:133], off
	s_add_i32 m0, s2, 0x11c00
	v_bfe_u32 v132, v164, 4, 1
	global_load_lds_dwordx4 v[130:131], off
	v_and_b32_e32 v130, 31, v164
	v_lshlrev_b32_e32 v131, 1, v134
	v_bfe_u32 v134, v164, 3, 3
	v_and_or_b32 v131, v131, 2, v132
	v_and_b32_e32 v132, 4, v134
	v_lshlrev_b32_e32 v130, 2, v130
	v_lshl_or_b32 v138, v158, 13, v130
	v_lshlrev_b32_e32 v154, 9, v132
	v_or_b32_e32 v133, v210, v132
	v_and_b32_e32 v130, 15, v164
	v_or_b32_e32 v132, v138, v154
	v_lshlrev_b32_e32 v135, 3, v133
	v_lshl_or_b32 v139, v131, 11, v221
	v_cmp_eq_u32_e32 vcc, 0, v130
	s_waitcnt vmcnt(8)
	ds_read2_b32 v[130:131], v132 offset1:32
	ds_read2_b32 v[132:133], v132 offset0:64 offset1:96
	v_pk_add_f32 v[136:137], v[136:137], 0 op_sel_hi:[1,0]
	v_pk_add_f32 v[140:141], v[140:141], 0 op_sel_hi:[1,0]
	s_mov_b32 s2, s67
	s_waitcnt lgkmcnt(0)
	v_mov_b32_e32 v142, v130
	v_mov_b32_e32 v143, v132
	v_mov_b32_e32 v130, v131
	v_mov_b32_e32 v131, v132
	v_pk_fma_f32 v[186:187], v[142:143], s[2:3], v[136:137] op_sel_hi:[1,0,1]
	v_pk_fma_f32 v[188:189], v[130:131], s[2:3], v[140:141] op_sel_hi:[1,0,1]
	v_pk_mul_f32 v[144:145], v[142:143], s[2:3] op_sel_hi:[1,0]
	v_pk_mul_f32 v[142:143], v[186:187], v[186:187]
	v_pk_mul_f32 v[130:131], v[188:189], v[188:189]
	v_pk_mov_b32 v[136:137], v[136:137], v[142:143] op_sel:[1,0]
	v_pk_mov_b32 v[130:131], v[144:145], v[130:131] op_sel:[1,0]
	v_add_f32_e32 v180, 0, v66
	v_pk_add_f32 v[130:131], v[136:137], v[130:131]
	v_pk_add_f32 v[136:137], v[186:187], v[188:189]
	v_pk_mul_f32 v[140:141], v[186:187], v[188:189]
	v_fmac_f32_e32 v180, 0x3fd744fd, v133
	v_mov_b32_e32 v137, v141
	v_pk_add_f32 v[130:131], v[136:137], v[130:131]
	v_mul_f32_e32 v181, v180, v180
	v_pk_add_f32 v[130:131], v[130:131], v[180:181]
	v_add_u32_e32 v181, v139, v135
	s_nop 0
	v_mov_b32_dpp v132, v130 quad_perm:[1,0,3,2] row_mask:0xf bank_mask:0xf bound_ctrl:1
	v_mov_b32_dpp v133, v131 quad_perm:[1,0,3,2] row_mask:0xf bank_mask:0xf bound_ctrl:1
	v_pk_add_f32 v[130:131], v[130:131], v[132:133]
	s_nop 1
	v_mov_b32_dpp v132, v130 quad_perm:[2,3,0,1] row_mask:0xf bank_mask:0xf bound_ctrl:1
	v_mov_b32_dpp v133, v131 quad_perm:[2,3,0,1] row_mask:0xf bank_mask:0xf bound_ctrl:1
	v_pk_add_f32 v[130:131], v[130:131], v[132:133]
	s_nop 1
	v_mov_b32_dpp v132, v130 row_half_mirror row_mask:0xf bank_mask:0xf bound_ctrl:1
	v_mov_b32_dpp v133, v131 row_half_mirror row_mask:0xf bank_mask:0xf bound_ctrl:1
	v_pk_add_f32 v[130:131], v[130:131], v[132:133]
	s_nop 1
	v_mov_b32_dpp v132, v130 row_mirror row_mask:0xf bank_mask:0xf bound_ctrl:1
	v_mov_b32_dpp v133, v131 row_mirror row_mask:0xf bank_mask:0xf bound_ctrl:1
	s_and_saveexec_b64 s[6:7], vcc
	v_pk_add_f32 v[130:131], v[130:131], v[132:133]
	ds_write_b64 v181, v[130:131]
	s_or_b64 exec, exec, s[6:7]
	v_add_u32_e32 v168, v138, v154
	ds_read2_b32 v[130:131], v168 offset0:128 offset1:160
	ds_read2_b32 v[132:133], v168 offset0:192 offset1:224
	v_mov_b32_e32 v82, v115
	v_add_f32_e32 v152, 0, v67
	v_pk_add_f32 v[66:67], v[82:83], 0 op_sel_hi:[1,0]
	v_mov_b32_e32 v82, v99
	v_pk_add_f32 v[82:83], v[82:83], 0 op_sel_hi:[1,0]
	s_waitcnt lgkmcnt(1)
	v_mov_b32_e32 v98, v130
	s_waitcnt lgkmcnt(0)
;   DI void operator()(f32x16 (&acc)[2][4], int grow0, int gcol0, int lane, int w, char* lds) {
;     ...
;       for (int qq = 0; qq < 2; ++qq)
; #pragma unroll
;         for (int e = 0; e < 4; ++e) {
;           const int i = 4 * (2 * (ps & 1) + qq) + e;
;           const float* xr = (const float*)(xs + (8 * qq + 4 * hh + e) * 512) + l31;
;           float s1 = 0.f, s2 = 0.f;
; #pragma unroll
;           for (int nt = 0; nt < 4; ++nt) {
;             float v = (acc[mt][nt][i] + bia[nt]) * csc[nt];
;             float z = ALPHA * xr[nt * 32] + hs * v;
;             acc[mt][nt][i] = z; s1 += z; s2 += z * z;
;           }
;           s1 = row16_sum(s1); s2 = row16_sum(s2);
;           if ((lane & 15) == 0) { f32x2 sv = {s1, s2}; *(f32x2*)(redw + (mt * 32 + (i & 3) + 8 * (i >> 2)) * 2) = sv; }
;         }
	v_mov_b32_e32 v99, v132
	s_mov_b32 s2, s67
	v_mov_b32_e32 v130, v131
	v_mov_b32_e32 v131, v132
	v_pk_fma_f32 v[166:167], v[98:99], s[2:3], v[66:67] op_sel_hi:[1,0,1]
	v_pk_fma_f32 v[172:173], v[130:131], s[2:3], v[82:83] op_sel_hi:[1,0,1]
	v_pk_mul_f32 v[114:115], v[98:99], s[2:3] op_sel_hi:[1,0]
	v_pk_mul_f32 v[98:99], v[166:167], v[166:167]
	v_pk_mul_f32 v[82:83], v[172:173], v[172:173]
	v_pk_mov_b32 v[66:67], v[66:67], v[98:99] op_sel:[1,0]
	v_pk_mov_b32 v[82:83], v[114:115], v[82:83] op_sel:[1,0]
	v_pk_mul_f32 v[98:99], v[166:167], v[172:173]
	v_pk_add_f32 v[66:67], v[66:67], v[82:83]
	v_pk_add_f32 v[82:83], v[166:167], v[172:173]
	v_fmac_f32_e32 v152, 0x3fd744fd, v133
	v_mov_b32_e32 v83, v99
	v_pk_add_f32 v[66:67], v[82:83], v[66:67]
	v_mul_f32_e32 v153, v152, v152
	v_pk_add_f32 v[66:67], v[66:67], v[152:153]
	s_nop 1
	v_mov_b32_dpp v82, v66 quad_perm:[1,0,3,2] row_mask:0xf bank_mask:0xf bound_ctrl:1
	v_mov_b32_dpp v83, v67 quad_perm:[1,0,3,2] row_mask:0xf bank_mask:0xf bound_ctrl:1
	v_pk_add_f32 v[66:67], v[66:67], v[82:83]
	s_nop 1
	v_mov_b32_dpp v82, v66 quad_perm:[2,3,0,1] row_mask:0xf bank_mask:0xf bound_ctrl:1
	v_mov_b32_dpp v83, v67 quad_perm:[2,3,0,1] row_mask:0xf bank_mask:0xf bound_ctrl:1
	v_pk_add_f32 v[66:67], v[66:67], v[82:83]
	s_nop 1
	v_mov_b32_dpp v82, v66 row_half_mirror row_mask:0xf bank_mask:0xf bound_ctrl:1
	v_mov_b32_dpp v83, v67 row_half_mirror row_mask:0xf bank_mask:0xf bound_ctrl:1
	v_pk_add_f32 v[66:67], v[66:67], v[82:83]
	s_nop 1
	v_mov_b32_dpp v82, v66 row_mirror row_mask:0xf bank_mask:0xf bound_ctrl:1
	v_mov_b32_dpp v83, v67 row_mirror row_mask:0xf bank_mask:0xf bound_ctrl:1
	s_and_saveexec_b64 s[6:7], vcc
	v_pk_add_f32 v[66:67], v[66:67], v[82:83]
	ds_write_b64 v181, v[66:67] offset:8
	s_or_b64 exec, exec, s[6:7]
	v_add_u32_e32 v153, 0x400, v168
	ds_read2_b32 v[82:83], v153 offset1:32
	ds_read2_b32 v[98:99], v153 offset0:64 offset1:96
	v_mov_b32_e32 v114, v116
	v_mov_b32_e32 v115, v84
	v_mov_b32_e32 v130, v100
	v_mov_b32_e32 v131, v84
	v_pk_add_f32 v[114:115], v[114:115], 0 op_sel_hi:[1,0]
	v_pk_add_f32 v[130:131], v[130:131], 0 op_sel_hi:[1,0]
	s_waitcnt lgkmcnt(1)
	v_mov_b32_e32 v132, v82
	s_waitcnt lgkmcnt(0)
	v_mov_b32_e32 v133, v98
	s_mov_b32 s2, s67
	v_mov_b32_e32 v140, v83
	v_mov_b32_e32 v141, v98
	v_pk_fma_f32 v[82:83], v[132:133], s[2:3], v[114:115] op_sel_hi:[1,0,1]
	v_pk_fma_f32 v[150:151], v[140:141], s[2:3], v[130:131] op_sel_hi:[1,0,1]
	v_pk_mul_f32 v[136:137], v[132:133], s[2:3] op_sel_hi:[1,0]
	v_pk_mul_f32 v[132:133], v[82:83], v[82:83]
	v_pk_mul_f32 v[130:131], v[150:151], v[150:151]
	v_pk_mov_b32 v[114:115], v[114:115], v[132:133] op_sel:[1,0]
	v_pk_mov_b32 v[130:131], v[136:137], v[130:131] op_sel:[1,0]
	v_add_f32_e32 v66, 0, v68
	v_pk_add_f32 v[114:115], v[114:115], v[130:131]
	v_pk_add_f32 v[130:131], v[82:83], v[150:151]
	v_pk_mul_f32 v[132:133], v[82:83], v[150:151]
	v_fmac_f32_e32 v66, 0x3fd744fd, v99
	v_mov_b32_e32 v131, v133
	v_pk_add_f32 v[114:115], v[130:131], v[114:115]
	v_mul_f32_e32 v67, v66, v66
	v_pk_add_f32 v[98:99], v[114:115], v[66:67]
	s_nop 1
	v_mov_b32_dpp v114, v98 quad_perm:[1,0,3,2] row_mask:0xf bank_mask:0xf bound_ctrl:1
	v_mov_b32_dpp v115, v99 quad_perm:[1,0,3,2] row_mask:0xf bank_mask:0xf bound_ctrl:1
	v_pk_add_f32 v[98:99], v[98:99], v[114:115]
	s_nop 1
	v_mov_b32_dpp v114, v98 quad_perm:[2,3,0,1] row_mask:0xf bank_mask:0xf bound_ctrl:1
	v_mov_b32_dpp v115, v99 quad_perm:[2,3,0,1] row_mask:0xf bank_mask:0xf bound_ctrl:1
	v_pk_add_f32 v[98:99], v[98:99], v[114:115]
	s_nop 1
	v_mov_b32_dpp v114, v98 row_half_mirror row_mask:0xf bank_mask:0xf bound_ctrl:1
	v_mov_b32_dpp v115, v99 row_half_mirror row_mask:0xf bank_mask:0xf bound_ctrl:1
	v_pk_add_f32 v[98:99], v[98:99], v[114:115]
	s_nop 1
	v_mov_b32_dpp v114, v98 row_mirror row_mask:0xf bank_mask:0xf bound_ctrl:1
	v_mov_b32_dpp v115, v99 row_mirror row_mask:0xf bank_mask:0xf bound_ctrl:1
	s_and_saveexec_b64 s[6:7], vcc
	v_pk_add_f32 v[98:99], v[98:99], v[114:115]
	ds_write_b64 v181, v[98:99] offset:16
	s_or_b64 exec, exec, s[6:7]
	v_lshlrev_b32_e32 v139, 9, v134
	v_or_b32_e32 v146, 0x600, v139
	v_add_u32_e32 v151, v138, v146
	ds_read2_b32 v[98:99], v151 offset1:32
	ds_read2_b32 v[114:115], v151 offset0:64 offset1:96
	v_mov_b32_e32 v84, v117
	v_pk_add_f32 v[116:117], v[84:85], 0 op_sel_hi:[1,0]
	v_mov_b32_e32 v84, v101
	v_pk_add_f32 v[84:85], v[84:85], 0 op_sel_hi:[1,0]
	s_waitcnt lgkmcnt(1)
	v_mov_b32_e32 v100, v98
	s_waitcnt lgkmcnt(0)
	v_mov_b32_e32 v101, v114
	s_mov_b32 s2, s67
	v_mov_b32_e32 v132, v99
	v_mov_b32_e32 v133, v114
	v_pk_mul_f32 v[130:131], v[100:101], s[2:3] op_sel_hi:[1,0]
	v_pk_fma_f32 v[98:99], v[100:101], s[2:3], v[116:117] op_sel_hi:[1,0,1]
	v_pk_fma_f32 v[100:101], v[132:133], s[2:3], v[84:85] op_sel_hi:[1,0,1]
	v_pk_mul_f32 v[134:135], v[98:99], v[98:99]
	v_pk_mul_f32 v[84:85], v[100:101], v[100:101]
	v_pk_mov_b32 v[116:117], v[116:117], v[134:135] op_sel:[1,0]
	v_pk_mov_b32 v[84:85], v[130:131], v[84:85] op_sel:[1,0]
	v_add_f32_e32 v68, 0, v69
	v_pk_add_f32 v[84:85], v[116:117], v[84:85]
	v_pk_add_f32 v[116:117], v[98:99], v[100:101]
	v_pk_mul_f32 v[130:131], v[98:99], v[100:101]
	v_fmac_f32_e32 v68, 0x3fd744fd, v115
	v_mov_b32_e32 v117, v131
	v_pk_add_f32 v[84:85], v[116:117], v[84:85]
	v_mul_f32_e32 v69, v68, v68
	v_pk_add_f32 v[84:85], v[84:85], v[68:69]
	s_nop 1
	v_mov_b32_dpp v114, v84 quad_perm:[1,0,3,2] row_mask:0xf bank_mask:0xf bound_ctrl:1
	v_mov_b32_dpp v115, v85 quad_perm:[1,0,3,2] row_mask:0xf bank_mask:0xf bound_ctrl:1
	v_pk_add_f32 v[84:85], v[84:85], v[114:115]
	s_nop 1
	v_mov_b32_dpp v114, v84 quad_perm:[2,3,0,1] row_mask:0xf bank_mask:0xf bound_ctrl:1
	v_mov_b32_dpp v115, v85 quad_perm:[2,3,0,1] row_mask:0xf bank_mask:0xf bound_ctrl:1
	v_pk_add_f32 v[84:85], v[84:85], v[114:115]
	s_nop 1
	v_mov_b32_dpp v114, v84 row_half_mirror row_mask:0xf bank_mask:0xf bound_ctrl:1
	v_mov_b32_dpp v115, v85 row_half_mirror row_mask:0xf bank_mask:0xf bound_ctrl:1
	v_pk_add_f32 v[84:85], v[84:85], v[114:115]
	s_nop 1
	v_mov_b32_dpp v114, v84 row_mirror row_mask:0xf bank_mask:0xf bound_ctrl:1
	v_mov_b32_dpp v115, v85 row_mirror row_mask:0xf bank_mask:0xf bound_ctrl:1
	s_and_saveexec_b64 s[6:7], vcc
	v_pk_add_f32 v[84:85], v[84:85], v[114:115]
	ds_write_b64 v181, v[84:85] offset:24
	s_or_b64 exec, exec, s[6:7]
	v_add_u32_e32 v67, 0x1000, v168
	ds_read2_b32 v[114:115], v67 offset1:32
	ds_read2_b32 v[130:131], v67 offset0:64 offset1:96
	v_mov_b32_e32 v116, v118
	v_mov_b32_e32 v117, v86
	v_pk_add_f32 v[132:133], v[116:117], 0 op_sel_hi:[1,0]
	v_mov_b32_e32 v116, v102
	v_pk_add_f32 v[116:117], v[116:117], 0 op_sel_hi:[1,0]
	s_waitcnt lgkmcnt(1)
;   DI void operator()(f32x16 (&acc)[2][4], int grow0, int gcol0, int lane, int w, char* lds) {
;     ...
;       for (int qq = 0; qq < 2; ++qq)
; #pragma unroll
;         for (int e = 0; e < 4; ++e) {
;           const int i = 4 * (2 * (ps & 1) + qq) + e;
;           const float* xr = (const float*)(xs + (8 * qq + 4 * hh + e) * 512) + l31;
;           float s1 = 0.f, s2 = 0.f;
; #pragma unroll
;           for (int nt = 0; nt < 4; ++nt) {
;             float v = (acc[mt][nt][i] + bia[nt]) * csc[nt];
;             float z = ALPHA * xr[nt * 32] + hs * v;
;             acc[mt][nt][i] = z; s1 += z; s2 += z * z;
;           }
;           s1 = row16_sum(s1); s2 = row16_sum(s2);
;           if ((lane & 15) == 0) { f32x2 sv = {s1, s2}; *(f32x2*)(redw + (mt * 32 + (i & 3) + 8 * (i >> 2)) * 2) = sv; }
;         }
	v_mov_b32_e32 v134, v114
	s_waitcnt lgkmcnt(0)
	v_mov_b32_e32 v135, v130
	s_mov_b32 s2, s67
	v_mov_b32_e32 v140, v115
	v_mov_b32_e32 v141, v130
	v_pk_fma_f32 v[114:115], v[134:135], s[2:3], v[132:133] op_sel_hi:[1,0,1]
	v_pk_fma_f32 v[116:117], v[140:141], s[2:3], v[116:117] op_sel_hi:[1,0,1]
	v_pk_mul_f32 v[136:137], v[134:135], s[2:3] op_sel_hi:[1,0]
	v_pk_mul_f32 v[134:135], v[114:115], v[114:115]
	v_pk_mul_f32 v[140:141], v[116:117], v[116:117]
	v_pk_mov_b32 v[132:133], v[132:133], v[134:135] op_sel:[1,0]
	v_pk_mov_b32 v[134:135], v[136:137], v[140:141] op_sel:[1,0]
	v_add_f32_e32 v84, 0, v70
	v_pk_add_f32 v[132:133], v[132:133], v[134:135]
	v_pk_add_f32 v[134:135], v[114:115], v[116:117]
	v_pk_mul_f32 v[136:137], v[114:115], v[116:117]
	v_fmac_f32_e32 v84, 0x3fd744fd, v131
	v_mov_b32_e32 v135, v137
	v_pk_add_f32 v[132:133], v[134:135], v[132:133]
	v_mul_f32_e32 v85, v84, v84
	v_pk_add_f32 v[130:131], v[132:133], v[84:85]
	s_nop 1
	v_mov_b32_dpp v132, v130 quad_perm:[1,0,3,2] row_mask:0xf bank_mask:0xf bound_ctrl:1
	v_mov_b32_dpp v133, v131 quad_perm:[1,0,3,2] row_mask:0xf bank_mask:0xf bound_ctrl:1
	v_pk_add_f32 v[130:131], v[130:131], v[132:133]
	s_nop 1
	v_mov_b32_dpp v132, v130 quad_perm:[2,3,0,1] row_mask:0xf bank_mask:0xf bound_ctrl:1
	v_mov_b32_dpp v133, v131 quad_perm:[2,3,0,1] row_mask:0xf bank_mask:0xf bound_ctrl:1
	v_pk_add_f32 v[130:131], v[130:131], v[132:133]
	s_nop 1
	v_mov_b32_dpp v132, v130 row_half_mirror row_mask:0xf bank_mask:0xf bound_ctrl:1
	v_mov_b32_dpp v133, v131 row_half_mirror row_mask:0xf bank_mask:0xf bound_ctrl:1
	v_pk_add_f32 v[130:131], v[130:131], v[132:133]
	s_nop 1
	v_mov_b32_dpp v132, v130 row_mirror row_mask:0xf bank_mask:0xf bound_ctrl:1
	v_mov_b32_dpp v133, v131 row_mirror row_mask:0xf bank_mask:0xf bound_ctrl:1
	s_and_saveexec_b64 s[6:7], vcc
	v_pk_add_f32 v[130:131], v[130:131], v[132:133]
	ds_write_b64 v181, v[130:131] offset:64
	s_or_b64 exec, exec, s[6:7]
	ds_read2_b32 v[130:131], v67 offset0:128 offset1:160
	ds_read2_b32 v[132:133], v67 offset0:192 offset1:224
	v_mov_b32_e32 v86, v119
	v_pk_add_f32 v[134:135], v[86:87], 0 op_sel_hi:[1,0]
	v_mov_b32_e32 v86, v103
	v_pk_add_f32 v[86:87], v[86:87], 0 op_sel_hi:[1,0]
	s_waitcnt lgkmcnt(1)
	v_mov_b32_e32 v102, v130
	s_waitcnt lgkmcnt(0)
	v_mov_b32_e32 v103, v132
	s_mov_b32 s2, s67
	v_mov_b32_e32 v118, v131
	v_mov_b32_e32 v119, v132
	v_pk_mul_f32 v[136:137], v[102:103], s[2:3] op_sel_hi:[1,0]
	v_pk_fma_f32 v[102:103], v[102:103], s[2:3], v[134:135] op_sel_hi:[1,0,1]
	v_pk_fma_f32 v[118:119], v[118:119], s[2:3], v[86:87] op_sel_hi:[1,0,1]
	v_pk_mul_f32 v[130:131], v[102:103], v[102:103]
	v_pk_mul_f32 v[86:87], v[118:119], v[118:119]
	v_pk_mov_b32 v[130:131], v[134:135], v[130:131] op_sel:[1,0]
	v_pk_mov_b32 v[86:87], v[136:137], v[86:87] op_sel:[1,0]
	v_add_f32_e32 v70, 0, v71
	v_pk_add_f32 v[86:87], v[130:131], v[86:87]
	v_pk_add_f32 v[130:131], v[102:103], v[118:119]
	v_pk_mul_f32 v[134:135], v[102:103], v[118:119]
	v_fmac_f32_e32 v70, 0x3fd744fd, v133
	v_mov_b32_e32 v131, v135
	v_pk_add_f32 v[86:87], v[130:131], v[86:87]
	v_mul_f32_e32 v71, v70, v70
	v_pk_add_f32 v[86:87], v[86:87], v[70:71]
	s_nop 1
	v_mov_b32_dpp v130, v86 quad_perm:[1,0,3,2] row_mask:0xf bank_mask:0xf bound_ctrl:1
	v_mov_b32_dpp v131, v87 quad_perm:[1,0,3,2] row_mask:0xf bank_mask:0xf bound_ctrl:1
	v_pk_add_f32 v[86:87], v[86:87], v[130:131]
	s_nop 1
	v_mov_b32_dpp v130, v86 quad_perm:[2,3,0,1] row_mask:0xf bank_mask:0xf bound_ctrl:1
	v_mov_b32_dpp v131, v87 quad_perm:[2,3,0,1] row_mask:0xf bank_mask:0xf bound_ctrl:1
	v_pk_add_f32 v[86:87], v[86:87], v[130:131]
	s_nop 1
	v_mov_b32_dpp v130, v86 row_half_mirror row_mask:0xf bank_mask:0xf bound_ctrl:1
	v_mov_b32_dpp v131, v87 row_half_mirror row_mask:0xf bank_mask:0xf bound_ctrl:1
	v_pk_add_f32 v[86:87], v[86:87], v[130:131]
	s_nop 1
	v_mov_b32_dpp v130, v86 row_mirror row_mask:0xf bank_mask:0xf bound_ctrl:1
	v_mov_b32_dpp v131, v87 row_mirror row_mask:0xf bank_mask:0xf bound_ctrl:1
	s_and_saveexec_b64 s[6:7], vcc
	v_pk_add_f32 v[86:87], v[86:87], v[130:131]
	ds_write_b64 v181, v[86:87] offset:72
	s_or_b64 exec, exec, s[6:7]
	v_add_u32_e32 v69, 0x1400, v168
	ds_read2_b32 v[130:131], v69 offset1:32
	ds_read2_b32 v[134:135], v69 offset0:64 offset1:96
	v_mov_b32_e32 v132, v120
	v_mov_b32_e32 v133, v88
	v_pk_add_f32 v[136:137], v[132:133], 0 op_sel_hi:[1,0]
	v_mov_b32_e32 v132, v104
	v_pk_add_f32 v[132:133], v[132:133], 0 op_sel_hi:[1,0]
	s_waitcnt lgkmcnt(1)
	v_mov_b32_e32 v140, v130
	s_waitcnt lgkmcnt(0)
	v_mov_b32_e32 v141, v134
	s_mov_b32 s2, s67
	v_mov_b32_e32 v144, v131
	v_mov_b32_e32 v145, v134
	v_pk_fma_f32 v[130:131], v[140:141], s[2:3], v[136:137] op_sel_hi:[1,0,1]
	v_pk_fma_f32 v[132:133], v[144:145], s[2:3], v[132:133] op_sel_hi:[1,0,1]
	v_pk_mul_f32 v[142:143], v[140:141], s[2:3] op_sel_hi:[1,0]
	v_pk_mul_f32 v[140:141], v[130:131], v[130:131]
	v_pk_mul_f32 v[144:145], v[132:133], v[132:133]
	v_pk_mov_b32 v[136:137], v[136:137], v[140:141] op_sel:[1,0]
	v_pk_mov_b32 v[140:141], v[142:143], v[144:145] op_sel:[1,0]
	v_add_f32_e32 v86, 0, v72
	v_pk_add_f32 v[136:137], v[136:137], v[140:141]
	v_pk_add_f32 v[140:141], v[130:131], v[132:133]
	v_pk_mul_f32 v[142:143], v[130:131], v[132:133]
	v_fmac_f32_e32 v86, 0x3fd744fd, v135
	v_mov_b32_e32 v141, v143
	v_pk_add_f32 v[136:137], v[140:141], v[136:137]
	v_mul_f32_e32 v87, v86, v86
	v_pk_add_f32 v[134:135], v[136:137], v[86:87]
	s_nop 1
	v_mov_b32_dpp v136, v134 quad_perm:[1,0,3,2] row_mask:0xf bank_mask:0xf bound_ctrl:1
	v_mov_b32_dpp v137, v135 quad_perm:[1,0,3,2] row_mask:0xf bank_mask:0xf bound_ctrl:1
	v_pk_add_f32 v[134:135], v[134:135], v[136:137]
	s_nop 1
	v_mov_b32_dpp v136, v134 quad_perm:[2,3,0,1] row_mask:0xf bank_mask:0xf bound_ctrl:1
	v_mov_b32_dpp v137, v135 quad_perm:[2,3,0,1] row_mask:0xf bank_mask:0xf bound_ctrl:1
	v_pk_add_f32 v[134:135], v[134:135], v[136:137]
	s_nop 1
	v_mov_b32_dpp v136, v134 row_half_mirror row_mask:0xf bank_mask:0xf bound_ctrl:1
	v_mov_b32_dpp v137, v135 row_half_mirror row_mask:0xf bank_mask:0xf bound_ctrl:1
	v_pk_add_f32 v[134:135], v[134:135], v[136:137]
	s_nop 1
	v_mov_b32_dpp v136, v134 row_mirror row_mask:0xf bank_mask:0xf bound_ctrl:1
	v_mov_b32_dpp v137, v135 row_mirror row_mask:0xf bank_mask:0xf bound_ctrl:1
	s_and_saveexec_b64 s[6:7], vcc
	v_pk_add_f32 v[134:135], v[134:135], v[136:137]
	ds_write_b64 v181, v[134:135] offset:80
	s_or_b64 exec, exec, s[6:7]
	v_or_b32_e32 v101, 0x1600, v139
	v_add_u32_e32 v71, v138, v101
	ds_read2_b32 v[134:135], v71 offset1:32
	ds_read2_b32 v[136:137], v71 offset0:64 offset1:96
	v_mov_b32_e32 v88, v121
	v_pk_add_f32 v[120:121], v[88:89], 0 op_sel_hi:[1,0]
	v_mov_b32_e32 v88, v105
	v_pk_add_f32 v[104:105], v[88:89], 0 op_sel_hi:[1,0]
	s_waitcnt lgkmcnt(1)
;   DI void operator()(f32x16 (&acc)[2][4], int grow0, int gcol0, int lane, int w, char* lds) {
;     ...
;     for (int ps = 0; ps < 4; ++ps) {
;       const int mt = ps >> 1;
;       if (ps + 1 < 4) {
;         if (ps >= 1) asm volatile("s_waitcnt lgkmcnt(0)" ::: "memory");
;         xpass(ps + 1, grow0, gcol0, lane, w, lds);
;         if (ps >= 1) asm volatile("s_waitcnt vmcnt(8)" ::: "memory");
;       } else asm volatile("s_waitcnt vmcnt(0)" ::: "memory");
;       const char* xs = lds + (ps & 1) * 65536 + w * 8192;
; #pragma unroll
;       for (int qq = 0; qq < 2; ++qq)
; #pragma unroll
;         for (int e = 0; e < 4; ++e) {
;           const int i = 4 * (2 * (ps & 1) + qq) + e;
;           const float* xr = (const float*)(xs + (8 * qq + 4 * hh + e) * 512) + l31;
;           float s1 = 0.f, s2 = 0.f;
; #pragma unroll
;           for (int nt = 0; nt < 4; ++nt) {
;             float v = (acc[mt][nt][i] + bia[nt]) * csc[nt];
;             float z = ALPHA * xr[nt * 32] + hs * v;
;             acc[mt][nt][i] = z; s1 += z; s2 += z * z;
;           }
;           s1 = row16_sum(s1); s2 = row16_sum(s2);
;           if ((lane & 15) == 0) { f32x2 sv = {s1, s2}; *(f32x2*)(redw + (mt * 32 + (i & 3) + 8 * (i >> 2)) * 2) = sv; }
;         }
	v_mov_b32_e32 v88, v134
	s_waitcnt lgkmcnt(0)
	v_mov_b32_e32 v89, v136
	s_mov_b32 s2, s67
	v_mov_b32_e32 v134, v135
	v_mov_b32_e32 v135, v136
	v_pk_mul_f32 v[140:141], v[88:89], s[2:3] op_sel_hi:[1,0]
	v_pk_fma_f32 v[88:89], v[88:89], s[2:3], v[120:121] op_sel_hi:[1,0,1]
	v_pk_fma_f32 v[104:105], v[134:135], s[2:3], v[104:105] op_sel_hi:[1,0,1]
	v_pk_mul_f32 v[142:143], v[88:89], v[88:89]
	v_pk_mul_f32 v[134:135], v[104:105], v[104:105]
	v_pk_mov_b32 v[120:121], v[120:121], v[142:143] op_sel:[1,0]
	v_pk_mov_b32 v[134:135], v[140:141], v[134:135] op_sel:[1,0]
	v_add_f32_e32 v72, 0, v73
	v_pk_add_f32 v[120:121], v[120:121], v[134:135]
	v_pk_add_f32 v[134:135], v[88:89], v[104:105]
	v_pk_mul_f32 v[140:141], v[88:89], v[104:105]
	v_fmac_f32_e32 v72, 0x3fd744fd, v137
	v_mov_b32_e32 v135, v141
	v_pk_add_f32 v[120:121], v[134:135], v[120:121]
	v_mul_f32_e32 v73, v72, v72
	v_pk_add_f32 v[120:121], v[120:121], v[72:73]
	s_nop 1
	v_mov_b32_dpp v134, v120 quad_perm:[1,0,3,2] row_mask:0xf bank_mask:0xf bound_ctrl:1
	v_mov_b32_dpp v135, v121 quad_perm:[1,0,3,2] row_mask:0xf bank_mask:0xf bound_ctrl:1
	v_pk_add_f32 v[120:121], v[120:121], v[134:135]
	s_nop 1
	v_mov_b32_dpp v134, v120 quad_perm:[2,3,0,1] row_mask:0xf bank_mask:0xf bound_ctrl:1
	v_mov_b32_dpp v135, v121 quad_perm:[2,3,0,1] row_mask:0xf bank_mask:0xf bound_ctrl:1
	v_pk_add_f32 v[120:121], v[120:121], v[134:135]
	s_nop 1
	v_mov_b32_dpp v134, v120 row_half_mirror row_mask:0xf bank_mask:0xf bound_ctrl:1
	v_mov_b32_dpp v135, v121 row_half_mirror row_mask:0xf bank_mask:0xf bound_ctrl:1
	v_pk_add_f32 v[120:121], v[120:121], v[134:135]
	s_nop 1
	v_mov_b32_dpp v134, v120 row_mirror row_mask:0xf bank_mask:0xf bound_ctrl:1
	v_mov_b32_dpp v135, v121 row_mirror row_mask:0xf bank_mask:0xf bound_ctrl:1
	s_and_saveexec_b64 s[6:7], vcc
	v_pk_add_f32 v[120:121], v[120:121], v[134:135]
	ds_write_b64 v181, v[120:121] offset:88
	s_or_b64 exec, exec, s[6:7]
	v_or_b32_e32 v120, 32, v159
	v_ashrrev_i32_e32 v121, 31, v120
	v_lshlrev_b64 v[120:121], 12, v[120:121]
	v_readfirstlane_b32 s2, v158
	v_lshl_add_u64 v[120:121], s[10:11], 0, v[120:121]
	s_lshl_b32 s2, s2, 13
	v_lshl_add_u64 v[120:121], v[184:185], 2, v[120:121]
	s_waitcnt lgkmcnt(0)
	v_lshl_add_u64 v[120:121], v[120:121], 0, v[0:1]
	s_mov_b32 m0, s2
	s_mov_b64 s[6:7], 0x2000
	global_load_lds_dwordx4 v[120:121], off
	v_lshl_add_u64 v[134:135], v[120:121], 0, s[6:7]
	s_or_b32 m0, s2, 0x400
	s_mov_b64 s[6:7], 0x4000
	global_load_lds_dwordx4 v[134:135], off
	v_lshl_add_u64 v[134:135], v[120:121], 0, s[6:7]
	s_or_b32 m0, s2, 0x800
	s_mov_b64 s[6:7], 0x6000
	global_load_lds_dwordx4 v[134:135], off
	v_lshl_add_u64 v[134:135], v[120:121], 0, s[6:7]
	s_or_b32 m0, s2, 0xc00
	s_mov_b64 s[6:7], 0x8000
	global_load_lds_dwordx4 v[134:135], off
	v_lshl_add_u64 v[134:135], v[120:121], 0, s[6:7]
	s_or_b32 m0, s2, 0x1000
	s_mov_b64 s[6:7], 0xa000
	global_load_lds_dwordx4 v[134:135], off
	v_lshl_add_u64 v[134:135], v[120:121], 0, s[6:7]
	s_or_b32 m0, s2, 0x1400
	s_mov_b64 s[6:7], 0xc000
	global_load_lds_dwordx4 v[134:135], off
	v_lshl_add_u64 v[134:135], v[120:121], 0, s[6:7]
	s_or_b32 m0, s2, 0x1800
	s_mov_b64 s[6:7], 0xe000
	global_load_lds_dwordx4 v[134:135], off
	v_lshl_add_u64 v[120:121], v[120:121], 0, s[6:7]
	s_or_b32 m0, s2, 0x1c00
	v_add_u32_e32 v105, 0x10000, v138
	global_load_lds_dwordx4 v[120:121], off
	s_waitcnt vmcnt(8)
	v_add_u32_e32 v73, v105, v154
	ds_read2_b32 v[134:135], v73 offset1:32
	ds_read2_b32 v[138:139], v73 offset0:64 offset1:96
	v_mov_b32_e32 v136, v122
	v_mov_b32_e32 v137, v90
	v_pk_add_f32 v[140:141], v[136:137], 0 op_sel_hi:[1,0]
	v_mov_b32_e32 v136, v106
	v_pk_add_f32 v[136:137], v[136:137], 0 op_sel_hi:[1,0]
	s_waitcnt lgkmcnt(0)
	v_mov_b32_e32 v142, v134
	v_mov_b32_e32 v143, v138
	s_mov_b32 s2, s67
	v_mov_b32_e32 v148, v135
	v_mov_b32_e32 v149, v138
	v_pk_fma_f32 v[134:135], v[142:143], s[2:3], v[140:141] op_sel_hi:[1,0,1]
	v_pk_fma_f32 v[136:137], v[148:149], s[2:3], v[136:137] op_sel_hi:[1,0,1]
	v_pk_mul_f32 v[144:145], v[142:143], s[2:3] op_sel_hi:[1,0]
	v_pk_mul_f32 v[142:143], v[134:135], v[134:135]
	v_pk_mul_f32 v[148:149], v[136:137], v[136:137]
	v_pk_mov_b32 v[140:141], v[140:141], v[142:143] op_sel:[1,0]
	v_pk_mov_b32 v[142:143], v[144:145], v[148:149] op_sel:[1,0]
	v_add_f32_e32 v120, 0, v74
	v_pk_add_f32 v[140:141], v[140:141], v[142:143]
	v_pk_add_f32 v[142:143], v[134:135], v[136:137]
	v_pk_mul_f32 v[144:145], v[134:135], v[136:137]
	v_fmac_f32_e32 v120, 0x3fd744fd, v139
	v_mov_b32_e32 v143, v145
	v_pk_add_f32 v[140:141], v[142:143], v[140:141]
	v_mul_f32_e32 v121, v120, v120
	v_pk_add_f32 v[138:139], v[140:141], v[120:121]
	s_nop 1
	v_mov_b32_dpp v140, v138 quad_perm:[1,0,3,2] row_mask:0xf bank_mask:0xf bound_ctrl:1
	v_mov_b32_dpp v141, v139 quad_perm:[1,0,3,2] row_mask:0xf bank_mask:0xf bound_ctrl:1
	v_pk_add_f32 v[138:139], v[138:139], v[140:141]
	s_nop 1
	v_mov_b32_dpp v140, v138 quad_perm:[2,3,0,1] row_mask:0xf bank_mask:0xf bound_ctrl:1
	v_mov_b32_dpp v141, v139 quad_perm:[2,3,0,1] row_mask:0xf bank_mask:0xf bound_ctrl:1
	v_pk_add_f32 v[138:139], v[138:139], v[140:141]
	s_nop 1
	v_mov_b32_dpp v140, v138 row_half_mirror row_mask:0xf bank_mask:0xf bound_ctrl:1
	v_mov_b32_dpp v141, v139 row_half_mirror row_mask:0xf bank_mask:0xf bound_ctrl:1
	v_pk_add_f32 v[138:139], v[138:139], v[140:141]
	s_nop 1
	v_mov_b32_dpp v140, v138 row_mirror row_mask:0xf bank_mask:0xf bound_ctrl:1
	v_mov_b32_dpp v141, v139 row_mirror row_mask:0xf bank_mask:0xf bound_ctrl:1
	s_and_saveexec_b64 s[6:7], vcc
	v_pk_add_f32 v[138:139], v[138:139], v[140:141]
	ds_write_b64 v181, v[138:139] offset:128
	s_or_b64 exec, exec, s[6:7]
	v_or_b32_e32 v74, 0x200, v154
	v_add_u32_e32 v85, v105, v74
	ds_read2_b32 v[138:139], v85 offset1:32
	ds_read2_b32 v[140:141], v85 offset0:64 offset1:96
	v_mov_b32_e32 v90, v123
	v_pk_add_f32 v[142:143], v[90:91], 0 op_sel_hi:[1,0]
	v_mov_b32_e32 v90, v107
	v_pk_add_f32 v[90:91], v[90:91], 0 op_sel_hi:[1,0]
	s_waitcnt lgkmcnt(1)
;   DI void operator()(f32x16 (&acc)[2][4], int grow0, int gcol0, int lane, int w, char* lds) {
;     ...
;       for (int qq = 0; qq < 2; ++qq)
; #pragma unroll
;         for (int e = 0; e < 4; ++e) {
;           const int i = 4 * (2 * (ps & 1) + qq) + e;
;           const float* xr = (const float*)(xs + (8 * qq + 4 * hh + e) * 512) + l31;
;           float s1 = 0.f, s2 = 0.f;
; #pragma unroll
;           for (int nt = 0; nt < 4; ++nt) {
;             float v = (acc[mt][nt][i] + bia[nt]) * csc[nt];
;             float z = ALPHA * xr[nt * 32] + hs * v;
;             acc[mt][nt][i] = z; s1 += z; s2 += z * z;
;           }
;           s1 = row16_sum(s1); s2 = row16_sum(s2);
;           if ((lane & 15) == 0) { f32x2 sv = {s1, s2}; *(f32x2*)(redw + (mt * 32 + (i & 3) + 8 * (i >> 2)) * 2) = sv; }
;         }
	v_mov_b32_e32 v106, v138
	s_waitcnt lgkmcnt(0)
	v_mov_b32_e32 v107, v140
	s_mov_b32 s2, s67
	v_mov_b32_e32 v122, v139
	v_mov_b32_e32 v123, v140
	v_pk_mul_f32 v[144:145], v[106:107], s[2:3] op_sel_hi:[1,0]
	v_pk_fma_f32 v[106:107], v[106:107], s[2:3], v[142:143] op_sel_hi:[1,0,1]
	v_pk_fma_f32 v[122:123], v[122:123], s[2:3], v[90:91] op_sel_hi:[1,0,1]
	v_pk_mul_f32 v[138:139], v[106:107], v[106:107]
	v_pk_mul_f32 v[90:91], v[122:123], v[122:123]
	v_pk_mov_b32 v[138:139], v[142:143], v[138:139] op_sel:[1,0]
	v_pk_mov_b32 v[90:91], v[144:145], v[90:91] op_sel:[1,0]
	v_add_f32_e32 v74, 0, v75
	v_pk_add_f32 v[90:91], v[138:139], v[90:91]
	v_pk_add_f32 v[138:139], v[106:107], v[122:123]
	v_pk_mul_f32 v[142:143], v[106:107], v[122:123]
	v_fmac_f32_e32 v74, 0x3fd744fd, v141
	v_mov_b32_e32 v139, v143
	v_pk_add_f32 v[90:91], v[138:139], v[90:91]
	v_mul_f32_e32 v75, v74, v74
	v_pk_add_f32 v[90:91], v[90:91], v[74:75]
	s_nop 1
	v_mov_b32_dpp v138, v90 quad_perm:[1,0,3,2] row_mask:0xf bank_mask:0xf bound_ctrl:1
	v_mov_b32_dpp v139, v91 quad_perm:[1,0,3,2] row_mask:0xf bank_mask:0xf bound_ctrl:1
	v_pk_add_f32 v[90:91], v[90:91], v[138:139]
	s_nop 1
	v_mov_b32_dpp v138, v90 quad_perm:[2,3,0,1] row_mask:0xf bank_mask:0xf bound_ctrl:1
	v_mov_b32_dpp v139, v91 quad_perm:[2,3,0,1] row_mask:0xf bank_mask:0xf bound_ctrl:1
	v_pk_add_f32 v[90:91], v[90:91], v[138:139]
	s_nop 1
	v_mov_b32_dpp v138, v90 row_half_mirror row_mask:0xf bank_mask:0xf bound_ctrl:1
	v_mov_b32_dpp v139, v91 row_half_mirror row_mask:0xf bank_mask:0xf bound_ctrl:1
	v_pk_add_f32 v[90:91], v[90:91], v[138:139]
	s_nop 1
	v_mov_b32_dpp v138, v90 row_mirror row_mask:0xf bank_mask:0xf bound_ctrl:1
	v_mov_b32_dpp v139, v91 row_mirror row_mask:0xf bank_mask:0xf bound_ctrl:1
	s_and_saveexec_b64 s[6:7], vcc
	v_pk_add_f32 v[90:91], v[90:91], v[138:139]
	ds_write_b64 v181, v[90:91] offset:136
	s_or_b64 exec, exec, s[6:7]
	v_or_b32_e32 v75, 0x400, v154
	v_add_u32_e32 v75, v105, v75
	ds_read2_b32 v[138:139], v75 offset1:32
	ds_read2_b32 v[142:143], v75 offset0:64 offset1:96
	v_mov_b32_e32 v140, v124
	v_mov_b32_e32 v141, v92
	v_pk_add_f32 v[144:145], v[140:141], 0 op_sel_hi:[1,0]
	v_mov_b32_e32 v140, v108
	v_pk_add_f32 v[140:141], v[140:141], 0 op_sel_hi:[1,0]
	s_waitcnt lgkmcnt(1)
	v_mov_b32_e32 v148, v138
	s_waitcnt lgkmcnt(0)
	v_mov_b32_e32 v149, v142
	s_mov_b32 s2, s67
	v_mov_b32_e32 v160, v139
	v_mov_b32_e32 v161, v142
	v_pk_fma_f32 v[138:139], v[148:149], s[2:3], v[144:145] op_sel_hi:[1,0,1]
	v_pk_fma_f32 v[140:141], v[160:161], s[2:3], v[140:141] op_sel_hi:[1,0,1]
	v_pk_mul_f32 v[156:157], v[148:149], s[2:3] op_sel_hi:[1,0]
	v_pk_mul_f32 v[148:149], v[138:139], v[138:139]
	v_pk_mul_f32 v[160:161], v[140:141], v[140:141]
	v_pk_mov_b32 v[144:145], v[144:145], v[148:149] op_sel:[1,0]
	v_pk_mov_b32 v[148:149], v[156:157], v[160:161] op_sel:[1,0]
	v_add_f32_e32 v90, 0, v76
	v_pk_add_f32 v[144:145], v[144:145], v[148:149]
	v_pk_add_f32 v[148:149], v[138:139], v[140:141]
	v_pk_mul_f32 v[156:157], v[138:139], v[140:141]
	v_fmac_f32_e32 v90, 0x3fd744fd, v143
	v_mov_b32_e32 v149, v157
	v_pk_add_f32 v[144:145], v[148:149], v[144:145]
	v_mul_f32_e32 v91, v90, v90
	v_pk_add_f32 v[142:143], v[144:145], v[90:91]
	s_nop 1
	v_mov_b32_dpp v144, v142 quad_perm:[1,0,3,2] row_mask:0xf bank_mask:0xf bound_ctrl:1
	v_mov_b32_dpp v145, v143 quad_perm:[1,0,3,2] row_mask:0xf bank_mask:0xf bound_ctrl:1
	v_pk_add_f32 v[142:143], v[142:143], v[144:145]
	s_nop 1
	v_mov_b32_dpp v144, v142 quad_perm:[2,3,0,1] row_mask:0xf bank_mask:0xf bound_ctrl:1
	v_mov_b32_dpp v145, v143 quad_perm:[2,3,0,1] row_mask:0xf bank_mask:0xf bound_ctrl:1
	v_pk_add_f32 v[142:143], v[142:143], v[144:145]
	s_nop 1
	v_mov_b32_dpp v144, v142 row_half_mirror row_mask:0xf bank_mask:0xf bound_ctrl:1
	v_mov_b32_dpp v145, v143 row_half_mirror row_mask:0xf bank_mask:0xf bound_ctrl:1
	v_pk_add_f32 v[142:143], v[142:143], v[144:145]
	s_nop 1
	v_mov_b32_dpp v144, v142 row_mirror row_mask:0xf bank_mask:0xf bound_ctrl:1
	v_mov_b32_dpp v145, v143 row_mirror row_mask:0xf bank_mask:0xf bound_ctrl:1
	s_and_saveexec_b64 s[6:7], vcc
	v_pk_add_f32 v[142:143], v[142:143], v[144:145]
	ds_write_b64 v181, v[142:143] offset:144
	s_or_b64 exec, exec, s[6:7]
	v_add_u32_e32 v87, v105, v146
	ds_read2_b32 v[142:143], v87 offset1:32
	ds_read2_b32 v[144:145], v87 offset0:64 offset1:96
	v_mov_b32_e32 v92, v125
	v_pk_add_f32 v[146:147], v[92:93], 0 op_sel_hi:[1,0]
	v_mov_b32_e32 v92, v109
	v_pk_add_f32 v[92:93], v[92:93], 0 op_sel_hi:[1,0]
	s_waitcnt lgkmcnt(1)
	v_mov_b32_e32 v108, v142
	s_waitcnt lgkmcnt(0)
;   DI void operator()(f32x16 (&acc)[2][4], int grow0, int gcol0, int lane, int w, char* lds) {
;     ...
;       for (int qq = 0; qq < 2; ++qq)
; #pragma unroll
;         for (int e = 0; e < 4; ++e) {
;           const int i = 4 * (2 * (ps & 1) + qq) + e;
;           const float* xr = (const float*)(xs + (8 * qq + 4 * hh + e) * 512) + l31;
;           float s1 = 0.f, s2 = 0.f;
; #pragma unroll
;           for (int nt = 0; nt < 4; ++nt) {
;             float v = (acc[mt][nt][i] + bia[nt]) * csc[nt];
;             float z = ALPHA * xr[nt * 32] + hs * v;
;             acc[mt][nt][i] = z; s1 += z; s2 += z * z;
;           }
;           s1 = row16_sum(s1); s2 = row16_sum(s2);
;           if ((lane & 15) == 0) { f32x2 sv = {s1, s2}; *(f32x2*)(redw + (mt * 32 + (i & 3) + 8 * (i >> 2)) * 2) = sv; }
;         }
	v_mov_b32_e32 v109, v144
	s_mov_b32 s2, s67
	v_mov_b32_e32 v124, v143
	v_mov_b32_e32 v125, v144
	v_pk_mul_f32 v[148:149], v[108:109], s[2:3] op_sel_hi:[1,0]
	v_pk_fma_f32 v[108:109], v[108:109], s[2:3], v[146:147] op_sel_hi:[1,0,1]
	v_pk_fma_f32 v[124:125], v[124:125], s[2:3], v[92:93] op_sel_hi:[1,0,1]
	v_pk_mul_f32 v[142:143], v[108:109], v[108:109]
	v_pk_mul_f32 v[92:93], v[124:125], v[124:125]
	v_pk_mov_b32 v[142:143], v[146:147], v[142:143] op_sel:[1,0]
	v_pk_mov_b32 v[92:93], v[148:149], v[92:93] op_sel:[1,0]
	v_add_f32_e32 v76, 0, v77
	v_pk_add_f32 v[92:93], v[142:143], v[92:93]
	v_pk_add_f32 v[142:143], v[108:109], v[124:125]
	v_pk_mul_f32 v[146:147], v[108:109], v[124:125]
	v_fmac_f32_e32 v76, 0x3fd744fd, v145
	v_mov_b32_e32 v143, v147
	v_pk_add_f32 v[92:93], v[142:143], v[92:93]
	v_mul_f32_e32 v77, v76, v76
	v_pk_add_f32 v[92:93], v[92:93], v[76:77]
	s_nop 1
	v_mov_b32_dpp v142, v92 quad_perm:[1,0,3,2] row_mask:0xf bank_mask:0xf bound_ctrl:1
	v_mov_b32_dpp v143, v93 quad_perm:[1,0,3,2] row_mask:0xf bank_mask:0xf bound_ctrl:1
	v_pk_add_f32 v[92:93], v[92:93], v[142:143]
	s_nop 1
	v_mov_b32_dpp v142, v92 quad_perm:[2,3,0,1] row_mask:0xf bank_mask:0xf bound_ctrl:1
	v_mov_b32_dpp v143, v93 quad_perm:[2,3,0,1] row_mask:0xf bank_mask:0xf bound_ctrl:1
	v_pk_add_f32 v[92:93], v[92:93], v[142:143]
	s_nop 1
	v_mov_b32_dpp v142, v92 row_half_mirror row_mask:0xf bank_mask:0xf bound_ctrl:1
	v_mov_b32_dpp v143, v93 row_half_mirror row_mask:0xf bank_mask:0xf bound_ctrl:1
	v_pk_add_f32 v[92:93], v[92:93], v[142:143]
	s_nop 1
	v_mov_b32_dpp v142, v92 row_mirror row_mask:0xf bank_mask:0xf bound_ctrl:1
	v_mov_b32_dpp v143, v93 row_mirror row_mask:0xf bank_mask:0xf bound_ctrl:1
	s_and_saveexec_b64 s[6:7], vcc
	v_pk_add_f32 v[92:93], v[92:93], v[142:143]
	ds_write_b64 v181, v[92:93] offset:152
	s_or_b64 exec, exec, s[6:7]
	v_or_b32_e32 v77, 0x1000, v154
	v_add_u32_e32 v77, v105, v77
	ds_read2_b32 v[142:143], v77 offset1:32
	ds_read2_b32 v[146:147], v77 offset0:64 offset1:96
	v_mov_b32_e32 v144, v126
	v_mov_b32_e32 v145, v94
	v_pk_add_f32 v[148:149], v[144:145], 0 op_sel_hi:[1,0]
	v_mov_b32_e32 v144, v110
	v_pk_add_f32 v[144:145], v[144:145], 0 op_sel_hi:[1,0]
	s_waitcnt lgkmcnt(1)
	v_mov_b32_e32 v156, v142
	s_waitcnt lgkmcnt(0)
	v_mov_b32_e32 v157, v146
	s_mov_b32 s2, s67
	v_mov_b32_e32 v170, v143
	v_mov_b32_e32 v171, v146
	v_pk_fma_f32 v[142:143], v[156:157], s[2:3], v[148:149] op_sel_hi:[1,0,1]
	v_pk_fma_f32 v[144:145], v[170:171], s[2:3], v[144:145] op_sel_hi:[1,0,1]
	v_pk_mul_f32 v[160:161], v[156:157], s[2:3] op_sel_hi:[1,0]
	v_pk_mul_f32 v[156:157], v[142:143], v[142:143]
	v_pk_mul_f32 v[170:171], v[144:145], v[144:145]
	v_pk_mov_b32 v[148:149], v[148:149], v[156:157] op_sel:[1,0]
	v_pk_mov_b32 v[156:157], v[160:161], v[170:171] op_sel:[1,0]
	v_add_f32_e32 v92, 0, v78
	v_pk_add_f32 v[148:149], v[148:149], v[156:157]
	v_pk_add_f32 v[156:157], v[142:143], v[144:145]
	v_pk_mul_f32 v[160:161], v[142:143], v[144:145]
	v_fmac_f32_e32 v92, 0x3fd744fd, v147
	v_mov_b32_e32 v157, v161
	v_pk_add_f32 v[148:149], v[156:157], v[148:149]
	v_mul_f32_e32 v93, v92, v92
	v_pk_add_f32 v[146:147], v[148:149], v[92:93]
	s_nop 1
	v_mov_b32_dpp v148, v146 quad_perm:[1,0,3,2] row_mask:0xf bank_mask:0xf bound_ctrl:1
	v_mov_b32_dpp v149, v147 quad_perm:[1,0,3,2] row_mask:0xf bank_mask:0xf bound_ctrl:1
	v_pk_add_f32 v[146:147], v[146:147], v[148:149]
	s_nop 1
	v_mov_b32_dpp v148, v146 quad_perm:[2,3,0,1] row_mask:0xf bank_mask:0xf bound_ctrl:1
	v_mov_b32_dpp v149, v147 quad_perm:[2,3,0,1] row_mask:0xf bank_mask:0xf bound_ctrl:1
	v_pk_add_f32 v[146:147], v[146:147], v[148:149]
	s_nop 1
	v_mov_b32_dpp v148, v146 row_half_mirror row_mask:0xf bank_mask:0xf bound_ctrl:1
	v_mov_b32_dpp v149, v147 row_half_mirror row_mask:0xf bank_mask:0xf bound_ctrl:1
	v_pk_add_f32 v[146:147], v[146:147], v[148:149]
	s_nop 1
	v_mov_b32_dpp v148, v146 row_mirror row_mask:0xf bank_mask:0xf bound_ctrl:1
	v_mov_b32_dpp v149, v147 row_mirror row_mask:0xf bank_mask:0xf bound_ctrl:1
	s_and_saveexec_b64 s[6:7], vcc
	v_pk_add_f32 v[146:147], v[146:147], v[148:149]
	ds_write_b64 v181, v[146:147] offset:192
	s_or_b64 exec, exec, s[6:7]
	v_or_b32_e32 v78, 0x1200, v154
	v_add_u32_e32 v91, v105, v78
	ds_read2_b32 v[146:147], v91 offset1:32
	ds_read2_b32 v[148:149], v91 offset0:64 offset1:96
	v_mov_b32_e32 v94, v127
	v_pk_add_f32 v[156:157], v[94:95], 0 op_sel_hi:[1,0]
	v_mov_b32_e32 v94, v111
	v_pk_add_f32 v[94:95], v[94:95], 0 op_sel_hi:[1,0]
	s_waitcnt lgkmcnt(1)
	v_mov_b32_e32 v110, v146
	s_waitcnt lgkmcnt(0)
	v_mov_b32_e32 v111, v148
	s_mov_b32 s2, s67
	v_mov_b32_e32 v126, v147
	v_mov_b32_e32 v127, v148
	v_pk_mul_f32 v[160:161], v[110:111], s[2:3] op_sel_hi:[1,0]
	v_pk_fma_f32 v[110:111], v[110:111], s[2:3], v[156:157] op_sel_hi:[1,0,1]
	v_pk_fma_f32 v[126:127], v[126:127], s[2:3], v[94:95] op_sel_hi:[1,0,1]
	v_pk_mul_f32 v[146:147], v[110:111], v[110:111]
	v_pk_mul_f32 v[94:95], v[126:127], v[126:127]
	v_pk_mov_b32 v[146:147], v[156:157], v[146:147] op_sel:[1,0]
	v_pk_mov_b32 v[94:95], v[160:161], v[94:95] op_sel:[1,0]
	v_add_f32_e32 v78, 0, v79
	v_pk_add_f32 v[94:95], v[146:147], v[94:95]
	v_pk_add_f32 v[146:147], v[110:111], v[126:127]
	v_pk_mul_f32 v[156:157], v[110:111], v[126:127]
	v_fmac_f32_e32 v78, 0x3fd744fd, v149
	v_mov_b32_e32 v147, v157
	v_pk_add_f32 v[94:95], v[146:147], v[94:95]
	v_mul_f32_e32 v79, v78, v78
	v_pk_add_f32 v[94:95], v[94:95], v[78:79]
	s_nop 1
	v_mov_b32_dpp v146, v94 quad_perm:[1,0,3,2] row_mask:0xf bank_mask:0xf bound_ctrl:1
	v_mov_b32_dpp v147, v95 quad_perm:[1,0,3,2] row_mask:0xf bank_mask:0xf bound_ctrl:1
	v_pk_add_f32 v[94:95], v[94:95], v[146:147]
	s_nop 1
	v_mov_b32_dpp v146, v94 quad_perm:[2,3,0,1] row_mask:0xf bank_mask:0xf bound_ctrl:1
	v_mov_b32_dpp v147, v95 quad_perm:[2,3,0,1] row_mask:0xf bank_mask:0xf bound_ctrl:1
	v_pk_add_f32 v[94:95], v[94:95], v[146:147]
	s_nop 1
	v_mov_b32_dpp v146, v94 row_half_mirror row_mask:0xf bank_mask:0xf bound_ctrl:1
	v_mov_b32_dpp v147, v95 row_half_mirror row_mask:0xf bank_mask:0xf bound_ctrl:1
	v_pk_add_f32 v[94:95], v[94:95], v[146:147]
	s_nop 1
	v_mov_b32_dpp v146, v94 row_mirror row_mask:0xf bank_mask:0xf bound_ctrl:1
	v_mov_b32_dpp v147, v95 row_mirror row_mask:0xf bank_mask:0xf bound_ctrl:1
	s_and_saveexec_b64 s[6:7], vcc
	v_pk_add_f32 v[94:95], v[94:95], v[146:147]
	ds_write_b64 v181, v[94:95] offset:200
	s_or_b64 exec, exec, s[6:7]
	v_or_b32_e32 v79, 0x1400, v154
	v_add_u32_e32 v79, v105, v79
	ds_read2_b32 v[146:147], v79 offset1:32
	ds_read2_b32 v[154:155], v79 offset0:64 offset1:96
	v_mov_b32_e32 v148, v128
	v_mov_b32_e32 v149, v96
	v_pk_add_f32 v[156:157], v[148:149], 0 op_sel_hi:[1,0]
	v_mov_b32_e32 v148, v112
	v_pk_add_f32 v[148:149], v[148:149], 0 op_sel_hi:[1,0]
	s_waitcnt lgkmcnt(1)
;   DI void operator()(f32x16 (&acc)[2][4], int grow0, int gcol0, int lane, int w, char* lds) {
;     ...
;     for (int ps = 0; ps < 4; ++ps) {
;       const int mt = ps >> 1;
;       if (ps + 1 < 4) {
;         if (ps >= 1) asm volatile("s_waitcnt lgkmcnt(0)" ::: "memory");
;         xpass(ps + 1, grow0, gcol0, lane, w, lds);
;         if (ps >= 1) asm volatile("s_waitcnt vmcnt(8)" ::: "memory");
;       } else asm volatile("s_waitcnt vmcnt(0)" ::: "memory");
;       const char* xs = lds + (ps & 1) * 65536 + w * 8192;
; #pragma unroll
;       for (int qq = 0; qq < 2; ++qq)
; #pragma unroll
;         for (int e = 0; e < 4; ++e) {
;           const int i = 4 * (2 * (ps & 1) + qq) + e;
;           const float* xr = (const float*)(xs + (8 * qq + 4 * hh + e) * 512) + l31;
;           float s1 = 0.f, s2 = 0.f;
; #pragma unroll
;           for (int nt = 0; nt < 4; ++nt) {
;             float v = (acc[mt][nt][i] + bia[nt]) * csc[nt];
;             float z = ALPHA * xr[nt * 32] + hs * v;
;             acc[mt][nt][i] = z; s1 += z; s2 += z * z;
;           }
;           s1 = row16_sum(s1); s2 = row16_sum(s2);
;           if ((lane & 15) == 0) { f32x2 sv = {s1, s2}; *(f32x2*)(redw + (mt * 32 + (i & 3) + 8 * (i >> 2)) * 2) = sv; }
;         }
	v_mov_b32_e32 v160, v146
	s_waitcnt lgkmcnt(0)
	v_mov_b32_e32 v161, v154
	s_mov_b32 s2, s67
	v_mov_b32_e32 v174, v147
	v_mov_b32_e32 v175, v154
	v_pk_fma_f32 v[146:147], v[160:161], s[2:3], v[156:157] op_sel_hi:[1,0,1]
	v_pk_fma_f32 v[148:149], v[174:175], s[2:3], v[148:149] op_sel_hi:[1,0,1]
	v_pk_mul_f32 v[170:171], v[160:161], s[2:3] op_sel_hi:[1,0]
	v_pk_mul_f32 v[160:161], v[146:147], v[146:147]
	v_pk_mul_f32 v[174:175], v[148:149], v[148:149]
	v_pk_mov_b32 v[156:157], v[156:157], v[160:161] op_sel:[1,0]
	v_pk_mov_b32 v[160:161], v[170:171], v[174:175] op_sel:[1,0]
	v_add_f32_e32 v94, 0, v80
	v_pk_add_f32 v[156:157], v[156:157], v[160:161]
	v_pk_add_f32 v[160:161], v[146:147], v[148:149]
	v_pk_mul_f32 v[170:171], v[146:147], v[148:149]
	v_fmac_f32_e32 v94, 0x3fd744fd, v155
	v_mov_b32_e32 v161, v171
	v_pk_add_f32 v[156:157], v[160:161], v[156:157]
	v_mul_f32_e32 v95, v94, v94
	v_pk_add_f32 v[154:155], v[156:157], v[94:95]
	s_nop 1
	v_mov_b32_dpp v156, v154 quad_perm:[1,0,3,2] row_mask:0xf bank_mask:0xf bound_ctrl:1
	v_mov_b32_dpp v157, v155 quad_perm:[1,0,3,2] row_mask:0xf bank_mask:0xf bound_ctrl:1
	v_pk_add_f32 v[154:155], v[154:155], v[156:157]
	s_nop 1
	v_mov_b32_dpp v156, v154 quad_perm:[2,3,0,1] row_mask:0xf bank_mask:0xf bound_ctrl:1
	v_mov_b32_dpp v157, v155 quad_perm:[2,3,0,1] row_mask:0xf bank_mask:0xf bound_ctrl:1
	v_pk_add_f32 v[154:155], v[154:155], v[156:157]
	s_nop 1
	v_mov_b32_dpp v156, v154 row_half_mirror row_mask:0xf bank_mask:0xf bound_ctrl:1
	v_mov_b32_dpp v157, v155 row_half_mirror row_mask:0xf bank_mask:0xf bound_ctrl:1
	v_pk_add_f32 v[154:155], v[154:155], v[156:157]
	s_nop 1
	v_mov_b32_dpp v156, v154 row_mirror row_mask:0xf bank_mask:0xf bound_ctrl:1
	v_mov_b32_dpp v157, v155 row_mirror row_mask:0xf bank_mask:0xf bound_ctrl:1
	s_and_saveexec_b64 s[6:7], vcc
	v_pk_add_f32 v[154:155], v[154:155], v[156:157]
	ds_write_b64 v181, v[154:155] offset:208
	s_or_b64 exec, exec, s[6:7]
	v_add_u32_e32 v93, v105, v101
	ds_read2_b32 v[154:155], v93 offset1:32
	ds_read2_b32 v[156:157], v93 offset0:64 offset1:96
	v_mov_b32_e32 v96, v129
	v_pk_add_f32 v[128:129], v[96:97], 0 op_sel_hi:[1,0]
	v_mov_b32_e32 v96, v113
	v_pk_add_f32 v[112:113], v[96:97], 0 op_sel_hi:[1,0]
	s_waitcnt lgkmcnt(1)
	v_mov_b32_e32 v96, v154
	s_waitcnt lgkmcnt(0)
	v_mov_b32_e32 v97, v156
	s_mov_b32 s2, s67
	v_mov_b32_e32 v154, v155
	v_mov_b32_e32 v155, v156
	v_pk_mul_f32 v[160:161], v[96:97], s[2:3] op_sel_hi:[1,0]
	v_pk_fma_f32 v[96:97], v[96:97], s[2:3], v[128:129] op_sel_hi:[1,0,1]
	v_pk_fma_f32 v[112:113], v[154:155], s[2:3], v[112:113] op_sel_hi:[1,0,1]
	v_pk_mul_f32 v[170:171], v[96:97], v[96:97]
	v_pk_mul_f32 v[154:155], v[112:113], v[112:113]
	v_pk_mov_b32 v[128:129], v[128:129], v[170:171] op_sel:[1,0]
	v_pk_mov_b32 v[154:155], v[160:161], v[154:155] op_sel:[1,0]
	v_add_f32_e32 v80, 0, v81
	v_pk_add_f32 v[128:129], v[128:129], v[154:155]
	v_pk_add_f32 v[154:155], v[96:97], v[112:113]
	v_pk_mul_f32 v[160:161], v[96:97], v[112:113]
	v_fmac_f32_e32 v80, 0x3fd744fd, v157
	v_mov_b32_e32 v155, v161
	v_pk_add_f32 v[128:129], v[154:155], v[128:129]
	v_mul_f32_e32 v81, v80, v80
	v_pk_add_f32 v[128:129], v[128:129], v[80:81]
	s_nop 1
	v_mov_b32_dpp v154, v128 quad_perm:[1,0,3,2] row_mask:0xf bank_mask:0xf bound_ctrl:1
	v_mov_b32_dpp v155, v129 quad_perm:[1,0,3,2] row_mask:0xf bank_mask:0xf bound_ctrl:1
	v_pk_add_f32 v[128:129], v[128:129], v[154:155]
	s_nop 1
	v_mov_b32_dpp v154, v128 quad_perm:[2,3,0,1] row_mask:0xf bank_mask:0xf bound_ctrl:1
	v_mov_b32_dpp v155, v129 quad_perm:[2,3,0,1] row_mask:0xf bank_mask:0xf bound_ctrl:1
	v_pk_add_f32 v[128:129], v[128:129], v[154:155]
	s_nop 1
	v_mov_b32_dpp v154, v128 row_half_mirror row_mask:0xf bank_mask:0xf bound_ctrl:1
	v_mov_b32_dpp v155, v129 row_half_mirror row_mask:0xf bank_mask:0xf bound_ctrl:1
	v_pk_add_f32 v[128:129], v[128:129], v[154:155]
	s_nop 1
	v_mov_b32_dpp v154, v128 row_mirror row_mask:0xf bank_mask:0xf bound_ctrl:1
	v_mov_b32_dpp v155, v129 row_mirror row_mask:0xf bank_mask:0xf bound_ctrl:1
	s_and_saveexec_b64 s[6:7], vcc
	v_pk_add_f32 v[128:129], v[128:129], v[154:155]
	ds_write_b64 v181, v[128:129] offset:216
	s_or_b64 exec, exec, s[6:7]
	v_or_b32_e32 v128, 48, v159
	v_ashrrev_i32_e32 v129, 31, v128
	v_lshlrev_b64 v[128:129], 12, v[128:129]
	v_readfirstlane_b32 s2, v158
	v_lshl_add_u64 v[128:129], s[10:11], 0, v[128:129]
	s_lshl_b32 s2, s2, 13
	v_lshl_add_u64 v[128:129], v[184:185], 2, v[128:129]
	s_waitcnt lgkmcnt(0)
	s_add_i32 m0, s2, 0x10000
	v_lshl_add_u64 v[128:129], v[128:129], 0, v[0:1]
	s_mov_b64 s[6:7], 0x2000
	global_load_lds_dwordx4 v[128:129], off
	v_lshl_add_u64 v[154:155], v[128:129], 0, s[6:7]
	s_add_i32 m0, s2, 0x10400
	s_mov_b64 s[6:7], 0x4000
	global_load_lds_dwordx4 v[154:155], off
	v_lshl_add_u64 v[154:155], v[128:129], 0, s[6:7]
	s_add_i32 m0, s2, 0x10800
	s_mov_b64 s[6:7], 0x6000
	global_load_lds_dwordx4 v[154:155], off
	v_lshl_add_u64 v[154:155], v[128:129], 0, s[6:7]
	s_add_i32 m0, s2, 0x10c00
	s_mov_b64 s[6:7], 0x8000
	global_load_lds_dwordx4 v[154:155], off
	v_lshl_add_u64 v[154:155], v[128:129], 0, s[6:7]
	s_add_i32 m0, s2, 0x11000
	s_mov_b64 s[6:7], 0xa000
	global_load_lds_dwordx4 v[154:155], off
	v_lshl_add_u64 v[154:155], v[128:129], 0, s[6:7]
	s_add_i32 m0, s2, 0x11400
	s_mov_b64 s[6:7], 0xc000
	global_load_lds_dwordx4 v[154:155], off
	v_lshl_add_u64 v[154:155], v[128:129], 0, s[6:7]
	s_add_i32 m0, s2, 0x11800
	s_mov_b64 s[6:7], 0xe000
	global_load_lds_dwordx4 v[154:155], off
	v_lshl_add_u64 v[128:129], v[128:129], 0, s[6:7]
	s_add_i32 m0, s2, 0x11c00
	v_mov_b32_e32 v156, v50
	global_load_lds_dwordx4 v[128:129], off
	s_waitcnt vmcnt(8)
;   DI void operator()(f32x16 (&acc)[2][4], int grow0, int gcol0, int lane, int w, char* lds) {
;     ...
;       for (int qq = 0; qq < 2; ++qq)
; #pragma unroll
;         for (int e = 0; e < 4; ++e) {
;           const int i = 4 * (2 * (ps & 1) + qq) + e;
;           const float* xr = (const float*)(xs + (8 * qq + 4 * hh + e) * 512) + l31;
;           float s1 = 0.f, s2 = 0.f;
; #pragma unroll
;           for (int nt = 0; nt < 4; ++nt) {
;             float v = (acc[mt][nt][i] + bia[nt]) * csc[nt];
;             float z = ALPHA * xr[nt * 32] + hs * v;
;             acc[mt][nt][i] = z; s1 += z; s2 += z * z;
;           }
;           s1 = row16_sum(s1); s2 = row16_sum(s2);
;           if ((lane & 15) == 0) { f32x2 sv = {s1, s2}; *(f32x2*)(redw + (mt * 32 + (i & 3) + 8 * (i >> 2)) * 2) = sv; }
;         }
	ds_read2_b32 v[154:155], v168 offset1:32
	ds_read2_b32 v[158:159], v168 offset0:64 offset1:96
	v_mov_b32_e32 v157, v18
	v_pk_add_f32 v[160:161], v[156:157], 0 op_sel_hi:[1,0]
	v_mov_b32_e32 v156, v34
	v_pk_add_f32 v[156:157], v[156:157], 0 op_sel_hi:[1,0]
	s_waitcnt lgkmcnt(0)
	v_mov_b32_e32 v170, v154
	v_mov_b32_e32 v171, v158
	s_mov_b32 s2, s67
	v_mov_b32_e32 v176, v155
	v_mov_b32_e32 v177, v158
	v_pk_fma_f32 v[154:155], v[170:171], s[2:3], v[160:161] op_sel_hi:[1,0,1]
	v_pk_fma_f32 v[156:157], v[176:177], s[2:3], v[156:157] op_sel_hi:[1,0,1]
	v_pk_mul_f32 v[174:175], v[170:171], s[2:3] op_sel_hi:[1,0]
	v_pk_mul_f32 v[170:171], v[154:155], v[154:155]
	v_pk_mul_f32 v[176:177], v[156:157], v[156:157]
	v_pk_mov_b32 v[160:161], v[160:161], v[170:171] op_sel:[1,0]
	v_pk_mov_b32 v[170:171], v[174:175], v[176:177] op_sel:[1,0]
	v_add_f32_e32 v128, 0, v2
	v_pk_add_f32 v[160:161], v[160:161], v[170:171]
	v_pk_add_f32 v[170:171], v[154:155], v[156:157]
	v_pk_mul_f32 v[174:175], v[154:155], v[156:157]
	v_fmac_f32_e32 v128, 0x3fd744fd, v159
	v_mov_b32_e32 v171, v175
	v_pk_add_f32 v[160:161], v[170:171], v[160:161]
	v_mul_f32_e32 v129, v128, v128
	v_pk_add_f32 v[158:159], v[160:161], v[128:129]
	s_nop 1
	v_mov_b32_dpp v160, v158 quad_perm:[1,0,3,2] row_mask:0xf bank_mask:0xf bound_ctrl:1
	v_mov_b32_dpp v161, v159 quad_perm:[1,0,3,2] row_mask:0xf bank_mask:0xf bound_ctrl:1
	v_pk_add_f32 v[158:159], v[158:159], v[160:161]
	s_nop 1
	v_mov_b32_dpp v160, v158 quad_perm:[2,3,0,1] row_mask:0xf bank_mask:0xf bound_ctrl:1
	v_mov_b32_dpp v161, v159 quad_perm:[2,3,0,1] row_mask:0xf bank_mask:0xf bound_ctrl:1
	v_pk_add_f32 v[158:159], v[158:159], v[160:161]
	s_nop 1
	v_mov_b32_dpp v160, v158 row_half_mirror row_mask:0xf bank_mask:0xf bound_ctrl:1
	v_mov_b32_dpp v161, v159 row_half_mirror row_mask:0xf bank_mask:0xf bound_ctrl:1
	v_pk_add_f32 v[158:159], v[158:159], v[160:161]
	s_nop 1
	v_mov_b32_dpp v160, v158 row_mirror row_mask:0xf bank_mask:0xf bound_ctrl:1
	v_mov_b32_dpp v161, v159 row_mirror row_mask:0xf bank_mask:0xf bound_ctrl:1
	s_and_saveexec_b64 s[6:7], vcc
	v_pk_add_f32 v[158:159], v[158:159], v[160:161]
	ds_write_b64 v181, v[158:159] offset:256
	s_or_b64 exec, exec, s[6:7]
	ds_read2_b32 v[158:159], v168 offset0:128 offset1:160
	ds_read2_b32 v[160:161], v168 offset0:192 offset1:224
	v_mov_b32_e32 v18, v51
	v_pk_add_f32 v[168:169], v[18:19], 0 op_sel_hi:[1,0]
	v_mov_b32_e32 v18, v35
	v_pk_add_f32 v[18:19], v[18:19], 0 op_sel_hi:[1,0]
	s_waitcnt lgkmcnt(1)
	v_mov_b32_e32 v34, v158
	s_waitcnt lgkmcnt(0)
	v_mov_b32_e32 v35, v160
	s_mov_b32 s2, s67
	v_mov_b32_e32 v50, v159
	v_mov_b32_e32 v51, v160
	v_pk_mul_f32 v[170:171], v[34:35], s[2:3] op_sel_hi:[1,0]
	v_pk_fma_f32 v[34:35], v[34:35], s[2:3], v[168:169] op_sel_hi:[1,0,1]
	v_pk_fma_f32 v[50:51], v[50:51], s[2:3], v[18:19] op_sel_hi:[1,0,1]
	v_pk_mul_f32 v[158:159], v[34:35], v[34:35]
	v_pk_mul_f32 v[18:19], v[50:51], v[50:51]
	v_pk_mov_b32 v[158:159], v[168:169], v[158:159] op_sel:[1,0]
	v_pk_mov_b32 v[18:19], v[170:171], v[18:19] op_sel:[1,0]
	v_add_f32_e32 v2, 0, v3
	v_pk_add_f32 v[18:19], v[158:159], v[18:19]
	v_pk_add_f32 v[158:159], v[34:35], v[50:51]
	v_pk_mul_f32 v[168:169], v[34:35], v[50:51]
	v_fmac_f32_e32 v2, 0x3fd744fd, v161
	v_mov_b32_e32 v159, v169
	v_pk_add_f32 v[18:19], v[158:159], v[18:19]
	v_mul_f32_e32 v3, v2, v2
	v_pk_add_f32 v[18:19], v[18:19], v[2:3]
	s_nop 1
	v_mov_b32_dpp v158, v18 quad_perm:[1,0,3,2] row_mask:0xf bank_mask:0xf bound_ctrl:1
	v_mov_b32_dpp v159, v19 quad_perm:[1,0,3,2] row_mask:0xf bank_mask:0xf bound_ctrl:1
	v_pk_add_f32 v[18:19], v[18:19], v[158:159]
	s_nop 1
	v_mov_b32_dpp v158, v18 quad_perm:[2,3,0,1] row_mask:0xf bank_mask:0xf bound_ctrl:1
	v_mov_b32_dpp v159, v19 quad_perm:[2,3,0,1] row_mask:0xf bank_mask:0xf bound_ctrl:1
	v_pk_add_f32 v[18:19], v[18:19], v[158:159]
	s_nop 1
	v_mov_b32_dpp v158, v18 row_half_mirror row_mask:0xf bank_mask:0xf bound_ctrl:1
	v_mov_b32_dpp v159, v19 row_half_mirror row_mask:0xf bank_mask:0xf bound_ctrl:1
	v_pk_add_f32 v[18:19], v[18:19], v[158:159]
	s_nop 1
	v_mov_b32_dpp v158, v18 row_mirror row_mask:0xf bank_mask:0xf bound_ctrl:1
	v_mov_b32_dpp v159, v19 row_mirror row_mask:0xf bank_mask:0xf bound_ctrl:1
	s_and_saveexec_b64 s[6:7], vcc
	v_pk_add_f32 v[18:19], v[18:19], v[158:159]
	ds_write_b64 v181, v[18:19] offset:264
	s_or_b64 exec, exec, s[6:7]
	ds_read2_b32 v[158:159], v153 offset1:32
	ds_read2_b32 v[168:169], v153 offset0:64 offset1:96
	v_mov_b32_e32 v160, v52
	v_mov_b32_e32 v161, v20
	v_pk_add_f32 v[170:171], v[160:161], 0 op_sel_hi:[1,0]
	v_mov_b32_e32 v160, v36
	v_pk_add_f32 v[160:161], v[160:161], 0 op_sel_hi:[1,0]
	s_waitcnt lgkmcnt(1)
	v_mov_b32_e32 v174, v158
	s_waitcnt lgkmcnt(0)
;   DI void operator()(f32x16 (&acc)[2][4], int grow0, int gcol0, int lane, int w, char* lds) {
;     ...
;       for (int qq = 0; qq < 2; ++qq)
; #pragma unroll
;         for (int e = 0; e < 4; ++e) {
;           const int i = 4 * (2 * (ps & 1) + qq) + e;
;           const float* xr = (const float*)(xs + (8 * qq + 4 * hh + e) * 512) + l31;
;           float s1 = 0.f, s2 = 0.f;
; #pragma unroll
;           for (int nt = 0; nt < 4; ++nt) {
;             float v = (acc[mt][nt][i] + bia[nt]) * csc[nt];
;             float z = ALPHA * xr[nt * 32] + hs * v;
;             acc[mt][nt][i] = z; s1 += z; s2 += z * z;
;           }
;           s1 = row16_sum(s1); s2 = row16_sum(s2);
;           if ((lane & 15) == 0) { f32x2 sv = {s1, s2}; *(f32x2*)(redw + (mt * 32 + (i & 3) + 8 * (i >> 2)) * 2) = sv; }
;         }
	v_mov_b32_e32 v175, v168
	s_mov_b32 s2, s67
	v_mov_b32_e32 v178, v159
	v_mov_b32_e32 v179, v168
	v_pk_fma_f32 v[158:159], v[174:175], s[2:3], v[170:171] op_sel_hi:[1,0,1]
	v_pk_fma_f32 v[160:161], v[178:179], s[2:3], v[160:161] op_sel_hi:[1,0,1]
	v_pk_mul_f32 v[176:177], v[174:175], s[2:3] op_sel_hi:[1,0]
	v_pk_mul_f32 v[174:175], v[158:159], v[158:159]
	v_pk_mul_f32 v[178:179], v[160:161], v[160:161]
	v_pk_mov_b32 v[170:171], v[170:171], v[174:175] op_sel:[1,0]
	v_pk_mov_b32 v[174:175], v[176:177], v[178:179] op_sel:[1,0]
	v_add_f32_e32 v18, 0, v4
	v_pk_add_f32 v[170:171], v[170:171], v[174:175]
	v_pk_add_f32 v[174:175], v[158:159], v[160:161]
	v_pk_mul_f32 v[176:177], v[158:159], v[160:161]
	v_fmac_f32_e32 v18, 0x3fd744fd, v169
	v_mov_b32_e32 v175, v177
	v_pk_add_f32 v[170:171], v[174:175], v[170:171]
	v_mul_f32_e32 v19, v18, v18
	v_pk_add_f32 v[168:169], v[170:171], v[18:19]
	s_nop 1
	v_mov_b32_dpp v170, v168 quad_perm:[1,0,3,2] row_mask:0xf bank_mask:0xf bound_ctrl:1
	v_mov_b32_dpp v171, v169 quad_perm:[1,0,3,2] row_mask:0xf bank_mask:0xf bound_ctrl:1
	v_pk_add_f32 v[168:169], v[168:169], v[170:171]
	s_nop 1
	v_mov_b32_dpp v170, v168 quad_perm:[2,3,0,1] row_mask:0xf bank_mask:0xf bound_ctrl:1
	v_mov_b32_dpp v171, v169 quad_perm:[2,3,0,1] row_mask:0xf bank_mask:0xf bound_ctrl:1
	v_pk_add_f32 v[168:169], v[168:169], v[170:171]
	s_nop 1
	v_mov_b32_dpp v170, v168 row_half_mirror row_mask:0xf bank_mask:0xf bound_ctrl:1
	v_mov_b32_dpp v171, v169 row_half_mirror row_mask:0xf bank_mask:0xf bound_ctrl:1
	v_pk_add_f32 v[168:169], v[168:169], v[170:171]
	s_nop 1
	v_mov_b32_dpp v170, v168 row_mirror row_mask:0xf bank_mask:0xf bound_ctrl:1
	v_mov_b32_dpp v171, v169 row_mirror row_mask:0xf bank_mask:0xf bound_ctrl:1
	s_and_saveexec_b64 s[6:7], vcc
	v_pk_add_f32 v[168:169], v[168:169], v[170:171]
	ds_write_b64 v181, v[168:169] offset:272
	s_or_b64 exec, exec, s[6:7]
	ds_read2_b32 v[168:169], v151 offset1:32
	ds_read2_b32 v[170:171], v151 offset0:64 offset1:96
	v_mov_b32_e32 v20, v53
	v_pk_add_f32 v[174:175], v[20:21], 0 op_sel_hi:[1,0]
	v_mov_b32_e32 v20, v37
	v_pk_add_f32 v[20:21], v[20:21], 0 op_sel_hi:[1,0]
	s_waitcnt lgkmcnt(1)
	v_mov_b32_e32 v36, v168
	s_waitcnt lgkmcnt(0)
	v_mov_b32_e32 v37, v170
	s_mov_b32 s2, s67
	v_mov_b32_e32 v52, v169
	v_mov_b32_e32 v53, v170
	v_pk_mul_f32 v[176:177], v[36:37], s[2:3] op_sel_hi:[1,0]
	v_pk_fma_f32 v[36:37], v[36:37], s[2:3], v[174:175] op_sel_hi:[1,0,1]
	v_pk_fma_f32 v[52:53], v[52:53], s[2:3], v[20:21] op_sel_hi:[1,0,1]
	v_pk_mul_f32 v[168:169], v[36:37], v[36:37]
	v_pk_mul_f32 v[20:21], v[52:53], v[52:53]
	v_pk_mov_b32 v[168:169], v[174:175], v[168:169] op_sel:[1,0]
	v_pk_mov_b32 v[20:21], v[176:177], v[20:21] op_sel:[1,0]
	v_add_f32_e32 v4, 0, v5
	v_pk_add_f32 v[20:21], v[168:169], v[20:21]
	v_pk_add_f32 v[168:169], v[36:37], v[52:53]
	v_pk_mul_f32 v[174:175], v[36:37], v[52:53]
	v_fmac_f32_e32 v4, 0x3fd744fd, v171
	v_mov_b32_e32 v169, v175
	v_pk_add_f32 v[20:21], v[168:169], v[20:21]
	v_mul_f32_e32 v5, v4, v4
	v_pk_add_f32 v[20:21], v[20:21], v[4:5]
	s_nop 1
	v_mov_b32_dpp v168, v20 quad_perm:[1,0,3,2] row_mask:0xf bank_mask:0xf bound_ctrl:1
	v_mov_b32_dpp v169, v21 quad_perm:[1,0,3,2] row_mask:0xf bank_mask:0xf bound_ctrl:1
	v_pk_add_f32 v[20:21], v[20:21], v[168:169]
	s_nop 1
	v_mov_b32_dpp v168, v20 quad_perm:[2,3,0,1] row_mask:0xf bank_mask:0xf bound_ctrl:1
	v_mov_b32_dpp v169, v21 quad_perm:[2,3,0,1] row_mask:0xf bank_mask:0xf bound_ctrl:1
	v_pk_add_f32 v[20:21], v[20:21], v[168:169]
	s_nop 1
	v_mov_b32_dpp v168, v20 row_half_mirror row_mask:0xf bank_mask:0xf bound_ctrl:1
	v_mov_b32_dpp v169, v21 row_half_mirror row_mask:0xf bank_mask:0xf bound_ctrl:1
	v_pk_add_f32 v[20:21], v[20:21], v[168:169]
	s_nop 1
	v_mov_b32_dpp v168, v20 row_mirror row_mask:0xf bank_mask:0xf bound_ctrl:1
	v_mov_b32_dpp v169, v21 row_mirror row_mask:0xf bank_mask:0xf bound_ctrl:1
	s_and_saveexec_b64 s[6:7], vcc
	v_pk_add_f32 v[20:21], v[20:21], v[168:169]
	ds_write_b64 v181, v[20:21] offset:280
	s_or_b64 exec, exec, s[6:7]
	ds_read2_b32 v[168:169], v67 offset1:32
	ds_read2_b32 v[174:175], v67 offset0:64 offset1:96
	v_mov_b32_e32 v170, v54
	v_mov_b32_e32 v171, v22
	v_pk_add_f32 v[176:177], v[170:171], 0 op_sel_hi:[1,0]
	v_mov_b32_e32 v170, v38
	v_pk_add_f32 v[170:171], v[170:171], 0 op_sel_hi:[1,0]
	s_waitcnt lgkmcnt(1)
	v_mov_b32_e32 v178, v168
	s_waitcnt lgkmcnt(0)
	v_mov_b32_e32 v179, v174
	s_mov_b32 s2, s67
	v_mov_b32_e32 v190, v169
	v_mov_b32_e32 v191, v174
	v_pk_fma_f32 v[168:169], v[178:179], s[2:3], v[176:177] op_sel_hi:[1,0,1]
	v_pk_fma_f32 v[170:171], v[190:191], s[2:3], v[170:171] op_sel_hi:[1,0,1]
	v_pk_mul_f32 v[182:183], v[178:179], s[2:3] op_sel_hi:[1,0]
	v_pk_mul_f32 v[178:179], v[168:169], v[168:169]
	v_pk_mul_f32 v[190:191], v[170:171], v[170:171]
	v_pk_mov_b32 v[176:177], v[176:177], v[178:179] op_sel:[1,0]
	v_pk_mov_b32 v[178:179], v[182:183], v[190:191] op_sel:[1,0]
	v_add_f32_e32 v20, 0, v6
	v_pk_add_f32 v[176:177], v[176:177], v[178:179]
	v_pk_add_f32 v[178:179], v[168:169], v[170:171]
	v_pk_mul_f32 v[182:183], v[168:169], v[170:171]
	v_fmac_f32_e32 v20, 0x3fd744fd, v175
	v_mov_b32_e32 v179, v183
	v_pk_add_f32 v[176:177], v[178:179], v[176:177]
	v_mul_f32_e32 v21, v20, v20
	v_pk_add_f32 v[174:175], v[176:177], v[20:21]
	s_nop 1
	v_mov_b32_dpp v176, v174 quad_perm:[1,0,3,2] row_mask:0xf bank_mask:0xf bound_ctrl:1
	v_mov_b32_dpp v177, v175 quad_perm:[1,0,3,2] row_mask:0xf bank_mask:0xf bound_ctrl:1
	v_pk_add_f32 v[174:175], v[174:175], v[176:177]
	s_nop 1
	v_mov_b32_dpp v176, v174 quad_perm:[2,3,0,1] row_mask:0xf bank_mask:0xf bound_ctrl:1
	v_mov_b32_dpp v177, v175 quad_perm:[2,3,0,1] row_mask:0xf bank_mask:0xf bound_ctrl:1
	v_pk_add_f32 v[174:175], v[174:175], v[176:177]
	s_nop 1
	v_mov_b32_dpp v176, v174 row_half_mirror row_mask:0xf bank_mask:0xf bound_ctrl:1
	v_mov_b32_dpp v177, v175 row_half_mirror row_mask:0xf bank_mask:0xf bound_ctrl:1
	v_pk_add_f32 v[174:175], v[174:175], v[176:177]
	s_nop 1
	v_mov_b32_dpp v176, v174 row_mirror row_mask:0xf bank_mask:0xf bound_ctrl:1
	v_mov_b32_dpp v177, v175 row_mirror row_mask:0xf bank_mask:0xf bound_ctrl:1
	s_and_saveexec_b64 s[6:7], vcc
	v_pk_add_f32 v[174:175], v[174:175], v[176:177]
	ds_write_b64 v181, v[174:175] offset:320
	s_or_b64 exec, exec, s[6:7]
	ds_read2_b32 v[174:175], v67 offset0:128 offset1:160
	ds_read2_b32 v[176:177], v67 offset0:192 offset1:224
	v_mov_b32_e32 v22, v55
	v_pk_add_f32 v[178:179], v[22:23], 0 op_sel_hi:[1,0]
	v_mov_b32_e32 v22, v39
	v_pk_add_f32 v[22:23], v[22:23], 0 op_sel_hi:[1,0]
	s_waitcnt lgkmcnt(1)
;   DI void operator()(f32x16 (&acc)[2][4], int grow0, int gcol0, int lane, int w, char* lds) {
;     ...
;     for (int ps = 0; ps < 4; ++ps) {
;       const int mt = ps >> 1;
;       if (ps + 1 < 4) {
;         if (ps >= 1) asm volatile("s_waitcnt lgkmcnt(0)" ::: "memory");
;         xpass(ps + 1, grow0, gcol0, lane, w, lds);
;         if (ps >= 1) asm volatile("s_waitcnt vmcnt(8)" ::: "memory");
;       } else asm volatile("s_waitcnt vmcnt(0)" ::: "memory");
;       const char* xs = lds + (ps & 1) * 65536 + w * 8192;
; #pragma unroll
;       for (int qq = 0; qq < 2; ++qq)
; #pragma unroll
;         for (int e = 0; e < 4; ++e) {
;           const int i = 4 * (2 * (ps & 1) + qq) + e;
;           const float* xr = (const float*)(xs + (8 * qq + 4 * hh + e) * 512) + l31;
;           float s1 = 0.f, s2 = 0.f;
; #pragma unroll
;           for (int nt = 0; nt < 4; ++nt) {
;             float v = (acc[mt][nt][i] + bia[nt]) * csc[nt];
;             float z = ALPHA * xr[nt * 32] + hs * v;
;             acc[mt][nt][i] = z; s1 += z; s2 += z * z;
;           }
;           s1 = row16_sum(s1); s2 = row16_sum(s2);
;           if ((lane & 15) == 0) { f32x2 sv = {s1, s2}; *(f32x2*)(redw + (mt * 32 + (i & 3) + 8 * (i >> 2)) * 2) = sv; }
;         }
	v_mov_b32_e32 v38, v174
	s_waitcnt lgkmcnt(0)
	v_mov_b32_e32 v39, v176
	s_mov_b32 s2, s67
	v_mov_b32_e32 v54, v175
	v_mov_b32_e32 v55, v176
	v_pk_mul_f32 v[182:183], v[38:39], s[2:3] op_sel_hi:[1,0]
	v_pk_fma_f32 v[38:39], v[38:39], s[2:3], v[178:179] op_sel_hi:[1,0,1]
	v_pk_fma_f32 v[54:55], v[54:55], s[2:3], v[22:23] op_sel_hi:[1,0,1]
	v_pk_mul_f32 v[174:175], v[38:39], v[38:39]
	v_pk_mul_f32 v[22:23], v[54:55], v[54:55]
	v_pk_mov_b32 v[174:175], v[178:179], v[174:175] op_sel:[1,0]
	v_pk_mov_b32 v[22:23], v[182:183], v[22:23] op_sel:[1,0]
	v_add_f32_e32 v6, 0, v7
	v_pk_add_f32 v[22:23], v[174:175], v[22:23]
	v_pk_add_f32 v[174:175], v[38:39], v[54:55]
	v_pk_mul_f32 v[178:179], v[38:39], v[54:55]
	v_fmac_f32_e32 v6, 0x3fd744fd, v177
	v_mov_b32_e32 v175, v179
	v_pk_add_f32 v[22:23], v[174:175], v[22:23]
	v_mul_f32_e32 v7, v6, v6
	v_pk_add_f32 v[22:23], v[22:23], v[6:7]
	s_nop 1
	v_mov_b32_dpp v174, v22 quad_perm:[1,0,3,2] row_mask:0xf bank_mask:0xf bound_ctrl:1
	v_mov_b32_dpp v175, v23 quad_perm:[1,0,3,2] row_mask:0xf bank_mask:0xf bound_ctrl:1
	v_pk_add_f32 v[22:23], v[22:23], v[174:175]
	s_nop 1
	v_mov_b32_dpp v174, v22 quad_perm:[2,3,0,1] row_mask:0xf bank_mask:0xf bound_ctrl:1
	v_mov_b32_dpp v175, v23 quad_perm:[2,3,0,1] row_mask:0xf bank_mask:0xf bound_ctrl:1
	v_pk_add_f32 v[22:23], v[22:23], v[174:175]
	s_nop 1
	v_mov_b32_dpp v174, v22 row_half_mirror row_mask:0xf bank_mask:0xf bound_ctrl:1
	v_mov_b32_dpp v175, v23 row_half_mirror row_mask:0xf bank_mask:0xf bound_ctrl:1
	v_pk_add_f32 v[22:23], v[22:23], v[174:175]
	s_nop 1
	v_mov_b32_dpp v174, v22 row_mirror row_mask:0xf bank_mask:0xf bound_ctrl:1
	v_mov_b32_dpp v175, v23 row_mirror row_mask:0xf bank_mask:0xf bound_ctrl:1
	s_and_saveexec_b64 s[6:7], vcc
	v_pk_add_f32 v[22:23], v[22:23], v[174:175]
	ds_write_b64 v181, v[22:23] offset:328
	s_or_b64 exec, exec, s[6:7]
	ds_read2_b32 v[174:175], v69 offset1:32
	ds_read2_b32 v[178:179], v69 offset0:64 offset1:96
	v_mov_b32_e32 v176, v56
	v_mov_b32_e32 v177, v24
	v_pk_add_f32 v[182:183], v[176:177], 0 op_sel_hi:[1,0]
	v_mov_b32_e32 v176, v40
	v_pk_add_f32 v[176:177], v[176:177], 0 op_sel_hi:[1,0]
	s_waitcnt lgkmcnt(1)
	v_mov_b32_e32 v190, v174
	s_waitcnt lgkmcnt(0)
	v_mov_b32_e32 v191, v178
	s_mov_b32 s2, s67
	v_mov_b32_e32 v194, v175
	v_mov_b32_e32 v195, v178
	v_pk_fma_f32 v[174:175], v[190:191], s[2:3], v[182:183] op_sel_hi:[1,0,1]
	v_pk_fma_f32 v[176:177], v[194:195], s[2:3], v[176:177] op_sel_hi:[1,0,1]
	v_pk_mul_f32 v[192:193], v[190:191], s[2:3] op_sel_hi:[1,0]
	v_pk_mul_f32 v[190:191], v[174:175], v[174:175]
	v_pk_mul_f32 v[194:195], v[176:177], v[176:177]
	v_pk_mov_b32 v[182:183], v[182:183], v[190:191] op_sel:[1,0]
	v_pk_mov_b32 v[190:191], v[192:193], v[194:195] op_sel:[1,0]
	v_add_f32_e32 v22, 0, v8
	v_pk_add_f32 v[182:183], v[182:183], v[190:191]
	v_pk_add_f32 v[190:191], v[174:175], v[176:177]
	v_pk_mul_f32 v[192:193], v[174:175], v[176:177]
	v_fmac_f32_e32 v22, 0x3fd744fd, v179
	v_mov_b32_e32 v191, v193
	v_pk_add_f32 v[182:183], v[190:191], v[182:183]
	v_mul_f32_e32 v23, v22, v22
	v_pk_add_f32 v[178:179], v[182:183], v[22:23]
	s_nop 1
	v_mov_b32_dpp v182, v178 quad_perm:[1,0,3,2] row_mask:0xf bank_mask:0xf bound_ctrl:1
	v_mov_b32_dpp v183, v179 quad_perm:[1,0,3,2] row_mask:0xf bank_mask:0xf bound_ctrl:1
	v_pk_add_f32 v[178:179], v[178:179], v[182:183]
	s_nop 1
	v_mov_b32_dpp v182, v178 quad_perm:[2,3,0,1] row_mask:0xf bank_mask:0xf bound_ctrl:1
	v_mov_b32_dpp v183, v179 quad_perm:[2,3,0,1] row_mask:0xf bank_mask:0xf bound_ctrl:1
	v_pk_add_f32 v[178:179], v[178:179], v[182:183]
	s_nop 1
	v_mov_b32_dpp v182, v178 row_half_mirror row_mask:0xf bank_mask:0xf bound_ctrl:1
	v_mov_b32_dpp v183, v179 row_half_mirror row_mask:0xf bank_mask:0xf bound_ctrl:1
	v_pk_add_f32 v[178:179], v[178:179], v[182:183]
	s_nop 1
	v_mov_b32_dpp v182, v178 row_mirror row_mask:0xf bank_mask:0xf bound_ctrl:1
	v_mov_b32_dpp v183, v179 row_mirror row_mask:0xf bank_mask:0xf bound_ctrl:1
	s_and_saveexec_b64 s[6:7], vcc
	v_pk_add_f32 v[178:179], v[178:179], v[182:183]
	ds_write_b64 v181, v[178:179] offset:336
	s_or_b64 exec, exec, s[6:7]
	ds_read2_b32 v[178:179], v71 offset1:32
	ds_read2_b32 v[182:183], v71 offset0:64 offset1:96
	v_mov_b32_e32 v24, v57
	v_pk_add_f32 v[190:191], v[24:25], 0 op_sel_hi:[1,0]
	v_mov_b32_e32 v24, v41
	v_pk_add_f32 v[24:25], v[24:25], 0 op_sel_hi:[1,0]
	s_waitcnt lgkmcnt(1)
	v_mov_b32_e32 v40, v178
	s_waitcnt lgkmcnt(0)
	v_mov_b32_e32 v41, v182
	s_mov_b32 s2, s67
	v_mov_b32_e32 v56, v179
	v_mov_b32_e32 v57, v182
	v_pk_mul_f32 v[192:193], v[40:41], s[2:3] op_sel_hi:[1,0]
	v_pk_fma_f32 v[40:41], v[40:41], s[2:3], v[190:191] op_sel_hi:[1,0,1]
	v_pk_fma_f32 v[56:57], v[56:57], s[2:3], v[24:25] op_sel_hi:[1,0,1]
	v_pk_mul_f32 v[178:179], v[40:41], v[40:41]
	v_pk_mul_f32 v[24:25], v[56:57], v[56:57]
	v_pk_mov_b32 v[178:179], v[190:191], v[178:179] op_sel:[1,0]
	v_pk_mov_b32 v[24:25], v[192:193], v[24:25] op_sel:[1,0]
	v_add_f32_e32 v8, 0, v9
	v_pk_add_f32 v[24:25], v[178:179], v[24:25]
	v_pk_add_f32 v[178:179], v[40:41], v[56:57]
	v_pk_mul_f32 v[190:191], v[40:41], v[56:57]
	v_fmac_f32_e32 v8, 0x3fd744fd, v183
	v_mov_b32_e32 v179, v191
	v_pk_add_f32 v[24:25], v[178:179], v[24:25]
	v_mul_f32_e32 v9, v8, v8
	v_pk_add_f32 v[24:25], v[24:25], v[8:9]
	s_nop 1
	v_mov_b32_dpp v178, v24 quad_perm:[1,0,3,2] row_mask:0xf bank_mask:0xf bound_ctrl:1
	v_mov_b32_dpp v179, v25 quad_perm:[1,0,3,2] row_mask:0xf bank_mask:0xf bound_ctrl:1
	v_pk_add_f32 v[24:25], v[24:25], v[178:179]
	s_nop 1
	v_mov_b32_dpp v178, v24 quad_perm:[2,3,0,1] row_mask:0xf bank_mask:0xf bound_ctrl:1
	v_mov_b32_dpp v179, v25 quad_perm:[2,3,0,1] row_mask:0xf bank_mask:0xf bound_ctrl:1
	v_pk_add_f32 v[24:25], v[24:25], v[178:179]
	s_nop 1
	v_mov_b32_dpp v178, v24 row_half_mirror row_mask:0xf bank_mask:0xf bound_ctrl:1
	v_mov_b32_dpp v179, v25 row_half_mirror row_mask:0xf bank_mask:0xf bound_ctrl:1
	v_pk_add_f32 v[24:25], v[24:25], v[178:179]
	s_nop 1
	v_mov_b32_dpp v178, v24 row_mirror row_mask:0xf bank_mask:0xf bound_ctrl:1
	v_mov_b32_dpp v179, v25 row_mirror row_mask:0xf bank_mask:0xf bound_ctrl:1
	s_and_saveexec_b64 s[6:7], vcc
	v_pk_add_f32 v[24:25], v[24:25], v[178:179]
	ds_write_b64 v181, v[24:25] offset:344
	s_or_b64 exec, exec, s[6:7]
	s_waitcnt vmcnt(0)
;   DI void operator()(f32x16 (&acc)[2][4], int grow0, int gcol0, int lane, int w, char* lds) {
;     ...
;       for (int qq = 0; qq < 2; ++qq)
; #pragma unroll
;         for (int e = 0; e < 4; ++e) {
;           const int i = 4 * (2 * (ps & 1) + qq) + e;
;           const float* xr = (const float*)(xs + (8 * qq + 4 * hh + e) * 512) + l31;
;           float s1 = 0.f, s2 = 0.f;
; #pragma unroll
;           for (int nt = 0; nt < 4; ++nt) {
;             float v = (acc[mt][nt][i] + bia[nt]) * csc[nt];
;             float z = ALPHA * xr[nt * 32] + hs * v;
;             acc[mt][nt][i] = z; s1 += z; s2 += z * z;
;           }
;           s1 = row16_sum(s1); s2 = row16_sum(s2);
;           if ((lane & 15) == 0) { f32x2 sv = {s1, s2}; *(f32x2*)(redw + (mt * 32 + (i & 3) + 8 * (i >> 2)) * 2) = sv; }
;         }
	ds_read2_b32 v[182:183], v73 offset1:32
	ds_read2_b32 v[192:193], v73 offset0:64 offset1:96
	v_add_f32_e32 v179, 0, v42
	v_mov_b32_e32 v190, v58
	v_mov_b32_e32 v191, v26
	s_waitcnt lgkmcnt(1)
	v_fmac_f32_e32 v179, 0x3fd744fd, v183
	v_pk_add_f32 v[194:195], v[190:191], 0 op_sel_hi:[1,0]
	s_waitcnt lgkmcnt(0)
	v_mov_b32_e32 v183, v192
	s_mov_b32 s2, s67
	v_pk_fma_f32 v[190:191], v[182:183], s[2:3], v[194:195] op_sel_hi:[1,0,1]
	v_mov_b32_e32 v178, v192
	v_pk_mul_f32 v[182:183], v[190:191], v[190:191]
	v_mov_b32_e32 v196, v165
	v_mov_b32_e32 v197, v179
	v_pk_mov_b32 v[182:183], v[194:195], v[182:183] op_sel:[1,0]
	v_add_f32_e32 v24, 0, v10
	v_pk_fma_f32 v[182:183], v[178:179], v[196:197], v[182:183]
	v_fmac_f32_e32 v24, 0x3fd744fd, v193
	v_pk_mov_b32 v[194:195], v[178:179], v[182:183] op_sel:[1,0]
	v_mul_f32_e32 v25, v24, v24
	v_pk_add_f32 v[196:197], v[190:191], v[194:195]
	v_pk_mul_f32 v[194:195], v[190:191], v[194:195]
	s_nop 0
	v_mov_b32_e32 v197, v195
	v_pk_add_f32 v[194:195], v[182:183], v[196:197]
	s_nop 0
	v_pk_add_f32 v[192:193], v[194:195], v[24:25]
	s_nop 1
	v_mov_b32_dpp v194, v192 quad_perm:[1,0,3,2] row_mask:0xf bank_mask:0xf bound_ctrl:1
	v_mov_b32_dpp v195, v193 quad_perm:[1,0,3,2] row_mask:0xf bank_mask:0xf bound_ctrl:1
	v_pk_add_f32 v[192:193], v[192:193], v[194:195]
	s_nop 1
	v_mov_b32_dpp v194, v192 quad_perm:[2,3,0,1] row_mask:0xf bank_mask:0xf bound_ctrl:1
	v_mov_b32_dpp v195, v193 quad_perm:[2,3,0,1] row_mask:0xf bank_mask:0xf bound_ctrl:1
	v_pk_add_f32 v[192:193], v[192:193], v[194:195]
	s_nop 1
	v_mov_b32_dpp v194, v192 row_half_mirror row_mask:0xf bank_mask:0xf bound_ctrl:1
	v_mov_b32_dpp v195, v193 row_half_mirror row_mask:0xf bank_mask:0xf bound_ctrl:1
	v_pk_add_f32 v[192:193], v[192:193], v[194:195]
	s_nop 1
	v_mov_b32_dpp v194, v192 row_mirror row_mask:0xf bank_mask:0xf bound_ctrl:1
	v_mov_b32_dpp v195, v193 row_mirror row_mask:0xf bank_mask:0xf bound_ctrl:1
	s_and_saveexec_b64 s[6:7], vcc
	v_pk_add_f32 v[192:193], v[192:193], v[194:195]
	ds_write_b64 v181, v[192:193] offset:384
	s_or_b64 exec, exec, s[6:7]
	ds_read2_b32 v[192:193], v85 offset1:32
	ds_read2_b32 v[194:195], v85 offset0:64 offset1:96
	v_mov_b32_e32 v26, v59
	v_pk_add_f32 v[196:197], v[26:27], 0 op_sel_hi:[1,0]
	v_mov_b32_e32 v26, v43
	v_pk_add_f32 v[26:27], v[26:27], 0 op_sel_hi:[1,0]
	s_waitcnt lgkmcnt(1)
	v_mov_b32_e32 v42, v192
	s_waitcnt lgkmcnt(0)
	v_mov_b32_e32 v43, v194
	s_mov_b32 s2, s67
	v_mov_b32_e32 v58, v193
	v_mov_b32_e32 v59, v194
	v_pk_mul_f32 v[198:199], v[42:43], s[2:3] op_sel_hi:[1,0]
	v_pk_fma_f32 v[42:43], v[42:43], s[2:3], v[196:197] op_sel_hi:[1,0,1]
	v_pk_fma_f32 v[58:59], v[58:59], s[2:3], v[26:27] op_sel_hi:[1,0,1]
	v_pk_mul_f32 v[192:193], v[42:43], v[42:43]
	v_pk_mul_f32 v[26:27], v[58:59], v[58:59]
	v_pk_mov_b32 v[192:193], v[196:197], v[192:193] op_sel:[1,0]
	v_pk_mov_b32 v[26:27], v[198:199], v[26:27] op_sel:[1,0]
	v_add_f32_e32 v10, 0, v11
	v_pk_add_f32 v[26:27], v[192:193], v[26:27]
	v_pk_add_f32 v[192:193], v[42:43], v[58:59]
	v_pk_mul_f32 v[196:197], v[42:43], v[58:59]
	v_fmac_f32_e32 v10, 0x3fd744fd, v195
	v_mov_b32_e32 v193, v197
	v_pk_add_f32 v[26:27], v[192:193], v[26:27]
	v_mul_f32_e32 v11, v10, v10
	v_pk_add_f32 v[26:27], v[26:27], v[10:11]
	s_nop 1
	v_mov_b32_dpp v192, v26 quad_perm:[1,0,3,2] row_mask:0xf bank_mask:0xf bound_ctrl:1
	v_mov_b32_dpp v193, v27 quad_perm:[1,0,3,2] row_mask:0xf bank_mask:0xf bound_ctrl:1
	v_pk_add_f32 v[26:27], v[26:27], v[192:193]
	s_nop 1
	v_mov_b32_dpp v192, v26 quad_perm:[2,3,0,1] row_mask:0xf bank_mask:0xf bound_ctrl:1
	v_mov_b32_dpp v193, v27 quad_perm:[2,3,0,1] row_mask:0xf bank_mask:0xf bound_ctrl:1
	v_pk_add_f32 v[26:27], v[26:27], v[192:193]
	s_nop 1
	v_mov_b32_dpp v192, v26 row_half_mirror row_mask:0xf bank_mask:0xf bound_ctrl:1
	v_mov_b32_dpp v193, v27 row_half_mirror row_mask:0xf bank_mask:0xf bound_ctrl:1
	v_pk_add_f32 v[26:27], v[26:27], v[192:193]
	s_nop 1
	v_mov_b32_dpp v192, v26 row_mirror row_mask:0xf bank_mask:0xf bound_ctrl:1
	v_mov_b32_dpp v193, v27 row_mirror row_mask:0xf bank_mask:0xf bound_ctrl:1
	s_and_saveexec_b64 s[6:7], vcc
	v_pk_add_f32 v[26:27], v[26:27], v[192:193]
	ds_write_b64 v181, v[26:27] offset:392
	s_or_b64 exec, exec, s[6:7]
	ds_read2_b32 v[192:193], v75 offset1:32
	ds_read2_b32 v[196:197], v75 offset0:64 offset1:96
	v_mov_b32_e32 v194, v60
	v_mov_b32_e32 v195, v28
	v_pk_add_f32 v[198:199], v[194:195], 0 op_sel_hi:[1,0]
	v_mov_b32_e32 v194, v44
	v_pk_add_f32 v[194:195], v[194:195], 0 op_sel_hi:[1,0]
	s_waitcnt lgkmcnt(1)
	v_mov_b32_e32 v202, v192
	s_waitcnt lgkmcnt(0)
	v_mov_b32_e32 v203, v196
	s_mov_b32 s2, s67
	v_mov_b32_e32 v206, v193
	v_mov_b32_e32 v207, v196
	v_pk_fma_f32 v[192:193], v[202:203], s[2:3], v[198:199] op_sel_hi:[1,0,1]
	v_pk_fma_f32 v[194:195], v[206:207], s[2:3], v[194:195] op_sel_hi:[1,0,1]
	v_pk_mul_f32 v[204:205], v[202:203], s[2:3] op_sel_hi:[1,0]
	v_pk_mul_f32 v[202:203], v[192:193], v[192:193]
	v_pk_mul_f32 v[206:207], v[194:195], v[194:195]
	v_pk_mov_b32 v[198:199], v[198:199], v[202:203] op_sel:[1,0]
	v_pk_mov_b32 v[202:203], v[204:205], v[206:207] op_sel:[1,0]
	v_add_f32_e32 v26, 0, v12
	v_pk_add_f32 v[198:199], v[198:199], v[202:203]
	v_pk_add_f32 v[202:203], v[192:193], v[194:195]
	v_pk_mul_f32 v[204:205], v[192:193], v[194:195]
	v_fmac_f32_e32 v26, 0x3fd744fd, v197
	v_mov_b32_e32 v203, v205
	v_pk_add_f32 v[198:199], v[202:203], v[198:199]
	v_mul_f32_e32 v27, v26, v26
	v_pk_add_f32 v[196:197], v[198:199], v[26:27]
	s_nop 1
	v_mov_b32_dpp v198, v196 quad_perm:[1,0,3,2] row_mask:0xf bank_mask:0xf bound_ctrl:1
	v_mov_b32_dpp v199, v197 quad_perm:[1,0,3,2] row_mask:0xf bank_mask:0xf bound_ctrl:1
	v_pk_add_f32 v[196:197], v[196:197], v[198:199]
	s_nop 1
	v_mov_b32_dpp v198, v196 quad_perm:[2,3,0,1] row_mask:0xf bank_mask:0xf bound_ctrl:1
	v_mov_b32_dpp v199, v197 quad_perm:[2,3,0,1] row_mask:0xf bank_mask:0xf bound_ctrl:1
	v_pk_add_f32 v[196:197], v[196:197], v[198:199]
	s_nop 1
	v_mov_b32_dpp v198, v196 row_half_mirror row_mask:0xf bank_mask:0xf bound_ctrl:1
	v_mov_b32_dpp v199, v197 row_half_mirror row_mask:0xf bank_mask:0xf bound_ctrl:1
	v_pk_add_f32 v[196:197], v[196:197], v[198:199]
	s_nop 1
	v_mov_b32_dpp v198, v196 row_mirror row_mask:0xf bank_mask:0xf bound_ctrl:1
	v_mov_b32_dpp v199, v197 row_mirror row_mask:0xf bank_mask:0xf bound_ctrl:1
	s_and_saveexec_b64 s[6:7], vcc
	v_pk_add_f32 v[196:197], v[196:197], v[198:199]
	ds_write_b64 v181, v[196:197] offset:400
	s_or_b64 exec, exec, s[6:7]
	ds_read2_b32 v[196:197], v87 offset1:32
	ds_read2_b32 v[198:199], v87 offset0:64 offset1:96
	v_mov_b32_e32 v28, v61
	v_pk_add_f32 v[202:203], v[28:29], 0 op_sel_hi:[1,0]
	v_mov_b32_e32 v28, v45
	v_pk_add_f32 v[28:29], v[28:29], 0 op_sel_hi:[1,0]
	s_waitcnt lgkmcnt(1)
;   DI void operator()(f32x16 (&acc)[2][4], int grow0, int gcol0, int lane, int w, char* lds) {
;     ...
;       for (int qq = 0; qq < 2; ++qq)
; #pragma unroll
;         for (int e = 0; e < 4; ++e) {
;           const int i = 4 * (2 * (ps & 1) + qq) + e;
;           const float* xr = (const float*)(xs + (8 * qq + 4 * hh + e) * 512) + l31;
;           float s1 = 0.f, s2 = 0.f;
; #pragma unroll
;           for (int nt = 0; nt < 4; ++nt) {
;             float v = (acc[mt][nt][i] + bia[nt]) * csc[nt];
;             float z = ALPHA * xr[nt * 32] + hs * v;
;             acc[mt][nt][i] = z; s1 += z; s2 += z * z;
;           }
;           s1 = row16_sum(s1); s2 = row16_sum(s2);
;           if ((lane & 15) == 0) { f32x2 sv = {s1, s2}; *(f32x2*)(redw + (mt * 32 + (i & 3) + 8 * (i >> 2)) * 2) = sv; }
;         }
	v_mov_b32_e32 v44, v196
	s_waitcnt lgkmcnt(0)
	v_mov_b32_e32 v45, v198
	s_mov_b32 s2, s67
	v_mov_b32_e32 v60, v197
	v_mov_b32_e32 v61, v198
	v_pk_mul_f32 v[204:205], v[44:45], s[2:3] op_sel_hi:[1,0]
	v_pk_fma_f32 v[44:45], v[44:45], s[2:3], v[202:203] op_sel_hi:[1,0,1]
	v_pk_fma_f32 v[60:61], v[60:61], s[2:3], v[28:29] op_sel_hi:[1,0,1]
	v_pk_mul_f32 v[196:197], v[44:45], v[44:45]
	v_pk_mul_f32 v[28:29], v[60:61], v[60:61]
	v_pk_mov_b32 v[196:197], v[202:203], v[196:197] op_sel:[1,0]
	v_pk_mov_b32 v[28:29], v[204:205], v[28:29] op_sel:[1,0]
	v_add_f32_e32 v12, 0, v13
	v_pk_add_f32 v[28:29], v[196:197], v[28:29]
	v_pk_add_f32 v[196:197], v[44:45], v[60:61]
	v_pk_mul_f32 v[202:203], v[44:45], v[60:61]
	v_fmac_f32_e32 v12, 0x3fd744fd, v199
	v_mov_b32_e32 v197, v203
	v_pk_add_f32 v[28:29], v[196:197], v[28:29]
	v_mul_f32_e32 v13, v12, v12
	v_pk_add_f32 v[28:29], v[28:29], v[12:13]
	s_nop 1
	v_mov_b32_dpp v196, v28 quad_perm:[1,0,3,2] row_mask:0xf bank_mask:0xf bound_ctrl:1
	v_mov_b32_dpp v197, v29 quad_perm:[1,0,3,2] row_mask:0xf bank_mask:0xf bound_ctrl:1
	v_pk_add_f32 v[28:29], v[28:29], v[196:197]
	s_nop 1
	v_mov_b32_dpp v196, v28 quad_perm:[2,3,0,1] row_mask:0xf bank_mask:0xf bound_ctrl:1
	v_mov_b32_dpp v197, v29 quad_perm:[2,3,0,1] row_mask:0xf bank_mask:0xf bound_ctrl:1
	v_pk_add_f32 v[28:29], v[28:29], v[196:197]
	s_nop 1
	v_mov_b32_dpp v196, v28 row_half_mirror row_mask:0xf bank_mask:0xf bound_ctrl:1
	v_mov_b32_dpp v197, v29 row_half_mirror row_mask:0xf bank_mask:0xf bound_ctrl:1
	v_pk_add_f32 v[28:29], v[28:29], v[196:197]
	s_nop 1
	v_mov_b32_dpp v196, v28 row_mirror row_mask:0xf bank_mask:0xf bound_ctrl:1
	v_mov_b32_dpp v197, v29 row_mirror row_mask:0xf bank_mask:0xf bound_ctrl:1
	s_and_saveexec_b64 s[6:7], vcc
	v_pk_add_f32 v[28:29], v[28:29], v[196:197]
	ds_write_b64 v181, v[28:29] offset:408
	s_or_b64 exec, exec, s[6:7]
	ds_read2_b32 v[196:197], v77 offset1:32
	ds_read2_b32 v[202:203], v77 offset0:64 offset1:96
	v_mov_b32_e32 v198, v62
	v_mov_b32_e32 v199, v30
	v_pk_add_f32 v[204:205], v[198:199], 0 op_sel_hi:[1,0]
	v_mov_b32_e32 v198, v46
	v_pk_add_f32 v[198:199], v[198:199], 0 op_sel_hi:[1,0]
	s_waitcnt lgkmcnt(1)
	v_mov_b32_e32 v206, v196
	s_waitcnt lgkmcnt(0)
	v_mov_b32_e32 v207, v202
	s_mov_b32 s2, s67
	v_mov_b32_e32 v212, v197
	v_mov_b32_e32 v213, v202
	v_pk_fma_f32 v[196:197], v[206:207], s[2:3], v[204:205] op_sel_hi:[1,0,1]
	v_pk_fma_f32 v[198:199], v[212:213], s[2:3], v[198:199] op_sel_hi:[1,0,1]
	v_pk_mul_f32 v[208:209], v[206:207], s[2:3] op_sel_hi:[1,0]
	v_pk_mul_f32 v[206:207], v[196:197], v[196:197]
	v_pk_mul_f32 v[212:213], v[198:199], v[198:199]
	v_pk_mov_b32 v[204:205], v[204:205], v[206:207] op_sel:[1,0]
	v_pk_mov_b32 v[206:207], v[208:209], v[212:213] op_sel:[1,0]
	v_add_f32_e32 v28, 0, v14
	v_pk_add_f32 v[204:205], v[204:205], v[206:207]
	v_pk_add_f32 v[206:207], v[196:197], v[198:199]
	v_pk_mul_f32 v[208:209], v[196:197], v[198:199]
	v_fmac_f32_e32 v28, 0x3fd744fd, v203
	v_mov_b32_e32 v207, v209
	v_pk_add_f32 v[204:205], v[206:207], v[204:205]
	v_mul_f32_e32 v29, v28, v28
	v_pk_add_f32 v[202:203], v[204:205], v[28:29]
	s_nop 1
	v_mov_b32_dpp v204, v202 quad_perm:[1,0,3,2] row_mask:0xf bank_mask:0xf bound_ctrl:1
	v_mov_b32_dpp v205, v203 quad_perm:[1,0,3,2] row_mask:0xf bank_mask:0xf bound_ctrl:1
	v_pk_add_f32 v[202:203], v[202:203], v[204:205]
	s_nop 1
	v_mov_b32_dpp v204, v202 quad_perm:[2,3,0,1] row_mask:0xf bank_mask:0xf bound_ctrl:1
	v_mov_b32_dpp v205, v203 quad_perm:[2,3,0,1] row_mask:0xf bank_mask:0xf bound_ctrl:1
	v_pk_add_f32 v[202:203], v[202:203], v[204:205]
	s_nop 1
	v_mov_b32_dpp v204, v202 row_half_mirror row_mask:0xf bank_mask:0xf bound_ctrl:1
	v_mov_b32_dpp v205, v203 row_half_mirror row_mask:0xf bank_mask:0xf bound_ctrl:1
	v_pk_add_f32 v[202:203], v[202:203], v[204:205]
	s_nop 1
	v_mov_b32_dpp v204, v202 row_mirror row_mask:0xf bank_mask:0xf bound_ctrl:1
	v_mov_b32_dpp v205, v203 row_mirror row_mask:0xf bank_mask:0xf bound_ctrl:1
	s_and_saveexec_b64 s[6:7], vcc
	v_pk_add_f32 v[202:203], v[202:203], v[204:205]
	ds_write_b64 v181, v[202:203] offset:448
	s_or_b64 exec, exec, s[6:7]
	ds_read2_b32 v[202:203], v91 offset1:32
	ds_read2_b32 v[204:205], v91 offset0:64 offset1:96
	v_mov_b32_e32 v30, v63
	v_pk_add_f32 v[206:207], v[30:31], 0 op_sel_hi:[1,0]
	v_mov_b32_e32 v30, v47
	v_pk_add_f32 v[30:31], v[30:31], 0 op_sel_hi:[1,0]
	s_waitcnt lgkmcnt(1)
	v_mov_b32_e32 v46, v202
	s_waitcnt lgkmcnt(0)
	v_mov_b32_e32 v47, v204
	s_mov_b32 s2, s67
	v_mov_b32_e32 v62, v203
	v_mov_b32_e32 v63, v204
	v_pk_mul_f32 v[208:209], v[46:47], s[2:3] op_sel_hi:[1,0]
	v_pk_fma_f32 v[46:47], v[46:47], s[2:3], v[206:207] op_sel_hi:[1,0,1]
	v_pk_fma_f32 v[62:63], v[62:63], s[2:3], v[30:31] op_sel_hi:[1,0,1]
	v_pk_mul_f32 v[202:203], v[46:47], v[46:47]
	v_pk_mul_f32 v[30:31], v[62:63], v[62:63]
	v_pk_mov_b32 v[202:203], v[206:207], v[202:203] op_sel:[1,0]
	v_pk_mov_b32 v[30:31], v[208:209], v[30:31] op_sel:[1,0]
	v_add_f32_e32 v14, 0, v15
	v_pk_add_f32 v[30:31], v[202:203], v[30:31]
	v_pk_add_f32 v[202:203], v[46:47], v[62:63]
	v_pk_mul_f32 v[206:207], v[46:47], v[62:63]
	v_fmac_f32_e32 v14, 0x3fd744fd, v205
	v_mov_b32_e32 v203, v207
	v_pk_add_f32 v[30:31], v[202:203], v[30:31]
	v_mul_f32_e32 v15, v14, v14
	v_pk_add_f32 v[30:31], v[30:31], v[14:15]
	s_nop 1
	v_mov_b32_dpp v202, v30 quad_perm:[1,0,3,2] row_mask:0xf bank_mask:0xf bound_ctrl:1
	v_mov_b32_dpp v203, v31 quad_perm:[1,0,3,2] row_mask:0xf bank_mask:0xf bound_ctrl:1
	v_pk_add_f32 v[30:31], v[30:31], v[202:203]
	s_nop 1
	v_mov_b32_dpp v202, v30 quad_perm:[2,3,0,1] row_mask:0xf bank_mask:0xf bound_ctrl:1
	v_mov_b32_dpp v203, v31 quad_perm:[2,3,0,1] row_mask:0xf bank_mask:0xf bound_ctrl:1
	v_pk_add_f32 v[30:31], v[30:31], v[202:203]
	s_nop 1
	v_mov_b32_dpp v202, v30 row_half_mirror row_mask:0xf bank_mask:0xf bound_ctrl:1
	v_mov_b32_dpp v203, v31 row_half_mirror row_mask:0xf bank_mask:0xf bound_ctrl:1
	v_pk_add_f32 v[30:31], v[30:31], v[202:203]
	s_nop 1
	v_mov_b32_dpp v202, v30 row_mirror row_mask:0xf bank_mask:0xf bound_ctrl:1
	v_mov_b32_dpp v203, v31 row_mirror row_mask:0xf bank_mask:0xf bound_ctrl:1
	s_and_saveexec_b64 s[6:7], vcc
	v_pk_add_f32 v[30:31], v[30:31], v[202:203]
	ds_write_b64 v181, v[30:31] offset:456
	s_or_b64 exec, exec, s[6:7]
	ds_read2_b32 v[202:203], v79 offset1:32
	ds_read2_b32 v[206:207], v79 offset0:64 offset1:96
	v_mov_b32_e32 v204, v64
	v_mov_b32_e32 v205, v32
	v_pk_add_f32 v[208:209], v[204:205], 0 op_sel_hi:[1,0]
	v_mov_b32_e32 v204, v48
	v_pk_add_f32 v[204:205], v[204:205], 0 op_sel_hi:[1,0]
	s_waitcnt lgkmcnt(1)
; DI void ag_st64(u64_t* p, u64_t v) { __hip_atomic_store(p, v, __ATOMIC_RELAXED, __HIP_MEMORY_SCOPE_AGENT); }
;   DI void operator()(f32x16 (&acc)[2][4], int grow0, int gcol0, int lane, int w, char* lds) {
;     ...
; #pragma unroll
;           for (int nt = 0; nt < 4; ++nt) {
;             float v = (acc[mt][nt][i] + bia[nt]) * csc[nt];
;             float z = ALPHA * xr[nt * 32] + hs * v;
;             acc[mt][nt][i] = z; s1 += z; s2 += z * z;
;           }
;           s1 = row16_sum(s1); s2 = row16_sum(s2);
;           if ((lane & 15) == 0) { f32x2 sv = {s1, s2}; *(f32x2*)(redw + (mt * 32 + (i & 3) + 8 * (i >> 2)) * 2) = sv; }
;         }
;     }
;     __syncthreads();
;     u64_t* myslots = xstat + ((size_t)pm * 256) * 4;
;     if (tid < 256) {
;       float s1 = (red[tid * 2] + red[(256 + tid) * 2]) + (red[(512 + tid) * 2] + red[(768 + tid) * 2]);
;       float s2 = (red[tid * 2 + 1] + red[(256 + tid) * 2 + 1]) + (red[(512 + tid) * 2 + 1] + red[(768 + tid) * 2 + 1]);
;       ag_st64(myslots + tid * 4 + pn, ((u64_t)__float_as_uint(s2) << 32) | (u64_t)__float_as_uint(s1));
	v_mov_b32_e32 v212, v202
	s_waitcnt lgkmcnt(0)
	v_mov_b32_e32 v213, v206
	s_mov_b32 s2, s67
	v_mov_b32_e32 v226, v203
	v_mov_b32_e32 v227, v206
	v_pk_fma_f32 v[202:203], v[212:213], s[2:3], v[208:209] op_sel_hi:[1,0,1]
	v_pk_fma_f32 v[204:205], v[226:227], s[2:3], v[204:205] op_sel_hi:[1,0,1]
	v_pk_mul_f32 v[214:215], v[212:213], s[2:3] op_sel_hi:[1,0]
	v_pk_mul_f32 v[212:213], v[202:203], v[202:203]
	v_pk_mul_f32 v[226:227], v[204:205], v[204:205]
	v_pk_mov_b32 v[208:209], v[208:209], v[212:213] op_sel:[1,0]
	v_pk_mov_b32 v[212:213], v[214:215], v[226:227] op_sel:[1,0]
	v_add_f32_e32 v30, 0, v16
	v_pk_add_f32 v[208:209], v[208:209], v[212:213]
	v_pk_add_f32 v[212:213], v[202:203], v[204:205]
	v_pk_mul_f32 v[214:215], v[202:203], v[204:205]
	v_fmac_f32_e32 v30, 0x3fd744fd, v207
	v_mov_b32_e32 v213, v215
	v_pk_add_f32 v[208:209], v[212:213], v[208:209]
	v_mul_f32_e32 v31, v30, v30
	v_pk_add_f32 v[206:207], v[208:209], v[30:31]
	s_nop 1
	v_mov_b32_dpp v208, v206 quad_perm:[1,0,3,2] row_mask:0xf bank_mask:0xf bound_ctrl:1
	v_mov_b32_dpp v209, v207 quad_perm:[1,0,3,2] row_mask:0xf bank_mask:0xf bound_ctrl:1
	v_pk_add_f32 v[206:207], v[206:207], v[208:209]
	s_nop 1
	v_mov_b32_dpp v208, v206 quad_perm:[2,3,0,1] row_mask:0xf bank_mask:0xf bound_ctrl:1
	v_mov_b32_dpp v209, v207 quad_perm:[2,3,0,1] row_mask:0xf bank_mask:0xf bound_ctrl:1
	v_pk_add_f32 v[206:207], v[206:207], v[208:209]
	s_nop 1
	v_mov_b32_dpp v208, v206 row_half_mirror row_mask:0xf bank_mask:0xf bound_ctrl:1
	v_mov_b32_dpp v209, v207 row_half_mirror row_mask:0xf bank_mask:0xf bound_ctrl:1
	v_pk_add_f32 v[206:207], v[206:207], v[208:209]
	s_nop 1
	v_mov_b32_dpp v208, v206 row_mirror row_mask:0xf bank_mask:0xf bound_ctrl:1
	v_mov_b32_dpp v209, v207 row_mirror row_mask:0xf bank_mask:0xf bound_ctrl:1
	s_and_saveexec_b64 s[6:7], vcc
	v_pk_add_f32 v[206:207], v[206:207], v[208:209]
	ds_write_b64 v181, v[206:207] offset:464
	s_or_b64 exec, exec, s[6:7]
	ds_read2_b32 v[206:207], v93 offset1:32
	ds_read2_b32 v[208:209], v93 offset0:64 offset1:96
	v_mov_b32_e32 v32, v65
	v_pk_add_f32 v[64:65], v[32:33], 0 op_sel_hi:[1,0]
	v_mov_b32_e32 v32, v49
	v_pk_add_f32 v[48:49], v[32:33], 0 op_sel_hi:[1,0]
	s_waitcnt lgkmcnt(1)
	v_mov_b32_e32 v32, v206
	s_waitcnt lgkmcnt(0)
	v_mov_b32_e32 v33, v208
	s_mov_b32 s2, s67
	v_mov_b32_e32 v206, v207
	v_mov_b32_e32 v207, v208
	v_pk_mul_f32 v[212:213], v[32:33], s[2:3] op_sel_hi:[1,0]
	v_pk_fma_f32 v[32:33], v[32:33], s[2:3], v[64:65] op_sel_hi:[1,0,1]
	v_pk_fma_f32 v[48:49], v[206:207], s[2:3], v[48:49] op_sel_hi:[1,0,1]
	v_pk_mul_f32 v[214:215], v[32:33], v[32:33]
	v_pk_mul_f32 v[206:207], v[48:49], v[48:49]
	v_pk_mov_b32 v[64:65], v[64:65], v[214:215] op_sel:[1,0]
	v_pk_mov_b32 v[206:207], v[212:213], v[206:207] op_sel:[1,0]
	v_add_f32_e32 v16, 0, v17
	v_pk_add_f32 v[64:65], v[64:65], v[206:207]
	v_pk_add_f32 v[206:207], v[32:33], v[48:49]
	v_pk_mul_f32 v[212:213], v[32:33], v[48:49]
	v_fmac_f32_e32 v16, 0x3fd744fd, v209
	v_mov_b32_e32 v207, v213
	v_pk_add_f32 v[64:65], v[206:207], v[64:65]
	v_mul_f32_e32 v17, v16, v16
	v_pk_add_f32 v[64:65], v[64:65], v[16:17]
	s_nop 1
	v_mov_b32_dpp v206, v64 quad_perm:[1,0,3,2] row_mask:0xf bank_mask:0xf bound_ctrl:1
	v_mov_b32_dpp v207, v65 quad_perm:[1,0,3,2] row_mask:0xf bank_mask:0xf bound_ctrl:1
	v_pk_add_f32 v[64:65], v[64:65], v[206:207]
	s_nop 1
	v_mov_b32_dpp v206, v64 quad_perm:[2,3,0,1] row_mask:0xf bank_mask:0xf bound_ctrl:1
	v_mov_b32_dpp v207, v65 quad_perm:[2,3,0,1] row_mask:0xf bank_mask:0xf bound_ctrl:1
	v_pk_add_f32 v[64:65], v[64:65], v[206:207]
	s_nop 1
	v_mov_b32_dpp v206, v64 row_half_mirror row_mask:0xf bank_mask:0xf bound_ctrl:1
	v_mov_b32_dpp v207, v65 row_half_mirror row_mask:0xf bank_mask:0xf bound_ctrl:1
	v_pk_add_f32 v[64:65], v[64:65], v[206:207]
	s_nop 1
	v_mov_b32_dpp v206, v64 row_mirror row_mask:0xf bank_mask:0xf bound_ctrl:1
	v_mov_b32_dpp v207, v65 row_mirror row_mask:0xf bank_mask:0xf bound_ctrl:1
	s_and_saveexec_b64 s[6:7], vcc
	v_pk_add_f32 v[64:65], v[64:65], v[206:207]
	ds_write_b64 v181, v[64:65] offset:472
	s_or_b64 exec, exec, s[6:7]
	v_ashrrev_i32_e32 v206, 8, v163
	v_ashrrev_i32_e32 v207, 31, v206
	v_lshlrev_b64 v[64:65], 13, v[206:207]
	v_lshl_add_u64 v[64:65], s[8:9], 0, v[64:65]
	v_cmp_gt_i32_e64 s[40:41], s60, v164
	v_ashrrev_i32_e32 v201, 31, v200
	s_waitcnt lgkmcnt(0)
	s_barrier
	s_and_saveexec_b64 s[6:7], s[40:41]
	s_cbranch_execz .LBB0_240
	v_lshl_add_u32 v0, v164, 3, v221
	ds_read2st64_b64 v[212:215], v0 offset1:4
	ds_read2st64_b64 v[226:229], v0 offset0:8 offset1:12
	v_ashrrev_i32_e32 v208, 8, v184
	v_ashrrev_i32_e32 v209, 31, v208
	s_waitcnt lgkmcnt(1)
	v_mov_b32_e32 v230, v212
	s_waitcnt lgkmcnt(0)
	v_mov_b32_e32 v231, v226
	v_mov_b32_e32 v232, v214
	v_mov_b32_e32 v233, v228
	v_mov_b32_e32 v226, v213
	v_mov_b32_e32 v228, v215
	v_pk_add_f32 v[230:231], v[230:231], v[232:233]
	v_pk_add_f32 v[212:213], v[226:227], v[228:229]
	v_pk_add_f32 v[230:231], v[230:231], v[230:231] op_sel:[0,1] op_sel_hi:[1,0]
	v_pk_add_f32 v[212:213], v[212:213], v[212:213] op_sel:[0,1] op_sel_hi:[1,0]
	v_lshl_add_u64 v[214:215], v[200:201], 3, v[64:65]
	v_lshl_add_u64 v[208:209], v[208:209], 3, v[214:215]
	v_mov_b32_e32 v231, v212
	global_store_dwordx2 v[208:209], v[230:231], off sc1

; DI f32x16 mfma(bf16x8 a, bf16x8 b, f32x16 c) { return __builtin_amdgcn_mfma_f32_32x32x16_bf16(a, b, c, 0, 0, 0); }
; template <int BK> DI int swz(int row) { constexpr int CPR = BK / 8; return (row / (16 / CPR)) % CPR; }
;     ...
;     bf16x8 fa[2][2], fb[2][NTW];
; #pragma unroll
;     for (int mt = 0; mt < 2; ++mt) { int row = wm * 64 + mt * 32 + l31; fa[0][mt] = *(const bf16x8*)(cur + row * (BK * 2) + ((hh ^ swz<BK>(row)) << 4)); }
; #pragma unroll
;     for (int nt = 0; nt < NTW; ++nt) { int row = wn * (32 * NTW) + nt * 32 + l31; fb[0][nt] = *(const bf16x8*)(cur + ABYTES + row * (BK * 2) + ((hh ^ swz<BK>(row)) << 4)); }
; #pragma unroll
;     for (int kk = 0; kk < NKK; ++kk) {
;       if (kk + 1 < NKK) {
;         const int ch = (kk + 1) * 2 + hh;
; #pragma unroll
;         for (int mt = 0; mt < 2; ++mt) { int row = wm * 64 + mt * 32 + l31; fa[(kk + 1) & 1][mt] = *(const bf16x8*)(cur + row * (BK * 2) + ((ch ^ swz<BK>(row)) << 4)); }
; #pragma unroll
;         for (int nt = 0; nt < NTW; ++nt) { int row = wn * (32 * NTW) + nt * 32 + l31; fb[(kk + 1) & 1][nt] = *(const bf16x8*)(cur + ABYTES + row * (BK * 2) + ((ch ^ swz<BK>(row)) << 4)); }
;       }
;       if (more) {
; #pragma unroll
;         for (int q = 0; q < PPK; ++q) {
;           const int pi = kk * PPK + q;
;           if (pi < NPA) stage_piece<BM, BK>(An, lda, nxt, tid, pi, wv);
;           else if (pi < NP) stage_piece<BN, BK>(Bn, ldb, nxt + ABYTES, tid, pi - NPA, wv);
;         }
;       }
;       __builtin_amdgcn_s_setprio(1);
; #pragma unroll
;       for (int mt = 0; mt < 2; ++mt)
; #pragma unroll
;         for (int nt = 0; nt < NTW; ++nt) acc[mt][nt] = mfma(fa[kk & 1][mt], fb[kk & 1][nt], acc[mt][nt]);
;       __builtin_amdgcn_s_setprio(0);
;       __builtin_amdgcn_sched_barrier(0);
;     }
.LBB0_284:
	s_and_b32 s35, s7, 0x10000
	s_xor_b32 s100, s35, 0x10000
	s_add_i32 s34, s35, s3
	v_add3_u32 v190, s100, v140, v161
	v_add3_u32 v194, s100, v142, v163
	ds_read_b128 v[190:193], v190
	v_add3_u32 v198, s100, v143, v159
	ds_read_b128 v[194:197], v194
	v_add3_u32 v202, s100, v152, v160
	ds_read_b128 v[198:201], v198 offset:32768
	v_add3_u32 v206, s100, v153, v157
	ds_read_b128 v[202:205], v202 offset:32768
	v_add3_u32 v210, s100, v156, v158
	ds_read_b128 v[206:209], v206 offset:32768
	ds_read_b128 v[210:213], v210 offset:32768
	v_lshl_add_u64 v[214:215], v[130:131], 0, s[30:31]
	v_lshl_add_u64 v[226:227], v[132:133], 0, s[30:31]
	s_mov_b32 m0, s34
	v_lshl_add_u64 v[228:229], v[214:215], 0, s[28:29]
	s_waitcnt lgkmcnt(6)
	v_mfma_f32_32x32x16_bf16 v[114:129], v[166:169], v[174:177], v[114:129]
	global_load_lds_dwordx4 v[228:229], off
	v_lshl_add_u64 v[228:229], v[214:215], 0, s[24:25]
	s_add_i32 m0, s34, 0x2000
	v_mfma_f32_32x32x16_bf16 v[98:113], v[166:169], v[178:181], v[98:113]
	global_load_lds_dwordx4 v[228:229], off
	v_lshl_add_u64 v[228:229], v[214:215], 0, s[26:27]
	s_add_i32 m0, s34, 0x4000
	v_mfma_f32_32x32x16_bf16 v[82:97], v[166:169], v[182:185], v[82:97]
	global_load_lds_dwordx4 v[228:229], off
	v_lshl_add_u64 v[228:229], v[214:215], 0, s[38:39]
	s_add_i32 m0, s34, 0x6000
	v_mfma_f32_32x32x16_bf16 v[66:81], v[166:169], v[186:189], v[66:81]
	global_load_lds_dwordx4 v[228:229], off
	v_lshl_add_u64 v[228:229], v[226:227], 0, s[28:29]
	s_add_i32 m0, s34, 0x8000
	v_mfma_f32_32x32x16_bf16 v[50:65], v[170:173], v[174:177], v[50:65]
	global_load_lds_dwordx4 v[228:229], off
	v_lshl_add_u64 v[228:229], v[226:227], 0, s[24:25]
	s_add_i32 m0, s34, 0xa000
	v_mfma_f32_32x32x16_bf16 v[34:49], v[170:173], v[178:181], v[34:49]
	global_load_lds_dwordx4 v[228:229], off
	v_lshl_add_u64 v[228:229], v[226:227], 0, s[26:27]
	s_add_i32 m0, s34, 0xc000
	v_mfma_f32_32x32x16_bf16 v[18:33], v[170:173], v[182:185], v[18:33]
	global_load_lds_dwordx4 v[228:229], off
	v_lshl_add_u64 v[228:229], v[226:227], 0, s[38:39]
	s_add_i32 m0, s34, 0xe000
	v_mfma_f32_32x32x16_bf16 v[2:17], v[170:173], v[186:189], v[2:17]
	global_load_lds_dwordx4 v[228:229], off
	v_add3_u32 v166, s100, v140, v149
	v_add3_u32 v170, s100, v142, v150
	ds_read_b128 v[166:169], v166
	v_add3_u32 v174, s100, v143, v147
	ds_read_b128 v[170:173], v170
	v_add3_u32 v178, s100, v152, v148
	ds_read_b128 v[174:177], v174 offset:32768
	v_add3_u32 v182, s100, v153, v145
	ds_read_b128 v[178:181], v178 offset:32768
	v_add3_u32 v186, s100, v156, v146
	ds_read_b128 v[182:185], v182 offset:32768
	ds_read_b128 v[186:189], v186 offset:32768
	s_waitcnt lgkmcnt(6)
	v_mfma_f32_32x32x16_bf16 v[114:129], v[190:193], v[198:201], v[114:129]
	v_mfma_f32_32x32x16_bf16 v[98:113], v[190:193], v[202:205], v[98:113]
	v_mfma_f32_32x32x16_bf16 v[82:97], v[190:193], v[206:209], v[82:97]
	v_mfma_f32_32x32x16_bf16 v[66:81], v[190:193], v[210:213], v[66:81]
	v_mfma_f32_32x32x16_bf16 v[50:65], v[194:197], v[198:201], v[50:65]
	v_mfma_f32_32x32x16_bf16 v[34:49], v[194:197], v[202:205], v[34:49]
	v_mfma_f32_32x32x16_bf16 v[18:33], v[194:197], v[206:209], v[18:33]
	v_mfma_f32_32x32x16_bf16 v[2:17], v[194:197], v[210:213], v[2:17]
	v_add3_u32 v190, s100, v140, v138
	v_add3_u32 v194, s100, v142, v139
	ds_read_b128 v[190:193], v190
	v_add3_u32 v198, s100, v143, v136
	ds_read_b128 v[194:197], v194
	v_add3_u32 v202, s100, v152, v137
	ds_read_b128 v[198:201], v198 offset:32768
	v_add3_u32 v206, s100, v153, v134
	ds_read_b128 v[202:205], v202 offset:32768
	v_add3_u32 v210, s100, v156, v135
	ds_read_b128 v[206:209], v206 offset:32768
	ds_read_b128 v[210:213], v210 offset:32768
	s_waitcnt lgkmcnt(6)
	v_mfma_f32_32x32x16_bf16 v[114:129], v[166:169], v[174:177], v[114:129]
	v_mfma_f32_32x32x16_bf16 v[98:113], v[166:169], v[178:181], v[98:113]
	v_mfma_f32_32x32x16_bf16 v[82:97], v[166:169], v[182:185], v[82:97]
	v_mfma_f32_32x32x16_bf16 v[66:81], v[166:169], v[186:189], v[66:81]
	v_mfma_f32_32x32x16_bf16 v[50:65], v[170:173], v[174:177], v[50:65]
	v_mfma_f32_32x32x16_bf16 v[34:49], v[170:173], v[178:181], v[34:49]
	v_mfma_f32_32x32x16_bf16 v[18:33], v[170:173], v[182:185], v[18:33]
	v_mfma_f32_32x32x16_bf16 v[2:17], v[170:173], v[186:189], v[2:17]
	s_add_u32 s30, s30, 0x80
	s_addc_u32 s31, s31, 0
	s_add_i32 s7, s7, 0x10000
	s_waitcnt vmcnt(0) lgkmcnt(0)
	s_barrier
	v_add3_u32 v166, s35, v140, v141
	v_add3_u32 v170, s35, v142, v144
	ds_read_b128 v[166:169], v166
	v_add3_u32 v174, s35, v143, v151
	ds_read_b128 v[170:173], v170
	v_add3_u32 v178, s35, v152, v154
	ds_read_b128 v[174:177], v174 offset:32768
	v_add3_u32 v182, s35, v153, v155
	ds_read_b128 v[178:181], v178 offset:32768
	v_add3_u32 v186, s35, v156, v164
	ds_read_b128 v[182:185], v182 offset:32768
	ds_read_b128 v[186:189], v186 offset:32768
	v_mfma_f32_32x32x16_bf16 v[114:129], v[190:193], v[198:201], v[114:129]
	v_mfma_f32_32x32x16_bf16 v[98:113], v[190:193], v[202:205], v[98:113]
	v_mfma_f32_32x32x16_bf16 v[82:97], v[190:193], v[206:209], v[82:97]
	v_mfma_f32_32x32x16_bf16 v[66:81], v[190:193], v[210:213], v[66:81]
	v_mfma_f32_32x32x16_bf16 v[50:65], v[194:197], v[198:201], v[50:65]
	v_mfma_f32_32x32x16_bf16 v[34:49], v[194:197], v[202:205], v[34:49]
	v_mfma_f32_32x32x16_bf16 v[18:33], v[194:197], v[206:209], v[18:33]
	v_mfma_f32_32x32x16_bf16 v[2:17], v[194:197], v[210:213], v[2:17]
	s_cmpk_eq_i32 s30, 0x780
	s_cbranch_scc0 .LBB0_284
; DI f32x16 mfma(bf16x8 a, bf16x8 b, f32x16 c) { return __builtin_amdgcn_mfma_f32_32x32x16_bf16(a, b, c, 0, 0, 0); }
; DI int launder(int x) { asm volatile("" : "+v"(x)); return x; }
; template <int BK> DI int swz(int row) { constexpr int CPR = BK / 8; return (row / (16 / CPR)) % CPR; }
; DI void wait_vm0() { asm volatile("s_waitcnt vmcnt(0)" ::: "memory"); }
;   DI void pre(int grow0, int gcol0, int lane, int w, char* lds) { xpass(0, grow0, gcol0, lane, w, lds); }
;     ...
;     for (int kk = 0; kk < NKK; ++kk) {
;       if (kk + 1 < NKK) {
;         const int ch = (kk + 1) * 2 + hh;
; #pragma unroll
;         for (int mt = 0; mt < 2; ++mt) { int row = wm * 64 + mt * 32 + l31; fa[(kk + 1) & 1][mt] = *(const bf16x8*)(cur + row * (BK * 2) + ((ch ^ swz<BK>(row)) << 4)); }
; #pragma unroll
;         for (int nt = 0; nt < NTW; ++nt) { int row = wn * (32 * NTW) + nt * 32 + l31; fb[(kk + 1) & 1][nt] = *(const bf16x8*)(cur + ABYTES + row * (BK * 2) + ((ch ^ swz<BK>(row)) << 4)); }
;       }
;       if (more) {
; #pragma unroll
;         for (int q = 0; q < PPK; ++q) {
;           const int pi = kk * PPK + q;
;           if (pi < NPA) stage_piece<BM, BK>(An, lda, nxt, tid, pi, wv);
;           else if (pi < NP) stage_piece<BN, BK>(Bn, ldb, nxt + ABYTES, tid, pi - NPA, wv);
;         }
;       }
;       __builtin_amdgcn_s_setprio(1);
; #pragma unroll
;       for (int mt = 0; mt < 2; ++mt)
; #pragma unroll
;         for (int nt = 0; nt < NTW; ++nt) acc[mt][nt] = mfma(fa[kk & 1][mt], fb[kk & 1][nt], acc[mt][nt]);
;       __builtin_amdgcn_s_setprio(0);
;       __builtin_amdgcn_sched_barrier(0);
;     }
;     wait_vm0();
;     __syncthreads();
;   }
;   if (has_next) { const int tid3 = launder(threadIdx.x); stage_tile<BM, BK>(A + (size_t)row0n * lda, lda, lds, tid3); stage_tile<BN, BK>(Bt + (size_t)col0n * ldb, ldb, lds + ABYTES, tid3); }
; template <class Epi>
; DI void gemm_phase256(const bf16_t* A, int lda, const bf16_t* Bt, int K, int nN, char* lds, Epi& epi, int vb) {
;     ...
;   for (int t = vb; t < ntiles; t += gridDim.x) {
;     const int x = t & 7, L = t >> 3; const int pm = 8 * x + (L & 7), pn = L >> 3;
;     const int t2 = t + gridDim.x; const bool hn = t2 < ntiles;
;     const int x2 = t2 & 7, L2 = t2 >> 3; const int pm2 = 8 * x2 + (L2 & 7), pn2 = L2 >> 3;
;     gemm_tile<4, 64>(A, lda, Bt, K, K, pm * 256, pn * 256, lds, epi, pre, hn, pm2 * 256, pn2 * 256);
;     pre = hn;
	s_waitcnt lgkmcnt(0)
	v_add_u32_e32 v0, 0x10000, v140
	v_add_u32_e32 v198, 0x10000, v142
	v_add_u32_e32 v130, v0, v141
	v_add_u32_e32 v140, v198, v144
	v_add_u32_e32 v199, 0x18000, v143
	v_add_u32_e32 v200, 0x18000, v152
	ds_read_b128 v[130:133], v130
	ds_read_b128 v[166:169], v140
	v_add_u32_e32 v140, v199, v151
	v_add_u32_e32 v144, v200, v154
	v_add_u32_e32 v201, 0x18000, v153
	ds_read_b128 v[140:143], v140
	ds_read_b128 v[170:173], v144
	v_add_u32_e32 v144, v201, v155
	v_add_u32_e32 v202, 0x18000, v156
	v_add_u32_e32 v151, v202, v164
	ds_read_b128 v[152:155], v144
	ds_read_b128 v[174:177], v151
	v_add_u32_e32 v144, v0, v161
	v_add_u32_e32 v151, v198, v163
	ds_read_b128 v[178:181], v144
	ds_read_b128 v[182:185], v151
	v_add_u32_e32 v144, v199, v159
	v_add_u32_e32 v151, v200, v160
	ds_read_b128 v[186:189], v144
	ds_read_b128 v[190:193], v151
	v_add_u32_e32 v144, v201, v157
	v_add_u32_e32 v151, v202, v158
	ds_read_b128 v[156:159], v144
	ds_read_b128 v[194:197], v151
	s_add_i32 s44, s44, s94
	s_cmpk_gt_i32 s44, 0xff
	s_cselect_b64 s[30:31], -1, 0
	s_cmpk_lt_i32 s44, 0x100
	s_setprio 1
	s_waitcnt lgkmcnt(9)
	v_mfma_f32_32x32x16_bf16 v[114:129], v[130:133], v[140:143], v[114:129]
	s_waitcnt lgkmcnt(8)
	v_mfma_f32_32x32x16_bf16 v[98:113], v[130:133], v[170:173], v[98:113]
	s_waitcnt lgkmcnt(7)
	v_mfma_f32_32x32x16_bf16 v[82:97], v[130:133], v[152:155], v[82:97]
	s_waitcnt lgkmcnt(6)
	v_mfma_f32_32x32x16_bf16 v[66:81], v[130:133], v[174:177], v[66:81]
	v_mfma_f32_32x32x16_bf16 v[50:65], v[166:169], v[140:143], v[50:65]
	v_mfma_f32_32x32x16_bf16 v[34:49], v[166:169], v[170:173], v[34:49]
	v_mfma_f32_32x32x16_bf16 v[18:33], v[166:169], v[152:155], v[18:33]
	v_mfma_f32_32x32x16_bf16 v[2:17], v[166:169], v[174:177], v[2:17]
	s_setprio 0
	v_add_u32_e32 v130, v0, v149
	v_add_u32_e32 v140, v198, v150
	v_add_u32_e32 v144, v199, v147
	ds_read_b128 v[130:133], v130
	ds_read_b128 v[140:143], v140
	v_add_u32_e32 v147, v200, v148
	ds_read_b128 v[148:151], v144
	ds_read_b128 v[152:155], v147
	v_add_u32_e32 v144, v201, v145
	v_add_u32_e32 v160, v202, v146
	ds_read_b128 v[144:147], v144
	ds_read_b128 v[166:169], v160
	s_setprio 1
	s_waitcnt lgkmcnt(9)
	v_mfma_f32_32x32x16_bf16 v[114:129], v[178:181], v[186:189], v[114:129]
	s_waitcnt lgkmcnt(8)
	v_mfma_f32_32x32x16_bf16 v[98:113], v[178:181], v[190:193], v[98:113]
	s_waitcnt lgkmcnt(7)
	v_mfma_f32_32x32x16_bf16 v[82:97], v[178:181], v[156:159], v[82:97]
	s_waitcnt lgkmcnt(6)
	v_mfma_f32_32x32x16_bf16 v[66:81], v[178:181], v[194:197], v[66:81]
	v_mfma_f32_32x32x16_bf16 v[50:65], v[182:185], v[186:189], v[50:65]
	v_mfma_f32_32x32x16_bf16 v[34:49], v[182:185], v[190:193], v[34:49]
	v_mfma_f32_32x32x16_bf16 v[18:33], v[182:185], v[156:159], v[18:33]
	v_mfma_f32_32x32x16_bf16 v[2:17], v[182:185], v[194:197], v[2:17]
	s_setprio 0
	v_add_u32_e32 v0, v0, v138
	v_add_u32_e32 v138, v198, v139
	ds_read_b128 v[156:159], v0
	ds_read_b128 v[170:173], v138
	v_add_u32_e32 v0, v199, v136
	v_add_u32_e32 v160, v200, v137
	ds_read_b128 v[136:139], v0
	ds_read_b128 v[174:177], v160
	v_add_u32_e32 v0, v201, v134
	v_add_u32_e32 v134, v202, v135
	ds_read_b128 v[178:181], v0
	ds_read_b128 v[182:185], v134
	s_setprio 1
	s_waitcnt lgkmcnt(9)
	v_mfma_f32_32x32x16_bf16 v[114:129], v[130:133], v[148:151], v[114:129]
	s_waitcnt lgkmcnt(8)
	v_mfma_f32_32x32x16_bf16 v[98:113], v[130:133], v[152:155], v[98:113]
	s_waitcnt lgkmcnt(7)
	v_mfma_f32_32x32x16_bf16 v[82:97], v[130:133], v[144:147], v[82:97]
	s_waitcnt lgkmcnt(6)
	v_mfma_f32_32x32x16_bf16 v[66:81], v[130:133], v[166:169], v[66:81]
	v_mfma_f32_32x32x16_bf16 v[50:65], v[140:143], v[148:151], v[50:65]
	v_mfma_f32_32x32x16_bf16 v[34:49], v[140:143], v[152:155], v[34:49]
	v_mfma_f32_32x32x16_bf16 v[18:33], v[140:143], v[144:147], v[18:33]
	v_mfma_f32_32x32x16_bf16 v[2:17], v[140:143], v[166:169], v[2:17]
	s_setprio 0
	s_setprio 1
	s_waitcnt lgkmcnt(3)
	v_mfma_f32_32x32x16_bf16 v[114:129], v[156:159], v[136:139], v[114:129]
	s_waitcnt lgkmcnt(2)
	v_mfma_f32_32x32x16_bf16 v[98:113], v[156:159], v[174:177], v[98:113]
	s_waitcnt lgkmcnt(1)
	v_mfma_f32_32x32x16_bf16 v[82:97], v[156:159], v[178:181], v[82:97]
	s_waitcnt lgkmcnt(0)
	v_mfma_f32_32x32x16_bf16 v[66:81], v[156:159], v[182:185], v[66:81]
	v_mfma_f32_32x32x16_bf16 v[50:65], v[170:173], v[136:139], v[50:65]
	v_mfma_f32_32x32x16_bf16 v[34:49], v[170:173], v[174:177], v[34:49]
	v_mfma_f32_32x32x16_bf16 v[18:33], v[170:173], v[178:181], v[18:33]
	v_mfma_f32_32x32x16_bf16 v[2:17], v[170:173], v[182:185], v[2:17]
	s_setprio 0
	s_waitcnt vmcnt(0)
	s_barrier
	s_cbranch_scc0 .LBB0_280
	v_mov_b32_e32 v132, v216
	s_lshl_b32 s3, s44, 3
	v_ashrrev_i32_e32 v0, 31, v132
	v_lshrrev_b32_e32 v130, 29, v0
	v_lshrrev_b32_e32 v0, 28, v0
	v_add_u32_e32 v0, v132, v0
	v_ashrrev_i32_e32 v0, 4, v0
	s_and_b32 s3, s3, 56
	s_bfe_u32 s7, s44, 0x30003
	v_lshrrev_b32_e32 v133, 29, v0
	s_or_b32 s3, s3, s7
	s_lshl_b32 s7, s44, 2
	v_add_u32_e32 v130, v132, v130
	v_add_u32_e32 v133, v0, v133
	s_and_b32 s34, s7, 0xffffff00
	s_lshl_b32 s3, s3, 19
	v_and_b32_e32 v131, 0xffffff8, v130
	v_and_b32_e32 v133, 0xffffff8, v133
	s_add_u32 s46, s12, s3
	v_sub_u32_e32 v131, v132, v131
	v_sub_u32_e32 v0, v0, v133
	v_lshlrev_b32_e32 v130, 8, v130
	v_readfirstlane_b32 s3, v132
	s_addc_u32 s47, s13, 0
	v_xor_b32_e32 v0, v0, v131
	v_and_b32_e32 v130, 0xfffff800, v130
	s_lshl_b32 s3, s3, 4
	v_lshl_add_u32 v0, v0, 4, v130
	s_and_b32 s3, s3, 0xfffffc00
	v_lshl_add_u64 v[130:131], s[46:47], 0, v[0:1]
	s_mov_b32 m0, s3
	v_lshl_add_u64 v[132:133], v[130:131], 0, s[58:59]
	global_load_lds_dwordx4 v0, s[46:47]
	s_add_i32 m0, s3, 0x2000
	s_ashr_i32 s35, s34, 31
	global_load_lds_dwordx4 v[132:133], off
	v_lshl_add_u64 v[132:133], v[130:131], 0, s[48:49]
	s_add_i32 m0, s3, 0x4000
	s_lshl_b64 s[34:35], s[34:35], 11
	global_load_lds_dwordx4 v[132:133], off
	s_add_i32 m0, s3, 0x6000
	s_add_u32 s34, s40, s34
	v_lshl_add_u64 v[130:131], v[130:131], 0, s[50:51]
	s_addc_u32 s35, s41, s35
	global_load_lds_dwordx4 v[130:131], off
	v_lshl_add_u64 v[130:131], s[34:35], 0, v[0:1]
	s_add_i32 m0, s3, 0x8000
	v_lshl_add_u64 v[132:133], v[130:131], 0, s[58:59]
	global_load_lds_dwordx4 v0, s[34:35]
	s_add_i32 m0, s3, 0xa000
	s_nop 0
	global_load_lds_dwordx4 v[132:133], off
	v_lshl_add_u64 v[132:133], v[130:131], 0, s[48:49]
	s_add_i32 m0, s3, 0xc000
	v_lshl_add_u64 v[130:131], v[130:131], 0, s[50:51]
	global_load_lds_dwordx4 v[132:133], off
	s_add_i32 m0, s3, 0xe000
	s_nop 0
	global_load_lds_dwordx4 v[130:131], off
	s_branch .LBB0_280

; DI f32x16 mfma(bf16x8 a, bf16x8 b, f32x16 c) { return __builtin_amdgcn_mfma_f32_32x32x16_bf16(a, b, c, 0, 0, 0); }
; template <int BK> DI int swz(int row) { constexpr int CPR = BK / 8; return (row / (16 / CPR)) % CPR; }
;     ...
;     bf16x8 fa[2][2], fb[2][NTW];
; #pragma unroll
;     for (int mt = 0; mt < 2; ++mt) { int row = wm * 64 + mt * 32 + l31; fa[0][mt] = *(const bf16x8*)(cur + row * (BK * 2) + ((hh ^ swz<BK>(row)) << 4)); }
; #pragma unroll
;     for (int nt = 0; nt < NTW; ++nt) { int row = wn * (32 * NTW) + nt * 32 + l31; fb[0][nt] = *(const bf16x8*)(cur + ABYTES + row * (BK * 2) + ((hh ^ swz<BK>(row)) << 4)); }
; #pragma unroll
;     for (int kk = 0; kk < NKK; ++kk) {
;       if (kk + 1 < NKK) {
;         const int ch = (kk + 1) * 2 + hh;
; #pragma unroll
;         for (int mt = 0; mt < 2; ++mt) { int row = wm * 64 + mt * 32 + l31; fa[(kk + 1) & 1][mt] = *(const bf16x8*)(cur + row * (BK * 2) + ((ch ^ swz<BK>(row)) << 4)); }
; #pragma unroll
;         for (int nt = 0; nt < NTW; ++nt) { int row = wn * (32 * NTW) + nt * 32 + l31; fb[(kk + 1) & 1][nt] = *(const bf16x8*)(cur + ABYTES + row * (BK * 2) + ((ch ^ swz<BK>(row)) << 4)); }
;       }
;       if (more) {
; #pragma unroll
;         for (int q = 0; q < PPK; ++q) {
;           const int pi = kk * PPK + q;
;           if (pi < NPA) stage_piece<BM, BK>(An, lda, nxt, tid, pi, wv);
;           else if (pi < NP) stage_piece<BN, BK>(Bn, ldb, nxt + ABYTES, tid, pi - NPA, wv);
;         }
;       }
;       __builtin_amdgcn_s_setprio(1);
; #pragma unroll
;       for (int mt = 0; mt < 2; ++mt)
; #pragma unroll
;         for (int nt = 0; nt < NTW; ++nt) acc[mt][nt] = mfma(fa[kk & 1][mt], fb[kk & 1][nt], acc[mt][nt]);
;       __builtin_amdgcn_s_setprio(0);
;       __builtin_amdgcn_sched_barrier(0);
;     }
.LBB0_292:
	s_and_b32 s30, s3, 0x10000
	s_xor_b32 s100, s30, 0x10000
	s_add_i32 s31, s30, s2
	v_add3_u32 v194, s100, v136, v164
	v_add3_u32 v198, s100, v144, v166
	ds_read_b128 v[194:197], v194
	v_add3_u32 v202, s100, v145, v161
	ds_read_b128 v[198:201], v198
	v_add3_u32 v206, s100, v152, v163
	ds_read_b128 v[202:205], v202 offset:32768
	v_add3_u32 v210, s100, v155, v159
	ds_read_b128 v[206:209], v206 offset:32768
	v_add3_u32 v226, s100, v158, v160
	ds_read_b128 v[210:213], v210 offset:32768
	ds_read_b128 v[226:229], v226 offset:32768
	v_lshl_add_u64 v[214:215], v[132:133], 0, s[6:7]
	v_lshl_add_u64 v[230:231], v[130:131], 0, s[6:7]
	s_mov_b32 m0, s31
	v_lshl_add_u64 v[232:233], v[214:215], 0, s[28:29]
	s_waitcnt lgkmcnt(6)
	v_mfma_f32_32x32x16_bf16 v[114:129], v[170:173], v[178:181], v[114:129]
	global_load_lds_dwordx4 v[232:233], off
	v_lshl_add_u64 v[232:233], v[214:215], 0, s[36:37]
	s_add_i32 m0, s31, 0x2000
	v_mfma_f32_32x32x16_bf16 v[98:113], v[170:173], v[182:185], v[98:113]
	global_load_lds_dwordx4 v[232:233], off
	v_lshl_add_u64 v[232:233], v[214:215], 0, s[40:41]
	s_add_i32 m0, s31, 0x4000
	v_mfma_f32_32x32x16_bf16 v[82:97], v[170:173], v[186:189], v[82:97]
	global_load_lds_dwordx4 v[232:233], off
	v_lshl_add_u64 v[232:233], v[214:215], 0, s[42:43]
	s_add_i32 m0, s31, 0x6000
	v_mfma_f32_32x32x16_bf16 v[66:81], v[170:173], v[190:193], v[66:81]
	global_load_lds_dwordx4 v[232:233], off
	v_lshl_add_u64 v[232:233], v[230:231], 0, s[28:29]
	s_add_i32 m0, s31, 0x8000
	v_mfma_f32_32x32x16_bf16 v[50:65], v[174:177], v[178:181], v[50:65]
	global_load_lds_dwordx4 v[232:233], off
	v_lshl_add_u64 v[232:233], v[230:231], 0, s[36:37]
	s_add_i32 m0, s31, 0xa000
	v_mfma_f32_32x32x16_bf16 v[34:49], v[174:177], v[182:185], v[34:49]
	global_load_lds_dwordx4 v[232:233], off
	v_lshl_add_u64 v[232:233], v[230:231], 0, s[40:41]
	s_add_i32 m0, s31, 0xc000
	v_mfma_f32_32x32x16_bf16 v[18:33], v[174:177], v[186:189], v[18:33]
	global_load_lds_dwordx4 v[232:233], off
	v_lshl_add_u64 v[232:233], v[230:231], 0, s[42:43]
	s_add_i32 m0, s31, 0xe000
	v_mfma_f32_32x32x16_bf16 v[2:17], v[174:177], v[190:193], v[2:17]
	global_load_lds_dwordx4 v[232:233], off
	v_add3_u32 v170, s100, v136, v153
	v_add3_u32 v174, s100, v144, v154
	ds_read_b128 v[170:173], v170
	v_add3_u32 v178, s100, v145, v149
	ds_read_b128 v[174:177], v174
	v_add3_u32 v182, s100, v152, v150
	ds_read_b128 v[178:181], v178 offset:32768
	v_add3_u32 v186, s100, v155, v147
	ds_read_b128 v[182:185], v182 offset:32768
	v_add3_u32 v190, s100, v158, v148
	ds_read_b128 v[186:189], v186 offset:32768
	ds_read_b128 v[190:193], v190 offset:32768
	s_waitcnt lgkmcnt(6)
	v_mfma_f32_32x32x16_bf16 v[114:129], v[194:197], v[202:205], v[114:129]
	v_mfma_f32_32x32x16_bf16 v[98:113], v[194:197], v[206:209], v[98:113]
	v_mfma_f32_32x32x16_bf16 v[82:97], v[194:197], v[210:213], v[82:97]
	v_mfma_f32_32x32x16_bf16 v[66:81], v[194:197], v[226:229], v[66:81]
	v_mfma_f32_32x32x16_bf16 v[50:65], v[198:201], v[202:205], v[50:65]
	v_mfma_f32_32x32x16_bf16 v[34:49], v[198:201], v[206:209], v[34:49]
	v_mfma_f32_32x32x16_bf16 v[18:33], v[198:201], v[210:213], v[18:33]
	v_mfma_f32_32x32x16_bf16 v[2:17], v[198:201], v[226:229], v[2:17]
	v_add3_u32 v194, s100, v136, v141
	v_add3_u32 v198, s100, v144, v142
	ds_read_b128 v[194:197], v194
	v_add3_u32 v202, s100, v145, v139
	ds_read_b128 v[198:201], v198
	v_add3_u32 v206, s100, v152, v140
	ds_read_b128 v[202:205], v202 offset:32768
	v_add3_u32 v210, s100, v155, v137
	ds_read_b128 v[206:209], v206 offset:32768
	v_add3_u32 v226, s100, v158, v138
	ds_read_b128 v[210:213], v210 offset:32768
	ds_read_b128 v[226:229], v226 offset:32768
	s_waitcnt lgkmcnt(6)
	v_mfma_f32_32x32x16_bf16 v[114:129], v[170:173], v[178:181], v[114:129]
	v_mfma_f32_32x32x16_bf16 v[98:113], v[170:173], v[182:185], v[98:113]
	v_mfma_f32_32x32x16_bf16 v[82:97], v[170:173], v[186:189], v[82:97]
	v_mfma_f32_32x32x16_bf16 v[66:81], v[170:173], v[190:193], v[66:81]
	v_mfma_f32_32x32x16_bf16 v[50:65], v[174:177], v[178:181], v[50:65]
	v_mfma_f32_32x32x16_bf16 v[34:49], v[174:177], v[182:185], v[34:49]
	v_mfma_f32_32x32x16_bf16 v[18:33], v[174:177], v[186:189], v[18:33]
	v_mfma_f32_32x32x16_bf16 v[2:17], v[174:177], v[190:193], v[2:17]
	s_add_u32 s6, s6, 0x80
	s_addc_u32 s7, s7, 0
	s_add_i32 s3, s3, 0x10000
	s_waitcnt vmcnt(0) lgkmcnt(0)
	s_barrier
	v_add3_u32 v170, s30, v136, v143
	v_add3_u32 v174, s30, v144, v146
	ds_read_b128 v[170:173], v170
	v_add3_u32 v178, s30, v145, v151
	ds_read_b128 v[174:177], v174
	v_add3_u32 v182, s30, v152, v156
	ds_read_b128 v[178:181], v178 offset:32768
	v_add3_u32 v186, s30, v155, v157
	ds_read_b128 v[182:185], v182 offset:32768
	v_add3_u32 v190, s30, v158, v167
	ds_read_b128 v[186:189], v186 offset:32768
	ds_read_b128 v[190:193], v190 offset:32768
	v_mfma_f32_32x32x16_bf16 v[114:129], v[194:197], v[202:205], v[114:129]
	v_mfma_f32_32x32x16_bf16 v[98:113], v[194:197], v[206:209], v[98:113]
	v_mfma_f32_32x32x16_bf16 v[82:97], v[194:197], v[210:213], v[82:97]
	v_mfma_f32_32x32x16_bf16 v[66:81], v[194:197], v[226:229], v[66:81]
	v_mfma_f32_32x32x16_bf16 v[50:65], v[198:201], v[202:205], v[50:65]
	v_mfma_f32_32x32x16_bf16 v[34:49], v[198:201], v[206:209], v[34:49]
	v_mfma_f32_32x32x16_bf16 v[18:33], v[198:201], v[210:213], v[18:33]
	v_mfma_f32_32x32x16_bf16 v[2:17], v[198:201], v[226:229], v[2:17]
	s_cmpk_lg_i32 s6, 0x1580
	s_cbranch_scc1 .LBB0_292
; DI f32x16 mfma(bf16x8 a, bf16x8 b, f32x16 c) { return __builtin_amdgcn_mfma_f32_32x32x16_bf16(a, b, c, 0, 0, 0); }
; DI void wait_vm0() { asm volatile("s_waitcnt vmcnt(0)" ::: "memory"); }
;     ...
;     if (!more) epi.pre(row0 + wm * 64, col0 + wn * (32 * NTW), lane, w, lds);
;     bf16x8 fa[2][2], fb[2][NTW];
; #pragma unroll
;     for (int mt = 0; mt < 2; ++mt) { int row = wm * 64 + mt * 32 + l31; fa[0][mt] = *(const bf16x8*)(cur + row * (BK * 2) + ((hh ^ swz<BK>(row)) << 4)); }
; #pragma unroll
;     for (int nt = 0; nt < NTW; ++nt) { int row = wn * (32 * NTW) + nt * 32 + l31; fb[0][nt] = *(const bf16x8*)(cur + ABYTES + row * (BK * 2) + ((hh ^ swz<BK>(row)) << 4)); }
; #pragma unroll
;     for (int kk = 0; kk < NKK; ++kk) {
;       if (kk + 1 < NKK) {
;         const int ch = (kk + 1) * 2 + hh;
; #pragma unroll
;         for (int mt = 0; mt < 2; ++mt) { int row = wm * 64 + mt * 32 + l31; fa[(kk + 1) & 1][mt] = *(const bf16x8*)(cur + row * (BK * 2) + ((ch ^ swz<BK>(row)) << 4)); }
; #pragma unroll
;         for (int nt = 0; nt < NTW; ++nt) { int row = wn * (32 * NTW) + nt * 32 + l31; fb[(kk + 1) & 1][nt] = *(const bf16x8*)(cur + ABYTES + row * (BK * 2) + ((ch ^ swz<BK>(row)) << 4)); }
;       }
;       if (more) {
; #pragma unroll
;         for (int q = 0; q < PPK; ++q) {
;           const int pi = kk * PPK + q;
;           if (pi < NPA) stage_piece<BM, BK>(An, lda, nxt, tid, pi, wv);
;           else if (pi < NP) stage_piece<BN, BK>(Bn, ldb, nxt + ABYTES, tid, pi - NPA, wv);
;         }
;       }
;       __builtin_amdgcn_s_setprio(1);
; #pragma unroll
;       for (int mt = 0; mt < 2; ++mt)
; #pragma unroll
;         for (int nt = 0; nt < NTW; ++nt) acc[mt][nt] = mfma(fa[kk & 1][mt], fb[kk & 1][nt], acc[mt][nt]);
;       __builtin_amdgcn_s_setprio(0);
;       __builtin_amdgcn_sched_barrier(0);
;     }
;     wait_vm0();
;     __syncthreads();
;   DI void xpass(int ps, int grow0, int gcol0, int lane, int w, char* lds) const {
;     char* xs = lds + (ps & 1) * 65536 + __builtin_amdgcn_readfirstlane(w) * 8192;
;     const float* xsrc = Xin + (size_t)(grow0 + (ps >> 1) * 32 + (ps & 1) * 16 + (lane >> 5)) * D_ + gcol0 + (lane & 31) * 4;
; #pragma unroll
;     for (int pc = 0; pc < 8; ++pc)
;       __builtin_amdgcn_global_load_lds((const unsigned*)(xsrc + (size_t)(2 * pc) * D_), (__attribute__((address_space(3))) unsigned*)(xs + pc * 1024), 16, 0, 0);
;   }
	s_waitcnt lgkmcnt(0)
	v_readlane_b32 s3, v253, 9
	v_readlane_b32 s6, v253, 27
	v_readlane_b32 s54, v255, 29
	v_or_b32_e32 v130, s3, v135
	v_add_u32_e32 v130, v130, v169
	v_ashrrev_i32_e32 v131, 31, v130
	v_lshlrev_b64 v[130:131], 12, v[130:131]
	v_add_u32_e32 v132, s6, v168
	v_readlane_b32 s55, v255, 30
	v_ashrrev_i32_e32 v133, 31, v132
	v_readfirstlane_b32 s2, v134
	v_lshl_add_u64 v[130:131], s[54:55], 0, v[130:131]
	v_lshlrev_b32_e32 v0, 4, v0
	s_lshl_b32 s2, s2, 13
	v_lshl_add_u64 v[130:131], v[132:133], 2, v[130:131]
	v_and_b32_e32 v0, 0x1f0, v0
	v_lshl_add_u64 v[130:131], v[130:131], 0, v[0:1]
	s_mov_b32 m0, s2
	s_mov_b64 s[34:35], 0x2000
	global_load_lds_dwordx4 v[130:131], off
	v_lshl_add_u64 v[132:133], v[130:131], 0, s[34:35]
	s_or_b32 m0, s2, 0x400
	s_mov_b64 s[36:37], 0x4000
	global_load_lds_dwordx4 v[132:133], off
	v_lshl_add_u64 v[132:133], v[130:131], 0, s[36:37]
	s_or_b32 m0, s2, 0x800
	s_mov_b64 s[40:41], 0x6000
	global_load_lds_dwordx4 v[132:133], off
	v_lshl_add_u64 v[132:133], v[130:131], 0, s[40:41]
	s_or_b32 m0, s2, 0xc00
	s_mov_b64 s[42:43], 0x8000
	global_load_lds_dwordx4 v[132:133], off
	v_lshl_add_u64 v[132:133], v[130:131], 0, s[42:43]
	s_or_b32 m0, s2, 0x1000
	s_mov_b64 s[44:45], 0xa000
	global_load_lds_dwordx4 v[132:133], off
	v_lshl_add_u64 v[132:133], v[130:131], 0, s[44:45]
	s_or_b32 m0, s2, 0x1400
	s_mov_b64 s[46:47], 0xc000
	global_load_lds_dwordx4 v[132:133], off
	v_lshl_add_u64 v[132:133], v[130:131], 0, s[46:47]
	s_or_b32 m0, s2, 0x1800
	s_mov_b64 s[52:53], 0xe000
	global_load_lds_dwordx4 v[132:133], off
	v_lshl_add_u64 v[130:131], v[130:131], 0, s[52:53]
	s_or_b32 m0, s2, 0x1c00
	v_add_u32_e32 v0, s30, v136
	global_load_lds_dwordx4 v[130:131], off
	v_add_u32_e32 v134, s30, v144
	v_add_u32_e32 v130, v0, v143
	v_add_u32_e32 v135, v134, v146
	s_waitcnt vmcnt(0)
	ds_read_b128 v[130:133], v130
	ds_read_b128 v[168:171], v135
	v_add_u32_e32 v135, s30, v145
	v_add_u32_e32 v136, v135, v151
	v_add_u32_e32 v143, s30, v152
	v_add_u32_e32 v144, v143, v156
	ds_read_b128 v[172:175], v136 offset:32768
	ds_read_b128 v[176:179], v144 offset:32768
	v_add_u32_e32 v136, s30, v155
	v_add_u32_e32 v144, v136, v157
	v_add_u32_e32 v208, s30, v158
	v_add_u32_e32 v145, v208, v167
	ds_read_b128 v[180:183], v144 offset:32768
	ds_read_b128 v[184:187], v145 offset:32768
	v_add_u32_e32 v144, v0, v164
	v_add_u32_e32 v145, v134, v166
	ds_read_b128 v[188:191], v144
	ds_read_b128 v[192:195], v145
	v_add_u32_e32 v144, v135, v161
	v_add_u32_e32 v145, v143, v163
	ds_read_b128 v[196:199], v144 offset:32768
	ds_read_b128 v[200:203], v145 offset:32768
	v_add_u32_e32 v144, v136, v159
	v_add_u32_e32 v145, v208, v160
	ds_read_b128 v[156:159], v144 offset:32768
	ds_read_b128 v[204:207], v145 offset:32768
	v_readlane_b32 s7, v253, 28
	s_setprio 1
	s_waitcnt lgkmcnt(0)
	v_mfma_f32_32x32x16_bf16 v[114:129], v[130:133], v[172:175], v[114:129]
	v_mfma_f32_32x32x16_bf16 v[98:113], v[130:133], v[176:179], v[98:113]
	v_mfma_f32_32x32x16_bf16 v[82:97], v[130:133], v[180:183], v[82:97]
	v_mfma_f32_32x32x16_bf16 v[66:81], v[130:133], v[184:187], v[66:81]
	v_mfma_f32_32x32x16_bf16 v[50:65], v[168:171], v[172:175], v[50:65]
	v_mfma_f32_32x32x16_bf16 v[34:49], v[168:171], v[176:179], v[34:49]
	v_mfma_f32_32x32x16_bf16 v[18:33], v[168:171], v[180:183], v[18:33]
	v_mfma_f32_32x32x16_bf16 v[2:17], v[168:171], v[184:187], v[2:17]
	s_setprio 0
	v_add_u32_e32 v130, v0, v153
	v_add_u32_e32 v144, v134, v154
	ds_read_b128 v[130:133], v130
	ds_read_b128 v[152:155], v144
	v_add_u32_e32 v144, v135, v149
	v_add_u32_e32 v145, v143, v150
	ds_read_b128 v[166:169], v144 offset:32768
	ds_read_b128 v[170:173], v145 offset:32768
	v_add_u32_e32 v144, v136, v147
	v_add_u32_e32 v148, v208, v148
	ds_read_b128 v[144:147], v144 offset:32768
	ds_read_b128 v[148:151], v148 offset:32768
	s_setprio 1
	v_mfma_f32_32x32x16_bf16 v[114:129], v[188:191], v[196:199], v[114:129]
	v_mfma_f32_32x32x16_bf16 v[98:113], v[188:191], v[200:203], v[98:113]
	v_mfma_f32_32x32x16_bf16 v[82:97], v[188:191], v[156:159], v[82:97]
	v_mfma_f32_32x32x16_bf16 v[66:81], v[188:191], v[204:207], v[66:81]
	v_mfma_f32_32x32x16_bf16 v[50:65], v[192:195], v[196:199], v[50:65]
	v_mfma_f32_32x32x16_bf16 v[34:49], v[192:195], v[200:203], v[34:49]
	v_mfma_f32_32x32x16_bf16 v[18:33], v[192:195], v[156:159], v[18:33]
	v_mfma_f32_32x32x16_bf16 v[2:17], v[192:195], v[204:207], v[2:17]
	s_setprio 0
	v_add_u32_e32 v0, v0, v141
	v_add_u32_e32 v134, v134, v142
	ds_read_b128 v[156:159], v0
	ds_read_b128 v[174:177], v134
	v_add_u32_e32 v0, v135, v139
	v_add_u32_e32 v134, v143, v140
	ds_read_b128 v[140:143], v0 offset:32768
	ds_read_b128 v[178:181], v134 offset:32768
	v_add_u32_e32 v0, v136, v137
	v_add_u32_e32 v138, v208, v138
	ds_read_b128 v[134:137], v0 offset:32768
	ds_read_b128 v[182:185], v138 offset:32768
	s_setprio 1
	s_waitcnt lgkmcnt(9)
	v_mfma_f32_32x32x16_bf16 v[114:129], v[130:133], v[166:169], v[114:129]
	s_waitcnt lgkmcnt(8)
	v_mfma_f32_32x32x16_bf16 v[98:113], v[130:133], v[170:173], v[98:113]
	s_waitcnt lgkmcnt(7)
	v_mfma_f32_32x32x16_bf16 v[82:97], v[130:133], v[144:147], v[82:97]
	s_waitcnt lgkmcnt(6)
	v_mfma_f32_32x32x16_bf16 v[66:81], v[130:133], v[148:151], v[66:81]
	v_mfma_f32_32x32x16_bf16 v[50:65], v[152:155], v[166:169], v[50:65]
	v_mfma_f32_32x32x16_bf16 v[34:49], v[152:155], v[170:173], v[34:49]
	v_mfma_f32_32x32x16_bf16 v[18:33], v[152:155], v[144:147], v[18:33]
	v_mfma_f32_32x32x16_bf16 v[2:17], v[152:155], v[148:151], v[2:17]
	s_setprio 0
	s_setprio 1
	s_waitcnt lgkmcnt(3)
	v_mfma_f32_32x32x16_bf16 v[114:129], v[156:159], v[140:143], v[114:129]
	s_waitcnt lgkmcnt(2)
	v_mfma_f32_32x32x16_bf16 v[98:113], v[156:159], v[178:181], v[98:113]
	s_waitcnt lgkmcnt(1)
	v_mfma_f32_32x32x16_bf16 v[82:97], v[156:159], v[134:137], v[82:97]
	s_waitcnt lgkmcnt(0)
	v_mfma_f32_32x32x16_bf16 v[66:81], v[156:159], v[182:185], v[66:81]
	v_mfma_f32_32x32x16_bf16 v[50:65], v[174:177], v[140:143], v[50:65]
	v_mfma_f32_32x32x16_bf16 v[34:49], v[174:177], v[178:181], v[34:49]
	v_mfma_f32_32x32x16_bf16 v[18:33], v[174:177], v[134:137], v[18:33]
	v_mfma_f32_32x32x16_bf16 v[2:17], v[174:177], v[182:185], v[2:17]
	s_setprio 0
	v_mov_b32_e32 v210, v216
	s_waitcnt vmcnt(0)
	s_barrier
;   DI void xpass(int ps, int grow0, int gcol0, int lane, int w, char* lds) const {
;     char* xs = lds + (ps & 1) * 65536 + __builtin_amdgcn_readfirstlane(w) * 8192;
;     const float* xsrc = Xin + (size_t)(grow0 + (ps >> 1) * 32 + (ps & 1) * 16 + (lane >> 5)) * D_ + gcol0 + (lane & 31) * 4;
; #pragma unroll
;     for (int pc = 0; pc < 8; ++pc)
;       __builtin_amdgcn_global_load_lds((const unsigned*)(xsrc + (size_t)(2 * pc) * D_), (__attribute__((address_space(3))) unsigned*)(xs + pc * 1024), 16, 0, 0);
;   }
;   DI void operator()(f32x16 (&acc)[2][4], int grow0, int gcol0, int lane, int w, char* lds) {
;     ...
;     for (int ps = 0; ps < 4; ++ps) {
;       const int mt = ps >> 1;
;       if (ps + 1 < 4) {
;         if (ps >= 1) asm volatile("s_waitcnt lgkmcnt(0)" ::: "memory");
;         xpass(ps + 1, grow0, gcol0, lane, w, lds);
;         if (ps >= 1) asm volatile("s_waitcnt vmcnt(8)" ::: "memory");
;       } else asm volatile("s_waitcnt vmcnt(0)" ::: "memory");
;       const char* xs = lds + (ps & 1) * 65536 + w * 8192;
; #pragma unroll
;       for (int qq = 0; qq < 2; ++qq)
; #pragma unroll
;         for (int e = 0; e < 4; ++e) {
;           const int i = 4 * (2 * (ps & 1) + qq) + e;
;           const float* xr = (const float*)(xs + (8 * qq + 4 * hh + e) * 512) + l31;
;           float s1 = 0.f, s2 = 0.f;
; #pragma unroll
;           for (int nt = 0; nt < 4; ++nt) {
;             float v = (acc[mt][nt][i] + bia[nt]) * csc[nt];
;             float z = ALPHA * xr[nt * 32] + hs * v;
;             acc[mt][nt][i] = z; s1 += z; s2 += z * z;
;           }
;           s1 = row16_sum(s1); s2 = row16_sum(s2);
;           if ((lane & 15) == 0) { f32x2 sv = {s1, s2}; *(f32x2*)(redw + (mt * 32 + (i & 3) + 8 * (i >> 2)) * 2) = sv; }
;         }
	v_add_f32_e32 v114, 0, v114
	v_ashrrev_i32_e32 v169, 6, v210
	v_lshrrev_b32_e32 v0, 30, v169
	v_add_u32_e32 v0, v169, v0
	v_ashrrev_i32_e32 v134, 2, v0
	v_mul_i32_i24_e32 v0, 4, v134
	v_sub_u32_e32 v0, v169, v0
	v_lshlrev_b32_e32 v135, 6, v0
	v_add_u32_e32 v164, s3, v135
	v_bfe_u32 v0, v210, 5, 1
	v_or_b32_e32 v176, v164, v0
	v_or_b32_e32 v130, 16, v176
	v_ashrrev_i32_e32 v131, 31, v130
	v_lshl_add_u32 v154, v134, 7, s6
	v_lshlrev_b32_e32 v168, 2, v210
	v_lshlrev_b64 v[130:131], 12, v[130:131]
	v_ashrrev_i32_e32 v155, 31, v154
	v_and_b32_e32 v0, 0x7c, v168
	v_readfirstlane_b32 s2, v169
	v_lshl_add_u64 v[130:131], s[54:55], 0, v[130:131]
	s_lshl_b32 s2, s2, 13
	v_lshl_add_u64 v[130:131], v[154:155], 2, v[130:131]
	v_lshlrev_b32_e32 v0, 2, v0
	s_add_i32 m0, s2, 0x10000
	v_lshl_add_u64 v[130:131], v[130:131], 0, v[0:1]
	global_load_lds_dwordx4 v[130:131], off
	v_lshl_add_u64 v[132:133], v[130:131], 0, s[34:35]
	s_add_i32 m0, s2, 0x10400
	v_and_b32_e32 v211, 0xc0, v135
	global_load_lds_dwordx4 v[132:133], off
	v_lshl_add_u64 v[132:133], v[130:131], 0, s[36:37]
	s_add_i32 m0, s2, 0x10800
	v_mov_b32_e32 v144, v98
	global_load_lds_dwordx4 v[132:133], off
	v_lshl_add_u64 v[132:133], v[130:131], 0, s[40:41]
	s_add_i32 m0, s2, 0x10c00
	v_mov_b32_e32 v145, v82
	global_load_lds_dwordx4 v[132:133], off
	v_lshl_add_u64 v[132:133], v[130:131], 0, s[42:43]
	s_add_i32 m0, s2, 0x11000
	v_mul_f32_e32 v141, 0.5, v114
	global_load_lds_dwordx4 v[132:133], off
	v_lshl_add_u64 v[132:133], v[130:131], 0, s[44:45]
	s_add_i32 m0, s2, 0x11400
	v_pk_add_f32 v[144:145], v[144:145], 0 op_sel_hi:[1,0]
	global_load_lds_dwordx4 v[132:133], off
	v_lshl_add_u64 v[132:133], v[130:131], 0, s[46:47]
	s_add_i32 m0, s2, 0x11800
	v_lshl_add_u64 v[130:131], v[130:131], 0, s[52:53]
	global_load_lds_dwordx4 v[132:133], off
	s_add_i32 m0, s2, 0x11c00
	v_bfe_u32 v132, v210, 4, 1
	global_load_lds_dwordx4 v[130:131], off
	v_and_b32_e32 v130, 31, v210
	v_lshlrev_b32_e32 v131, 1, v134
	v_bfe_u32 v134, v210, 3, 3
	v_and_or_b32 v131, v131, 2, v132
	v_and_b32_e32 v132, 4, v134
	v_lshlrev_b32_e32 v130, 2, v130
	v_or_b32_e32 v133, v211, v132
	v_lshl_or_b32 v138, v169, 13, v130
	v_lshlrev_b32_e32 v172, 9, v132
	v_lshlrev_b32_e32 v135, 3, v133
	v_or_b32_e32 v132, v138, v172
	v_and_b32_e32 v133, 15, v210
	v_lshl_or_b32 v139, v131, 11, v221
	s_waitcnt vmcnt(8)
	ds_read2_b32 v[130:131], v132 offset1:32
	v_cmp_eq_u32_e32 vcc, 0, v133
	ds_read2_b32 v[132:133], v132 offset0:64 offset1:96
	v_mov_b32_e32 v140, v82
	v_mov_b32_e32 v136, v1
	s_waitcnt lgkmcnt(0)
	v_mul_f32_e32 v137, 0x3fd744fd, v130
	v_mov_b32_e32 v130, v131
	v_mov_b32_e32 v131, v132
	s_mov_b32 s2, s67
	v_pk_add_f32 v[160:161], v[140:141], v[136:137]
	v_pk_mul_f32 v[130:131], v[130:131], s[2:3] op_sel_hi:[1,0]
	v_pk_mul_f32 v[136:137], v[144:145], 0.5 op_sel_hi:[1,0]
	v_pk_fma_f32 v[158:159], v[144:145], 0.5, v[130:131] op_sel_hi:[1,0,1]
	v_mov_b32_e32 v136, v161
	v_mov_b32_e32 v144, v1
	v_mov_b32_e32 v145, v131
	v_add_f32_e32 v142, 0, v66
	v_mov_b32_e32 v143, v133
	v_pk_mul_f32 v[140:141], v[158:159], v[158:159]
	v_pk_add_f32 v[136:137], v[136:137], v[144:145]
	v_mul_f32_e32 v66, 0x3fd744fd, v133
	v_mov_b32_e32 v163, v161
	v_pk_mov_b32 v[130:131], v[130:131], v[140:141] op_sel:[1,0]
	v_pk_add_f32 v[140:141], v[158:159], v[136:137]
	v_pk_mul_f32 v[136:137], v[158:159], v[136:137]
	v_pk_fma_f32 v[166:167], v[142:143], s[66:67], v[66:67] op_sel_hi:[1,1,0]
	v_pk_fma_f32 v[130:131], v[160:161], v[162:163], v[130:131]
	v_mov_b32_e32 v141, v137
	v_pk_mul_f32 v[132:133], v[166:167], v[166:167]
	v_pk_add_f32 v[130:131], v[140:141], v[130:131]
	v_mov_b32_e32 v167, v132
	v_pk_add_f32 v[130:131], v[130:131], v[166:167]
	v_add_u32_e32 v160, v139, v135
	s_nop 0
	v_mov_b32_dpp v132, v130 quad_perm:[1,0,3,2] row_mask:0xf bank_mask:0xf bound_ctrl:1
	v_mov_b32_dpp v133, v131 quad_perm:[1,0,3,2] row_mask:0xf bank_mask:0xf bound_ctrl:1
	v_pk_add_f32 v[130:131], v[130:131], v[132:133]
	s_nop 1
	v_mov_b32_dpp v132, v130 quad_perm:[2,3,0,1] row_mask:0xf bank_mask:0xf bound_ctrl:1
	v_mov_b32_dpp v133, v131 quad_perm:[2,3,0,1] row_mask:0xf bank_mask:0xf bound_ctrl:1
	v_pk_add_f32 v[130:131], v[130:131], v[132:133]
	s_nop 1
	v_mov_b32_dpp v132, v130 row_half_mirror row_mask:0xf bank_mask:0xf bound_ctrl:1
	v_mov_b32_dpp v133, v131 row_half_mirror row_mask:0xf bank_mask:0xf bound_ctrl:1
	v_pk_add_f32 v[130:131], v[130:131], v[132:133]
	s_nop 1
	v_mov_b32_dpp v132, v130 row_mirror row_mask:0xf bank_mask:0xf bound_ctrl:1
	v_mov_b32_dpp v133, v131 row_mirror row_mask:0xf bank_mask:0xf bound_ctrl:1
	s_and_saveexec_b64 s[6:7], vcc
	v_pk_add_f32 v[130:131], v[130:131], v[132:133]
	ds_write_b64 v160, v[130:131]
	s_or_b64 exec, exec, s[6:7]
	v_add_u32_e32 v167, v138, v172
	ds_read2_b32 v[130:131], v167 offset0:128 offset1:160
	ds_read2_b32 v[132:133], v167 offset0:192 offset1:224
	v_add_f32_e32 v82, 0, v115
	v_mul_f32_e32 v115, 0.5, v82
	v_mov_b32_e32 v82, v99
	s_waitcnt lgkmcnt(1)
	v_mul_f32_e32 v137, 0x3fd744fd, v130
	v_pk_add_f32 v[98:99], v[82:83], 0 op_sel_hi:[1,0]
	v_mov_b32_e32 v114, v83
	v_mov_b32_e32 v136, v1
	v_mov_b32_e32 v82, v131
	s_waitcnt lgkmcnt(0)
;   DI void operator()(f32x16 (&acc)[2][4], int grow0, int gcol0, int lane, int w, char* lds) {
;     ...
;       for (int qq = 0; qq < 2; ++qq)
; #pragma unroll
;         for (int e = 0; e < 4; ++e) {
;           const int i = 4 * (2 * (ps & 1) + qq) + e;
;           const float* xr = (const float*)(xs + (8 * qq + 4 * hh + e) * 512) + l31;
;           float s1 = 0.f, s2 = 0.f;
; #pragma unroll
;           for (int nt = 0; nt < 4; ++nt) {
;             float v = (acc[mt][nt][i] + bia[nt]) * csc[nt];
;             float z = ALPHA * xr[nt * 32] + hs * v;
;             acc[mt][nt][i] = z; s1 += z; s2 += z * z;
;           }
;           s1 = row16_sum(s1); s2 = row16_sum(s2);
;           if ((lane & 15) == 0) { f32x2 sv = {s1, s2}; *(f32x2*)(redw + (mt * 32 + (i & 3) + 8 * (i >> 2)) * 2) = sv; }
;         }
	v_mov_b32_e32 v83, v132
	s_mov_b32 s2, s67
	v_pk_add_f32 v[170:171], v[114:115], v[136:137]
	v_pk_mul_f32 v[82:83], v[82:83], s[2:3] op_sel_hi:[1,0]
	v_pk_mul_f32 v[114:115], v[98:99], 0.5 op_sel_hi:[1,0]
	v_pk_fma_f32 v[148:149], v[98:99], 0.5, v[82:83] op_sel_hi:[1,0,1]
	v_mov_b32_e32 v114, v171
	v_mov_b32_e32 v130, v1
	v_mov_b32_e32 v131, v83
	v_pk_mul_f32 v[98:99], v[148:149], v[148:149]
	v_pk_add_f32 v[114:115], v[114:115], v[130:131]
	v_mov_b32_e32 v163, v171
	v_pk_mov_b32 v[82:83], v[82:83], v[98:99] op_sel:[1,0]
	v_pk_add_f32 v[98:99], v[148:149], v[114:115]
	v_pk_mul_f32 v[114:115], v[148:149], v[114:115]
	v_pk_fma_f32 v[82:83], v[170:171], v[162:163], v[82:83]
	v_mov_b32_e32 v99, v115
	v_add_f32_e32 v66, 0, v67
	v_mov_b32_e32 v67, v133
	v_pk_add_f32 v[82:83], v[98:99], v[82:83]
	v_mul_f32_e32 v98, 0x3fd744fd, v133
	v_pk_fma_f32 v[142:143], v[66:67], s[66:67], v[98:99] op_sel_hi:[1,1,0]
	s_nop 0
	v_pk_mul_f32 v[66:67], v[142:143], v[142:143]
	s_nop 0
	v_mov_b32_e32 v143, v66
	v_pk_add_f32 v[66:67], v[82:83], v[142:143]
	s_nop 1
	v_mov_b32_dpp v82, v66 quad_perm:[1,0,3,2] row_mask:0xf bank_mask:0xf bound_ctrl:1
	v_mov_b32_dpp v83, v67 quad_perm:[1,0,3,2] row_mask:0xf bank_mask:0xf bound_ctrl:1
	v_pk_add_f32 v[66:67], v[66:67], v[82:83]
	s_nop 1
	v_mov_b32_dpp v82, v66 quad_perm:[2,3,0,1] row_mask:0xf bank_mask:0xf bound_ctrl:1
	v_mov_b32_dpp v83, v67 quad_perm:[2,3,0,1] row_mask:0xf bank_mask:0xf bound_ctrl:1
	v_pk_add_f32 v[66:67], v[66:67], v[82:83]
	s_nop 1
	v_mov_b32_dpp v82, v66 row_half_mirror row_mask:0xf bank_mask:0xf bound_ctrl:1
	v_mov_b32_dpp v83, v67 row_half_mirror row_mask:0xf bank_mask:0xf bound_ctrl:1
	v_pk_add_f32 v[66:67], v[66:67], v[82:83]
	s_nop 1
	v_mov_b32_dpp v82, v66 row_mirror row_mask:0xf bank_mask:0xf bound_ctrl:1
	v_mov_b32_dpp v83, v67 row_mirror row_mask:0xf bank_mask:0xf bound_ctrl:1
	s_and_saveexec_b64 s[6:7], vcc
	v_pk_add_f32 v[66:67], v[66:67], v[82:83]
	ds_write_b64 v160, v[66:67] offset:8
	s_or_b64 exec, exec, s[6:7]
	v_add_u32_e32 v143, 0x400, v167
	ds_read2_b32 v[66:67], v143 offset1:32
	ds_read2_b32 v[82:83], v143 offset0:64 offset1:96
	v_add_f32_e32 v99, 0, v116
	v_mov_b32_e32 v132, v100
	v_mov_b32_e32 v133, v84
	v_mul_f32_e32 v115, 0.5, v99
	s_waitcnt lgkmcnt(1)
	v_mul_f32_e32 v131, 0x3fd744fd, v66
	v_pk_add_f32 v[132:133], v[132:133], 0 op_sel_hi:[1,0]
	v_mov_b32_e32 v114, v84
	v_mov_b32_e32 v130, v1
	v_mov_b32_e32 v66, v67
	s_waitcnt lgkmcnt(0)
	v_mov_b32_e32 v67, v82
	s_mov_b32 s2, s67
	v_pk_add_f32 v[144:145], v[114:115], v[130:131]
	v_pk_mul_f32 v[114:115], v[66:67], s[2:3] op_sel_hi:[1,0]
	v_pk_mul_f32 v[130:131], v[132:133], 0.5 op_sel_hi:[1,0]
	v_pk_fma_f32 v[66:67], v[132:133], 0.5, v[114:115] op_sel_hi:[1,0,1]
	v_mov_b32_e32 v130, v145
	v_mov_b32_e32 v136, v1
	v_mov_b32_e32 v137, v115
	v_add_f32_e32 v98, 0, v68
	v_mov_b32_e32 v99, v83
	v_pk_mul_f32 v[132:133], v[66:67], v[66:67]
	v_pk_add_f32 v[130:131], v[130:131], v[136:137]
	v_mul_f32_e32 v68, 0x3fd744fd, v83
	v_mov_b32_e32 v163, v145
	v_pk_mov_b32 v[114:115], v[114:115], v[132:133] op_sel:[1,0]
	v_pk_add_f32 v[132:133], v[66:67], v[130:131]
	v_pk_mul_f32 v[130:131], v[66:67], v[130:131]
	v_pk_fma_f32 v[82:83], v[98:99], s[66:67], v[68:69] op_sel_hi:[1,1,0]
	v_pk_fma_f32 v[114:115], v[144:145], v[162:163], v[114:115]
	v_mov_b32_e32 v133, v131
	v_pk_mul_f32 v[98:99], v[82:83], v[82:83]
	v_pk_add_f32 v[114:115], v[132:133], v[114:115]
	v_mov_b32_e32 v83, v98
	v_pk_add_f32 v[98:99], v[114:115], v[82:83]
	s_nop 1
	v_mov_b32_dpp v114, v98 quad_perm:[1,0,3,2] row_mask:0xf bank_mask:0xf bound_ctrl:1
	v_mov_b32_dpp v115, v99 quad_perm:[1,0,3,2] row_mask:0xf bank_mask:0xf bound_ctrl:1
	v_pk_add_f32 v[98:99], v[98:99], v[114:115]
	s_nop 1
	v_mov_b32_dpp v114, v98 quad_perm:[2,3,0,1] row_mask:0xf bank_mask:0xf bound_ctrl:1
	v_mov_b32_dpp v115, v99 quad_perm:[2,3,0,1] row_mask:0xf bank_mask:0xf bound_ctrl:1
	v_pk_add_f32 v[98:99], v[98:99], v[114:115]
	s_nop 1
	v_mov_b32_dpp v114, v98 row_half_mirror row_mask:0xf bank_mask:0xf bound_ctrl:1
	v_mov_b32_dpp v115, v99 row_half_mirror row_mask:0xf bank_mask:0xf bound_ctrl:1
	v_pk_add_f32 v[98:99], v[98:99], v[114:115]
	s_nop 1
	v_mov_b32_dpp v114, v98 row_mirror row_mask:0xf bank_mask:0xf bound_ctrl:1
	v_mov_b32_dpp v115, v99 row_mirror row_mask:0xf bank_mask:0xf bound_ctrl:1
	s_and_saveexec_b64 s[6:7], vcc
	v_pk_add_f32 v[98:99], v[98:99], v[114:115]
	ds_write_b64 v160, v[98:99] offset:16
	s_or_b64 exec, exec, s[6:7]
	v_lshlrev_b32_e32 v139, 9, v134
	v_or_b32_e32 v152, 0x600, v139
	v_add_u32_e32 v144, v138, v152
	ds_read2_b32 v[114:115], v144 offset1:32
	ds_read2_b32 v[130:131], v144 offset0:64 offset1:96
	v_add_f32_e32 v68, 0, v117
	v_add_f32_e32 v116, 0, v69
	v_mul_f32_e32 v69, 0.5, v68
	s_waitcnt lgkmcnt(1)
	v_mul_f32_e32 v99, 0x3fd744fd, v114
	v_mov_b32_e32 v84, v101
	v_mov_b32_e32 v68, v85
	v_mov_b32_e32 v98, v1
	v_pk_add_f32 v[100:101], v[84:85], 0 op_sel_hi:[1,0]
	v_pk_add_f32 v[98:99], v[68:69], v[98:99]
	v_mov_b32_e32 v68, v115
	s_waitcnt lgkmcnt(0)
;   DI void operator()(f32x16 (&acc)[2][4], int grow0, int gcol0, int lane, int w, char* lds) {
;     ...
;     for (int ps = 0; ps < 4; ++ps) {
;       const int mt = ps >> 1;
;       if (ps + 1 < 4) {
;         if (ps >= 1) asm volatile("s_waitcnt lgkmcnt(0)" ::: "memory");
;         xpass(ps + 1, grow0, gcol0, lane, w, lds);
;         if (ps >= 1) asm volatile("s_waitcnt vmcnt(8)" ::: "memory");
;       } else asm volatile("s_waitcnt vmcnt(0)" ::: "memory");
;       const char* xs = lds + (ps & 1) * 65536 + w * 8192;
; #pragma unroll
;       for (int qq = 0; qq < 2; ++qq)
; #pragma unroll
;         for (int e = 0; e < 4; ++e) {
;           const int i = 4 * (2 * (ps & 1) + qq) + e;
;           const float* xr = (const float*)(xs + (8 * qq + 4 * hh + e) * 512) + l31;
;           float s1 = 0.f, s2 = 0.f;
; #pragma unroll
;           for (int nt = 0; nt < 4; ++nt) {
;             float v = (acc[mt][nt][i] + bia[nt]) * csc[nt];
;             float z = ALPHA * xr[nt * 32] + hs * v;
;             acc[mt][nt][i] = z; s1 += z; s2 += z * z;
;           }
;           s1 = row16_sum(s1); s2 = row16_sum(s2);
;           if ((lane & 15) == 0) { f32x2 sv = {s1, s2}; *(f32x2*)(redw + (mt * 32 + (i & 3) + 8 * (i >> 2)) * 2) = sv; }
;         }
	v_mov_b32_e32 v69, v130
	s_mov_b32 s2, s67
	v_pk_mul_f32 v[84:85], v[68:69], s[2:3] op_sel_hi:[1,0]
	v_pk_mul_f32 v[114:115], v[100:101], 0.5 op_sel_hi:[1,0]
	v_pk_fma_f32 v[68:69], v[100:101], 0.5, v[84:85] op_sel_hi:[1,0,1]
	v_mov_b32_e32 v114, v99
	v_mov_b32_e32 v132, v1
	v_mov_b32_e32 v133, v85
	v_pk_mul_f32 v[100:101], v[68:69], v[68:69]
	v_pk_add_f32 v[114:115], v[114:115], v[132:133]
	v_mov_b32_e32 v163, v99
	v_pk_mov_b32 v[84:85], v[84:85], v[100:101] op_sel:[1,0]
	v_pk_add_f32 v[100:101], v[68:69], v[114:115]
	v_pk_mul_f32 v[114:115], v[68:69], v[114:115]
	v_pk_fma_f32 v[84:85], v[98:99], v[162:163], v[84:85]
	v_mov_b32_e32 v101, v115
	v_mov_b32_e32 v117, v131
	v_pk_add_f32 v[100:101], v[100:101], v[84:85]
	v_mul_f32_e32 v84, 0x3fd744fd, v131
	v_pk_fma_f32 v[84:85], v[116:117], s[66:67], v[84:85] op_sel_hi:[1,1,0]
	s_nop 0
	v_pk_mul_f32 v[114:115], v[84:85], v[84:85]
	s_nop 0
	v_mov_b32_e32 v85, v114
	v_pk_add_f32 v[100:101], v[100:101], v[84:85]
	s_nop 1
	v_mov_b32_dpp v114, v100 quad_perm:[1,0,3,2] row_mask:0xf bank_mask:0xf bound_ctrl:1
	v_mov_b32_dpp v115, v101 quad_perm:[1,0,3,2] row_mask:0xf bank_mask:0xf bound_ctrl:1
	v_pk_add_f32 v[100:101], v[100:101], v[114:115]
	s_nop 1
	v_mov_b32_dpp v114, v100 quad_perm:[2,3,0,1] row_mask:0xf bank_mask:0xf bound_ctrl:1
	v_mov_b32_dpp v115, v101 quad_perm:[2,3,0,1] row_mask:0xf bank_mask:0xf bound_ctrl:1
	v_pk_add_f32 v[100:101], v[100:101], v[114:115]
	s_nop 1
	v_mov_b32_dpp v114, v100 row_half_mirror row_mask:0xf bank_mask:0xf bound_ctrl:1
	v_mov_b32_dpp v115, v101 row_half_mirror row_mask:0xf bank_mask:0xf bound_ctrl:1
	v_pk_add_f32 v[100:101], v[100:101], v[114:115]
	s_nop 1
	v_mov_b32_dpp v114, v100 row_mirror row_mask:0xf bank_mask:0xf bound_ctrl:1
	v_mov_b32_dpp v115, v101 row_mirror row_mask:0xf bank_mask:0xf bound_ctrl:1
	s_and_saveexec_b64 s[6:7], vcc
	v_pk_add_f32 v[100:101], v[100:101], v[114:115]
	ds_write_b64 v160, v[100:101] offset:24
	s_or_b64 exec, exec, s[6:7]
	v_add_u32_e32 v83, 0x1000, v167
	ds_read2_b32 v[100:101], v83 offset1:32
	ds_read2_b32 v[114:115], v83 offset0:64 offset1:96
	v_add_f32_e32 v85, 0, v118
	v_mov_b32_e32 v134, v102
	v_mov_b32_e32 v135, v86
	v_mul_f32_e32 v117, 0.5, v85
	s_waitcnt lgkmcnt(1)
	v_mul_f32_e32 v133, 0x3fd744fd, v100
	v_pk_add_f32 v[134:135], v[134:135], 0 op_sel_hi:[1,0]
	v_mov_b32_e32 v116, v86
	v_mov_b32_e32 v132, v1
	v_mov_b32_e32 v100, v101
	s_waitcnt lgkmcnt(0)
	v_mov_b32_e32 v101, v114
	s_mov_b32 s2, s67
	v_pk_add_f32 v[116:117], v[116:117], v[132:133]
	v_pk_mul_f32 v[132:133], v[100:101], s[2:3] op_sel_hi:[1,0]
	v_pk_mul_f32 v[136:137], v[134:135], 0.5 op_sel_hi:[1,0]
	v_pk_fma_f32 v[100:101], v[134:135], 0.5, v[132:133] op_sel_hi:[1,0,1]
	v_mov_b32_e32 v136, v117
	v_mov_b32_e32 v140, v1
	v_mov_b32_e32 v141, v133
	v_add_f32_e32 v130, 0, v70
	v_mov_b32_e32 v131, v115
	v_pk_mul_f32 v[134:135], v[100:101], v[100:101]
	v_pk_add_f32 v[136:137], v[136:137], v[140:141]
	v_mul_f32_e32 v70, 0x3fd744fd, v115
	v_mov_b32_e32 v163, v117
	v_pk_mov_b32 v[132:133], v[132:133], v[134:135] op_sel:[1,0]
	v_pk_add_f32 v[134:135], v[100:101], v[136:137]
	v_pk_mul_f32 v[136:137], v[100:101], v[136:137]
	v_pk_fma_f32 v[114:115], v[130:131], s[66:67], v[70:71] op_sel_hi:[1,1,0]
	v_pk_fma_f32 v[132:133], v[116:117], v[162:163], v[132:133]
	v_mov_b32_e32 v135, v137
	v_pk_mul_f32 v[130:131], v[114:115], v[114:115]
	v_pk_add_f32 v[132:133], v[134:135], v[132:133]
	v_mov_b32_e32 v115, v130
	v_pk_add_f32 v[130:131], v[132:133], v[114:115]
	s_nop 1
	v_mov_b32_dpp v132, v130 quad_perm:[1,0,3,2] row_mask:0xf bank_mask:0xf bound_ctrl:1
	v_mov_b32_dpp v133, v131 quad_perm:[1,0,3,2] row_mask:0xf bank_mask:0xf bound_ctrl:1
	v_pk_add_f32 v[130:131], v[130:131], v[132:133]
	s_nop 1
	v_mov_b32_dpp v132, v130 quad_perm:[2,3,0,1] row_mask:0xf bank_mask:0xf bound_ctrl:1
	v_mov_b32_dpp v133, v131 quad_perm:[2,3,0,1] row_mask:0xf bank_mask:0xf bound_ctrl:1
	v_pk_add_f32 v[130:131], v[130:131], v[132:133]
	s_nop 1
	v_mov_b32_dpp v132, v130 row_half_mirror row_mask:0xf bank_mask:0xf bound_ctrl:1
	v_mov_b32_dpp v133, v131 row_half_mirror row_mask:0xf bank_mask:0xf bound_ctrl:1
	v_pk_add_f32 v[130:131], v[130:131], v[132:133]
	s_nop 1
	v_mov_b32_dpp v132, v130 row_mirror row_mask:0xf bank_mask:0xf bound_ctrl:1
	v_mov_b32_dpp v133, v131 row_mirror row_mask:0xf bank_mask:0xf bound_ctrl:1
	s_and_saveexec_b64 s[6:7], vcc
	v_pk_add_f32 v[130:131], v[130:131], v[132:133]
	ds_write_b64 v160, v[130:131] offset:64
	s_or_b64 exec, exec, s[6:7]
	ds_read2_b32 v[130:131], v83 offset0:128 offset1:160
	ds_read2_b32 v[132:133], v83 offset0:192 offset1:224
	v_add_f32_e32 v70, 0, v119
	v_add_f32_e32 v118, 0, v71
	v_mul_f32_e32 v71, 0.5, v70
	s_waitcnt lgkmcnt(1)
	v_mul_f32_e32 v135, 0x3fd744fd, v130
	v_mov_b32_e32 v86, v103
	v_mov_b32_e32 v70, v87
	v_mov_b32_e32 v134, v1
	v_pk_add_f32 v[136:137], v[86:87], 0 op_sel_hi:[1,0]
	v_pk_add_f32 v[102:103], v[70:71], v[134:135]
	v_mov_b32_e32 v70, v131
	s_waitcnt lgkmcnt(0)
;   DI void operator()(f32x16 (&acc)[2][4], int grow0, int gcol0, int lane, int w, char* lds) {
;     ...
;     for (int ps = 0; ps < 4; ++ps) {
;       const int mt = ps >> 1;
;       if (ps + 1 < 4) {
;         if (ps >= 1) asm volatile("s_waitcnt lgkmcnt(0)" ::: "memory");
;         xpass(ps + 1, grow0, gcol0, lane, w, lds);
;         if (ps >= 1) asm volatile("s_waitcnt vmcnt(8)" ::: "memory");
;       } else asm volatile("s_waitcnt vmcnt(0)" ::: "memory");
;       const char* xs = lds + (ps & 1) * 65536 + w * 8192;
; #pragma unroll
;       for (int qq = 0; qq < 2; ++qq)
; #pragma unroll
;         for (int e = 0; e < 4; ++e) {
;           const int i = 4 * (2 * (ps & 1) + qq) + e;
;           const float* xr = (const float*)(xs + (8 * qq + 4 * hh + e) * 512) + l31;
;           float s1 = 0.f, s2 = 0.f;
; #pragma unroll
;           for (int nt = 0; nt < 4; ++nt) {
;             float v = (acc[mt][nt][i] + bia[nt]) * csc[nt];
;             float z = ALPHA * xr[nt * 32] + hs * v;
;             acc[mt][nt][i] = z; s1 += z; s2 += z * z;
;           }
;           s1 = row16_sum(s1); s2 = row16_sum(s2);
;           if ((lane & 15) == 0) { f32x2 sv = {s1, s2}; *(f32x2*)(redw + (mt * 32 + (i & 3) + 8 * (i >> 2)) * 2) = sv; }
;         }
	v_mov_b32_e32 v71, v132
	s_mov_b32 s2, s67
	v_pk_mul_f32 v[86:87], v[70:71], s[2:3] op_sel_hi:[1,0]
	v_pk_mul_f32 v[130:131], v[136:137], 0.5 op_sel_hi:[1,0]
	v_pk_fma_f32 v[70:71], v[136:137], 0.5, v[86:87] op_sel_hi:[1,0,1]
	v_mov_b32_e32 v130, v103
	v_mov_b32_e32 v136, v1
	v_mov_b32_e32 v137, v87
	v_pk_mul_f32 v[134:135], v[70:71], v[70:71]
	v_pk_add_f32 v[130:131], v[130:131], v[136:137]
	v_mov_b32_e32 v163, v103
	v_pk_mov_b32 v[86:87], v[86:87], v[134:135] op_sel:[1,0]
	v_pk_add_f32 v[134:135], v[70:71], v[130:131]
	v_pk_mul_f32 v[130:131], v[70:71], v[130:131]
	v_pk_fma_f32 v[86:87], v[102:103], v[162:163], v[86:87]
	v_mov_b32_e32 v135, v131
	v_mov_b32_e32 v119, v133
	v_pk_add_f32 v[130:131], v[134:135], v[86:87]
	v_mul_f32_e32 v86, 0x3fd744fd, v133
	v_pk_fma_f32 v[86:87], v[118:119], s[66:67], v[86:87] op_sel_hi:[1,1,0]
	s_nop 0
	v_pk_mul_f32 v[118:119], v[86:87], v[86:87]
	s_nop 0
	v_mov_b32_e32 v87, v118
	v_pk_add_f32 v[118:119], v[130:131], v[86:87]
	s_nop 1
	v_mov_b32_dpp v130, v118 quad_perm:[1,0,3,2] row_mask:0xf bank_mask:0xf bound_ctrl:1
	v_mov_b32_dpp v131, v119 quad_perm:[1,0,3,2] row_mask:0xf bank_mask:0xf bound_ctrl:1
	v_pk_add_f32 v[118:119], v[118:119], v[130:131]
	s_nop 1
	v_mov_b32_dpp v130, v118 quad_perm:[2,3,0,1] row_mask:0xf bank_mask:0xf bound_ctrl:1
	v_mov_b32_dpp v131, v119 quad_perm:[2,3,0,1] row_mask:0xf bank_mask:0xf bound_ctrl:1
	v_pk_add_f32 v[118:119], v[118:119], v[130:131]
	s_nop 1
	v_mov_b32_dpp v130, v118 row_half_mirror row_mask:0xf bank_mask:0xf bound_ctrl:1
	v_mov_b32_dpp v131, v119 row_half_mirror row_mask:0xf bank_mask:0xf bound_ctrl:1
	v_pk_add_f32 v[118:119], v[118:119], v[130:131]
	s_nop 1
	v_mov_b32_dpp v130, v118 row_mirror row_mask:0xf bank_mask:0xf bound_ctrl:1
	v_mov_b32_dpp v131, v119 row_mirror row_mask:0xf bank_mask:0xf bound_ctrl:1
	s_and_saveexec_b64 s[6:7], vcc
	v_pk_add_f32 v[118:119], v[118:119], v[130:131]
	ds_write_b64 v160, v[118:119] offset:72
	s_or_b64 exec, exec, s[6:7]
	v_add_u32_e32 v85, 0x1400, v167
	ds_read2_b32 v[118:119], v85 offset1:32
	ds_read2_b32 v[130:131], v85 offset0:64 offset1:96
	v_add_f32_e32 v87, 0, v120
	v_mov_b32_e32 v140, v104
	v_mov_b32_e32 v141, v88
	v_mul_f32_e32 v133, 0.5, v87
	s_waitcnt lgkmcnt(1)
	v_mul_f32_e32 v137, 0x3fd744fd, v118
	v_pk_add_f32 v[140:141], v[140:141], 0 op_sel_hi:[1,0]
	v_mov_b32_e32 v132, v88
	v_mov_b32_e32 v136, v1
	v_mov_b32_e32 v118, v119
	s_waitcnt lgkmcnt(0)
	v_mov_b32_e32 v119, v130
	s_mov_b32 s2, s67
	v_pk_add_f32 v[132:133], v[132:133], v[136:137]
	v_pk_mul_f32 v[136:137], v[118:119], s[2:3] op_sel_hi:[1,0]
	v_pk_mul_f32 v[146:147], v[140:141], 0.5 op_sel_hi:[1,0]
	v_pk_fma_f32 v[118:119], v[140:141], 0.5, v[136:137] op_sel_hi:[1,0,1]
	v_mov_b32_e32 v146, v133
	v_mov_b32_e32 v150, v1
	v_mov_b32_e32 v151, v137
	v_add_f32_e32 v134, 0, v72
	v_mov_b32_e32 v135, v131
	v_pk_mul_f32 v[140:141], v[118:119], v[118:119]
	v_pk_add_f32 v[146:147], v[146:147], v[150:151]
	v_mul_f32_e32 v72, 0x3fd744fd, v131
	v_mov_b32_e32 v163, v133
	v_pk_mov_b32 v[136:137], v[136:137], v[140:141] op_sel:[1,0]
	v_pk_add_f32 v[140:141], v[118:119], v[146:147]
	v_pk_mul_f32 v[146:147], v[118:119], v[146:147]
	v_pk_fma_f32 v[130:131], v[134:135], s[66:67], v[72:73] op_sel_hi:[1,1,0]
	v_pk_fma_f32 v[136:137], v[132:133], v[162:163], v[136:137]
	v_mov_b32_e32 v141, v147
	v_pk_mul_f32 v[134:135], v[130:131], v[130:131]
	v_pk_add_f32 v[136:137], v[140:141], v[136:137]
	v_mov_b32_e32 v131, v134
	v_pk_add_f32 v[134:135], v[136:137], v[130:131]
	s_nop 1
	v_mov_b32_dpp v136, v134 quad_perm:[1,0,3,2] row_mask:0xf bank_mask:0xf bound_ctrl:1
	v_mov_b32_dpp v137, v135 quad_perm:[1,0,3,2] row_mask:0xf bank_mask:0xf bound_ctrl:1
	v_pk_add_f32 v[134:135], v[134:135], v[136:137]
	s_nop 1
	v_mov_b32_dpp v136, v134 quad_perm:[2,3,0,1] row_mask:0xf bank_mask:0xf bound_ctrl:1
	v_mov_b32_dpp v137, v135 quad_perm:[2,3,0,1] row_mask:0xf bank_mask:0xf bound_ctrl:1
	v_pk_add_f32 v[134:135], v[134:135], v[136:137]
	s_nop 1
	v_mov_b32_dpp v136, v134 row_half_mirror row_mask:0xf bank_mask:0xf bound_ctrl:1
	v_mov_b32_dpp v137, v135 row_half_mirror row_mask:0xf bank_mask:0xf bound_ctrl:1
	v_pk_add_f32 v[134:135], v[134:135], v[136:137]
	s_nop 1
	v_mov_b32_dpp v136, v134 row_mirror row_mask:0xf bank_mask:0xf bound_ctrl:1
	v_mov_b32_dpp v137, v135 row_mirror row_mask:0xf bank_mask:0xf bound_ctrl:1
	s_and_saveexec_b64 s[6:7], vcc
	v_pk_add_f32 v[134:135], v[134:135], v[136:137]
	ds_write_b64 v160, v[134:135] offset:80
	s_or_b64 exec, exec, s[6:7]
	v_or_b32_e32 v115, 0x1600, v139
	v_add_u32_e32 v87, v138, v115
	ds_read2_b32 v[134:135], v87 offset1:32
	ds_read2_b32 v[136:137], v87 offset0:64 offset1:96
	v_add_f32_e32 v72, 0, v121
	v_add_f32_e32 v120, 0, v73
	v_mul_f32_e32 v73, 0.5, v72
	s_waitcnt lgkmcnt(1)
	v_mul_f32_e32 v141, 0x3fd744fd, v134
	v_mov_b32_e32 v88, v105
	v_mov_b32_e32 v72, v89
	v_mov_b32_e32 v140, v1
	v_pk_add_f32 v[146:147], v[88:89], 0 op_sel_hi:[1,0]
	v_pk_add_f32 v[104:105], v[72:73], v[140:141]
	v_mov_b32_e32 v72, v135
	s_waitcnt lgkmcnt(0)
;   DI void xpass(int ps, int grow0, int gcol0, int lane, int w, char* lds) const {
;     char* xs = lds + (ps & 1) * 65536 + __builtin_amdgcn_readfirstlane(w) * 8192;
;     const float* xsrc = Xin + (size_t)(grow0 + (ps >> 1) * 32 + (ps & 1) * 16 + (lane >> 5)) * D_ + gcol0 + (lane & 31) * 4;
; #pragma unroll
;     for (int pc = 0; pc < 8; ++pc)
;       __builtin_amdgcn_global_load_lds((const unsigned*)(xsrc + (size_t)(2 * pc) * D_), (__attribute__((address_space(3))) unsigned*)(xs + pc * 1024), 16, 0, 0);
;   }
;   DI void operator()(f32x16 (&acc)[2][4], int grow0, int gcol0, int lane, int w, char* lds) {
;     ...
;     for (int ps = 0; ps < 4; ++ps) {
;       const int mt = ps >> 1;
;       if (ps + 1 < 4) {
;         if (ps >= 1) asm volatile("s_waitcnt lgkmcnt(0)" ::: "memory");
;         xpass(ps + 1, grow0, gcol0, lane, w, lds);
;         if (ps >= 1) asm volatile("s_waitcnt vmcnt(8)" ::: "memory");
;       } else asm volatile("s_waitcnt vmcnt(0)" ::: "memory");
;       const char* xs = lds + (ps & 1) * 65536 + w * 8192;
; #pragma unroll
;       for (int qq = 0; qq < 2; ++qq)
; #pragma unroll
;         for (int e = 0; e < 4; ++e) {
;           const int i = 4 * (2 * (ps & 1) + qq) + e;
;           const float* xr = (const float*)(xs + (8 * qq + 4 * hh + e) * 512) + l31;
;           float s1 = 0.f, s2 = 0.f;
; #pragma unroll
;           for (int nt = 0; nt < 4; ++nt) {
;             float v = (acc[mt][nt][i] + bia[nt]) * csc[nt];
;             float z = ALPHA * xr[nt * 32] + hs * v;
;             acc[mt][nt][i] = z; s1 += z; s2 += z * z;
;           }
;           s1 = row16_sum(s1); s2 = row16_sum(s2);
;           if ((lane & 15) == 0) { f32x2 sv = {s1, s2}; *(f32x2*)(redw + (mt * 32 + (i & 3) + 8 * (i >> 2)) * 2) = sv; }
;         }
	v_mov_b32_e32 v73, v136
	s_mov_b32 s2, s67
	v_pk_mul_f32 v[88:89], v[72:73], s[2:3] op_sel_hi:[1,0]
	v_pk_mul_f32 v[134:135], v[146:147], 0.5 op_sel_hi:[1,0]
	v_pk_fma_f32 v[72:73], v[146:147], 0.5, v[88:89] op_sel_hi:[1,0,1]
	v_mov_b32_e32 v134, v105
	v_mov_b32_e32 v146, v1
	v_mov_b32_e32 v147, v89
	v_pk_mul_f32 v[140:141], v[72:73], v[72:73]
	v_pk_add_f32 v[134:135], v[134:135], v[146:147]
	v_mov_b32_e32 v163, v105
	v_pk_mov_b32 v[88:89], v[88:89], v[140:141] op_sel:[1,0]
	v_pk_add_f32 v[140:141], v[72:73], v[134:135]
	v_pk_mul_f32 v[134:135], v[72:73], v[134:135]
	v_pk_fma_f32 v[88:89], v[104:105], v[162:163], v[88:89]
	v_mov_b32_e32 v141, v135
	v_mov_b32_e32 v121, v137
	v_pk_add_f32 v[134:135], v[140:141], v[88:89]
	v_mul_f32_e32 v88, 0x3fd744fd, v137
	v_pk_fma_f32 v[88:89], v[120:121], s[66:67], v[88:89] op_sel_hi:[1,1,0]
	s_nop 0
	v_pk_mul_f32 v[120:121], v[88:89], v[88:89]
	s_nop 0
	v_mov_b32_e32 v89, v120
	v_pk_add_f32 v[120:121], v[134:135], v[88:89]
	s_nop 1
	v_mov_b32_dpp v134, v120 quad_perm:[1,0,3,2] row_mask:0xf bank_mask:0xf bound_ctrl:1
	v_mov_b32_dpp v135, v121 quad_perm:[1,0,3,2] row_mask:0xf bank_mask:0xf bound_ctrl:1
	v_pk_add_f32 v[120:121], v[120:121], v[134:135]
	s_nop 1
	v_mov_b32_dpp v134, v120 quad_perm:[2,3,0,1] row_mask:0xf bank_mask:0xf bound_ctrl:1
	v_mov_b32_dpp v135, v121 quad_perm:[2,3,0,1] row_mask:0xf bank_mask:0xf bound_ctrl:1
	v_pk_add_f32 v[120:121], v[120:121], v[134:135]
	s_nop 1
	v_mov_b32_dpp v134, v120 row_half_mirror row_mask:0xf bank_mask:0xf bound_ctrl:1
	v_mov_b32_dpp v135, v121 row_half_mirror row_mask:0xf bank_mask:0xf bound_ctrl:1
	v_pk_add_f32 v[120:121], v[120:121], v[134:135]
	s_nop 1
	v_mov_b32_dpp v134, v120 row_mirror row_mask:0xf bank_mask:0xf bound_ctrl:1
	v_mov_b32_dpp v135, v121 row_mirror row_mask:0xf bank_mask:0xf bound_ctrl:1
	s_and_saveexec_b64 s[6:7], vcc
	v_pk_add_f32 v[120:121], v[120:121], v[134:135]
	ds_write_b64 v160, v[120:121] offset:88
	s_or_b64 exec, exec, s[6:7]
	v_or_b32_e32 v120, 32, v176
	v_ashrrev_i32_e32 v121, 31, v120
	v_readlane_b32 s6, v255, 29
	v_lshlrev_b64 v[120:121], 12, v[120:121]
	v_readlane_b32 s7, v255, 30
	v_readfirstlane_b32 s2, v169
	s_lshl_b32 s2, s2, 13
	v_lshl_add_u64 v[120:121], s[6:7], 0, v[120:121]
	v_lshl_add_u64 v[120:121], v[154:155], 2, v[120:121]
	s_waitcnt lgkmcnt(0)
	v_lshl_add_u64 v[120:121], v[120:121], 0, v[0:1]
	s_mov_b32 m0, s2
	s_mov_b64 s[6:7], 0x2000
	global_load_lds_dwordx4 v[120:121], off
	v_lshl_add_u64 v[134:135], v[120:121], 0, s[6:7]
	s_or_b32 m0, s2, 0x400
	s_mov_b64 s[6:7], 0x4000
	global_load_lds_dwordx4 v[134:135], off
	v_lshl_add_u64 v[134:135], v[120:121], 0, s[6:7]
	s_or_b32 m0, s2, 0x800
	s_mov_b64 s[6:7], 0x6000
	global_load_lds_dwordx4 v[134:135], off
	v_lshl_add_u64 v[134:135], v[120:121], 0, s[6:7]
	s_or_b32 m0, s2, 0xc00
	s_mov_b64 s[6:7], 0x8000
	global_load_lds_dwordx4 v[134:135], off
	v_lshl_add_u64 v[134:135], v[120:121], 0, s[6:7]
	s_or_b32 m0, s2, 0x1000
	s_mov_b64 s[6:7], 0xa000
	global_load_lds_dwordx4 v[134:135], off
	v_lshl_add_u64 v[134:135], v[120:121], 0, s[6:7]
	s_or_b32 m0, s2, 0x1400
	s_mov_b64 s[6:7], 0xc000
	global_load_lds_dwordx4 v[134:135], off
	v_lshl_add_u64 v[134:135], v[120:121], 0, s[6:7]
	s_or_b32 m0, s2, 0x1800
	s_mov_b64 s[6:7], 0xe000
	global_load_lds_dwordx4 v[134:135], off
	v_lshl_add_u64 v[120:121], v[120:121], 0, s[6:7]
	s_or_b32 m0, s2, 0x1c00
	v_add_u32_e32 v116, 0x10000, v138
	global_load_lds_dwordx4 v[120:121], off
	s_waitcnt vmcnt(8)
	v_add_u32_e32 v89, v116, v172
	ds_read2_b32 v[120:121], v89 offset1:32
	ds_read2_b32 v[134:135], v89 offset0:64 offset1:96
	v_add_f32_e32 v98, 0, v122
	v_mov_b32_e32 v146, v106
	v_mov_b32_e32 v147, v90
	s_waitcnt lgkmcnt(0)
	v_mul_f32_e32 v137, 0x3fd744fd, v120
	v_mul_f32_e32 v139, 0.5, v98
	v_pk_add_f32 v[146:147], v[146:147], 0 op_sel_hi:[1,0]
	v_mov_b32_e32 v138, v90
	v_mov_b32_e32 v136, v1
	v_mov_b32_e32 v120, v121
	v_mov_b32_e32 v121, v134
	s_mov_b32 s2, s67
	v_pk_add_f32 v[136:137], v[138:139], v[136:137]
	v_pk_mul_f32 v[138:139], v[120:121], s[2:3] op_sel_hi:[1,0]
	v_pk_mul_f32 v[150:151], v[146:147], 0.5 op_sel_hi:[1,0]
	v_pk_fma_f32 v[120:121], v[146:147], 0.5, v[138:139] op_sel_hi:[1,0,1]
	v_mov_b32_e32 v150, v137
	v_mov_b32_e32 v156, v1
	v_mov_b32_e32 v157, v139
	v_add_f32_e32 v140, 0, v74
	v_mov_b32_e32 v141, v135
	v_pk_mul_f32 v[146:147], v[120:121], v[120:121]
	v_pk_add_f32 v[150:151], v[150:151], v[156:157]
	v_mul_f32_e32 v74, 0x3fd744fd, v135
	v_mov_b32_e32 v163, v137
	v_pk_mov_b32 v[138:139], v[138:139], v[146:147] op_sel:[1,0]
	v_pk_add_f32 v[146:147], v[120:121], v[150:151]
	v_pk_mul_f32 v[150:151], v[120:121], v[150:151]
	v_pk_fma_f32 v[134:135], v[140:141], s[66:67], v[74:75] op_sel_hi:[1,1,0]
	v_pk_fma_f32 v[138:139], v[136:137], v[162:163], v[138:139]
	v_mov_b32_e32 v147, v151
	v_pk_mul_f32 v[140:141], v[134:135], v[134:135]
	v_pk_add_f32 v[138:139], v[146:147], v[138:139]
	v_mov_b32_e32 v135, v140
	v_pk_add_f32 v[138:139], v[138:139], v[134:135]
	s_nop 1
	v_mov_b32_dpp v140, v138 quad_perm:[1,0,3,2] row_mask:0xf bank_mask:0xf bound_ctrl:1
	v_mov_b32_dpp v141, v139 quad_perm:[1,0,3,2] row_mask:0xf bank_mask:0xf bound_ctrl:1
	v_pk_add_f32 v[138:139], v[138:139], v[140:141]
	s_nop 1
	v_mov_b32_dpp v140, v138 quad_perm:[2,3,0,1] row_mask:0xf bank_mask:0xf bound_ctrl:1
	v_mov_b32_dpp v141, v139 quad_perm:[2,3,0,1] row_mask:0xf bank_mask:0xf bound_ctrl:1
	v_pk_add_f32 v[138:139], v[138:139], v[140:141]
	s_nop 1
	v_mov_b32_dpp v140, v138 row_half_mirror row_mask:0xf bank_mask:0xf bound_ctrl:1
	v_mov_b32_dpp v141, v139 row_half_mirror row_mask:0xf bank_mask:0xf bound_ctrl:1
	v_pk_add_f32 v[138:139], v[138:139], v[140:141]
	s_nop 1
	v_mov_b32_dpp v140, v138 row_mirror row_mask:0xf bank_mask:0xf bound_ctrl:1
	v_mov_b32_dpp v141, v139 row_mirror row_mask:0xf bank_mask:0xf bound_ctrl:1
	s_and_saveexec_b64 s[6:7], vcc
	v_pk_add_f32 v[138:139], v[138:139], v[140:141]
	ds_write_b64 v160, v[138:139] offset:128
	s_or_b64 exec, exec, s[6:7]
	v_or_b32_e32 v74, 0x200, v172
	v_add_u32_e32 v98, v116, v74
	ds_read2_b32 v[138:139], v98 offset1:32
	ds_read2_b32 v[140:141], v98 offset0:64 offset1:96
	v_add_f32_e32 v74, 0, v123
	v_add_f32_e32 v122, 0, v75
	v_mul_f32_e32 v75, 0.5, v74
	s_waitcnt lgkmcnt(1)
;   DI void operator()(f32x16 (&acc)[2][4], int grow0, int gcol0, int lane, int w, char* lds) {
;     ...
;     for (int ps = 0; ps < 4; ++ps) {
;       const int mt = ps >> 1;
;       if (ps + 1 < 4) {
;         if (ps >= 1) asm volatile("s_waitcnt lgkmcnt(0)" ::: "memory");
;         xpass(ps + 1, grow0, gcol0, lane, w, lds);
;         if (ps >= 1) asm volatile("s_waitcnt vmcnt(8)" ::: "memory");
;       } else asm volatile("s_waitcnt vmcnt(0)" ::: "memory");
;       const char* xs = lds + (ps & 1) * 65536 + w * 8192;
; #pragma unroll
;       for (int qq = 0; qq < 2; ++qq)
; #pragma unroll
;         for (int e = 0; e < 4; ++e) {
;           const int i = 4 * (2 * (ps & 1) + qq) + e;
;           const float* xr = (const float*)(xs + (8 * qq + 4 * hh + e) * 512) + l31;
;           float s1 = 0.f, s2 = 0.f;
; #pragma unroll
;           for (int nt = 0; nt < 4; ++nt) {
;             float v = (acc[mt][nt][i] + bia[nt]) * csc[nt];
;             float z = ALPHA * xr[nt * 32] + hs * v;
;             acc[mt][nt][i] = z; s1 += z; s2 += z * z;
;           }
;           s1 = row16_sum(s1); s2 = row16_sum(s2);
;           if ((lane & 15) == 0) { f32x2 sv = {s1, s2}; *(f32x2*)(redw + (mt * 32 + (i & 3) + 8 * (i >> 2)) * 2) = sv; }
;         }
	v_mul_f32_e32 v147, 0x3fd744fd, v138
	v_mov_b32_e32 v90, v107
	v_mov_b32_e32 v74, v91
	v_mov_b32_e32 v146, v1
	v_pk_add_f32 v[150:151], v[90:91], 0 op_sel_hi:[1,0]
	v_pk_add_f32 v[106:107], v[74:75], v[146:147]
	v_mov_b32_e32 v74, v139
	s_waitcnt lgkmcnt(0)
	v_mov_b32_e32 v75, v140
	s_mov_b32 s2, s67
	v_pk_mul_f32 v[90:91], v[74:75], s[2:3] op_sel_hi:[1,0]
	v_pk_mul_f32 v[138:139], v[150:151], 0.5 op_sel_hi:[1,0]
	v_pk_fma_f32 v[74:75], v[150:151], 0.5, v[90:91] op_sel_hi:[1,0,1]
	v_mov_b32_e32 v138, v107
	v_mov_b32_e32 v150, v1
	v_mov_b32_e32 v151, v91
	v_pk_mul_f32 v[146:147], v[74:75], v[74:75]
	v_pk_add_f32 v[138:139], v[138:139], v[150:151]
	v_mov_b32_e32 v163, v107
	v_pk_mov_b32 v[90:91], v[90:91], v[146:147] op_sel:[1,0]
	v_pk_add_f32 v[146:147], v[74:75], v[138:139]
	v_pk_mul_f32 v[138:139], v[74:75], v[138:139]
	v_pk_fma_f32 v[90:91], v[106:107], v[162:163], v[90:91]
	v_mov_b32_e32 v147, v139
	v_mov_b32_e32 v123, v141
	v_pk_add_f32 v[138:139], v[146:147], v[90:91]
	v_mul_f32_e32 v90, 0x3fd744fd, v141
	v_pk_fma_f32 v[90:91], v[122:123], s[66:67], v[90:91] op_sel_hi:[1,1,0]
	s_nop 0
	v_pk_mul_f32 v[122:123], v[90:91], v[90:91]
	s_nop 0
	v_mov_b32_e32 v91, v122
	v_pk_add_f32 v[122:123], v[138:139], v[90:91]
	s_nop 1
	v_mov_b32_dpp v138, v122 quad_perm:[1,0,3,2] row_mask:0xf bank_mask:0xf bound_ctrl:1
	v_mov_b32_dpp v139, v123 quad_perm:[1,0,3,2] row_mask:0xf bank_mask:0xf bound_ctrl:1
	v_pk_add_f32 v[122:123], v[122:123], v[138:139]
	s_nop 1
	v_mov_b32_dpp v138, v122 quad_perm:[2,3,0,1] row_mask:0xf bank_mask:0xf bound_ctrl:1
	v_mov_b32_dpp v139, v123 quad_perm:[2,3,0,1] row_mask:0xf bank_mask:0xf bound_ctrl:1
	v_pk_add_f32 v[122:123], v[122:123], v[138:139]
	s_nop 1
	v_mov_b32_dpp v138, v122 row_half_mirror row_mask:0xf bank_mask:0xf bound_ctrl:1
	v_mov_b32_dpp v139, v123 row_half_mirror row_mask:0xf bank_mask:0xf bound_ctrl:1
	v_pk_add_f32 v[122:123], v[122:123], v[138:139]
	s_nop 1
	v_mov_b32_dpp v138, v122 row_mirror row_mask:0xf bank_mask:0xf bound_ctrl:1
	v_mov_b32_dpp v139, v123 row_mirror row_mask:0xf bank_mask:0xf bound_ctrl:1
	s_and_saveexec_b64 s[6:7], vcc
	v_pk_add_f32 v[122:123], v[122:123], v[138:139]
	ds_write_b64 v160, v[122:123] offset:136
	s_or_b64 exec, exec, s[6:7]
	v_or_b32_e32 v91, 0x400, v172
	v_add_u32_e32 v102, v116, v91
	ds_read2_b32 v[122:123], v102 offset1:32
	ds_read2_b32 v[138:139], v102 offset0:64 offset1:96
	v_add_f32_e32 v91, 0, v124
	v_mov_b32_e32 v156, v108
	v_mov_b32_e32 v157, v92
	v_mul_f32_e32 v141, 0.5, v91
	s_waitcnt lgkmcnt(1)
	v_mul_f32_e32 v151, 0x3fd744fd, v122
	v_pk_add_f32 v[156:157], v[156:157], 0 op_sel_hi:[1,0]
	v_mov_b32_e32 v140, v92
	v_mov_b32_e32 v150, v1
	v_mov_b32_e32 v122, v123
	s_waitcnt lgkmcnt(0)
	v_mov_b32_e32 v123, v138
	s_mov_b32 s2, s67
	v_pk_add_f32 v[140:141], v[140:141], v[150:151]
	v_pk_mul_f32 v[150:151], v[122:123], s[2:3] op_sel_hi:[1,0]
	v_pk_mul_f32 v[174:175], v[156:157], 0.5 op_sel_hi:[1,0]
	v_pk_fma_f32 v[122:123], v[156:157], 0.5, v[150:151] op_sel_hi:[1,0,1]
	v_mov_b32_e32 v174, v141
	v_mov_b32_e32 v178, v1
	v_mov_b32_e32 v179, v151
	v_add_f32_e32 v146, 0, v76
	v_mov_b32_e32 v147, v139
	v_pk_mul_f32 v[156:157], v[122:123], v[122:123]
	v_pk_add_f32 v[174:175], v[174:175], v[178:179]
	v_mul_f32_e32 v76, 0x3fd744fd, v139
	v_mov_b32_e32 v163, v141
	v_pk_mov_b32 v[150:151], v[150:151], v[156:157] op_sel:[1,0]
	v_pk_add_f32 v[156:157], v[122:123], v[174:175]
	v_pk_mul_f32 v[174:175], v[122:123], v[174:175]
	v_pk_fma_f32 v[138:139], v[146:147], s[66:67], v[76:77] op_sel_hi:[1,1,0]
	v_pk_fma_f32 v[150:151], v[140:141], v[162:163], v[150:151]
	v_mov_b32_e32 v157, v175
	v_pk_mul_f32 v[146:147], v[138:139], v[138:139]
	v_pk_add_f32 v[150:151], v[156:157], v[150:151]
	v_mov_b32_e32 v139, v146
	v_pk_add_f32 v[146:147], v[150:151], v[138:139]
	s_nop 1
	v_mov_b32_dpp v150, v146 quad_perm:[1,0,3,2] row_mask:0xf bank_mask:0xf bound_ctrl:1
	v_mov_b32_dpp v151, v147 quad_perm:[1,0,3,2] row_mask:0xf bank_mask:0xf bound_ctrl:1
	v_pk_add_f32 v[146:147], v[146:147], v[150:151]
	s_nop 1
	v_mov_b32_dpp v150, v146 quad_perm:[2,3,0,1] row_mask:0xf bank_mask:0xf bound_ctrl:1
	v_mov_b32_dpp v151, v147 quad_perm:[2,3,0,1] row_mask:0xf bank_mask:0xf bound_ctrl:1
	v_pk_add_f32 v[146:147], v[146:147], v[150:151]
	s_nop 1
	v_mov_b32_dpp v150, v146 row_half_mirror row_mask:0xf bank_mask:0xf bound_ctrl:1
	v_mov_b32_dpp v151, v147 row_half_mirror row_mask:0xf bank_mask:0xf bound_ctrl:1
	v_pk_add_f32 v[146:147], v[146:147], v[150:151]
	s_nop 1
	v_mov_b32_dpp v150, v146 row_mirror row_mask:0xf bank_mask:0xf bound_ctrl:1
	v_mov_b32_dpp v151, v147 row_mirror row_mask:0xf bank_mask:0xf bound_ctrl:1
	s_and_saveexec_b64 s[6:7], vcc
	v_pk_add_f32 v[146:147], v[146:147], v[150:151]
	ds_write_b64 v160, v[146:147] offset:144
	s_or_b64 exec, exec, s[6:7]
	v_add_u32_e32 v104, v116, v152
	ds_read2_b32 v[146:147], v104 offset1:32
	ds_read2_b32 v[150:151], v104 offset0:64 offset1:96
	v_add_f32_e32 v76, 0, v125
	v_add_f32_e32 v124, 0, v77
	v_mul_f32_e32 v77, 0.5, v76
	s_waitcnt lgkmcnt(1)
	v_mul_f32_e32 v153, 0x3fd744fd, v146
	v_mov_b32_e32 v92, v109
	v_mov_b32_e32 v76, v93
	v_mov_b32_e32 v152, v1
	v_pk_add_f32 v[156:157], v[92:93], 0 op_sel_hi:[1,0]
	v_pk_add_f32 v[108:109], v[76:77], v[152:153]
	v_mov_b32_e32 v76, v147
	s_waitcnt lgkmcnt(0)
;   DI void operator()(f32x16 (&acc)[2][4], int grow0, int gcol0, int lane, int w, char* lds) {
;     ...
;     for (int ps = 0; ps < 4; ++ps) {
;       const int mt = ps >> 1;
;       if (ps + 1 < 4) {
;         if (ps >= 1) asm volatile("s_waitcnt lgkmcnt(0)" ::: "memory");
;         xpass(ps + 1, grow0, gcol0, lane, w, lds);
;         if (ps >= 1) asm volatile("s_waitcnt vmcnt(8)" ::: "memory");
;       } else asm volatile("s_waitcnt vmcnt(0)" ::: "memory");
;       const char* xs = lds + (ps & 1) * 65536 + w * 8192;
; #pragma unroll
;       for (int qq = 0; qq < 2; ++qq)
; #pragma unroll
;         for (int e = 0; e < 4; ++e) {
;           const int i = 4 * (2 * (ps & 1) + qq) + e;
;           const float* xr = (const float*)(xs + (8 * qq + 4 * hh + e) * 512) + l31;
;           float s1 = 0.f, s2 = 0.f;
; #pragma unroll
;           for (int nt = 0; nt < 4; ++nt) {
;             float v = (acc[mt][nt][i] + bia[nt]) * csc[nt];
;             float z = ALPHA * xr[nt * 32] + hs * v;
;             acc[mt][nt][i] = z; s1 += z; s2 += z * z;
;           }
;           s1 = row16_sum(s1); s2 = row16_sum(s2);
;           if ((lane & 15) == 0) { f32x2 sv = {s1, s2}; *(f32x2*)(redw + (mt * 32 + (i & 3) + 8 * (i >> 2)) * 2) = sv; }
;         }
	v_mov_b32_e32 v77, v150
	s_mov_b32 s2, s67
	v_pk_mul_f32 v[92:93], v[76:77], s[2:3] op_sel_hi:[1,0]
	v_pk_mul_f32 v[146:147], v[156:157], 0.5 op_sel_hi:[1,0]
	v_pk_fma_f32 v[76:77], v[156:157], 0.5, v[92:93] op_sel_hi:[1,0,1]
	v_mov_b32_e32 v146, v109
	v_mov_b32_e32 v156, v1
	v_mov_b32_e32 v157, v93
	v_pk_mul_f32 v[152:153], v[76:77], v[76:77]
	v_pk_add_f32 v[146:147], v[146:147], v[156:157]
	v_mov_b32_e32 v163, v109
	v_pk_mov_b32 v[92:93], v[92:93], v[152:153] op_sel:[1,0]
	v_pk_add_f32 v[152:153], v[76:77], v[146:147]
	v_pk_mul_f32 v[146:147], v[76:77], v[146:147]
	v_pk_fma_f32 v[92:93], v[108:109], v[162:163], v[92:93]
	v_mov_b32_e32 v153, v147
	v_mov_b32_e32 v125, v151
	v_pk_add_f32 v[146:147], v[152:153], v[92:93]
	v_mul_f32_e32 v92, 0x3fd744fd, v151
	v_pk_fma_f32 v[92:93], v[124:125], s[66:67], v[92:93] op_sel_hi:[1,1,0]
	s_nop 0
	v_pk_mul_f32 v[124:125], v[92:93], v[92:93]
	s_nop 0
	v_mov_b32_e32 v93, v124
	v_pk_add_f32 v[124:125], v[146:147], v[92:93]
	s_nop 1
	v_mov_b32_dpp v146, v124 quad_perm:[1,0,3,2] row_mask:0xf bank_mask:0xf bound_ctrl:1
	v_mov_b32_dpp v147, v125 quad_perm:[1,0,3,2] row_mask:0xf bank_mask:0xf bound_ctrl:1
	v_pk_add_f32 v[124:125], v[124:125], v[146:147]
	s_nop 1
	v_mov_b32_dpp v146, v124 quad_perm:[2,3,0,1] row_mask:0xf bank_mask:0xf bound_ctrl:1
	v_mov_b32_dpp v147, v125 quad_perm:[2,3,0,1] row_mask:0xf bank_mask:0xf bound_ctrl:1
	v_pk_add_f32 v[124:125], v[124:125], v[146:147]
	s_nop 1
	v_mov_b32_dpp v146, v124 row_half_mirror row_mask:0xf bank_mask:0xf bound_ctrl:1
	v_mov_b32_dpp v147, v125 row_half_mirror row_mask:0xf bank_mask:0xf bound_ctrl:1
	v_pk_add_f32 v[124:125], v[124:125], v[146:147]
	s_nop 1
	v_mov_b32_dpp v146, v124 row_mirror row_mask:0xf bank_mask:0xf bound_ctrl:1
	v_mov_b32_dpp v147, v125 row_mirror row_mask:0xf bank_mask:0xf bound_ctrl:1
	s_and_saveexec_b64 s[6:7], vcc
	v_pk_add_f32 v[124:125], v[124:125], v[146:147]
	ds_write_b64 v160, v[124:125] offset:152
	s_or_b64 exec, exec, s[6:7]
	v_or_b32_e32 v91, 0x1000, v172
	v_add_u32_e32 v93, v116, v91
	ds_read2_b32 v[124:125], v93 offset1:32
	ds_read2_b32 v[146:147], v93 offset0:64 offset1:96
	v_add_f32_e32 v91, 0, v126
	v_mov_b32_e32 v174, v110
	v_mov_b32_e32 v175, v94
	v_mul_f32_e32 v151, 0.5, v91
	s_waitcnt lgkmcnt(1)
	v_mul_f32_e32 v157, 0x3fd744fd, v124
	v_pk_add_f32 v[174:175], v[174:175], 0 op_sel_hi:[1,0]
	v_mov_b32_e32 v150, v94
	v_mov_b32_e32 v156, v1
	v_mov_b32_e32 v124, v125
	s_waitcnt lgkmcnt(0)
	v_mov_b32_e32 v125, v146
	s_mov_b32 s2, s67
	v_pk_add_f32 v[150:151], v[150:151], v[156:157]
	v_pk_mul_f32 v[156:157], v[124:125], s[2:3] op_sel_hi:[1,0]
	v_pk_mul_f32 v[178:179], v[174:175], 0.5 op_sel_hi:[1,0]
	v_pk_fma_f32 v[124:125], v[174:175], 0.5, v[156:157] op_sel_hi:[1,0,1]
	v_mov_b32_e32 v178, v151
	v_mov_b32_e32 v180, v1
	v_mov_b32_e32 v181, v157
	v_add_f32_e32 v152, 0, v78
	v_mov_b32_e32 v153, v147
	v_pk_mul_f32 v[174:175], v[124:125], v[124:125]
	v_pk_add_f32 v[178:179], v[178:179], v[180:181]
	v_mul_f32_e32 v78, 0x3fd744fd, v147
	v_mov_b32_e32 v163, v151
	v_pk_mov_b32 v[156:157], v[156:157], v[174:175] op_sel:[1,0]
	v_pk_add_f32 v[174:175], v[124:125], v[178:179]
	v_pk_mul_f32 v[178:179], v[124:125], v[178:179]
	v_pk_fma_f32 v[146:147], v[152:153], s[66:67], v[78:79] op_sel_hi:[1,1,0]
	v_pk_fma_f32 v[156:157], v[150:151], v[162:163], v[156:157]
	v_mov_b32_e32 v175, v179
	v_pk_mul_f32 v[152:153], v[146:147], v[146:147]
	v_pk_add_f32 v[156:157], v[174:175], v[156:157]
	v_mov_b32_e32 v147, v152
	v_pk_add_f32 v[152:153], v[156:157], v[146:147]
	s_nop 1
	v_mov_b32_dpp v156, v152 quad_perm:[1,0,3,2] row_mask:0xf bank_mask:0xf bound_ctrl:1
	v_mov_b32_dpp v157, v153 quad_perm:[1,0,3,2] row_mask:0xf bank_mask:0xf bound_ctrl:1
	v_pk_add_f32 v[152:153], v[152:153], v[156:157]
	s_nop 1
	v_mov_b32_dpp v156, v152 quad_perm:[2,3,0,1] row_mask:0xf bank_mask:0xf bound_ctrl:1
	v_mov_b32_dpp v157, v153 quad_perm:[2,3,0,1] row_mask:0xf bank_mask:0xf bound_ctrl:1
	v_pk_add_f32 v[152:153], v[152:153], v[156:157]
	s_nop 1
	v_mov_b32_dpp v156, v152 row_half_mirror row_mask:0xf bank_mask:0xf bound_ctrl:1
	v_mov_b32_dpp v157, v153 row_half_mirror row_mask:0xf bank_mask:0xf bound_ctrl:1
	v_pk_add_f32 v[152:153], v[152:153], v[156:157]
	s_nop 1
	v_mov_b32_dpp v156, v152 row_mirror row_mask:0xf bank_mask:0xf bound_ctrl:1
	v_mov_b32_dpp v157, v153 row_mirror row_mask:0xf bank_mask:0xf bound_ctrl:1
	s_and_saveexec_b64 s[6:7], vcc
	v_pk_add_f32 v[152:153], v[152:153], v[156:157]
	ds_write_b64 v160, v[152:153] offset:192
	s_or_b64 exec, exec, s[6:7]
	v_or_b32_e32 v78, 0x1200, v172
	v_add_u32_e32 v106, v116, v78
	ds_read2_b32 v[152:153], v106 offset1:32
	ds_read2_b32 v[156:157], v106 offset0:64 offset1:96
	v_add_f32_e32 v78, 0, v127
	v_add_f32_e32 v126, 0, v79
	v_mul_f32_e32 v79, 0.5, v78
	s_waitcnt lgkmcnt(1)
	v_mul_f32_e32 v175, 0x3fd744fd, v152
	v_mov_b32_e32 v94, v111
	v_mov_b32_e32 v78, v95
	v_mov_b32_e32 v174, v1
	v_pk_add_f32 v[178:179], v[94:95], 0 op_sel_hi:[1,0]
	v_pk_add_f32 v[110:111], v[78:79], v[174:175]
	v_mov_b32_e32 v78, v153
	s_waitcnt lgkmcnt(0)
;   DI void operator()(f32x16 (&acc)[2][4], int grow0, int gcol0, int lane, int w, char* lds) {
;     ...
;     for (int ps = 0; ps < 4; ++ps) {
;       const int mt = ps >> 1;
;       if (ps + 1 < 4) {
;         if (ps >= 1) asm volatile("s_waitcnt lgkmcnt(0)" ::: "memory");
;         xpass(ps + 1, grow0, gcol0, lane, w, lds);
;         if (ps >= 1) asm volatile("s_waitcnt vmcnt(8)" ::: "memory");
;       } else asm volatile("s_waitcnt vmcnt(0)" ::: "memory");
;       const char* xs = lds + (ps & 1) * 65536 + w * 8192;
; #pragma unroll
;       for (int qq = 0; qq < 2; ++qq)
; #pragma unroll
;         for (int e = 0; e < 4; ++e) {
;           const int i = 4 * (2 * (ps & 1) + qq) + e;
;           const float* xr = (const float*)(xs + (8 * qq + 4 * hh + e) * 512) + l31;
;           float s1 = 0.f, s2 = 0.f;
; #pragma unroll
;           for (int nt = 0; nt < 4; ++nt) {
;             float v = (acc[mt][nt][i] + bia[nt]) * csc[nt];
;             float z = ALPHA * xr[nt * 32] + hs * v;
;             acc[mt][nt][i] = z; s1 += z; s2 += z * z;
;           }
;           s1 = row16_sum(s1); s2 = row16_sum(s2);
;           if ((lane & 15) == 0) { f32x2 sv = {s1, s2}; *(f32x2*)(redw + (mt * 32 + (i & 3) + 8 * (i >> 2)) * 2) = sv; }
;         }
	v_mov_b32_e32 v79, v156
	s_mov_b32 s2, s67
	v_pk_mul_f32 v[94:95], v[78:79], s[2:3] op_sel_hi:[1,0]
	v_pk_mul_f32 v[152:153], v[178:179], 0.5 op_sel_hi:[1,0]
	v_pk_fma_f32 v[78:79], v[178:179], 0.5, v[94:95] op_sel_hi:[1,0,1]
	v_mov_b32_e32 v152, v111
	v_mov_b32_e32 v178, v1
	v_mov_b32_e32 v179, v95
	v_pk_mul_f32 v[174:175], v[78:79], v[78:79]
	v_pk_add_f32 v[152:153], v[152:153], v[178:179]
	v_mov_b32_e32 v163, v111
	v_pk_mov_b32 v[94:95], v[94:95], v[174:175] op_sel:[1,0]
	v_pk_add_f32 v[174:175], v[78:79], v[152:153]
	v_pk_mul_f32 v[152:153], v[78:79], v[152:153]
	v_pk_fma_f32 v[94:95], v[110:111], v[162:163], v[94:95]
	v_mov_b32_e32 v175, v153
	v_mov_b32_e32 v127, v157
	v_pk_add_f32 v[152:153], v[174:175], v[94:95]
	v_mul_f32_e32 v94, 0x3fd744fd, v157
	v_pk_fma_f32 v[94:95], v[126:127], s[66:67], v[94:95] op_sel_hi:[1,1,0]
	s_nop 0
	v_pk_mul_f32 v[126:127], v[94:95], v[94:95]
	s_nop 0
	v_mov_b32_e32 v95, v126
	v_pk_add_f32 v[126:127], v[152:153], v[94:95]
	s_nop 1
	v_mov_b32_dpp v152, v126 quad_perm:[1,0,3,2] row_mask:0xf bank_mask:0xf bound_ctrl:1
	v_mov_b32_dpp v153, v127 quad_perm:[1,0,3,2] row_mask:0xf bank_mask:0xf bound_ctrl:1
	v_pk_add_f32 v[126:127], v[126:127], v[152:153]
	s_nop 1
	v_mov_b32_dpp v152, v126 quad_perm:[2,3,0,1] row_mask:0xf bank_mask:0xf bound_ctrl:1
	v_mov_b32_dpp v153, v127 quad_perm:[2,3,0,1] row_mask:0xf bank_mask:0xf bound_ctrl:1
	v_pk_add_f32 v[126:127], v[126:127], v[152:153]
	s_nop 1
	v_mov_b32_dpp v152, v126 row_half_mirror row_mask:0xf bank_mask:0xf bound_ctrl:1
	v_mov_b32_dpp v153, v127 row_half_mirror row_mask:0xf bank_mask:0xf bound_ctrl:1
	v_pk_add_f32 v[126:127], v[126:127], v[152:153]
	s_nop 1
	v_mov_b32_dpp v152, v126 row_mirror row_mask:0xf bank_mask:0xf bound_ctrl:1
	v_mov_b32_dpp v153, v127 row_mirror row_mask:0xf bank_mask:0xf bound_ctrl:1
	s_and_saveexec_b64 s[6:7], vcc
	v_pk_add_f32 v[126:127], v[126:127], v[152:153]
	ds_write_b64 v160, v[126:127] offset:200
	s_or_b64 exec, exec, s[6:7]
	v_or_b32_e32 v91, 0x1400, v172
	v_add_u32_e32 v95, v116, v91
	ds_read2_b32 v[126:127], v95 offset1:32
	ds_read2_b32 v[152:153], v95 offset0:64 offset1:96
	v_add_f32_e32 v91, 0, v128
	v_mov_b32_e32 v178, v112
	v_mov_b32_e32 v179, v96
	v_mul_f32_e32 v157, 0.5, v91
	s_waitcnt lgkmcnt(1)
	v_mul_f32_e32 v175, 0x3fd744fd, v126
	v_pk_add_f32 v[178:179], v[178:179], 0 op_sel_hi:[1,0]
	v_mov_b32_e32 v156, v96
	v_mov_b32_e32 v174, v1
	v_mov_b32_e32 v126, v127
	s_waitcnt lgkmcnt(0)
	v_mov_b32_e32 v127, v152
	s_mov_b32 s2, s67
	v_pk_add_f32 v[156:157], v[156:157], v[174:175]
	v_pk_mul_f32 v[174:175], v[126:127], s[2:3] op_sel_hi:[1,0]
	v_pk_mul_f32 v[180:181], v[178:179], 0.5 op_sel_hi:[1,0]
	v_pk_fma_f32 v[126:127], v[178:179], 0.5, v[174:175] op_sel_hi:[1,0,1]
	v_mov_b32_e32 v180, v157
	v_mov_b32_e32 v182, v1
	v_mov_b32_e32 v183, v175
	v_add_f32_e32 v172, 0, v80
	v_mov_b32_e32 v173, v153
	v_pk_mul_f32 v[178:179], v[126:127], v[126:127]
	v_pk_add_f32 v[180:181], v[180:181], v[182:183]
	v_mul_f32_e32 v80, 0x3fd744fd, v153
	v_mov_b32_e32 v163, v157
	v_pk_mov_b32 v[174:175], v[174:175], v[178:179] op_sel:[1,0]
	v_pk_add_f32 v[178:179], v[126:127], v[180:181]
	v_pk_mul_f32 v[180:181], v[126:127], v[180:181]
	v_pk_fma_f32 v[152:153], v[172:173], s[66:67], v[80:81] op_sel_hi:[1,1,0]
	v_pk_fma_f32 v[174:175], v[156:157], v[162:163], v[174:175]
	v_mov_b32_e32 v179, v181
	v_pk_mul_f32 v[172:173], v[152:153], v[152:153]
	v_pk_add_f32 v[174:175], v[178:179], v[174:175]
	v_mov_b32_e32 v153, v172
	v_pk_add_f32 v[172:173], v[174:175], v[152:153]
	s_nop 1
	v_mov_b32_dpp v174, v172 quad_perm:[1,0,3,2] row_mask:0xf bank_mask:0xf bound_ctrl:1
	v_mov_b32_dpp v175, v173 quad_perm:[1,0,3,2] row_mask:0xf bank_mask:0xf bound_ctrl:1
	v_pk_add_f32 v[172:173], v[172:173], v[174:175]
	s_nop 1
	v_mov_b32_dpp v174, v172 quad_perm:[2,3,0,1] row_mask:0xf bank_mask:0xf bound_ctrl:1
	v_mov_b32_dpp v175, v173 quad_perm:[2,3,0,1] row_mask:0xf bank_mask:0xf bound_ctrl:1
	v_pk_add_f32 v[172:173], v[172:173], v[174:175]
	s_nop 1
	v_mov_b32_dpp v174, v172 row_half_mirror row_mask:0xf bank_mask:0xf bound_ctrl:1
	v_mov_b32_dpp v175, v173 row_half_mirror row_mask:0xf bank_mask:0xf bound_ctrl:1
	v_pk_add_f32 v[172:173], v[172:173], v[174:175]
	s_nop 1
	v_mov_b32_dpp v174, v172 row_mirror row_mask:0xf bank_mask:0xf bound_ctrl:1
	v_mov_b32_dpp v175, v173 row_mirror row_mask:0xf bank_mask:0xf bound_ctrl:1
	s_and_saveexec_b64 s[6:7], vcc
	v_pk_add_f32 v[172:173], v[172:173], v[174:175]
	ds_write_b64 v160, v[172:173] offset:208
	s_or_b64 exec, exec, s[6:7]
	v_add_u32_e32 v91, v116, v115
	v_add_f32_e32 v80, 0, v129
	ds_read2_b32 v[128:129], v91 offset1:32
	ds_read2_b32 v[178:179], v91 offset0:64 offset1:96
	v_mov_b32_e32 v96, v113
	v_mul_f32_e32 v175, 0.5, v80
	v_add_f32_e32 v180, 0, v81
	s_waitcnt lgkmcnt(1)
	v_mul_f32_e32 v173, 0x3fd744fd, v128
	v_pk_add_f32 v[80:81], v[96:97], 0 op_sel_hi:[1,0]
	v_mov_b32_e32 v174, v97
	v_mov_b32_e32 v172, v1
	v_mov_b32_e32 v96, v129
	s_waitcnt lgkmcnt(0)
;   DI void xpass(int ps, int grow0, int gcol0, int lane, int w, char* lds) const {
;     char* xs = lds + (ps & 1) * 65536 + __builtin_amdgcn_readfirstlane(w) * 8192;
;     const float* xsrc = Xin + (size_t)(grow0 + (ps >> 1) * 32 + (ps & 1) * 16 + (lane >> 5)) * D_ + gcol0 + (lane & 31) * 4;
; #pragma unroll
;     for (int pc = 0; pc < 8; ++pc)
;       __builtin_amdgcn_global_load_lds((const unsigned*)(xsrc + (size_t)(2 * pc) * D_), (__attribute__((address_space(3))) unsigned*)(xs + pc * 1024), 16, 0, 0);
;   }
;   DI void operator()(f32x16 (&acc)[2][4], int grow0, int gcol0, int lane, int w, char* lds) {
;     ...
;     for (int ps = 0; ps < 4; ++ps) {
;       const int mt = ps >> 1;
;       if (ps + 1 < 4) {
;         if (ps >= 1) asm volatile("s_waitcnt lgkmcnt(0)" ::: "memory");
;         xpass(ps + 1, grow0, gcol0, lane, w, lds);
;         if (ps >= 1) asm volatile("s_waitcnt vmcnt(8)" ::: "memory");
;       } else asm volatile("s_waitcnt vmcnt(0)" ::: "memory");
;       const char* xs = lds + (ps & 1) * 65536 + w * 8192;
; #pragma unroll
;       for (int qq = 0; qq < 2; ++qq)
; #pragma unroll
;         for (int e = 0; e < 4; ++e) {
;           const int i = 4 * (2 * (ps & 1) + qq) + e;
;           const float* xr = (const float*)(xs + (8 * qq + 4 * hh + e) * 512) + l31;
;           float s1 = 0.f, s2 = 0.f;
; #pragma unroll
;           for (int nt = 0; nt < 4; ++nt) {
;             float v = (acc[mt][nt][i] + bia[nt]) * csc[nt];
;             float z = ALPHA * xr[nt * 32] + hs * v;
;             acc[mt][nt][i] = z; s1 += z; s2 += z * z;
;           }
;           s1 = row16_sum(s1); s2 = row16_sum(s2);
;           if ((lane & 15) == 0) { f32x2 sv = {s1, s2}; *(f32x2*)(redw + (mt * 32 + (i & 3) + 8 * (i >> 2)) * 2) = sv; }
;         }
	v_mov_b32_e32 v97, v178
	s_mov_b32 s2, s67
	v_pk_add_f32 v[112:113], v[174:175], v[172:173]
	v_pk_mul_f32 v[96:97], v[96:97], s[2:3] op_sel_hi:[1,0]
	v_pk_mul_f32 v[128:129], v[80:81], 0.5 op_sel_hi:[1,0]
	v_pk_fma_f32 v[80:81], v[80:81], 0.5, v[96:97] op_sel_hi:[1,0,1]
	v_mov_b32_e32 v128, v113
	v_mov_b32_e32 v174, v1
	v_mov_b32_e32 v175, v97
	v_pk_mul_f32 v[172:173], v[80:81], v[80:81]
	v_pk_add_f32 v[128:129], v[128:129], v[174:175]
	v_mov_b32_e32 v163, v113
	v_pk_mov_b32 v[96:97], v[96:97], v[172:173] op_sel:[1,0]
	v_pk_add_f32 v[172:173], v[80:81], v[128:129]
	v_pk_mul_f32 v[128:129], v[80:81], v[128:129]
	v_pk_fma_f32 v[96:97], v[112:113], v[162:163], v[96:97]
	v_mov_b32_e32 v173, v129
	v_mov_b32_e32 v181, v179
	v_pk_add_f32 v[128:129], v[172:173], v[96:97]
	v_mul_f32_e32 v96, 0x3fd744fd, v179
	v_pk_fma_f32 v[96:97], v[180:181], s[66:67], v[96:97] op_sel_hi:[1,1,0]
	s_nop 0
	v_pk_mul_f32 v[172:173], v[96:97], v[96:97]
	s_nop 0
	v_mov_b32_e32 v97, v172
	v_pk_add_f32 v[128:129], v[128:129], v[96:97]
	s_nop 1
	v_mov_b32_dpp v172, v128 quad_perm:[1,0,3,2] row_mask:0xf bank_mask:0xf bound_ctrl:1
	v_mov_b32_dpp v173, v129 quad_perm:[1,0,3,2] row_mask:0xf bank_mask:0xf bound_ctrl:1
	v_pk_add_f32 v[128:129], v[128:129], v[172:173]
	s_nop 1
	v_mov_b32_dpp v172, v128 quad_perm:[2,3,0,1] row_mask:0xf bank_mask:0xf bound_ctrl:1
	v_mov_b32_dpp v173, v129 quad_perm:[2,3,0,1] row_mask:0xf bank_mask:0xf bound_ctrl:1
	v_pk_add_f32 v[128:129], v[128:129], v[172:173]
	s_nop 1
	v_mov_b32_dpp v172, v128 row_half_mirror row_mask:0xf bank_mask:0xf bound_ctrl:1
	v_mov_b32_dpp v173, v129 row_half_mirror row_mask:0xf bank_mask:0xf bound_ctrl:1
	v_pk_add_f32 v[128:129], v[128:129], v[172:173]
	s_nop 1
	v_mov_b32_dpp v172, v128 row_mirror row_mask:0xf bank_mask:0xf bound_ctrl:1
	v_mov_b32_dpp v173, v129 row_mirror row_mask:0xf bank_mask:0xf bound_ctrl:1
	s_and_saveexec_b64 s[6:7], vcc
	v_pk_add_f32 v[128:129], v[128:129], v[172:173]
	ds_write_b64 v160, v[128:129] offset:216
	s_or_b64 exec, exec, s[6:7]
	v_or_b32_e32 v128, 48, v176
	v_ashrrev_i32_e32 v129, 31, v128
	v_readlane_b32 s6, v255, 29
	v_lshlrev_b64 v[128:129], 12, v[128:129]
	v_readlane_b32 s7, v255, 30
	v_readfirstlane_b32 s2, v169
	s_lshl_b32 s2, s2, 13
	v_lshl_add_u64 v[128:129], s[6:7], 0, v[128:129]
	v_lshl_add_u64 v[128:129], v[154:155], 2, v[128:129]
	s_waitcnt lgkmcnt(0)
	s_add_i32 m0, s2, 0x10000
	v_lshl_add_u64 v[128:129], v[128:129], 0, v[0:1]
	s_mov_b64 s[6:7], 0x2000
	global_load_lds_dwordx4 v[128:129], off
	v_lshl_add_u64 v[172:173], v[128:129], 0, s[6:7]
	s_add_i32 m0, s2, 0x10400
	s_mov_b64 s[6:7], 0x4000
	global_load_lds_dwordx4 v[172:173], off
	v_lshl_add_u64 v[172:173], v[128:129], 0, s[6:7]
	s_add_i32 m0, s2, 0x10800
	s_mov_b64 s[6:7], 0x6000
	global_load_lds_dwordx4 v[172:173], off
	v_lshl_add_u64 v[172:173], v[128:129], 0, s[6:7]
	s_add_i32 m0, s2, 0x10c00
	s_mov_b64 s[6:7], 0x8000
	global_load_lds_dwordx4 v[172:173], off
	v_lshl_add_u64 v[172:173], v[128:129], 0, s[6:7]
	s_add_i32 m0, s2, 0x11000
	s_mov_b64 s[6:7], 0xa000
	global_load_lds_dwordx4 v[172:173], off
	v_lshl_add_u64 v[172:173], v[128:129], 0, s[6:7]
	s_add_i32 m0, s2, 0x11400
	s_mov_b64 s[6:7], 0xc000
	global_load_lds_dwordx4 v[172:173], off
	v_lshl_add_u64 v[172:173], v[128:129], 0, s[6:7]
	s_add_i32 m0, s2, 0x11800
	s_mov_b64 s[6:7], 0xe000
	global_load_lds_dwordx4 v[172:173], off
	v_lshl_add_u64 v[128:129], v[128:129], 0, s[6:7]
	s_add_i32 m0, s2, 0x11c00
	v_add_f32_e32 v0, 0, v50
	global_load_lds_dwordx4 v[128:129], off
	s_waitcnt vmcnt(8)
	ds_read2_b32 v[128:129], v167 offset1:32
	ds_read2_b32 v[172:173], v167 offset0:64 offset1:96
	v_mov_b32_e32 v180, v34
	v_mov_b32_e32 v181, v18
	v_mul_f32_e32 v177, 0.5, v0
	s_waitcnt lgkmcnt(0)
	v_mul_f32_e32 v175, 0x3fd744fd, v128
	v_pk_add_f32 v[180:181], v[180:181], 0 op_sel_hi:[1,0]
	v_mov_b32_e32 v176, v18
	v_mov_b32_e32 v174, v1
	v_mov_b32_e32 v128, v129
	v_mov_b32_e32 v129, v172
	s_mov_b32 s2, s67
	v_pk_add_f32 v[174:175], v[176:177], v[174:175]
	v_pk_mul_f32 v[176:177], v[128:129], s[2:3] op_sel_hi:[1,0]
	v_pk_mul_f32 v[182:183], v[180:181], 0.5 op_sel_hi:[1,0]
	v_pk_fma_f32 v[128:129], v[180:181], 0.5, v[176:177] op_sel_hi:[1,0,1]
	v_mov_b32_e32 v182, v175
	v_mov_b32_e32 v184, v1
	v_mov_b32_e32 v185, v177
	v_add_f32_e32 v178, 0, v2
	v_mov_b32_e32 v179, v173
	v_pk_mul_f32 v[180:181], v[128:129], v[128:129]
	v_pk_add_f32 v[182:183], v[182:183], v[184:185]
	v_mul_f32_e32 v0, 0x3fd744fd, v173
	v_mov_b32_e32 v163, v175
	v_pk_mov_b32 v[176:177], v[176:177], v[180:181] op_sel:[1,0]
	v_pk_add_f32 v[180:181], v[128:129], v[182:183]
	v_pk_mul_f32 v[182:183], v[128:129], v[182:183]
	v_pk_fma_f32 v[172:173], v[178:179], s[66:67], v[0:1] op_sel_hi:[1,1,0]
	v_pk_fma_f32 v[176:177], v[174:175], v[162:163], v[176:177]
	v_mov_b32_e32 v181, v183
	v_pk_mul_f32 v[178:179], v[172:173], v[172:173]
	v_pk_add_f32 v[176:177], v[180:181], v[176:177]
	v_mov_b32_e32 v173, v178
	v_pk_add_f32 v[176:177], v[176:177], v[172:173]
	s_nop 1
	v_mov_b32_dpp v178, v176 quad_perm:[1,0,3,2] row_mask:0xf bank_mask:0xf bound_ctrl:1
	v_mov_b32_dpp v179, v177 quad_perm:[1,0,3,2] row_mask:0xf bank_mask:0xf bound_ctrl:1
	v_pk_add_f32 v[176:177], v[176:177], v[178:179]
	s_nop 1
	v_mov_b32_dpp v178, v176 quad_perm:[2,3,0,1] row_mask:0xf bank_mask:0xf bound_ctrl:1
	v_mov_b32_dpp v179, v177 quad_perm:[2,3,0,1] row_mask:0xf bank_mask:0xf bound_ctrl:1
	v_pk_add_f32 v[176:177], v[176:177], v[178:179]
	s_nop 1
	v_mov_b32_dpp v178, v176 row_half_mirror row_mask:0xf bank_mask:0xf bound_ctrl:1
	v_mov_b32_dpp v179, v177 row_half_mirror row_mask:0xf bank_mask:0xf bound_ctrl:1
	v_pk_add_f32 v[176:177], v[176:177], v[178:179]
	s_nop 1
	v_mov_b32_dpp v178, v176 row_mirror row_mask:0xf bank_mask:0xf bound_ctrl:1
	v_mov_b32_dpp v179, v177 row_mirror row_mask:0xf bank_mask:0xf bound_ctrl:1
	s_and_saveexec_b64 s[6:7], vcc
	v_pk_add_f32 v[176:177], v[176:177], v[178:179]
	ds_write_b64 v160, v[176:177] offset:256
	s_or_b64 exec, exec, s[6:7]
	ds_read2_b32 v[176:177], v167 offset0:128 offset1:160
	ds_read2_b32 v[178:179], v167 offset0:192 offset1:224
	v_add_f32_e32 v0, 0, v51
	v_add_f32_e32 v50, 0, v3
	v_mul_f32_e32 v3, 0.5, v0
	s_waitcnt lgkmcnt(1)
;   DI void operator()(f32x16 (&acc)[2][4], int grow0, int gcol0, int lane, int w, char* lds) {
;     ...
;     for (int ps = 0; ps < 4; ++ps) {
;       const int mt = ps >> 1;
;       if (ps + 1 < 4) {
;         if (ps >= 1) asm volatile("s_waitcnt lgkmcnt(0)" ::: "memory");
;         xpass(ps + 1, grow0, gcol0, lane, w, lds);
;         if (ps >= 1) asm volatile("s_waitcnt vmcnt(8)" ::: "memory");
;       } else asm volatile("s_waitcnt vmcnt(0)" ::: "memory");
;       const char* xs = lds + (ps & 1) * 65536 + w * 8192;
; #pragma unroll
;       for (int qq = 0; qq < 2; ++qq)
; #pragma unroll
;         for (int e = 0; e < 4; ++e) {
;           const int i = 4 * (2 * (ps & 1) + qq) + e;
;           const float* xr = (const float*)(xs + (8 * qq + 4 * hh + e) * 512) + l31;
;           float s1 = 0.f, s2 = 0.f;
; #pragma unroll
;           for (int nt = 0; nt < 4; ++nt) {
;             float v = (acc[mt][nt][i] + bia[nt]) * csc[nt];
;             float z = ALPHA * xr[nt * 32] + hs * v;
;             acc[mt][nt][i] = z; s1 += z; s2 += z * z;
;           }
;           s1 = row16_sum(s1); s2 = row16_sum(s2);
;           if ((lane & 15) == 0) { f32x2 sv = {s1, s2}; *(f32x2*)(redw + (mt * 32 + (i & 3) + 8 * (i >> 2)) * 2) = sv; }
;         }
	v_mul_f32_e32 v181, 0x3fd744fd, v176
	v_mov_b32_e32 v18, v35
	v_mov_b32_e32 v2, v19
	v_mov_b32_e32 v180, v1
	v_pk_add_f32 v[182:183], v[18:19], 0 op_sel_hi:[1,0]
	v_pk_add_f32 v[34:35], v[2:3], v[180:181]
	v_mov_b32_e32 v2, v177
	s_waitcnt lgkmcnt(0)
	v_mov_b32_e32 v3, v178
	s_mov_b32 s2, s67
	v_pk_mul_f32 v[18:19], v[2:3], s[2:3] op_sel_hi:[1,0]
	v_pk_mul_f32 v[176:177], v[182:183], 0.5 op_sel_hi:[1,0]
	v_pk_fma_f32 v[2:3], v[182:183], 0.5, v[18:19] op_sel_hi:[1,0,1]
	v_mov_b32_e32 v176, v35
	v_mov_b32_e32 v182, v1
	v_mov_b32_e32 v183, v19
	v_pk_mul_f32 v[180:181], v[2:3], v[2:3]
	v_pk_add_f32 v[176:177], v[176:177], v[182:183]
	v_mov_b32_e32 v163, v35
	v_pk_mov_b32 v[18:19], v[18:19], v[180:181] op_sel:[1,0]
	v_pk_add_f32 v[180:181], v[2:3], v[176:177]
	v_pk_mul_f32 v[176:177], v[2:3], v[176:177]
	v_mov_b32_e32 v51, v179
	v_pk_fma_f32 v[18:19], v[34:35], v[162:163], v[18:19]
	v_mov_b32_e32 v181, v177
	v_mul_f32_e32 v0, 0x3fd744fd, v179
	v_pk_add_f32 v[176:177], v[180:181], v[18:19]
	v_pk_fma_f32 v[18:19], v[50:51], s[66:67], v[0:1] op_sel_hi:[1,1,0]
	s_nop 0
	v_pk_mul_f32 v[50:51], v[18:19], v[18:19]
	s_nop 0
	v_mov_b32_e32 v19, v50
	v_pk_add_f32 v[50:51], v[176:177], v[18:19]
	s_nop 1
	v_mov_b32_dpp v176, v50 quad_perm:[1,0,3,2] row_mask:0xf bank_mask:0xf bound_ctrl:1
	v_mov_b32_dpp v177, v51 quad_perm:[1,0,3,2] row_mask:0xf bank_mask:0xf bound_ctrl:1
	v_pk_add_f32 v[50:51], v[50:51], v[176:177]
	s_nop 1
	v_mov_b32_dpp v176, v50 quad_perm:[2,3,0,1] row_mask:0xf bank_mask:0xf bound_ctrl:1
	v_mov_b32_dpp v177, v51 quad_perm:[2,3,0,1] row_mask:0xf bank_mask:0xf bound_ctrl:1
	v_pk_add_f32 v[50:51], v[50:51], v[176:177]
	s_nop 1
	v_mov_b32_dpp v176, v50 row_half_mirror row_mask:0xf bank_mask:0xf bound_ctrl:1
	v_mov_b32_dpp v177, v51 row_half_mirror row_mask:0xf bank_mask:0xf bound_ctrl:1
	v_pk_add_f32 v[50:51], v[50:51], v[176:177]
	s_nop 1
	v_mov_b32_dpp v176, v50 row_mirror row_mask:0xf bank_mask:0xf bound_ctrl:1
	v_mov_b32_dpp v177, v51 row_mirror row_mask:0xf bank_mask:0xf bound_ctrl:1
	s_and_saveexec_b64 s[6:7], vcc
	v_pk_add_f32 v[50:51], v[50:51], v[176:177]
	ds_write_b64 v160, v[50:51] offset:264
	s_or_b64 exec, exec, s[6:7]
	ds_read2_b32 v[50:51], v143 offset1:32
	ds_read2_b32 v[176:177], v143 offset0:64 offset1:96
	v_add_f32_e32 v0, 0, v52
	v_mov_b32_e32 v184, v36
	v_mov_b32_e32 v185, v20
	v_mul_f32_e32 v179, 0.5, v0
	s_waitcnt lgkmcnt(1)
	v_mul_f32_e32 v183, 0x3fd744fd, v50
	v_pk_add_f32 v[184:185], v[184:185], 0 op_sel_hi:[1,0]
	v_mov_b32_e32 v178, v20
	v_mov_b32_e32 v182, v1
	v_mov_b32_e32 v50, v51
	s_waitcnt lgkmcnt(0)
	v_mov_b32_e32 v51, v176
	s_mov_b32 s2, s67
	v_pk_add_f32 v[178:179], v[178:179], v[182:183]
	v_pk_mul_f32 v[182:183], v[50:51], s[2:3] op_sel_hi:[1,0]
	v_pk_mul_f32 v[186:187], v[184:185], 0.5 op_sel_hi:[1,0]
	v_pk_fma_f32 v[50:51], v[184:185], 0.5, v[182:183] op_sel_hi:[1,0,1]
	v_mov_b32_e32 v186, v179
	v_mov_b32_e32 v188, v1
	v_mov_b32_e32 v189, v183
	v_add_f32_e32 v180, 0, v4
	v_mov_b32_e32 v181, v177
	v_pk_mul_f32 v[184:185], v[50:51], v[50:51]
	v_pk_add_f32 v[186:187], v[186:187], v[188:189]
	v_mul_f32_e32 v0, 0x3fd744fd, v177
	v_mov_b32_e32 v163, v179
	v_pk_mov_b32 v[182:183], v[182:183], v[184:185] op_sel:[1,0]
	v_pk_add_f32 v[184:185], v[50:51], v[186:187]
	v_pk_mul_f32 v[186:187], v[50:51], v[186:187]
	v_pk_fma_f32 v[176:177], v[180:181], s[66:67], v[0:1] op_sel_hi:[1,1,0]
	v_pk_fma_f32 v[182:183], v[178:179], v[162:163], v[182:183]
	v_mov_b32_e32 v185, v187
	v_pk_mul_f32 v[180:181], v[176:177], v[176:177]
	v_pk_add_f32 v[182:183], v[184:185], v[182:183]
	v_mov_b32_e32 v177, v180
	v_pk_add_f32 v[180:181], v[182:183], v[176:177]
	s_nop 1
	v_mov_b32_dpp v182, v180 quad_perm:[1,0,3,2] row_mask:0xf bank_mask:0xf bound_ctrl:1
	v_mov_b32_dpp v183, v181 quad_perm:[1,0,3,2] row_mask:0xf bank_mask:0xf bound_ctrl:1
	v_pk_add_f32 v[180:181], v[180:181], v[182:183]
	s_nop 1
	v_mov_b32_dpp v182, v180 quad_perm:[2,3,0,1] row_mask:0xf bank_mask:0xf bound_ctrl:1
	v_mov_b32_dpp v183, v181 quad_perm:[2,3,0,1] row_mask:0xf bank_mask:0xf bound_ctrl:1
	v_pk_add_f32 v[180:181], v[180:181], v[182:183]
	s_nop 1
	v_mov_b32_dpp v182, v180 row_half_mirror row_mask:0xf bank_mask:0xf bound_ctrl:1
	v_mov_b32_dpp v183, v181 row_half_mirror row_mask:0xf bank_mask:0xf bound_ctrl:1
	v_pk_add_f32 v[180:181], v[180:181], v[182:183]
	s_nop 1
	v_mov_b32_dpp v182, v180 row_mirror row_mask:0xf bank_mask:0xf bound_ctrl:1
	v_mov_b32_dpp v183, v181 row_mirror row_mask:0xf bank_mask:0xf bound_ctrl:1
	s_and_saveexec_b64 s[6:7], vcc
	v_pk_add_f32 v[180:181], v[180:181], v[182:183]
	ds_write_b64 v160, v[180:181] offset:272
	s_or_b64 exec, exec, s[6:7]
	ds_read2_b32 v[180:181], v144 offset1:32
	ds_read2_b32 v[182:183], v144 offset0:64 offset1:96
	v_add_f32_e32 v0, 0, v53
	v_add_f32_e32 v52, 0, v5
	v_mul_f32_e32 v5, 0.5, v0
	s_waitcnt lgkmcnt(1)
	v_mul_f32_e32 v185, 0x3fd744fd, v180
	v_mov_b32_e32 v20, v37
	v_mov_b32_e32 v4, v21
	v_mov_b32_e32 v184, v1
	v_pk_add_f32 v[186:187], v[20:21], 0 op_sel_hi:[1,0]
	v_pk_add_f32 v[36:37], v[4:5], v[184:185]
	v_mov_b32_e32 v4, v181
	s_waitcnt lgkmcnt(0)
;   DI void operator()(f32x16 (&acc)[2][4], int grow0, int gcol0, int lane, int w, char* lds) {
;     ...
;     for (int ps = 0; ps < 4; ++ps) {
;       const int mt = ps >> 1;
;       if (ps + 1 < 4) {
;         if (ps >= 1) asm volatile("s_waitcnt lgkmcnt(0)" ::: "memory");
;         xpass(ps + 1, grow0, gcol0, lane, w, lds);
;         if (ps >= 1) asm volatile("s_waitcnt vmcnt(8)" ::: "memory");
;       } else asm volatile("s_waitcnt vmcnt(0)" ::: "memory");
;       const char* xs = lds + (ps & 1) * 65536 + w * 8192;
; #pragma unroll
;       for (int qq = 0; qq < 2; ++qq)
; #pragma unroll
;         for (int e = 0; e < 4; ++e) {
;           const int i = 4 * (2 * (ps & 1) + qq) + e;
;           const float* xr = (const float*)(xs + (8 * qq + 4 * hh + e) * 512) + l31;
;           float s1 = 0.f, s2 = 0.f;
; #pragma unroll
;           for (int nt = 0; nt < 4; ++nt) {
;             float v = (acc[mt][nt][i] + bia[nt]) * csc[nt];
;             float z = ALPHA * xr[nt * 32] + hs * v;
;             acc[mt][nt][i] = z; s1 += z; s2 += z * z;
;           }
;           s1 = row16_sum(s1); s2 = row16_sum(s2);
;           if ((lane & 15) == 0) { f32x2 sv = {s1, s2}; *(f32x2*)(redw + (mt * 32 + (i & 3) + 8 * (i >> 2)) * 2) = sv; }
;         }
	v_mov_b32_e32 v5, v182
	s_mov_b32 s2, s67
	v_pk_mul_f32 v[20:21], v[4:5], s[2:3] op_sel_hi:[1,0]
	v_pk_mul_f32 v[180:181], v[186:187], 0.5 op_sel_hi:[1,0]
	v_pk_fma_f32 v[4:5], v[186:187], 0.5, v[20:21] op_sel_hi:[1,0,1]
	v_mov_b32_e32 v180, v37
	v_mov_b32_e32 v186, v1
	v_mov_b32_e32 v187, v21
	v_pk_mul_f32 v[184:185], v[4:5], v[4:5]
	v_pk_add_f32 v[180:181], v[180:181], v[186:187]
	v_mov_b32_e32 v163, v37
	v_pk_mov_b32 v[20:21], v[20:21], v[184:185] op_sel:[1,0]
	v_pk_add_f32 v[184:185], v[4:5], v[180:181]
	v_pk_mul_f32 v[180:181], v[4:5], v[180:181]
	v_mov_b32_e32 v53, v183
	v_pk_fma_f32 v[20:21], v[36:37], v[162:163], v[20:21]
	v_mov_b32_e32 v185, v181
	v_mul_f32_e32 v0, 0x3fd744fd, v183
	v_pk_add_f32 v[180:181], v[184:185], v[20:21]
	v_pk_fma_f32 v[20:21], v[52:53], s[66:67], v[0:1] op_sel_hi:[1,1,0]
	s_nop 0
	v_pk_mul_f32 v[52:53], v[20:21], v[20:21]
	s_nop 0
	v_mov_b32_e32 v21, v52
	v_pk_add_f32 v[52:53], v[180:181], v[20:21]
	s_nop 1
	v_mov_b32_dpp v180, v52 quad_perm:[1,0,3,2] row_mask:0xf bank_mask:0xf bound_ctrl:1
	v_mov_b32_dpp v181, v53 quad_perm:[1,0,3,2] row_mask:0xf bank_mask:0xf bound_ctrl:1
	v_pk_add_f32 v[52:53], v[52:53], v[180:181]
	s_nop 1
	v_mov_b32_dpp v180, v52 quad_perm:[2,3,0,1] row_mask:0xf bank_mask:0xf bound_ctrl:1
	v_mov_b32_dpp v181, v53 quad_perm:[2,3,0,1] row_mask:0xf bank_mask:0xf bound_ctrl:1
	v_pk_add_f32 v[52:53], v[52:53], v[180:181]
	s_nop 1
	v_mov_b32_dpp v180, v52 row_half_mirror row_mask:0xf bank_mask:0xf bound_ctrl:1
	v_mov_b32_dpp v181, v53 row_half_mirror row_mask:0xf bank_mask:0xf bound_ctrl:1
	v_pk_add_f32 v[52:53], v[52:53], v[180:181]
	s_nop 1
	v_mov_b32_dpp v180, v52 row_mirror row_mask:0xf bank_mask:0xf bound_ctrl:1
	v_mov_b32_dpp v181, v53 row_mirror row_mask:0xf bank_mask:0xf bound_ctrl:1
	s_and_saveexec_b64 s[6:7], vcc
	v_pk_add_f32 v[52:53], v[52:53], v[180:181]
	ds_write_b64 v160, v[52:53] offset:280
	s_or_b64 exec, exec, s[6:7]
	ds_read2_b32 v[52:53], v83 offset1:32
	ds_read2_b32 v[180:181], v83 offset0:64 offset1:96
	v_add_f32_e32 v0, 0, v54
	v_mov_b32_e32 v188, v38
	v_mov_b32_e32 v189, v22
	v_mul_f32_e32 v183, 0.5, v0
	s_waitcnt lgkmcnt(1)
	v_mul_f32_e32 v187, 0x3fd744fd, v52
	v_pk_add_f32 v[188:189], v[188:189], 0 op_sel_hi:[1,0]
	v_mov_b32_e32 v182, v22
	v_mov_b32_e32 v186, v1
	v_mov_b32_e32 v52, v53
	s_waitcnt lgkmcnt(0)
	v_mov_b32_e32 v53, v180
	s_mov_b32 s2, s67
	v_pk_add_f32 v[182:183], v[182:183], v[186:187]
	v_pk_mul_f32 v[186:187], v[52:53], s[2:3] op_sel_hi:[1,0]
	v_pk_mul_f32 v[190:191], v[188:189], 0.5 op_sel_hi:[1,0]
	v_pk_fma_f32 v[52:53], v[188:189], 0.5, v[186:187] op_sel_hi:[1,0,1]
	v_mov_b32_e32 v190, v183
	v_mov_b32_e32 v192, v1
	v_mov_b32_e32 v193, v187
	v_add_f32_e32 v184, 0, v6
	v_mov_b32_e32 v185, v181
	v_pk_mul_f32 v[188:189], v[52:53], v[52:53]
	v_pk_add_f32 v[190:191], v[190:191], v[192:193]
	v_mul_f32_e32 v0, 0x3fd744fd, v181
	v_mov_b32_e32 v163, v183
	v_pk_mov_b32 v[186:187], v[186:187], v[188:189] op_sel:[1,0]
	v_pk_add_f32 v[188:189], v[52:53], v[190:191]
	v_pk_mul_f32 v[190:191], v[52:53], v[190:191]
	v_pk_fma_f32 v[180:181], v[184:185], s[66:67], v[0:1] op_sel_hi:[1,1,0]
	v_pk_fma_f32 v[186:187], v[182:183], v[162:163], v[186:187]
	v_mov_b32_e32 v189, v191
	v_pk_mul_f32 v[184:185], v[180:181], v[180:181]
	v_pk_add_f32 v[186:187], v[188:189], v[186:187]
	v_mov_b32_e32 v181, v184
	v_pk_add_f32 v[184:185], v[186:187], v[180:181]
	s_nop 1
	v_mov_b32_dpp v186, v184 quad_perm:[1,0,3,2] row_mask:0xf bank_mask:0xf bound_ctrl:1
	v_mov_b32_dpp v187, v185 quad_perm:[1,0,3,2] row_mask:0xf bank_mask:0xf bound_ctrl:1
	v_pk_add_f32 v[184:185], v[184:185], v[186:187]
	s_nop 1
	v_mov_b32_dpp v186, v184 quad_perm:[2,3,0,1] row_mask:0xf bank_mask:0xf bound_ctrl:1
	v_mov_b32_dpp v187, v185 quad_perm:[2,3,0,1] row_mask:0xf bank_mask:0xf bound_ctrl:1
	v_pk_add_f32 v[184:185], v[184:185], v[186:187]
	s_nop 1
	v_mov_b32_dpp v186, v184 row_half_mirror row_mask:0xf bank_mask:0xf bound_ctrl:1
	v_mov_b32_dpp v187, v185 row_half_mirror row_mask:0xf bank_mask:0xf bound_ctrl:1
	v_pk_add_f32 v[184:185], v[184:185], v[186:187]
	s_nop 1
	v_mov_b32_dpp v186, v184 row_mirror row_mask:0xf bank_mask:0xf bound_ctrl:1
	v_mov_b32_dpp v187, v185 row_mirror row_mask:0xf bank_mask:0xf bound_ctrl:1
	s_and_saveexec_b64 s[6:7], vcc
	v_pk_add_f32 v[184:185], v[184:185], v[186:187]
	ds_write_b64 v160, v[184:185] offset:320
	s_or_b64 exec, exec, s[6:7]
	ds_read2_b32 v[184:185], v83 offset0:128 offset1:160
	ds_read2_b32 v[186:187], v83 offset0:192 offset1:224
	v_add_f32_e32 v0, 0, v55
	v_add_f32_e32 v54, 0, v7
	v_mul_f32_e32 v7, 0.5, v0
	s_waitcnt lgkmcnt(1)
	v_mul_f32_e32 v189, 0x3fd744fd, v184
	v_mov_b32_e32 v22, v39
	v_mov_b32_e32 v6, v23
	v_mov_b32_e32 v188, v1
	v_pk_add_f32 v[190:191], v[22:23], 0 op_sel_hi:[1,0]
	v_pk_add_f32 v[38:39], v[6:7], v[188:189]
	v_mov_b32_e32 v6, v185
	s_waitcnt lgkmcnt(0)
;   DI void operator()(f32x16 (&acc)[2][4], int grow0, int gcol0, int lane, int w, char* lds) {
;     ...
;     for (int ps = 0; ps < 4; ++ps) {
;       const int mt = ps >> 1;
;       if (ps + 1 < 4) {
;         if (ps >= 1) asm volatile("s_waitcnt lgkmcnt(0)" ::: "memory");
;         xpass(ps + 1, grow0, gcol0, lane, w, lds);
;         if (ps >= 1) asm volatile("s_waitcnt vmcnt(8)" ::: "memory");
;       } else asm volatile("s_waitcnt vmcnt(0)" ::: "memory");
;       const char* xs = lds + (ps & 1) * 65536 + w * 8192;
; #pragma unroll
;       for (int qq = 0; qq < 2; ++qq)
; #pragma unroll
;         for (int e = 0; e < 4; ++e) {
;           const int i = 4 * (2 * (ps & 1) + qq) + e;
;           const float* xr = (const float*)(xs + (8 * qq + 4 * hh + e) * 512) + l31;
;           float s1 = 0.f, s2 = 0.f;
; #pragma unroll
;           for (int nt = 0; nt < 4; ++nt) {
;             float v = (acc[mt][nt][i] + bia[nt]) * csc[nt];
;             float z = ALPHA * xr[nt * 32] + hs * v;
;             acc[mt][nt][i] = z; s1 += z; s2 += z * z;
;           }
;           s1 = row16_sum(s1); s2 = row16_sum(s2);
;           if ((lane & 15) == 0) { f32x2 sv = {s1, s2}; *(f32x2*)(redw + (mt * 32 + (i & 3) + 8 * (i >> 2)) * 2) = sv; }
;         }
	v_mov_b32_e32 v7, v186
	s_mov_b32 s2, s67
	v_pk_mul_f32 v[22:23], v[6:7], s[2:3] op_sel_hi:[1,0]
	v_pk_mul_f32 v[184:185], v[190:191], 0.5 op_sel_hi:[1,0]
	v_pk_fma_f32 v[6:7], v[190:191], 0.5, v[22:23] op_sel_hi:[1,0,1]
	v_mov_b32_e32 v184, v39
	v_mov_b32_e32 v190, v1
	v_mov_b32_e32 v191, v23
	v_pk_mul_f32 v[188:189], v[6:7], v[6:7]
	v_pk_add_f32 v[184:185], v[184:185], v[190:191]
	v_mov_b32_e32 v163, v39
	v_pk_mov_b32 v[22:23], v[22:23], v[188:189] op_sel:[1,0]
	v_pk_add_f32 v[188:189], v[6:7], v[184:185]
	v_pk_mul_f32 v[184:185], v[6:7], v[184:185]
	v_mov_b32_e32 v55, v187
	v_pk_fma_f32 v[22:23], v[38:39], v[162:163], v[22:23]
	v_mov_b32_e32 v189, v185
	v_mul_f32_e32 v0, 0x3fd744fd, v187
	v_pk_add_f32 v[184:185], v[188:189], v[22:23]
	v_pk_fma_f32 v[22:23], v[54:55], s[66:67], v[0:1] op_sel_hi:[1,1,0]
	s_nop 0
	v_pk_mul_f32 v[54:55], v[22:23], v[22:23]
	s_nop 0
	v_mov_b32_e32 v23, v54
	v_pk_add_f32 v[54:55], v[184:185], v[22:23]
	s_nop 1
	v_mov_b32_dpp v184, v54 quad_perm:[1,0,3,2] row_mask:0xf bank_mask:0xf bound_ctrl:1
	v_mov_b32_dpp v185, v55 quad_perm:[1,0,3,2] row_mask:0xf bank_mask:0xf bound_ctrl:1
	v_pk_add_f32 v[54:55], v[54:55], v[184:185]
	s_nop 1
	v_mov_b32_dpp v184, v54 quad_perm:[2,3,0,1] row_mask:0xf bank_mask:0xf bound_ctrl:1
	v_mov_b32_dpp v185, v55 quad_perm:[2,3,0,1] row_mask:0xf bank_mask:0xf bound_ctrl:1
	v_pk_add_f32 v[54:55], v[54:55], v[184:185]
	s_nop 1
	v_mov_b32_dpp v184, v54 row_half_mirror row_mask:0xf bank_mask:0xf bound_ctrl:1
	v_mov_b32_dpp v185, v55 row_half_mirror row_mask:0xf bank_mask:0xf bound_ctrl:1
	v_pk_add_f32 v[54:55], v[54:55], v[184:185]
	s_nop 1
	v_mov_b32_dpp v184, v54 row_mirror row_mask:0xf bank_mask:0xf bound_ctrl:1
	v_mov_b32_dpp v185, v55 row_mirror row_mask:0xf bank_mask:0xf bound_ctrl:1
	s_and_saveexec_b64 s[6:7], vcc
	v_pk_add_f32 v[54:55], v[54:55], v[184:185]
	ds_write_b64 v160, v[54:55] offset:328
	s_or_b64 exec, exec, s[6:7]
	ds_read2_b32 v[54:55], v85 offset1:32
	ds_read2_b32 v[184:185], v85 offset0:64 offset1:96
	v_add_f32_e32 v0, 0, v56
	v_mov_b32_e32 v192, v40
	v_mov_b32_e32 v193, v24
	v_mul_f32_e32 v187, 0.5, v0
	s_waitcnt lgkmcnt(1)
	v_mul_f32_e32 v191, 0x3fd744fd, v54
	v_pk_add_f32 v[192:193], v[192:193], 0 op_sel_hi:[1,0]
	v_mov_b32_e32 v186, v24
	v_mov_b32_e32 v190, v1
	v_mov_b32_e32 v54, v55
	s_waitcnt lgkmcnt(0)
	v_mov_b32_e32 v55, v184
	s_mov_b32 s2, s67
	v_pk_add_f32 v[186:187], v[186:187], v[190:191]
	v_pk_mul_f32 v[190:191], v[54:55], s[2:3] op_sel_hi:[1,0]
	v_pk_mul_f32 v[194:195], v[192:193], 0.5 op_sel_hi:[1,0]
	v_pk_fma_f32 v[54:55], v[192:193], 0.5, v[190:191] op_sel_hi:[1,0,1]
	v_mov_b32_e32 v194, v187
	v_mov_b32_e32 v196, v1
	v_mov_b32_e32 v197, v191
	v_add_f32_e32 v188, 0, v8
	v_mov_b32_e32 v189, v185
	v_pk_mul_f32 v[192:193], v[54:55], v[54:55]
	v_pk_add_f32 v[194:195], v[194:195], v[196:197]
	v_mul_f32_e32 v0, 0x3fd744fd, v185
	v_mov_b32_e32 v163, v187
	v_pk_mov_b32 v[190:191], v[190:191], v[192:193] op_sel:[1,0]
	v_pk_add_f32 v[192:193], v[54:55], v[194:195]
	v_pk_mul_f32 v[194:195], v[54:55], v[194:195]
	v_pk_fma_f32 v[184:185], v[188:189], s[66:67], v[0:1] op_sel_hi:[1,1,0]
	v_pk_fma_f32 v[190:191], v[186:187], v[162:163], v[190:191]
	v_mov_b32_e32 v193, v195
	v_pk_mul_f32 v[188:189], v[184:185], v[184:185]
	v_pk_add_f32 v[190:191], v[192:193], v[190:191]
	v_mov_b32_e32 v185, v188
	v_pk_add_f32 v[188:189], v[190:191], v[184:185]
	s_nop 1
	v_mov_b32_dpp v190, v188 quad_perm:[1,0,3,2] row_mask:0xf bank_mask:0xf bound_ctrl:1
	v_mov_b32_dpp v191, v189 quad_perm:[1,0,3,2] row_mask:0xf bank_mask:0xf bound_ctrl:1
	v_pk_add_f32 v[188:189], v[188:189], v[190:191]
	s_nop 1
	v_mov_b32_dpp v190, v188 quad_perm:[2,3,0,1] row_mask:0xf bank_mask:0xf bound_ctrl:1
	v_mov_b32_dpp v191, v189 quad_perm:[2,3,0,1] row_mask:0xf bank_mask:0xf bound_ctrl:1
	v_pk_add_f32 v[188:189], v[188:189], v[190:191]
	s_nop 1
	v_mov_b32_dpp v190, v188 row_half_mirror row_mask:0xf bank_mask:0xf bound_ctrl:1
	v_mov_b32_dpp v191, v189 row_half_mirror row_mask:0xf bank_mask:0xf bound_ctrl:1
	v_pk_add_f32 v[188:189], v[188:189], v[190:191]
	s_nop 1
	v_mov_b32_dpp v190, v188 row_mirror row_mask:0xf bank_mask:0xf bound_ctrl:1
	v_mov_b32_dpp v191, v189 row_mirror row_mask:0xf bank_mask:0xf bound_ctrl:1
	s_and_saveexec_b64 s[6:7], vcc
	v_pk_add_f32 v[188:189], v[188:189], v[190:191]
	ds_write_b64 v160, v[188:189] offset:336
	s_or_b64 exec, exec, s[6:7]
	ds_read2_b32 v[188:189], v87 offset1:32
	ds_read2_b32 v[190:191], v87 offset0:64 offset1:96
	v_add_f32_e32 v0, 0, v57
	v_add_f32_e32 v56, 0, v9
	v_mul_f32_e32 v9, 0.5, v0
	s_waitcnt lgkmcnt(1)
	v_mul_f32_e32 v193, 0x3fd744fd, v188
	v_mov_b32_e32 v24, v41
	v_mov_b32_e32 v8, v25
	v_mov_b32_e32 v192, v1
	v_pk_add_f32 v[194:195], v[24:25], 0 op_sel_hi:[1,0]
	v_pk_add_f32 v[40:41], v[8:9], v[192:193]
	v_mov_b32_e32 v8, v189
	s_waitcnt lgkmcnt(0)
;   DI void operator()(f32x16 (&acc)[2][4], int grow0, int gcol0, int lane, int w, char* lds) {
;     ...
;     for (int ps = 0; ps < 4; ++ps) {
;       const int mt = ps >> 1;
;       if (ps + 1 < 4) {
;         if (ps >= 1) asm volatile("s_waitcnt lgkmcnt(0)" ::: "memory");
;         xpass(ps + 1, grow0, gcol0, lane, w, lds);
;         if (ps >= 1) asm volatile("s_waitcnt vmcnt(8)" ::: "memory");
;       } else asm volatile("s_waitcnt vmcnt(0)" ::: "memory");
;       const char* xs = lds + (ps & 1) * 65536 + w * 8192;
; #pragma unroll
;       for (int qq = 0; qq < 2; ++qq)
; #pragma unroll
;         for (int e = 0; e < 4; ++e) {
;           const int i = 4 * (2 * (ps & 1) + qq) + e;
;           const float* xr = (const float*)(xs + (8 * qq + 4 * hh + e) * 512) + l31;
;           float s1 = 0.f, s2 = 0.f;
; #pragma unroll
;           for (int nt = 0; nt < 4; ++nt) {
;             float v = (acc[mt][nt][i] + bia[nt]) * csc[nt];
;             float z = ALPHA * xr[nt * 32] + hs * v;
;             acc[mt][nt][i] = z; s1 += z; s2 += z * z;
;           }
;           s1 = row16_sum(s1); s2 = row16_sum(s2);
;           if ((lane & 15) == 0) { f32x2 sv = {s1, s2}; *(f32x2*)(redw + (mt * 32 + (i & 3) + 8 * (i >> 2)) * 2) = sv; }
;         }
	v_mov_b32_e32 v9, v190
	s_mov_b32 s2, s67
	v_pk_mul_f32 v[24:25], v[8:9], s[2:3] op_sel_hi:[1,0]
	v_pk_mul_f32 v[188:189], v[194:195], 0.5 op_sel_hi:[1,0]
	v_pk_fma_f32 v[8:9], v[194:195], 0.5, v[24:25] op_sel_hi:[1,0,1]
	v_mov_b32_e32 v188, v41
	v_mov_b32_e32 v194, v1
	v_mov_b32_e32 v195, v25
	v_pk_mul_f32 v[192:193], v[8:9], v[8:9]
	v_pk_add_f32 v[188:189], v[188:189], v[194:195]
	v_mov_b32_e32 v163, v41
	v_pk_mov_b32 v[24:25], v[24:25], v[192:193] op_sel:[1,0]
	v_pk_add_f32 v[192:193], v[8:9], v[188:189]
	v_pk_mul_f32 v[188:189], v[8:9], v[188:189]
	v_mov_b32_e32 v57, v191
	v_pk_fma_f32 v[24:25], v[40:41], v[162:163], v[24:25]
	v_mov_b32_e32 v193, v189
	v_mul_f32_e32 v0, 0x3fd744fd, v191
	v_pk_add_f32 v[188:189], v[192:193], v[24:25]
	v_pk_fma_f32 v[24:25], v[56:57], s[66:67], v[0:1] op_sel_hi:[1,1,0]
	s_nop 0
	v_pk_mul_f32 v[56:57], v[24:25], v[24:25]
	s_nop 0
	v_mov_b32_e32 v25, v56
	v_pk_add_f32 v[56:57], v[188:189], v[24:25]
	s_nop 1
	v_mov_b32_dpp v188, v56 quad_perm:[1,0,3,2] row_mask:0xf bank_mask:0xf bound_ctrl:1
	v_mov_b32_dpp v189, v57 quad_perm:[1,0,3,2] row_mask:0xf bank_mask:0xf bound_ctrl:1
	v_pk_add_f32 v[56:57], v[56:57], v[188:189]
	s_nop 1
	v_mov_b32_dpp v188, v56 quad_perm:[2,3,0,1] row_mask:0xf bank_mask:0xf bound_ctrl:1
	v_mov_b32_dpp v189, v57 quad_perm:[2,3,0,1] row_mask:0xf bank_mask:0xf bound_ctrl:1
	v_pk_add_f32 v[56:57], v[56:57], v[188:189]
	s_nop 1
	v_mov_b32_dpp v188, v56 row_half_mirror row_mask:0xf bank_mask:0xf bound_ctrl:1
	v_mov_b32_dpp v189, v57 row_half_mirror row_mask:0xf bank_mask:0xf bound_ctrl:1
	v_pk_add_f32 v[56:57], v[56:57], v[188:189]
	s_nop 1
	v_mov_b32_dpp v188, v56 row_mirror row_mask:0xf bank_mask:0xf bound_ctrl:1
	v_mov_b32_dpp v189, v57 row_mirror row_mask:0xf bank_mask:0xf bound_ctrl:1
	s_and_saveexec_b64 s[6:7], vcc
	v_pk_add_f32 v[56:57], v[56:57], v[188:189]
	ds_write_b64 v160, v[56:57] offset:344
	s_or_b64 exec, exec, s[6:7]
	s_waitcnt vmcnt(0)
	ds_read2_b32 v[56:57], v89 offset1:32
	ds_read2_b32 v[190:191], v89 offset0:64 offset1:96
	v_add_f32_e32 v0, 0, v58
	v_mul_f32_e32 v189, 0.5, v0
	v_mov_b32_e32 v188, v26
	s_waitcnt lgkmcnt(1)
	v_mul_f32_e32 v193, 0x3fd744fd, v56
	v_add_f32_e32 v56, 0, v42
	v_mul_f32_e32 v0, 0x3fd744fd, v57
	v_mov_b32_e32 v192, v1
	v_pk_fma_f32 v[56:57], v[56:57], s[66:67], v[0:1] op_sel_hi:[1,1,0]
	v_pk_add_f32 v[192:193], v[188:189], v[192:193]
	s_waitcnt lgkmcnt(0)
	v_mov_b32_e32 v188, v190
	v_mov_b32_e32 v189, v56
	v_mov_b32_e32 v196, v165
	v_mov_b32_e32 v197, v56
	v_mov_b32_e32 v163, v193
	v_pk_mul_f32 v[196:197], v[188:189], v[196:197]
	v_pk_mul_f32 v[198:199], v[192:193], v[162:163]
	v_mov_b32_e32 v200, v1
	v_pk_mov_b32 v[198:199], v[192:193], v[198:199] op_sel:[1,0]
	v_mov_b32_e32 v201, v196
	v_add_f32_e32 v194, 0, v10
	v_mov_b32_e32 v195, v191
	v_pk_fma_f32 v[188:189], v[192:193], v[162:163], v[196:197]
	v_pk_add_f32 v[196:197], v[198:199], v[200:201]
	v_mul_f32_e32 v0, 0x3fd744fd, v191
	v_pk_add_f32 v[198:199], v[56:57], v[196:197]
	v_pk_mul_f32 v[196:197], v[188:189], v[196:197] op_sel_hi:[0,1]
	v_pk_fma_f32 v[190:191], v[194:195], s[66:67], v[0:1] op_sel_hi:[1,1,0]
	v_mov_b32_e32 v199, v197
	v_pk_mul_f32 v[194:195], v[190:191], v[190:191]
	v_pk_add_f32 v[196:197], v[188:189], v[198:199]
	v_mov_b32_e32 v191, v194
	v_pk_add_f32 v[194:195], v[196:197], v[190:191]
	s_nop 1
	v_mov_b32_dpp v196, v194 quad_perm:[1,0,3,2] row_mask:0xf bank_mask:0xf bound_ctrl:1
	v_mov_b32_dpp v197, v195 quad_perm:[1,0,3,2] row_mask:0xf bank_mask:0xf bound_ctrl:1
	v_pk_add_f32 v[194:195], v[194:195], v[196:197]
	s_nop 1
	v_mov_b32_dpp v196, v194 quad_perm:[2,3,0,1] row_mask:0xf bank_mask:0xf bound_ctrl:1
	v_mov_b32_dpp v197, v195 quad_perm:[2,3,0,1] row_mask:0xf bank_mask:0xf bound_ctrl:1
	v_pk_add_f32 v[194:195], v[194:195], v[196:197]
	s_nop 1
	v_mov_b32_dpp v196, v194 row_half_mirror row_mask:0xf bank_mask:0xf bound_ctrl:1
	v_mov_b32_dpp v197, v195 row_half_mirror row_mask:0xf bank_mask:0xf bound_ctrl:1
	v_pk_add_f32 v[194:195], v[194:195], v[196:197]
	s_nop 1
	v_mov_b32_dpp v196, v194 row_mirror row_mask:0xf bank_mask:0xf bound_ctrl:1
	v_mov_b32_dpp v197, v195 row_mirror row_mask:0xf bank_mask:0xf bound_ctrl:1
	s_and_saveexec_b64 s[6:7], vcc
	v_pk_add_f32 v[194:195], v[194:195], v[196:197]
	ds_write_b64 v160, v[194:195] offset:384
	s_or_b64 exec, exec, s[6:7]
	ds_read2_b32 v[194:195], v98 offset1:32
	ds_read2_b32 v[196:197], v98 offset0:64 offset1:96
	v_add_f32_e32 v0, 0, v59
	v_add_f32_e32 v58, 0, v11
	v_mul_f32_e32 v11, 0.5, v0
	s_waitcnt lgkmcnt(1)
	v_mul_f32_e32 v199, 0x3fd744fd, v194
	v_mov_b32_e32 v26, v43
	v_mov_b32_e32 v10, v27
	v_mov_b32_e32 v198, v1
	v_pk_add_f32 v[200:201], v[26:27], 0 op_sel_hi:[1,0]
	v_pk_add_f32 v[42:43], v[10:11], v[198:199]
	v_mov_b32_e32 v10, v195
	s_waitcnt lgkmcnt(0)
;   DI void operator()(f32x16 (&acc)[2][4], int grow0, int gcol0, int lane, int w, char* lds) {
;     ...
;     for (int ps = 0; ps < 4; ++ps) {
;       const int mt = ps >> 1;
;       if (ps + 1 < 4) {
;         if (ps >= 1) asm volatile("s_waitcnt lgkmcnt(0)" ::: "memory");
;         xpass(ps + 1, grow0, gcol0, lane, w, lds);
;         if (ps >= 1) asm volatile("s_waitcnt vmcnt(8)" ::: "memory");
;       } else asm volatile("s_waitcnt vmcnt(0)" ::: "memory");
;       const char* xs = lds + (ps & 1) * 65536 + w * 8192;
; #pragma unroll
;       for (int qq = 0; qq < 2; ++qq)
; #pragma unroll
;         for (int e = 0; e < 4; ++e) {
;           const int i = 4 * (2 * (ps & 1) + qq) + e;
;           const float* xr = (const float*)(xs + (8 * qq + 4 * hh + e) * 512) + l31;
;           float s1 = 0.f, s2 = 0.f;
; #pragma unroll
;           for (int nt = 0; nt < 4; ++nt) {
;             float v = (acc[mt][nt][i] + bia[nt]) * csc[nt];
;             float z = ALPHA * xr[nt * 32] + hs * v;
;             acc[mt][nt][i] = z; s1 += z; s2 += z * z;
;           }
;           s1 = row16_sum(s1); s2 = row16_sum(s2);
;           if ((lane & 15) == 0) { f32x2 sv = {s1, s2}; *(f32x2*)(redw + (mt * 32 + (i & 3) + 8 * (i >> 2)) * 2) = sv; }
;         }
	v_mov_b32_e32 v11, v196
	s_mov_b32 s2, s67
	v_pk_mul_f32 v[26:27], v[10:11], s[2:3] op_sel_hi:[1,0]
	v_pk_mul_f32 v[194:195], v[200:201], 0.5 op_sel_hi:[1,0]
	v_pk_fma_f32 v[10:11], v[200:201], 0.5, v[26:27] op_sel_hi:[1,0,1]
	v_mov_b32_e32 v194, v43
	v_mov_b32_e32 v200, v1
	v_mov_b32_e32 v201, v27
	v_pk_mul_f32 v[198:199], v[10:11], v[10:11]
	v_pk_add_f32 v[194:195], v[194:195], v[200:201]
	v_mov_b32_e32 v163, v43
	v_pk_mov_b32 v[26:27], v[26:27], v[198:199] op_sel:[1,0]
	v_pk_add_f32 v[198:199], v[10:11], v[194:195]
	v_pk_mul_f32 v[194:195], v[10:11], v[194:195]
	v_mov_b32_e32 v59, v197
	v_pk_fma_f32 v[26:27], v[42:43], v[162:163], v[26:27]
	v_mov_b32_e32 v199, v195
	v_mul_f32_e32 v0, 0x3fd744fd, v197
	v_pk_add_f32 v[194:195], v[198:199], v[26:27]
	v_pk_fma_f32 v[26:27], v[58:59], s[66:67], v[0:1] op_sel_hi:[1,1,0]
	s_nop 0
	v_pk_mul_f32 v[58:59], v[26:27], v[26:27]
	s_nop 0
	v_mov_b32_e32 v27, v58
	v_pk_add_f32 v[58:59], v[194:195], v[26:27]
	s_nop 1
	v_mov_b32_dpp v194, v58 quad_perm:[1,0,3,2] row_mask:0xf bank_mask:0xf bound_ctrl:1
	v_mov_b32_dpp v195, v59 quad_perm:[1,0,3,2] row_mask:0xf bank_mask:0xf bound_ctrl:1
	v_pk_add_f32 v[58:59], v[58:59], v[194:195]
	s_nop 1
	v_mov_b32_dpp v194, v58 quad_perm:[2,3,0,1] row_mask:0xf bank_mask:0xf bound_ctrl:1
	v_mov_b32_dpp v195, v59 quad_perm:[2,3,0,1] row_mask:0xf bank_mask:0xf bound_ctrl:1
	v_pk_add_f32 v[58:59], v[58:59], v[194:195]
	s_nop 1
	v_mov_b32_dpp v194, v58 row_half_mirror row_mask:0xf bank_mask:0xf bound_ctrl:1
	v_mov_b32_dpp v195, v59 row_half_mirror row_mask:0xf bank_mask:0xf bound_ctrl:1
	v_pk_add_f32 v[58:59], v[58:59], v[194:195]
	s_nop 1
	v_mov_b32_dpp v194, v58 row_mirror row_mask:0xf bank_mask:0xf bound_ctrl:1
	v_mov_b32_dpp v195, v59 row_mirror row_mask:0xf bank_mask:0xf bound_ctrl:1
	s_and_saveexec_b64 s[6:7], vcc
	v_pk_add_f32 v[58:59], v[58:59], v[194:195]
	ds_write_b64 v160, v[58:59] offset:392
	s_or_b64 exec, exec, s[6:7]
	ds_read2_b32 v[58:59], v102 offset1:32
	ds_read2_b32 v[194:195], v102 offset0:64 offset1:96
	v_add_f32_e32 v0, 0, v60
	v_mov_b32_e32 v202, v44
	v_mov_b32_e32 v203, v28
	v_mul_f32_e32 v197, 0.5, v0
	s_waitcnt lgkmcnt(1)
	v_mul_f32_e32 v201, 0x3fd744fd, v58
	v_pk_add_f32 v[202:203], v[202:203], 0 op_sel_hi:[1,0]
	v_mov_b32_e32 v196, v28
	v_mov_b32_e32 v200, v1
	v_mov_b32_e32 v58, v59
	s_waitcnt lgkmcnt(0)
	v_mov_b32_e32 v59, v194
	s_mov_b32 s2, s67
	v_pk_add_f32 v[196:197], v[196:197], v[200:201]
	v_pk_mul_f32 v[200:201], v[58:59], s[2:3] op_sel_hi:[1,0]
	v_pk_mul_f32 v[204:205], v[202:203], 0.5 op_sel_hi:[1,0]
	v_pk_fma_f32 v[58:59], v[202:203], 0.5, v[200:201] op_sel_hi:[1,0,1]
	v_mov_b32_e32 v204, v197
	v_mov_b32_e32 v206, v1
	v_mov_b32_e32 v207, v201
	v_add_f32_e32 v198, 0, v12
	v_mov_b32_e32 v199, v195
	v_pk_mul_f32 v[202:203], v[58:59], v[58:59]
	v_pk_add_f32 v[204:205], v[204:205], v[206:207]
	v_mul_f32_e32 v0, 0x3fd744fd, v195
	v_mov_b32_e32 v163, v197
	v_pk_mov_b32 v[200:201], v[200:201], v[202:203] op_sel:[1,0]
	v_pk_add_f32 v[202:203], v[58:59], v[204:205]
	v_pk_mul_f32 v[204:205], v[58:59], v[204:205]
	v_pk_fma_f32 v[194:195], v[198:199], s[66:67], v[0:1] op_sel_hi:[1,1,0]
	v_pk_fma_f32 v[200:201], v[196:197], v[162:163], v[200:201]
	v_mov_b32_e32 v203, v205
	v_pk_mul_f32 v[198:199], v[194:195], v[194:195]
	v_pk_add_f32 v[200:201], v[202:203], v[200:201]
	v_mov_b32_e32 v195, v198
	v_pk_add_f32 v[198:199], v[200:201], v[194:195]
	s_nop 1
	v_mov_b32_dpp v200, v198 quad_perm:[1,0,3,2] row_mask:0xf bank_mask:0xf bound_ctrl:1
	v_mov_b32_dpp v201, v199 quad_perm:[1,0,3,2] row_mask:0xf bank_mask:0xf bound_ctrl:1
	v_pk_add_f32 v[198:199], v[198:199], v[200:201]
	s_nop 1
	v_mov_b32_dpp v200, v198 quad_perm:[2,3,0,1] row_mask:0xf bank_mask:0xf bound_ctrl:1
	v_mov_b32_dpp v201, v199 quad_perm:[2,3,0,1] row_mask:0xf bank_mask:0xf bound_ctrl:1
	v_pk_add_f32 v[198:199], v[198:199], v[200:201]
	s_nop 1
	v_mov_b32_dpp v200, v198 row_half_mirror row_mask:0xf bank_mask:0xf bound_ctrl:1
	v_mov_b32_dpp v201, v199 row_half_mirror row_mask:0xf bank_mask:0xf bound_ctrl:1
	v_pk_add_f32 v[198:199], v[198:199], v[200:201]
	s_nop 1
	v_mov_b32_dpp v200, v198 row_mirror row_mask:0xf bank_mask:0xf bound_ctrl:1
	v_mov_b32_dpp v201, v199 row_mirror row_mask:0xf bank_mask:0xf bound_ctrl:1
	s_and_saveexec_b64 s[6:7], vcc
	v_pk_add_f32 v[198:199], v[198:199], v[200:201]
	ds_write_b64 v160, v[198:199] offset:400
	s_or_b64 exec, exec, s[6:7]
	ds_read2_b32 v[198:199], v104 offset1:32
	ds_read2_b32 v[200:201], v104 offset0:64 offset1:96
	v_add_f32_e32 v0, 0, v61
	v_add_f32_e32 v60, 0, v13
	v_mul_f32_e32 v13, 0.5, v0
	s_waitcnt lgkmcnt(1)
	v_mul_f32_e32 v203, 0x3fd744fd, v198
	v_mov_b32_e32 v28, v45
	v_mov_b32_e32 v12, v29
	v_mov_b32_e32 v202, v1
	v_pk_add_f32 v[204:205], v[28:29], 0 op_sel_hi:[1,0]
	v_pk_add_f32 v[44:45], v[12:13], v[202:203]
	v_mov_b32_e32 v12, v199
	s_waitcnt lgkmcnt(0)
;   DI void operator()(f32x16 (&acc)[2][4], int grow0, int gcol0, int lane, int w, char* lds) {
;     ...
;     for (int ps = 0; ps < 4; ++ps) {
;       const int mt = ps >> 1;
;       if (ps + 1 < 4) {
;         if (ps >= 1) asm volatile("s_waitcnt lgkmcnt(0)" ::: "memory");
;         xpass(ps + 1, grow0, gcol0, lane, w, lds);
;         if (ps >= 1) asm volatile("s_waitcnt vmcnt(8)" ::: "memory");
;       } else asm volatile("s_waitcnt vmcnt(0)" ::: "memory");
;       const char* xs = lds + (ps & 1) * 65536 + w * 8192;
; #pragma unroll
;       for (int qq = 0; qq < 2; ++qq)
; #pragma unroll
;         for (int e = 0; e < 4; ++e) {
;           const int i = 4 * (2 * (ps & 1) + qq) + e;
;           const float* xr = (const float*)(xs + (8 * qq + 4 * hh + e) * 512) + l31;
;           float s1 = 0.f, s2 = 0.f;
; #pragma unroll
;           for (int nt = 0; nt < 4; ++nt) {
;             float v = (acc[mt][nt][i] + bia[nt]) * csc[nt];
;             float z = ALPHA * xr[nt * 32] + hs * v;
;             acc[mt][nt][i] = z; s1 += z; s2 += z * z;
;           }
;           s1 = row16_sum(s1); s2 = row16_sum(s2);
;           if ((lane & 15) == 0) { f32x2 sv = {s1, s2}; *(f32x2*)(redw + (mt * 32 + (i & 3) + 8 * (i >> 2)) * 2) = sv; }
;         }
	v_mov_b32_e32 v13, v200
	s_mov_b32 s2, s67
	v_pk_mul_f32 v[28:29], v[12:13], s[2:3] op_sel_hi:[1,0]
	v_pk_mul_f32 v[198:199], v[204:205], 0.5 op_sel_hi:[1,0]
	v_pk_fma_f32 v[12:13], v[204:205], 0.5, v[28:29] op_sel_hi:[1,0,1]
	v_mov_b32_e32 v198, v45
	v_mov_b32_e32 v204, v1
	v_mov_b32_e32 v205, v29
	v_pk_mul_f32 v[202:203], v[12:13], v[12:13]
	v_pk_add_f32 v[198:199], v[198:199], v[204:205]
	v_mov_b32_e32 v163, v45
	v_pk_mov_b32 v[28:29], v[28:29], v[202:203] op_sel:[1,0]
	v_pk_add_f32 v[202:203], v[12:13], v[198:199]
	v_pk_mul_f32 v[198:199], v[12:13], v[198:199]
	v_mov_b32_e32 v61, v201
	v_pk_fma_f32 v[28:29], v[44:45], v[162:163], v[28:29]
	v_mov_b32_e32 v203, v199
	v_mul_f32_e32 v0, 0x3fd744fd, v201
	v_pk_add_f32 v[198:199], v[202:203], v[28:29]
	v_pk_fma_f32 v[28:29], v[60:61], s[66:67], v[0:1] op_sel_hi:[1,1,0]
	s_nop 0
	v_pk_mul_f32 v[60:61], v[28:29], v[28:29]
	s_nop 0
	v_mov_b32_e32 v29, v60
	v_pk_add_f32 v[60:61], v[198:199], v[28:29]
	s_nop 1
	v_mov_b32_dpp v198, v60 quad_perm:[1,0,3,2] row_mask:0xf bank_mask:0xf bound_ctrl:1
	v_mov_b32_dpp v199, v61 quad_perm:[1,0,3,2] row_mask:0xf bank_mask:0xf bound_ctrl:1
	v_pk_add_f32 v[60:61], v[60:61], v[198:199]
	s_nop 1
	v_mov_b32_dpp v198, v60 quad_perm:[2,3,0,1] row_mask:0xf bank_mask:0xf bound_ctrl:1
	v_mov_b32_dpp v199, v61 quad_perm:[2,3,0,1] row_mask:0xf bank_mask:0xf bound_ctrl:1
	v_pk_add_f32 v[60:61], v[60:61], v[198:199]
	s_nop 1
	v_mov_b32_dpp v198, v60 row_half_mirror row_mask:0xf bank_mask:0xf bound_ctrl:1
	v_mov_b32_dpp v199, v61 row_half_mirror row_mask:0xf bank_mask:0xf bound_ctrl:1
	v_pk_add_f32 v[60:61], v[60:61], v[198:199]
	s_nop 1
	v_mov_b32_dpp v198, v60 row_mirror row_mask:0xf bank_mask:0xf bound_ctrl:1
	v_mov_b32_dpp v199, v61 row_mirror row_mask:0xf bank_mask:0xf bound_ctrl:1
	s_and_saveexec_b64 s[6:7], vcc
	v_pk_add_f32 v[60:61], v[60:61], v[198:199]
	ds_write_b64 v160, v[60:61] offset:408
	s_or_b64 exec, exec, s[6:7]
	ds_read2_b32 v[60:61], v93 offset1:32
	ds_read2_b32 v[198:199], v93 offset0:64 offset1:96
	v_add_f32_e32 v0, 0, v62
	v_mov_b32_e32 v206, v46
	v_mov_b32_e32 v207, v30
	v_mul_f32_e32 v201, 0.5, v0
	s_waitcnt lgkmcnt(1)
	v_mul_f32_e32 v205, 0x3fd744fd, v60
	v_pk_add_f32 v[206:207], v[206:207], 0 op_sel_hi:[1,0]
	v_mov_b32_e32 v200, v30
	v_mov_b32_e32 v204, v1
	v_mov_b32_e32 v60, v61
	s_waitcnt lgkmcnt(0)
	v_mov_b32_e32 v61, v198
	s_mov_b32 s2, s67
	v_pk_add_f32 v[200:201], v[200:201], v[204:205]
	v_pk_mul_f32 v[204:205], v[60:61], s[2:3] op_sel_hi:[1,0]
	v_pk_mul_f32 v[208:209], v[206:207], 0.5 op_sel_hi:[1,0]
	v_pk_fma_f32 v[60:61], v[206:207], 0.5, v[204:205] op_sel_hi:[1,0,1]
	v_mov_b32_e32 v208, v201
	v_mov_b32_e32 v212, v1
	v_mov_b32_e32 v213, v205
	v_add_f32_e32 v202, 0, v14
	v_mov_b32_e32 v203, v199
	v_pk_mul_f32 v[206:207], v[60:61], v[60:61]
	v_pk_add_f32 v[208:209], v[208:209], v[212:213]
	v_mul_f32_e32 v0, 0x3fd744fd, v199
	v_mov_b32_e32 v163, v201
	v_pk_mov_b32 v[204:205], v[204:205], v[206:207] op_sel:[1,0]
	v_pk_add_f32 v[206:207], v[60:61], v[208:209]
	v_pk_mul_f32 v[208:209], v[60:61], v[208:209]
	v_pk_fma_f32 v[198:199], v[202:203], s[66:67], v[0:1] op_sel_hi:[1,1,0]
	v_pk_fma_f32 v[204:205], v[200:201], v[162:163], v[204:205]
	v_mov_b32_e32 v207, v209
	v_pk_mul_f32 v[202:203], v[198:199], v[198:199]
	v_pk_add_f32 v[204:205], v[206:207], v[204:205]
	v_mov_b32_e32 v199, v202
	v_pk_add_f32 v[202:203], v[204:205], v[198:199]
	s_nop 1
	v_mov_b32_dpp v204, v202 quad_perm:[1,0,3,2] row_mask:0xf bank_mask:0xf bound_ctrl:1
	v_mov_b32_dpp v205, v203 quad_perm:[1,0,3,2] row_mask:0xf bank_mask:0xf bound_ctrl:1
	v_pk_add_f32 v[202:203], v[202:203], v[204:205]
	s_nop 1
	v_mov_b32_dpp v204, v202 quad_perm:[2,3,0,1] row_mask:0xf bank_mask:0xf bound_ctrl:1
	v_mov_b32_dpp v205, v203 quad_perm:[2,3,0,1] row_mask:0xf bank_mask:0xf bound_ctrl:1
	v_pk_add_f32 v[202:203], v[202:203], v[204:205]
	s_nop 1
	v_mov_b32_dpp v204, v202 row_half_mirror row_mask:0xf bank_mask:0xf bound_ctrl:1
	v_mov_b32_dpp v205, v203 row_half_mirror row_mask:0xf bank_mask:0xf bound_ctrl:1
	v_pk_add_f32 v[202:203], v[202:203], v[204:205]
	s_nop 1
	v_mov_b32_dpp v204, v202 row_mirror row_mask:0xf bank_mask:0xf bound_ctrl:1
	v_mov_b32_dpp v205, v203 row_mirror row_mask:0xf bank_mask:0xf bound_ctrl:1
	s_and_saveexec_b64 s[6:7], vcc
	v_pk_add_f32 v[202:203], v[202:203], v[204:205]
	ds_write_b64 v160, v[202:203] offset:448
	s_or_b64 exec, exec, s[6:7]
	ds_read2_b32 v[202:203], v106 offset1:32
	ds_read2_b32 v[204:205], v106 offset0:64 offset1:96
	v_add_f32_e32 v0, 0, v63
	v_add_f32_e32 v62, 0, v15
	v_mul_f32_e32 v15, 0.5, v0
	s_waitcnt lgkmcnt(1)
	v_mul_f32_e32 v207, 0x3fd744fd, v202
	v_mov_b32_e32 v30, v47
	v_mov_b32_e32 v14, v31
	v_mov_b32_e32 v206, v1
	v_pk_add_f32 v[208:209], v[30:31], 0 op_sel_hi:[1,0]
	v_pk_add_f32 v[46:47], v[14:15], v[206:207]
	v_mov_b32_e32 v14, v203
	s_waitcnt lgkmcnt(0)
;   DI void operator()(f32x16 (&acc)[2][4], int grow0, int gcol0, int lane, int w, char* lds) {
;     ...
;     for (int ps = 0; ps < 4; ++ps) {
;       const int mt = ps >> 1;
;       if (ps + 1 < 4) {
;         if (ps >= 1) asm volatile("s_waitcnt lgkmcnt(0)" ::: "memory");
;         xpass(ps + 1, grow0, gcol0, lane, w, lds);
;         if (ps >= 1) asm volatile("s_waitcnt vmcnt(8)" ::: "memory");
;       } else asm volatile("s_waitcnt vmcnt(0)" ::: "memory");
;       const char* xs = lds + (ps & 1) * 65536 + w * 8192;
; #pragma unroll
;       for (int qq = 0; qq < 2; ++qq)
; #pragma unroll
;         for (int e = 0; e < 4; ++e) {
;           const int i = 4 * (2 * (ps & 1) + qq) + e;
;           const float* xr = (const float*)(xs + (8 * qq + 4 * hh + e) * 512) + l31;
;           float s1 = 0.f, s2 = 0.f;
; #pragma unroll
;           for (int nt = 0; nt < 4; ++nt) {
;             float v = (acc[mt][nt][i] + bia[nt]) * csc[nt];
;             float z = ALPHA * xr[nt * 32] + hs * v;
;             acc[mt][nt][i] = z; s1 += z; s2 += z * z;
;           }
;           s1 = row16_sum(s1); s2 = row16_sum(s2);
;           if ((lane & 15) == 0) { f32x2 sv = {s1, s2}; *(f32x2*)(redw + (mt * 32 + (i & 3) + 8 * (i >> 2)) * 2) = sv; }
;         }
;     }
;     __syncthreads();
;     u64_t* myslots = xstat + ((size_t)pm * 256) * 4;
	v_mov_b32_e32 v15, v204
	s_mov_b32 s2, s67
	v_pk_mul_f32 v[30:31], v[14:15], s[2:3] op_sel_hi:[1,0]
	v_pk_mul_f32 v[202:203], v[208:209], 0.5 op_sel_hi:[1,0]
	v_pk_fma_f32 v[14:15], v[208:209], 0.5, v[30:31] op_sel_hi:[1,0,1]
	v_mov_b32_e32 v202, v47
	v_mov_b32_e32 v208, v1
	v_mov_b32_e32 v209, v31
	v_pk_mul_f32 v[206:207], v[14:15], v[14:15]
	v_pk_add_f32 v[202:203], v[202:203], v[208:209]
	v_mov_b32_e32 v163, v47
	v_pk_mov_b32 v[30:31], v[30:31], v[206:207] op_sel:[1,0]
	v_pk_add_f32 v[206:207], v[14:15], v[202:203]
	v_pk_mul_f32 v[202:203], v[14:15], v[202:203]
	v_mov_b32_e32 v63, v205
	v_pk_fma_f32 v[30:31], v[46:47], v[162:163], v[30:31]
	v_mov_b32_e32 v207, v203
	v_mul_f32_e32 v0, 0x3fd744fd, v205
	v_pk_add_f32 v[202:203], v[206:207], v[30:31]
	v_pk_fma_f32 v[30:31], v[62:63], s[66:67], v[0:1] op_sel_hi:[1,1,0]
	s_nop 0
	v_pk_mul_f32 v[62:63], v[30:31], v[30:31]
	s_nop 0
	v_mov_b32_e32 v31, v62
	v_pk_add_f32 v[62:63], v[202:203], v[30:31]
	s_nop 1
	v_mov_b32_dpp v202, v62 quad_perm:[1,0,3,2] row_mask:0xf bank_mask:0xf bound_ctrl:1
	v_mov_b32_dpp v203, v63 quad_perm:[1,0,3,2] row_mask:0xf bank_mask:0xf bound_ctrl:1
	v_pk_add_f32 v[62:63], v[62:63], v[202:203]
	s_nop 1
	v_mov_b32_dpp v202, v62 quad_perm:[2,3,0,1] row_mask:0xf bank_mask:0xf bound_ctrl:1
	v_mov_b32_dpp v203, v63 quad_perm:[2,3,0,1] row_mask:0xf bank_mask:0xf bound_ctrl:1
	v_pk_add_f32 v[62:63], v[62:63], v[202:203]
	s_nop 1
	v_mov_b32_dpp v202, v62 row_half_mirror row_mask:0xf bank_mask:0xf bound_ctrl:1
	v_mov_b32_dpp v203, v63 row_half_mirror row_mask:0xf bank_mask:0xf bound_ctrl:1
	v_pk_add_f32 v[62:63], v[62:63], v[202:203]
	s_nop 1
	v_mov_b32_dpp v202, v62 row_mirror row_mask:0xf bank_mask:0xf bound_ctrl:1
	v_mov_b32_dpp v203, v63 row_mirror row_mask:0xf bank_mask:0xf bound_ctrl:1
	s_and_saveexec_b64 s[6:7], vcc
	v_pk_add_f32 v[62:63], v[62:63], v[202:203]
	ds_write_b64 v160, v[62:63] offset:456
	s_or_b64 exec, exec, s[6:7]
	ds_read2_b32 v[62:63], v95 offset1:32
	ds_read2_b32 v[202:203], v95 offset0:64 offset1:96
	v_add_f32_e32 v0, 0, v64
	v_mov_b32_e32 v212, v48
	v_mov_b32_e32 v213, v32
	v_mul_f32_e32 v205, 0.5, v0
	s_waitcnt lgkmcnt(1)
	v_mul_f32_e32 v209, 0x3fd744fd, v62
	v_pk_add_f32 v[212:213], v[212:213], 0 op_sel_hi:[1,0]
	v_mov_b32_e32 v204, v32
	v_mov_b32_e32 v208, v1
	v_mov_b32_e32 v62, v63
	s_waitcnt lgkmcnt(0)
	v_mov_b32_e32 v63, v202
	s_mov_b32 s2, s67
	v_pk_add_f32 v[204:205], v[204:205], v[208:209]
	v_pk_mul_f32 v[208:209], v[62:63], s[2:3] op_sel_hi:[1,0]
	v_pk_mul_f32 v[214:215], v[212:213], 0.5 op_sel_hi:[1,0]
	v_pk_fma_f32 v[62:63], v[212:213], 0.5, v[208:209] op_sel_hi:[1,0,1]
	v_mov_b32_e32 v214, v205
	v_mov_b32_e32 v226, v1
	v_mov_b32_e32 v227, v209
	v_add_f32_e32 v206, 0, v16
	v_mov_b32_e32 v207, v203
	v_pk_mul_f32 v[212:213], v[62:63], v[62:63]
	v_pk_add_f32 v[214:215], v[214:215], v[226:227]
	v_mul_f32_e32 v0, 0x3fd744fd, v203
	v_mov_b32_e32 v163, v205
	v_pk_mov_b32 v[208:209], v[208:209], v[212:213] op_sel:[1,0]
	v_pk_add_f32 v[212:213], v[62:63], v[214:215]
	v_pk_mul_f32 v[214:215], v[62:63], v[214:215]
	v_pk_fma_f32 v[202:203], v[206:207], s[66:67], v[0:1] op_sel_hi:[1,1,0]
	v_pk_fma_f32 v[208:209], v[204:205], v[162:163], v[208:209]
	v_mov_b32_e32 v213, v215
	v_pk_mul_f32 v[206:207], v[202:203], v[202:203]
	v_pk_add_f32 v[208:209], v[212:213], v[208:209]
	v_mov_b32_e32 v203, v206
	v_pk_add_f32 v[206:207], v[208:209], v[202:203]
	s_nop 1
	v_mov_b32_dpp v208, v206 quad_perm:[1,0,3,2] row_mask:0xf bank_mask:0xf bound_ctrl:1
	v_mov_b32_dpp v209, v207 quad_perm:[1,0,3,2] row_mask:0xf bank_mask:0xf bound_ctrl:1
	v_pk_add_f32 v[206:207], v[206:207], v[208:209]
	s_nop 1
	v_mov_b32_dpp v208, v206 quad_perm:[2,3,0,1] row_mask:0xf bank_mask:0xf bound_ctrl:1
	v_mov_b32_dpp v209, v207 quad_perm:[2,3,0,1] row_mask:0xf bank_mask:0xf bound_ctrl:1
	v_pk_add_f32 v[206:207], v[206:207], v[208:209]
	s_nop 1
	v_mov_b32_dpp v208, v206 row_half_mirror row_mask:0xf bank_mask:0xf bound_ctrl:1
	v_mov_b32_dpp v209, v207 row_half_mirror row_mask:0xf bank_mask:0xf bound_ctrl:1
	v_pk_add_f32 v[206:207], v[206:207], v[208:209]
	s_nop 1
	v_mov_b32_dpp v208, v206 row_mirror row_mask:0xf bank_mask:0xf bound_ctrl:1
	v_mov_b32_dpp v209, v207 row_mirror row_mask:0xf bank_mask:0xf bound_ctrl:1
	s_and_saveexec_b64 s[6:7], vcc
	v_pk_add_f32 v[206:207], v[206:207], v[208:209]
	ds_write_b64 v160, v[206:207] offset:464
	s_or_b64 exec, exec, s[6:7]
	v_add_f32_e32 v0, 0, v65
	ds_read2_b32 v[64:65], v91 offset1:32
	ds_read2_b32 v[212:213], v91 offset0:64 offset1:96
	v_mov_b32_e32 v32, v49
	v_mul_f32_e32 v209, 0.5, v0
	v_add_f32_e32 v214, 0, v17
	s_waitcnt lgkmcnt(1)
	v_mul_f32_e32 v207, 0x3fd744fd, v64
	v_pk_add_f32 v[16:17], v[32:33], 0 op_sel_hi:[1,0]
	v_mov_b32_e32 v208, v33
	v_mov_b32_e32 v206, v1
	v_mov_b32_e32 v32, v65
	s_waitcnt lgkmcnt(0)
	v_mov_b32_e32 v33, v212
	s_mov_b32 s2, s67
	v_pk_add_f32 v[48:49], v[208:209], v[206:207]
	v_pk_mul_f32 v[32:33], v[32:33], s[2:3] op_sel_hi:[1,0]
	v_pk_mul_f32 v[64:65], v[16:17], 0.5 op_sel_hi:[1,0]
	v_pk_fma_f32 v[16:17], v[16:17], 0.5, v[32:33] op_sel_hi:[1,0,1]
	v_mov_b32_e32 v64, v49
	v_mov_b32_e32 v208, v1
	v_mov_b32_e32 v209, v33
	v_pk_mul_f32 v[206:207], v[16:17], v[16:17]
	v_pk_add_f32 v[64:65], v[64:65], v[208:209]
	v_mov_b32_e32 v163, v49
	v_pk_mov_b32 v[32:33], v[32:33], v[206:207] op_sel:[1,0]
	v_pk_add_f32 v[206:207], v[16:17], v[64:65]
	v_pk_mul_f32 v[64:65], v[16:17], v[64:65]
	v_mov_b32_e32 v215, v213
	v_pk_fma_f32 v[32:33], v[48:49], v[162:163], v[32:33]
	v_mov_b32_e32 v207, v65
	v_mul_f32_e32 v0, 0x3fd744fd, v213
	v_pk_add_f32 v[64:65], v[206:207], v[32:33]
	v_pk_fma_f32 v[32:33], v[214:215], s[66:67], v[0:1] op_sel_hi:[1,1,0]
	s_nop 0
	v_pk_mul_f32 v[206:207], v[32:33], v[32:33]
	s_nop 0
	v_mov_b32_e32 v33, v206
	v_pk_add_f32 v[64:65], v[64:65], v[32:33]
	s_nop 1
	v_mov_b32_dpp v206, v64 quad_perm:[1,0,3,2] row_mask:0xf bank_mask:0xf bound_ctrl:1
	v_mov_b32_dpp v207, v65 quad_perm:[1,0,3,2] row_mask:0xf bank_mask:0xf bound_ctrl:1
	v_pk_add_f32 v[64:65], v[64:65], v[206:207]
	s_nop 1
	v_mov_b32_dpp v206, v64 quad_perm:[2,3,0,1] row_mask:0xf bank_mask:0xf bound_ctrl:1
	v_mov_b32_dpp v207, v65 quad_perm:[2,3,0,1] row_mask:0xf bank_mask:0xf bound_ctrl:1
	v_pk_add_f32 v[64:65], v[64:65], v[206:207]
	s_nop 1
	v_mov_b32_dpp v206, v64 row_half_mirror row_mask:0xf bank_mask:0xf bound_ctrl:1
	v_mov_b32_dpp v207, v65 row_half_mirror row_mask:0xf bank_mask:0xf bound_ctrl:1
	v_pk_add_f32 v[64:65], v[64:65], v[206:207]
	s_nop 1
	v_mov_b32_dpp v206, v64 row_mirror row_mask:0xf bank_mask:0xf bound_ctrl:1
	v_mov_b32_dpp v207, v65 row_mirror row_mask:0xf bank_mask:0xf bound_ctrl:1
	s_and_saveexec_b64 s[6:7], vcc
	v_pk_add_f32 v[64:65], v[64:65], v[206:207]
	ds_write_b64 v160, v[64:65] offset:472
	s_or_b64 exec, exec, s[6:7]
	v_ashrrev_i32_e32 v206, 8, v164
	v_ashrrev_i32_e32 v207, 31, v206
	v_lshlrev_b64 v[64:65], 13, v[206:207]
	v_lshl_add_u64 v[64:65], s[8:9], 0, v[64:65]
	v_cmp_gt_i32_e64 s[40:41], s60, v210
	v_ashrrev_i32_e32 v169, 31, v168
	s_waitcnt lgkmcnt(0)
	s_barrier
; DI void ag_st64(u64_t* p, u64_t v) { __hip_atomic_store(p, v, __ATOMIC_RELAXED, __HIP_MEMORY_SCOPE_AGENT); }
;   DI void operator()(f32x16 (&acc)[2][4], int grow0, int gcol0, int lane, int w, char* lds) {
;     ...
;     u64_t* myslots = xstat + ((size_t)pm * 256) * 4;
;     if (tid < 256) {
;       float s1 = (red[tid * 2] + red[(256 + tid) * 2]) + (red[(512 + tid) * 2] + red[(768 + tid) * 2]);
;       float s2 = (red[tid * 2 + 1] + red[(256 + tid) * 2 + 1]) + (red[(512 + tid) * 2 + 1] + red[(768 + tid) * 2 + 1]);
;       ag_st64(myslots + tid * 4 + pn, ((u64_t)__float_as_uint(s2) << 32) | (u64_t)__float_as_uint(s1));
;     }
	s_and_saveexec_b64 s[6:7], s[40:41]
	s_cbranch_execz .LBB0_359
	v_lshl_add_u32 v0, v210, 3, v221
	ds_read2st64_b64 v[212:215], v0 offset1:4
	ds_read2st64_b64 v[226:229], v0 offset0:8 offset1:12
	v_ashrrev_i32_e32 v208, 8, v154
	v_ashrrev_i32_e32 v209, 31, v208
	s_waitcnt lgkmcnt(1)
	v_mov_b32_e32 v230, v212
	s_waitcnt lgkmcnt(0)
	v_mov_b32_e32 v231, v226
	v_mov_b32_e32 v232, v214
	v_mov_b32_e32 v233, v228
	v_mov_b32_e32 v226, v213
	v_mov_b32_e32 v228, v215
	v_pk_add_f32 v[230:231], v[230:231], v[232:233]
	v_pk_add_f32 v[212:213], v[226:227], v[228:229]
	v_pk_add_f32 v[230:231], v[230:231], v[230:231] op_sel:[0,1] op_sel_hi:[1,0]
	v_pk_add_f32 v[212:213], v[212:213], v[212:213] op_sel:[0,1] op_sel_hi:[1,0]
	v_lshl_add_u64 v[214:215], v[168:169], 3, v[64:65]
	v_lshl_add_u64 v[208:209], v[208:209], 3, v[214:215]
	v_mov_b32_e32 v231, v212
	global_store_dwordx2 v[208:209], v[230:231], off sc1

; DI f32x16 mfma(bf16x8 a, bf16x8 b, f32x16 c) { return __builtin_amdgcn_mfma_f32_32x32x16_bf16(a, b, c, 0, 0, 0); }
; template <int BK> DI int swz(int row) { constexpr int CPR = BK / 8; return (row / (16 / CPR)) % CPR; }
; DI void wait_vm0() { asm volatile("s_waitcnt vmcnt(0)" ::: "memory"); }
;   DI void pre(int grow0, int gcol0, int lane, int w, char* lds) { xpass(0, grow0, gcol0, lane, w, lds); }
;     ...
;   for (int kt = 0; kt < nk; ++kt) {
;     char* cur = lds + (kt & 1) * STG; char* nxt = lds + ((kt + 1) & 1) * STG;
;     const bool more = kt + 1 < nk;
;     const bf16_t* An = Ag + (kt + 1) * BK; const bf16_t* Bn = Bg + (kt + 1) * BK;
;     if (!more) epi.pre(row0 + wm * 64, col0 + wn * (32 * NTW), lane, w, lds);
;     bf16x8 fa[2][2], fb[2][NTW];
; #pragma unroll
;     for (int mt = 0; mt < 2; ++mt) { int row = wm * 64 + mt * 32 + l31; fa[0][mt] = *(const bf16x8*)(cur + row * (BK * 2) + ((hh ^ swz<BK>(row)) << 4)); }
; #pragma unroll
;     for (int nt = 0; nt < NTW; ++nt) { int row = wn * (32 * NTW) + nt * 32 + l31; fb[0][nt] = *(const bf16x8*)(cur + ABYTES + row * (BK * 2) + ((hh ^ swz<BK>(row)) << 4)); }
; #pragma unroll
;     for (int kk = 0; kk < NKK; ++kk) {
;       if (kk + 1 < NKK) {
;         const int ch = (kk + 1) * 2 + hh;
; #pragma unroll
;         for (int mt = 0; mt < 2; ++mt) { int row = wm * 64 + mt * 32 + l31; fa[(kk + 1) & 1][mt] = *(const bf16x8*)(cur + row * (BK * 2) + ((ch ^ swz<BK>(row)) << 4)); }
; #pragma unroll
;         for (int nt = 0; nt < NTW; ++nt) { int row = wn * (32 * NTW) + nt * 32 + l31; fb[(kk + 1) & 1][nt] = *(const bf16x8*)(cur + ABYTES + row * (BK * 2) + ((ch ^ swz<BK>(row)) << 4)); }
;       }
;       if (more) {
; #pragma unroll
;         for (int q = 0; q < PPK; ++q) {
;           const int pi = kk * PPK + q;
;           if (pi < NPA) stage_piece<BM, BK>(An, lda, nxt, tid, pi, wv);
;           else if (pi < NP) stage_piece<BN, BK>(Bn, ldb, nxt + ABYTES, tid, pi - NPA, wv);
;         }
;       }
;       __builtin_amdgcn_s_setprio(1);
; #pragma unroll
;       for (int mt = 0; mt < 2; ++mt)
; #pragma unroll
;         for (int nt = 0; nt < NTW; ++nt) acc[mt][nt] = mfma(fa[kk & 1][mt], fb[kk & 1][nt], acc[mt][nt]);
;       __builtin_amdgcn_s_setprio(0);
;       __builtin_amdgcn_sched_barrier(0);
;     }
;     wait_vm0();
;     __syncthreads();
;   }
.LBB0_382:
	s_and_b32 s42, s7, 0x10000
	s_xor_b32 s100, s42, 0x10000
	s_add_i32 s37, s3, s42
	v_add3_u32 v190, s100, v140, v161
	v_add3_u32 v194, s100, v142, v163
	ds_read_b128 v[190:193], v190
	v_add3_u32 v198, s100, v143, v159
	ds_read_b128 v[194:197], v194
	v_add3_u32 v202, s100, v152, v160
	ds_read_b128 v[198:201], v198 offset:32768
	v_add3_u32 v206, s100, v153, v157
	ds_read_b128 v[202:205], v202 offset:32768
	v_add3_u32 v210, s100, v156, v158
	ds_read_b128 v[206:209], v206 offset:32768
	ds_read_b128 v[210:213], v210 offset:32768
	v_lshl_add_u64 v[214:215], v[130:131], 0, s[30:31]
	v_lshl_add_u64 v[226:227], v[132:133], 0, s[30:31]
	s_mov_b32 m0, s37
	v_lshl_add_u64 v[228:229], v[214:215], 0, s[28:29]
	s_waitcnt lgkmcnt(6)
	v_mfma_f32_32x32x16_bf16 v[114:129], v[166:169], v[174:177], v[114:129]
	global_load_lds_dwordx4 v[228:229], off
	v_lshl_add_u64 v[228:229], v[214:215], 0, s[24:25]
	s_add_i32 m0, s37, 0x2000
	v_mfma_f32_32x32x16_bf16 v[98:113], v[166:169], v[178:181], v[98:113]
	global_load_lds_dwordx4 v[228:229], off
	v_lshl_add_u64 v[228:229], v[214:215], 0, s[26:27]
	s_add_i32 m0, s37, 0x4000
	v_mfma_f32_32x32x16_bf16 v[82:97], v[166:169], v[182:185], v[82:97]
	global_load_lds_dwordx4 v[228:229], off
	v_lshl_add_u64 v[228:229], v[214:215], 0, s[38:39]
	s_add_i32 m0, s37, 0x6000
	v_mfma_f32_32x32x16_bf16 v[66:81], v[166:169], v[186:189], v[66:81]
	global_load_lds_dwordx4 v[228:229], off
	v_lshl_add_u64 v[228:229], v[226:227], 0, s[28:29]
	s_add_i32 m0, s37, 0x8000
	v_mfma_f32_32x32x16_bf16 v[50:65], v[170:173], v[174:177], v[50:65]
	global_load_lds_dwordx4 v[228:229], off
	v_lshl_add_u64 v[228:229], v[226:227], 0, s[24:25]
	s_add_i32 m0, s37, 0xa000
	v_mfma_f32_32x32x16_bf16 v[34:49], v[170:173], v[178:181], v[34:49]
	global_load_lds_dwordx4 v[228:229], off
	v_lshl_add_u64 v[228:229], v[226:227], 0, s[26:27]
	s_add_i32 m0, s37, 0xc000
	v_mfma_f32_32x32x16_bf16 v[18:33], v[170:173], v[182:185], v[18:33]
	global_load_lds_dwordx4 v[228:229], off
	v_lshl_add_u64 v[228:229], v[226:227], 0, s[38:39]
	s_add_i32 m0, s37, 0xe000
	v_mfma_f32_32x32x16_bf16 v[2:17], v[170:173], v[186:189], v[2:17]
	global_load_lds_dwordx4 v[228:229], off
	v_add3_u32 v166, s100, v140, v149
	v_add3_u32 v170, s100, v142, v150
	ds_read_b128 v[166:169], v166
	v_add3_u32 v174, s100, v143, v147
	ds_read_b128 v[170:173], v170
	v_add3_u32 v178, s100, v152, v148
	ds_read_b128 v[174:177], v174 offset:32768
	v_add3_u32 v182, s100, v153, v145
	ds_read_b128 v[178:181], v178 offset:32768
	v_add3_u32 v186, s100, v156, v146
	ds_read_b128 v[182:185], v182 offset:32768
	ds_read_b128 v[186:189], v186 offset:32768
	s_waitcnt lgkmcnt(6)
	v_mfma_f32_32x32x16_bf16 v[114:129], v[190:193], v[198:201], v[114:129]
	v_mfma_f32_32x32x16_bf16 v[98:113], v[190:193], v[202:205], v[98:113]
	v_mfma_f32_32x32x16_bf16 v[82:97], v[190:193], v[206:209], v[82:97]
	v_mfma_f32_32x32x16_bf16 v[66:81], v[190:193], v[210:213], v[66:81]
	v_mfma_f32_32x32x16_bf16 v[50:65], v[194:197], v[198:201], v[50:65]
	v_mfma_f32_32x32x16_bf16 v[34:49], v[194:197], v[202:205], v[34:49]
	v_mfma_f32_32x32x16_bf16 v[18:33], v[194:197], v[206:209], v[18:33]
	v_mfma_f32_32x32x16_bf16 v[2:17], v[194:197], v[210:213], v[2:17]
	v_add3_u32 v190, s100, v140, v138
	v_add3_u32 v194, s100, v142, v139
	ds_read_b128 v[190:193], v190
	v_add3_u32 v198, s100, v143, v136
	ds_read_b128 v[194:197], v194
	v_add3_u32 v202, s100, v152, v137
	ds_read_b128 v[198:201], v198 offset:32768
	v_add3_u32 v206, s100, v153, v134
	ds_read_b128 v[202:205], v202 offset:32768
	v_add3_u32 v210, s100, v156, v135
	ds_read_b128 v[206:209], v206 offset:32768
	ds_read_b128 v[210:213], v210 offset:32768
	s_waitcnt lgkmcnt(6)
	v_mfma_f32_32x32x16_bf16 v[114:129], v[166:169], v[174:177], v[114:129]
	v_mfma_f32_32x32x16_bf16 v[98:113], v[166:169], v[178:181], v[98:113]
	v_mfma_f32_32x32x16_bf16 v[82:97], v[166:169], v[182:185], v[82:97]
	v_mfma_f32_32x32x16_bf16 v[66:81], v[166:169], v[186:189], v[66:81]
	v_mfma_f32_32x32x16_bf16 v[50:65], v[170:173], v[174:177], v[50:65]
	v_mfma_f32_32x32x16_bf16 v[34:49], v[170:173], v[178:181], v[34:49]
	v_mfma_f32_32x32x16_bf16 v[18:33], v[170:173], v[182:185], v[18:33]
	v_mfma_f32_32x32x16_bf16 v[2:17], v[170:173], v[186:189], v[2:17]
	s_add_u32 s30, s30, 0x80
	s_addc_u32 s31, s31, 0
	s_add_i32 s7, s7, 0x10000
	s_waitcnt vmcnt(0) lgkmcnt(0)
	s_barrier
	v_add3_u32 v166, s42, v140, v141
	v_add3_u32 v170, s42, v142, v144
	ds_read_b128 v[166:169], v166
	v_add3_u32 v174, s42, v143, v151
	ds_read_b128 v[170:173], v170
	v_add3_u32 v178, s42, v152, v154
	ds_read_b128 v[174:177], v174 offset:32768
	v_add3_u32 v182, s42, v153, v155
	ds_read_b128 v[178:181], v178 offset:32768
	v_add3_u32 v186, s42, v156, v164
	ds_read_b128 v[182:185], v182 offset:32768
	ds_read_b128 v[186:189], v186 offset:32768
	v_mfma_f32_32x32x16_bf16 v[114:129], v[190:193], v[198:201], v[114:129]
	v_mfma_f32_32x32x16_bf16 v[98:113], v[190:193], v[202:205], v[98:113]
	v_mfma_f32_32x32x16_bf16 v[82:97], v[190:193], v[206:209], v[82:97]
	v_mfma_f32_32x32x16_bf16 v[66:81], v[190:193], v[210:213], v[66:81]
	v_mfma_f32_32x32x16_bf16 v[50:65], v[194:197], v[198:201], v[50:65]
	v_mfma_f32_32x32x16_bf16 v[34:49], v[194:197], v[202:205], v[34:49]
	v_mfma_f32_32x32x16_bf16 v[18:33], v[194:197], v[206:209], v[18:33]
	v_mfma_f32_32x32x16_bf16 v[2:17], v[194:197], v[210:213], v[2:17]
	s_cmpk_eq_i32 s30, 0x780
	s_cbranch_scc0 .LBB0_382
;     ...
;   for (int kt = 0; kt < nk; ++kt) {
;     char* cur = lds + (kt & 1) * STG; char* nxt = lds + ((kt + 1) & 1) * STG;
;     const bool more = kt + 1 < nk;
;     const bf16_t* An = Ag + (kt + 1) * BK; const bf16_t* Bn = Bg + (kt + 1) * BK;
;     if (!more) epi.pre(row0 + wm * 64, col0 + wn * (32 * NTW), lane, w, lds);
;     bf16x8 fa[2][2], fb[2][NTW];
; #pragma unroll
;     for (int mt = 0; mt < 2; ++mt) { int row = wm * 64 + mt * 32 + l31; fa[0][mt] = *(const bf16x8*)(cur + row * (BK * 2) + ((hh ^ swz<BK>(row)) << 4)); }
; #pragma unroll
;     for (int nt = 0; nt < NTW; ++nt) { int row = wn * (32 * NTW) + nt * 32 + l31; fb[0][nt] = *(const bf16x8*)(cur + ABYTES + row * (BK * 2) + ((hh ^ swz<BK>(row)) << 4)); }
; #pragma unroll
;     for (int kk = 0; kk < NKK; ++kk) {
;       if (kk + 1 < NKK) {
;         const int ch = (kk + 1) * 2 + hh;
; #pragma unroll
;         for (int mt = 0; mt < 2; ++mt) { int row = wm * 64 + mt * 32 + l31; fa[(kk + 1) & 1][mt] = *(const bf16x8*)(cur + row * (BK * 2) + ((ch ^ swz<BK>(row)) << 4)); }
; #pragma unroll
;         for (int nt = 0; nt < NTW; ++nt) { int row = wn * (32 * NTW) + nt * 32 + l31; fb[(kk + 1) & 1][nt] = *(const bf16x8*)(cur + ABYTES + row * (BK * 2) + ((ch ^ swz<BK>(row)) << 4)); }
;       }
;       if (more) {
; #pragma unroll
;         for (int q = 0; q < PPK; ++q) {
;           const int pi = kk * PPK + q;
;           if (pi < NPA) stage_piece<BM, BK>(An, lda, nxt, tid, pi, wv);
;           else if (pi < NP) stage_piece<BN, BK>(Bn, ldb, nxt + ABYTES, tid, pi - NPA, wv);
;         }
;       }
;       __builtin_amdgcn_s_setprio(1);
; #pragma unroll
;       for (int mt = 0; mt < 2; ++mt)
; #pragma unroll
;         for (int nt = 0; nt < NTW; ++nt) acc[mt][nt] = mfma(fa[kk & 1][mt], fb[kk & 1][nt], acc[mt][nt]);
;       __builtin_amdgcn_s_setprio(0);
;       __builtin_amdgcn_sched_barrier(0);
;     }
;     wait_vm0();
;     __syncthreads();
;   }
;   if (has_next) { const int tid3 = launder(threadIdx.x); stage_tile<BM, BK>(A + (size_t)row0n * lda, lda, lds, tid3); stage_tile<BN, BK>(Bt + (size_t)col0n * ldb, ldb, lds + ABYTES, tid3); }
; template <class Epi>
; DI void gemm_phase256(const bf16_t* A, int lda, const bf16_t* Bt, int K, int nN, char* lds, Epi& epi, int vb) {
;     ...
;   for (int t = vb; t < ntiles; t += gridDim.x) {
;     const int x = t & 7, L = t >> 3; const int pm = 8 * x + (L & 7), pn = L >> 3;
	s_waitcnt lgkmcnt(0)
	v_add_u32_e32 v0, 0x10000, v140
	v_add_u32_e32 v198, 0x10000, v142
	v_add_u32_e32 v130, v0, v141
	v_add_u32_e32 v140, v198, v144
	v_add_u32_e32 v199, 0x18000, v143
	v_add_u32_e32 v200, 0x18000, v152
	ds_read_b128 v[130:133], v130
	ds_read_b128 v[166:169], v140
	v_add_u32_e32 v140, v199, v151
	v_add_u32_e32 v144, v200, v154
	v_add_u32_e32 v201, 0x18000, v153
	ds_read_b128 v[140:143], v140
	ds_read_b128 v[170:173], v144
	v_add_u32_e32 v144, v201, v155
	v_add_u32_e32 v202, 0x18000, v156
	v_add_u32_e32 v151, v202, v164
	ds_read_b128 v[152:155], v144
	ds_read_b128 v[174:177], v151
	v_add_u32_e32 v144, v0, v161
	v_add_u32_e32 v151, v198, v163
	ds_read_b128 v[178:181], v144
	ds_read_b128 v[182:185], v151
	v_add_u32_e32 v144, v199, v159
	v_add_u32_e32 v151, v200, v160
	ds_read_b128 v[186:189], v144
	ds_read_b128 v[190:193], v151
	v_add_u32_e32 v144, v201, v157
	v_add_u32_e32 v151, v202, v158
	ds_read_b128 v[156:159], v144
	ds_read_b128 v[194:197], v151
	s_add_i32 s36, s36, s94
	s_cmpk_gt_i32 s36, 0x4ff
	s_cselect_b64 s[42:43], -1, 0
	s_cmpk_lt_i32 s36, 0x500
	s_setprio 1
	s_waitcnt lgkmcnt(9)
	v_mfma_f32_32x32x16_bf16 v[114:129], v[130:133], v[140:143], v[114:129]
	s_waitcnt lgkmcnt(8)
	v_mfma_f32_32x32x16_bf16 v[98:113], v[130:133], v[170:173], v[98:113]
	s_waitcnt lgkmcnt(7)
	v_mfma_f32_32x32x16_bf16 v[82:97], v[130:133], v[152:155], v[82:97]
	s_waitcnt lgkmcnt(6)
	v_mfma_f32_32x32x16_bf16 v[66:81], v[130:133], v[174:177], v[66:81]
	v_mfma_f32_32x32x16_bf16 v[50:65], v[166:169], v[140:143], v[50:65]
	v_mfma_f32_32x32x16_bf16 v[34:49], v[166:169], v[170:173], v[34:49]
	v_mfma_f32_32x32x16_bf16 v[18:33], v[166:169], v[152:155], v[18:33]
	v_mfma_f32_32x32x16_bf16 v[2:17], v[166:169], v[174:177], v[2:17]
	s_setprio 0
	v_add_u32_e32 v130, v0, v149
	v_add_u32_e32 v140, v198, v150
	v_add_u32_e32 v144, v199, v147
	ds_read_b128 v[130:133], v130
	ds_read_b128 v[140:143], v140
	v_add_u32_e32 v147, v200, v148
	ds_read_b128 v[148:151], v144
	ds_read_b128 v[152:155], v147
	v_add_u32_e32 v144, v201, v145
	v_add_u32_e32 v160, v202, v146
	ds_read_b128 v[144:147], v144
	ds_read_b128 v[166:169], v160
	s_setprio 1
	s_waitcnt lgkmcnt(9)
	v_mfma_f32_32x32x16_bf16 v[114:129], v[178:181], v[186:189], v[114:129]
	s_waitcnt lgkmcnt(8)
	v_mfma_f32_32x32x16_bf16 v[98:113], v[178:181], v[190:193], v[98:113]
	s_waitcnt lgkmcnt(7)
	v_mfma_f32_32x32x16_bf16 v[82:97], v[178:181], v[156:159], v[82:97]
	s_waitcnt lgkmcnt(6)
	v_mfma_f32_32x32x16_bf16 v[66:81], v[178:181], v[194:197], v[66:81]
	v_mfma_f32_32x32x16_bf16 v[50:65], v[182:185], v[186:189], v[50:65]
	v_mfma_f32_32x32x16_bf16 v[34:49], v[182:185], v[190:193], v[34:49]
	v_mfma_f32_32x32x16_bf16 v[18:33], v[182:185], v[156:159], v[18:33]
	v_mfma_f32_32x32x16_bf16 v[2:17], v[182:185], v[194:197], v[2:17]
	s_setprio 0
	v_add_u32_e32 v0, v0, v138
	v_add_u32_e32 v138, v198, v139
	ds_read_b128 v[156:159], v0
	ds_read_b128 v[170:173], v138
	v_add_u32_e32 v0, v199, v136
	v_add_u32_e32 v160, v200, v137
	ds_read_b128 v[136:139], v0
	ds_read_b128 v[174:177], v160
	v_add_u32_e32 v0, v201, v134
	v_add_u32_e32 v134, v202, v135
	ds_read_b128 v[178:181], v0
	ds_read_b128 v[182:185], v134
	s_setprio 1
	s_waitcnt lgkmcnt(9)
	v_mfma_f32_32x32x16_bf16 v[114:129], v[130:133], v[148:151], v[114:129]
	s_waitcnt lgkmcnt(8)
	v_mfma_f32_32x32x16_bf16 v[98:113], v[130:133], v[152:155], v[98:113]
	s_waitcnt lgkmcnt(7)
	v_mfma_f32_32x32x16_bf16 v[82:97], v[130:133], v[144:147], v[82:97]
	s_waitcnt lgkmcnt(6)
	v_mfma_f32_32x32x16_bf16 v[66:81], v[130:133], v[166:169], v[66:81]
	v_mfma_f32_32x32x16_bf16 v[50:65], v[140:143], v[148:151], v[50:65]
	v_mfma_f32_32x32x16_bf16 v[34:49], v[140:143], v[152:155], v[34:49]
	v_mfma_f32_32x32x16_bf16 v[18:33], v[140:143], v[144:147], v[18:33]
	v_mfma_f32_32x32x16_bf16 v[2:17], v[140:143], v[166:169], v[2:17]
	s_setprio 0
	s_setprio 1
	s_waitcnt lgkmcnt(3)
	v_mfma_f32_32x32x16_bf16 v[114:129], v[156:159], v[136:139], v[114:129]
	s_waitcnt lgkmcnt(2)
	v_mfma_f32_32x32x16_bf16 v[98:113], v[156:159], v[174:177], v[98:113]
	s_waitcnt lgkmcnt(1)
	v_mfma_f32_32x32x16_bf16 v[82:97], v[156:159], v[178:181], v[82:97]
	s_waitcnt lgkmcnt(0)
	v_mfma_f32_32x32x16_bf16 v[66:81], v[156:159], v[182:185], v[66:81]
	v_mfma_f32_32x32x16_bf16 v[50:65], v[170:173], v[136:139], v[50:65]
	v_mfma_f32_32x32x16_bf16 v[34:49], v[170:173], v[174:177], v[34:49]
	v_mfma_f32_32x32x16_bf16 v[18:33], v[170:173], v[178:181], v[18:33]
	v_mfma_f32_32x32x16_bf16 v[2:17], v[170:173], v[182:185], v[2:17]
	s_setprio 0
	s_waitcnt vmcnt(0)
	s_barrier
	s_cbranch_scc0 .LBB0_378
	v_mov_b32_e32 v132, v216
	s_lshl_b32 s3, s36, 3
	v_ashrrev_i32_e32 v0, 31, v132
	v_lshrrev_b32_e32 v130, 29, v0
	v_lshrrev_b32_e32 v0, 28, v0
	v_add_u32_e32 v0, v132, v0
	v_ashrrev_i32_e32 v0, 4, v0
	s_and_b32 s3, s3, 56
	s_bfe_u32 s7, s36, 0x30003
	v_lshrrev_b32_e32 v133, 29, v0
	s_or_b32 s3, s3, s7
	s_lshl_b32 s7, s36, 2
	v_add_u32_e32 v130, v132, v130
	v_add_u32_e32 v133, v0, v133
	s_and_b32 s30, s7, 0xffffff00
	s_lshl_b32 s3, s3, 19
	v_and_b32_e32 v131, 0xffffff8, v130
	v_and_b32_e32 v133, 0xffffff8, v133
	s_add_u32 s44, s12, s3
	v_sub_u32_e32 v131, v132, v131
	v_sub_u32_e32 v0, v0, v133
	v_lshlrev_b32_e32 v130, 8, v130
	v_readfirstlane_b32 s3, v132
	s_addc_u32 s45, s13, 0
	v_xor_b32_e32 v0, v0, v131
	v_and_b32_e32 v130, 0xfffff800, v130
	s_lshl_b32 s3, s3, 4
	v_lshl_add_u32 v0, v0, 4, v130
	s_and_b32 s3, s3, 0xfffffc00
	v_lshl_add_u64 v[130:131], s[44:45], 0, v[0:1]
	s_mov_b32 m0, s3
	v_lshl_add_u64 v[132:133], v[130:131], 0, s[58:59]
	global_load_lds_dwordx4 v0, s[44:45]
	s_add_i32 m0, s3, 0x2000
	s_ashr_i32 s31, s30, 31
	global_load_lds_dwordx4 v[132:133], off
	v_lshl_add_u64 v[132:133], v[130:131], 0, s[48:49]
	s_add_i32 m0, s3, 0x4000
	s_lshl_b64 s[30:31], s[30:31], 11
	global_load_lds_dwordx4 v[132:133], off
	s_add_i32 m0, s3, 0x6000
	s_add_u32 s30, s40, s30
	v_lshl_add_u64 v[130:131], v[130:131], 0, s[50:51]
	s_addc_u32 s31, s41, s31
	global_load_lds_dwordx4 v[130:131], off
	v_lshl_add_u64 v[130:131], s[30:31], 0, v[0:1]
	s_add_i32 m0, s3, 0x8000
	v_lshl_add_u64 v[132:133], v[130:131], 0, s[58:59]
	global_load_lds_dwordx4 v0, s[30:31]
	s_add_i32 m0, s3, 0xa000
	s_nop 0
	global_load_lds_dwordx4 v[132:133], off
	v_lshl_add_u64 v[132:133], v[130:131], 0, s[48:49]
	s_add_i32 m0, s3, 0xc000
	v_lshl_add_u64 v[130:131], v[130:131], 0, s[50:51]
	global_load_lds_dwordx4 v[132:133], off
	s_add_i32 m0, s3, 0xe000
	s_nop 0
	global_load_lds_dwordx4 v[130:131], off
	s_branch .LBB0_378

; DI f32x16 mfma(bf16x8 a, bf16x8 b, f32x16 c) { return __builtin_amdgcn_mfma_f32_32x32x16_bf16(a, b, c, 0, 0, 0); }
; template <int BK> DI int swz(int row) { constexpr int CPR = BK / 8; return (row / (16 / CPR)) % CPR; }
; DI void wait_vm0() { asm volatile("s_waitcnt vmcnt(0)" ::: "memory"); }
;   DI void pre(int grow0, int gcol0, int lane, int w, char* lds) { xpass(0, grow0, gcol0, lane, w, lds); }
;     ...
;   for (int kt = 0; kt < nk; ++kt) {
;     char* cur = lds + (kt & 1) * STG; char* nxt = lds + ((kt + 1) & 1) * STG;
;     const bool more = kt + 1 < nk;
;     const bf16_t* An = Ag + (kt + 1) * BK; const bf16_t* Bn = Bg + (kt + 1) * BK;
;     if (!more) epi.pre(row0 + wm * 64, col0 + wn * (32 * NTW), lane, w, lds);
;     bf16x8 fa[2][2], fb[2][NTW];
; #pragma unroll
;     for (int mt = 0; mt < 2; ++mt) { int row = wm * 64 + mt * 32 + l31; fa[0][mt] = *(const bf16x8*)(cur + row * (BK * 2) + ((hh ^ swz<BK>(row)) << 4)); }
; #pragma unroll
;     for (int nt = 0; nt < NTW; ++nt) { int row = wn * (32 * NTW) + nt * 32 + l31; fb[0][nt] = *(const bf16x8*)(cur + ABYTES + row * (BK * 2) + ((hh ^ swz<BK>(row)) << 4)); }
; #pragma unroll
;     for (int kk = 0; kk < NKK; ++kk) {
;       if (kk + 1 < NKK) {
;         const int ch = (kk + 1) * 2 + hh;
; #pragma unroll
;         for (int mt = 0; mt < 2; ++mt) { int row = wm * 64 + mt * 32 + l31; fa[(kk + 1) & 1][mt] = *(const bf16x8*)(cur + row * (BK * 2) + ((ch ^ swz<BK>(row)) << 4)); }
; #pragma unroll
;         for (int nt = 0; nt < NTW; ++nt) { int row = wn * (32 * NTW) + nt * 32 + l31; fb[(kk + 1) & 1][nt] = *(const bf16x8*)(cur + ABYTES + row * (BK * 2) + ((ch ^ swz<BK>(row)) << 4)); }
;       }
;       if (more) {
; #pragma unroll
;         for (int q = 0; q < PPK; ++q) {
;           const int pi = kk * PPK + q;
;           if (pi < NPA) stage_piece<BM, BK>(An, lda, nxt, tid, pi, wv);
;           else if (pi < NP) stage_piece<BN, BK>(Bn, ldb, nxt + ABYTES, tid, pi - NPA, wv);
;         }
;       }
;       __builtin_amdgcn_s_setprio(1);
; #pragma unroll
;       for (int mt = 0; mt < 2; ++mt)
; #pragma unroll
;         for (int nt = 0; nt < NTW; ++nt) acc[mt][nt] = mfma(fa[kk & 1][mt], fb[kk & 1][nt], acc[mt][nt]);
;       __builtin_amdgcn_s_setprio(0);
;       __builtin_amdgcn_sched_barrier(0);
;     }
;     wait_vm0();
;     __syncthreads();
;   }
.LBB0_439:
	s_and_b32 s40, s7, 0x10000
	s_xor_b32 s100, s40, 0x10000
	s_add_i32 s37, s40, s3
	v_add3_u32 v190, s100, v140, v161
	v_add3_u32 v194, s100, v142, v163
	ds_read_b128 v[190:193], v190
	v_add3_u32 v198, s100, v143, v159
	ds_read_b128 v[194:197], v194
	v_add3_u32 v202, s100, v152, v160
	ds_read_b128 v[198:201], v198 offset:32768
	v_add3_u32 v206, s100, v153, v157
	ds_read_b128 v[202:205], v202 offset:32768
	v_add3_u32 v210, s100, v156, v158
	ds_read_b128 v[206:209], v206 offset:32768
	ds_read_b128 v[210:213], v210 offset:32768
	v_lshl_add_u64 v[214:215], v[130:131], 0, s[30:31]
	v_lshl_add_u64 v[226:227], v[132:133], 0, s[30:31]
	s_mov_b32 m0, s37
	v_lshl_add_u64 v[228:229], v[214:215], 0, s[28:29]
	s_waitcnt lgkmcnt(6)
	v_mfma_f32_32x32x16_bf16 v[114:129], v[166:169], v[174:177], v[114:129]
	global_load_lds_dwordx4 v[228:229], off
	v_lshl_add_u64 v[228:229], v[214:215], 0, s[24:25]
	s_add_i32 m0, s37, 0x2000
	v_mfma_f32_32x32x16_bf16 v[98:113], v[166:169], v[178:181], v[98:113]
	global_load_lds_dwordx4 v[228:229], off
	v_lshl_add_u64 v[228:229], v[214:215], 0, s[26:27]
	s_add_i32 m0, s37, 0x4000
	v_mfma_f32_32x32x16_bf16 v[50:65], v[166:169], v[182:185], v[50:65]
	global_load_lds_dwordx4 v[228:229], off
	v_lshl_add_u64 v[228:229], v[214:215], 0, s[38:39]
	s_add_i32 m0, s37, 0x6000
	v_mfma_f32_32x32x16_bf16 v[34:49], v[166:169], v[186:189], v[34:49]
	global_load_lds_dwordx4 v[228:229], off
	v_lshl_add_u64 v[228:229], v[226:227], 0, s[28:29]
	s_add_i32 m0, s37, 0x8000
	v_mfma_f32_32x32x16_bf16 v[82:97], v[170:173], v[174:177], v[82:97]
	global_load_lds_dwordx4 v[228:229], off
	v_lshl_add_u64 v[228:229], v[226:227], 0, s[24:25]
	s_add_i32 m0, s37, 0xa000
	v_mfma_f32_32x32x16_bf16 v[66:81], v[170:173], v[178:181], v[66:81]
	global_load_lds_dwordx4 v[228:229], off
	v_lshl_add_u64 v[228:229], v[226:227], 0, s[26:27]
	s_add_i32 m0, s37, 0xc000
	v_mfma_f32_32x32x16_bf16 v[18:33], v[170:173], v[182:185], v[18:33]
	global_load_lds_dwordx4 v[228:229], off
	v_lshl_add_u64 v[228:229], v[226:227], 0, s[38:39]
	s_add_i32 m0, s37, 0xe000
	v_mfma_f32_32x32x16_bf16 v[2:17], v[170:173], v[186:189], v[2:17]
	global_load_lds_dwordx4 v[228:229], off
	v_add3_u32 v166, s100, v140, v149
	v_add3_u32 v170, s100, v142, v150
	ds_read_b128 v[166:169], v166
	v_add3_u32 v174, s100, v143, v147
	ds_read_b128 v[170:173], v170
	v_add3_u32 v178, s100, v152, v148
	ds_read_b128 v[174:177], v174 offset:32768
	v_add3_u32 v182, s100, v153, v145
	ds_read_b128 v[178:181], v178 offset:32768
	v_add3_u32 v186, s100, v156, v146
	ds_read_b128 v[182:185], v182 offset:32768
	ds_read_b128 v[186:189], v186 offset:32768
	s_waitcnt lgkmcnt(6)
	v_mfma_f32_32x32x16_bf16 v[114:129], v[190:193], v[198:201], v[114:129]
	v_mfma_f32_32x32x16_bf16 v[98:113], v[190:193], v[202:205], v[98:113]
	v_mfma_f32_32x32x16_bf16 v[50:65], v[190:193], v[206:209], v[50:65]
	v_mfma_f32_32x32x16_bf16 v[34:49], v[190:193], v[210:213], v[34:49]
	v_mfma_f32_32x32x16_bf16 v[82:97], v[194:197], v[198:201], v[82:97]
	v_mfma_f32_32x32x16_bf16 v[66:81], v[194:197], v[202:205], v[66:81]
	v_mfma_f32_32x32x16_bf16 v[18:33], v[194:197], v[206:209], v[18:33]
	v_mfma_f32_32x32x16_bf16 v[2:17], v[194:197], v[210:213], v[2:17]
	v_add3_u32 v190, s100, v140, v138
	v_add3_u32 v194, s100, v142, v139
	ds_read_b128 v[190:193], v190
	v_add3_u32 v198, s100, v143, v136
	ds_read_b128 v[194:197], v194
	v_add3_u32 v202, s100, v152, v137
	ds_read_b128 v[198:201], v198 offset:32768
	v_add3_u32 v206, s100, v153, v134
	ds_read_b128 v[202:205], v202 offset:32768
	v_add3_u32 v210, s100, v156, v135
	ds_read_b128 v[206:209], v206 offset:32768
	ds_read_b128 v[210:213], v210 offset:32768
	s_waitcnt lgkmcnt(6)
	v_mfma_f32_32x32x16_bf16 v[114:129], v[166:169], v[174:177], v[114:129]
	v_mfma_f32_32x32x16_bf16 v[98:113], v[166:169], v[178:181], v[98:113]
	v_mfma_f32_32x32x16_bf16 v[50:65], v[166:169], v[182:185], v[50:65]
	v_mfma_f32_32x32x16_bf16 v[34:49], v[166:169], v[186:189], v[34:49]
	v_mfma_f32_32x32x16_bf16 v[82:97], v[170:173], v[174:177], v[82:97]
	v_mfma_f32_32x32x16_bf16 v[66:81], v[170:173], v[178:181], v[66:81]
	v_mfma_f32_32x32x16_bf16 v[18:33], v[170:173], v[182:185], v[18:33]
	v_mfma_f32_32x32x16_bf16 v[2:17], v[170:173], v[186:189], v[2:17]
	s_add_u32 s30, s30, 0x80
	s_addc_u32 s31, s31, 0
	s_add_i32 s7, s7, 0x10000
	s_waitcnt vmcnt(0) lgkmcnt(0)
	s_barrier
	v_add3_u32 v166, s40, v140, v141
	v_add3_u32 v170, s40, v142, v144
	ds_read_b128 v[166:169], v166
	v_add3_u32 v174, s40, v143, v151
	ds_read_b128 v[170:173], v170
	v_add3_u32 v178, s40, v152, v154
	ds_read_b128 v[174:177], v174 offset:32768
	v_add3_u32 v182, s40, v153, v155
	ds_read_b128 v[178:181], v178 offset:32768
	v_add3_u32 v186, s40, v156, v164
	ds_read_b128 v[182:185], v182 offset:32768
	ds_read_b128 v[186:189], v186 offset:32768
	v_mfma_f32_32x32x16_bf16 v[114:129], v[190:193], v[198:201], v[114:129]
	v_mfma_f32_32x32x16_bf16 v[98:113], v[190:193], v[202:205], v[98:113]
	v_mfma_f32_32x32x16_bf16 v[50:65], v[190:193], v[206:209], v[50:65]
	v_mfma_f32_32x32x16_bf16 v[34:49], v[190:193], v[210:213], v[34:49]
	v_mfma_f32_32x32x16_bf16 v[82:97], v[194:197], v[198:201], v[82:97]
	v_mfma_f32_32x32x16_bf16 v[66:81], v[194:197], v[202:205], v[66:81]
	v_mfma_f32_32x32x16_bf16 v[18:33], v[194:197], v[206:209], v[18:33]
	v_mfma_f32_32x32x16_bf16 v[2:17], v[194:197], v[210:213], v[2:17]
	s_cmpk_eq_i32 s30, 0x780
	s_cbranch_scc0 .LBB0_439
;     ...
;   for (int kt = 0; kt < nk; ++kt) {
;     char* cur = lds + (kt & 1) * STG; char* nxt = lds + ((kt + 1) & 1) * STG;
;     const bool more = kt + 1 < nk;
;     const bf16_t* An = Ag + (kt + 1) * BK; const bf16_t* Bn = Bg + (kt + 1) * BK;
;     if (!more) epi.pre(row0 + wm * 64, col0 + wn * (32 * NTW), lane, w, lds);
;     bf16x8 fa[2][2], fb[2][NTW];
; #pragma unroll
;     for (int mt = 0; mt < 2; ++mt) { int row = wm * 64 + mt * 32 + l31; fa[0][mt] = *(const bf16x8*)(cur + row * (BK * 2) + ((hh ^ swz<BK>(row)) << 4)); }
; #pragma unroll
;     for (int nt = 0; nt < NTW; ++nt) { int row = wn * (32 * NTW) + nt * 32 + l31; fb[0][nt] = *(const bf16x8*)(cur + ABYTES + row * (BK * 2) + ((hh ^ swz<BK>(row)) << 4)); }
; #pragma unroll
;     for (int kk = 0; kk < NKK; ++kk) {
;       if (kk + 1 < NKK) {
;         const int ch = (kk + 1) * 2 + hh;
; #pragma unroll
;         for (int mt = 0; mt < 2; ++mt) { int row = wm * 64 + mt * 32 + l31; fa[(kk + 1) & 1][mt] = *(const bf16x8*)(cur + row * (BK * 2) + ((ch ^ swz<BK>(row)) << 4)); }
; #pragma unroll
;         for (int nt = 0; nt < NTW; ++nt) { int row = wn * (32 * NTW) + nt * 32 + l31; fb[(kk + 1) & 1][nt] = *(const bf16x8*)(cur + ABYTES + row * (BK * 2) + ((ch ^ swz<BK>(row)) << 4)); }
;       }
;       if (more) {
; #pragma unroll
;         for (int q = 0; q < PPK; ++q) {
;           const int pi = kk * PPK + q;
;           if (pi < NPA) stage_piece<BM, BK>(An, lda, nxt, tid, pi, wv);
;           else if (pi < NP) stage_piece<BN, BK>(Bn, ldb, nxt + ABYTES, tid, pi - NPA, wv);
;         }
;       }
;       __builtin_amdgcn_s_setprio(1);
; #pragma unroll
;       for (int mt = 0; mt < 2; ++mt)
; #pragma unroll
;         for (int nt = 0; nt < NTW; ++nt) acc[mt][nt] = mfma(fa[kk & 1][mt], fb[kk & 1][nt], acc[mt][nt]);
;       __builtin_amdgcn_s_setprio(0);
;       __builtin_amdgcn_sched_barrier(0);
;     }
;     wait_vm0();
;     __syncthreads();
;   }
;   if (has_next) { const int tid3 = launder(threadIdx.x); stage_tile<BM, BK>(A + (size_t)row0n * lda, lda, lds, tid3); stage_tile<BN, BK>(Bt + (size_t)col0n * ldb, ldb, lds + ABYTES, tid3); }
; template <class Epi>
; DI void gemm_phase256(const bf16_t* A, int lda, const bf16_t* Bt, int K, int nN, char* lds, Epi& epi, int vb) {
;     ...
;   for (int t = vb; t < ntiles; t += gridDim.x) {
;     const int x = t & 7, L = t >> 3; const int pm = 8 * x + (L & 7), pn = L >> 3;
	s_waitcnt lgkmcnt(0)
	v_add_u32_e32 v0, 0x10000, v140
	v_add_u32_e32 v198, 0x10000, v142
	v_add_u32_e32 v130, v0, v141
	v_add_u32_e32 v140, v198, v144
	v_add_u32_e32 v199, 0x18000, v143
	v_add_u32_e32 v200, 0x18000, v152
	ds_read_b128 v[130:133], v130
	ds_read_b128 v[166:169], v140
	v_add_u32_e32 v140, v199, v151
	v_add_u32_e32 v144, v200, v154
	v_add_u32_e32 v201, 0x18000, v153
	ds_read_b128 v[140:143], v140
	ds_read_b128 v[170:173], v144
	v_add_u32_e32 v144, v201, v155
	v_add_u32_e32 v202, 0x18000, v156
	v_add_u32_e32 v151, v202, v164
	ds_read_b128 v[152:155], v144
	ds_read_b128 v[174:177], v151
	v_add_u32_e32 v144, v0, v161
	v_add_u32_e32 v151, v198, v163
	ds_read_b128 v[178:181], v144
	ds_read_b128 v[182:185], v151
	v_add_u32_e32 v144, v199, v159
	v_add_u32_e32 v151, v200, v160
	ds_read_b128 v[186:189], v144
	ds_read_b128 v[190:193], v151
	v_add_u32_e32 v144, v201, v157
	v_add_u32_e32 v151, v202, v158
	ds_read_b128 v[156:159], v144
	ds_read_b128 v[194:197], v151
	s_add_i32 s36, s36, s94
	s_cmpk_gt_i32 s36, 0x5ff
	s_cselect_b64 s[42:43], -1, 0
	s_cmpk_lt_i32 s36, 0x600
	s_setprio 1
	s_waitcnt lgkmcnt(9)
	v_mfma_f32_32x32x16_bf16 v[114:129], v[130:133], v[140:143], v[114:129]
	s_waitcnt lgkmcnt(8)
	v_mfma_f32_32x32x16_bf16 v[98:113], v[130:133], v[170:173], v[98:113]
	s_waitcnt lgkmcnt(7)
	v_mfma_f32_32x32x16_bf16 v[50:65], v[130:133], v[152:155], v[50:65]
	s_waitcnt lgkmcnt(6)
	v_mfma_f32_32x32x16_bf16 v[34:49], v[130:133], v[174:177], v[34:49]
	v_mfma_f32_32x32x16_bf16 v[82:97], v[166:169], v[140:143], v[82:97]
	v_mfma_f32_32x32x16_bf16 v[66:81], v[166:169], v[170:173], v[66:81]
	v_mfma_f32_32x32x16_bf16 v[18:33], v[166:169], v[152:155], v[18:33]
	v_mfma_f32_32x32x16_bf16 v[2:17], v[166:169], v[174:177], v[2:17]
	s_setprio 0
	v_add_u32_e32 v130, v0, v149
	v_add_u32_e32 v140, v198, v150
	v_add_u32_e32 v144, v199, v147
	ds_read_b128 v[130:133], v130
	ds_read_b128 v[140:143], v140
	v_add_u32_e32 v147, v200, v148
	ds_read_b128 v[148:151], v144
	ds_read_b128 v[152:155], v147
	v_add_u32_e32 v144, v201, v145
	v_add_u32_e32 v160, v202, v146
	ds_read_b128 v[144:147], v144
	ds_read_b128 v[166:169], v160
	s_setprio 1
	s_waitcnt lgkmcnt(9)
	v_mfma_f32_32x32x16_bf16 v[114:129], v[178:181], v[186:189], v[114:129]
	s_waitcnt lgkmcnt(8)
	v_mfma_f32_32x32x16_bf16 v[98:113], v[178:181], v[190:193], v[98:113]
	s_waitcnt lgkmcnt(7)
	v_mfma_f32_32x32x16_bf16 v[50:65], v[178:181], v[156:159], v[50:65]
	s_waitcnt lgkmcnt(6)
	v_mfma_f32_32x32x16_bf16 v[34:49], v[178:181], v[194:197], v[34:49]
	v_mfma_f32_32x32x16_bf16 v[82:97], v[182:185], v[186:189], v[82:97]
	v_mfma_f32_32x32x16_bf16 v[66:81], v[182:185], v[190:193], v[66:81]
	v_mfma_f32_32x32x16_bf16 v[18:33], v[182:185], v[156:159], v[18:33]
	v_mfma_f32_32x32x16_bf16 v[2:17], v[182:185], v[194:197], v[2:17]
	s_setprio 0
	v_add_u32_e32 v0, v0, v138
	v_add_u32_e32 v138, v198, v139
	ds_read_b128 v[156:159], v0
	ds_read_b128 v[170:173], v138
	v_add_u32_e32 v0, v199, v136
	v_add_u32_e32 v160, v200, v137
	ds_read_b128 v[136:139], v0
	ds_read_b128 v[174:177], v160
	v_add_u32_e32 v0, v201, v134
	v_add_u32_e32 v134, v202, v135
	ds_read_b128 v[178:181], v0
	ds_read_b128 v[182:185], v134
	s_setprio 1
	s_waitcnt lgkmcnt(9)
	v_mfma_f32_32x32x16_bf16 v[114:129], v[130:133], v[148:151], v[114:129]
	s_waitcnt lgkmcnt(8)
	v_mfma_f32_32x32x16_bf16 v[98:113], v[130:133], v[152:155], v[98:113]
	s_waitcnt lgkmcnt(7)
	v_mfma_f32_32x32x16_bf16 v[50:65], v[130:133], v[144:147], v[50:65]
	s_waitcnt lgkmcnt(6)
	v_mfma_f32_32x32x16_bf16 v[34:49], v[130:133], v[166:169], v[34:49]
	v_mfma_f32_32x32x16_bf16 v[82:97], v[140:143], v[148:151], v[82:97]
	v_mfma_f32_32x32x16_bf16 v[66:81], v[140:143], v[152:155], v[66:81]
	v_mfma_f32_32x32x16_bf16 v[18:33], v[140:143], v[144:147], v[18:33]
	v_mfma_f32_32x32x16_bf16 v[2:17], v[140:143], v[166:169], v[2:17]
	s_setprio 0
	s_setprio 1
	s_waitcnt lgkmcnt(3)
	v_mfma_f32_32x32x16_bf16 v[114:129], v[156:159], v[136:139], v[114:129]
	s_waitcnt lgkmcnt(2)
	v_mfma_f32_32x32x16_bf16 v[98:113], v[156:159], v[174:177], v[98:113]
	s_waitcnt lgkmcnt(1)
	v_mfma_f32_32x32x16_bf16 v[50:65], v[156:159], v[178:181], v[50:65]
	s_waitcnt lgkmcnt(0)
	v_mfma_f32_32x32x16_bf16 v[34:49], v[156:159], v[182:185], v[34:49]
	v_mfma_f32_32x32x16_bf16 v[82:97], v[170:173], v[136:139], v[82:97]
	v_mfma_f32_32x32x16_bf16 v[66:81], v[170:173], v[174:177], v[66:81]
	v_mfma_f32_32x32x16_bf16 v[18:33], v[170:173], v[178:181], v[18:33]
	v_mfma_f32_32x32x16_bf16 v[2:17], v[170:173], v[182:185], v[2:17]
	s_setprio 0
	s_waitcnt vmcnt(0)
	s_barrier
	s_cbranch_scc0 .LBB0_442
	v_mov_b32_e32 v132, v216
	s_lshl_b32 s3, s36, 3
	v_ashrrev_i32_e32 v0, 31, v132
	v_lshrrev_b32_e32 v130, 29, v0
	v_lshrrev_b32_e32 v0, 28, v0
	v_add_u32_e32 v0, v132, v0
	v_ashrrev_i32_e32 v0, 4, v0
	s_and_b32 s3, s3, 56
	s_bfe_u32 s7, s36, 0x30003
	v_lshrrev_b32_e32 v133, 29, v0
	s_or_b32 s3, s3, s7
	s_lshl_b32 s7, s36, 2
	v_add_u32_e32 v130, v132, v130
	v_add_u32_e32 v133, v0, v133
	s_and_b32 s30, s7, 0xffffff00
	s_lshl_b32 s3, s3, 19
	v_and_b32_e32 v131, 0xffffff8, v130
	v_and_b32_e32 v133, 0xffffff8, v133
	s_add_u32 s40, s12, s3
	v_sub_u32_e32 v131, v132, v131
	v_sub_u32_e32 v0, v0, v133
	v_lshlrev_b32_e32 v130, 8, v130
	v_readfirstlane_b32 s3, v132
	s_addc_u32 s41, s13, 0
	v_xor_b32_e32 v0, v0, v131
	v_and_b32_e32 v130, 0xfffff800, v130
	s_lshl_b32 s3, s3, 4
	v_lshl_add_u32 v0, v0, 4, v130
	s_and_b32 s3, s3, 0xfffffc00
	s_load_dwordx4 s[44:47], s[0:1], 0x1a0
	v_lshl_add_u64 v[130:131], s[40:41], 0, v[0:1]
	s_mov_b32 m0, s3
	v_lshl_add_u64 v[132:133], v[130:131], 0, s[58:59]
	global_load_lds_dwordx4 v0, s[40:41]
	s_add_i32 m0, s3, 0x2000
	s_ashr_i32 s31, s30, 31
	global_load_lds_dwordx4 v[132:133], off
	v_lshl_add_u64 v[132:133], v[130:131], 0, s[48:49]
	s_add_i32 m0, s3, 0x4000
	s_lshl_b64 s[30:31], s[30:31], 11
	global_load_lds_dwordx4 v[132:133], off
	s_add_i32 m0, s3, 0x6000
	s_waitcnt lgkmcnt(0)
	s_add_u32 s30, s46, s30
	v_lshl_add_u64 v[130:131], v[130:131], 0, s[50:51]
	s_addc_u32 s31, s47, s31
	global_load_lds_dwordx4 v[130:131], off
	v_lshl_add_u64 v[130:131], s[30:31], 0, v[0:1]
	s_add_i32 m0, s3, 0x8000
	v_lshl_add_u64 v[132:133], v[130:131], 0, s[58:59]
	global_load_lds_dwordx4 v0, s[30:31]
	s_add_i32 m0, s3, 0xa000
	s_nop 0
	global_load_lds_dwordx4 v[132:133], off
	v_lshl_add_u64 v[132:133], v[130:131], 0, s[48:49]
	s_add_i32 m0, s3, 0xc000
	v_lshl_add_u64 v[130:131], v[130:131], 0, s[50:51]
	global_load_lds_dwordx4 v[132:133], off
	s_add_i32 m0, s3, 0xe000
	s_nop 0
	global_load_lds_dwordx4 v[130:131], off

; DI f32x16 mfma(bf16x8 a, bf16x8 b, f32x16 c) { return __builtin_amdgcn_mfma_f32_32x32x16_bf16(a, b, c, 0, 0, 0); }
; template <int BK> DI int swz(int row) { constexpr int CPR = BK / 8; return (row / (16 / CPR)) % CPR; }
; DI void wait_vm0() { asm volatile("s_waitcnt vmcnt(0)" ::: "memory"); }
;   DI void pre(int grow0, int gcol0, int lane, int w, char* lds) { xpass(0, grow0, gcol0, lane, w, lds); }
;     ...
;   for (int kt = 0; kt < nk; ++kt) {
;     char* cur = lds + (kt & 1) * STG; char* nxt = lds + ((kt + 1) & 1) * STG;
;     const bool more = kt + 1 < nk;
;     const bf16_t* An = Ag + (kt + 1) * BK; const bf16_t* Bn = Bg + (kt + 1) * BK;
;     if (!more) epi.pre(row0 + wm * 64, col0 + wn * (32 * NTW), lane, w, lds);
;     bf16x8 fa[2][2], fb[2][NTW];
; #pragma unroll
;     for (int mt = 0; mt < 2; ++mt) { int row = wm * 64 + mt * 32 + l31; fa[0][mt] = *(const bf16x8*)(cur + row * (BK * 2) + ((hh ^ swz<BK>(row)) << 4)); }
; #pragma unroll
;     for (int nt = 0; nt < NTW; ++nt) { int row = wn * (32 * NTW) + nt * 32 + l31; fb[0][nt] = *(const bf16x8*)(cur + ABYTES + row * (BK * 2) + ((hh ^ swz<BK>(row)) << 4)); }
; #pragma unroll
;     for (int kk = 0; kk < NKK; ++kk) {
;       if (kk + 1 < NKK) {
;         const int ch = (kk + 1) * 2 + hh;
; #pragma unroll
;         for (int mt = 0; mt < 2; ++mt) { int row = wm * 64 + mt * 32 + l31; fa[(kk + 1) & 1][mt] = *(const bf16x8*)(cur + row * (BK * 2) + ((ch ^ swz<BK>(row)) << 4)); }
; #pragma unroll
;         for (int nt = 0; nt < NTW; ++nt) { int row = wn * (32 * NTW) + nt * 32 + l31; fb[(kk + 1) & 1][nt] = *(const bf16x8*)(cur + ABYTES + row * (BK * 2) + ((ch ^ swz<BK>(row)) << 4)); }
;       }
;       if (more) {
; #pragma unroll
;         for (int q = 0; q < PPK; ++q) {
;           const int pi = kk * PPK + q;
;           if (pi < NPA) stage_piece<BM, BK>(An, lda, nxt, tid, pi, wv);
;           else if (pi < NP) stage_piece<BN, BK>(Bn, ldb, nxt + ABYTES, tid, pi - NPA, wv);
;         }
;       }
;       __builtin_amdgcn_s_setprio(1);
; #pragma unroll
;       for (int mt = 0; mt < 2; ++mt)
; #pragma unroll
;         for (int nt = 0; nt < NTW; ++nt) acc[mt][nt] = mfma(fa[kk & 1][mt], fb[kk & 1][nt], acc[mt][nt]);
;       __builtin_amdgcn_s_setprio(0);
;       __builtin_amdgcn_sched_barrier(0);
;     }
;     wait_vm0();
;     __syncthreads();
;   }
.LBB0_519:
	s_and_b32 s42, s7, 0x10000
	s_xor_b32 s100, s42, 0x10000
	s_add_i32 s37, s42, s3
	v_add3_u32 v190, s100, v140, v161
	v_add3_u32 v194, s100, v142, v163
	ds_read_b128 v[190:193], v190
	v_add3_u32 v198, s100, v143, v159
	ds_read_b128 v[194:197], v194
	v_add3_u32 v202, s100, v152, v160
	ds_read_b128 v[198:201], v198 offset:32768
	v_add3_u32 v206, s100, v153, v157
	ds_read_b128 v[202:205], v202 offset:32768
	v_add3_u32 v210, s100, v156, v158
	ds_read_b128 v[206:209], v206 offset:32768
	ds_read_b128 v[210:213], v210 offset:32768
	v_lshl_add_u64 v[214:215], v[130:131], 0, s[30:31]
	v_lshl_add_u64 v[226:227], v[132:133], 0, s[30:31]
	s_mov_b32 m0, s37
	v_lshl_add_u64 v[228:229], v[214:215], 0, s[28:29]
	s_waitcnt lgkmcnt(6)
	v_mfma_f32_32x32x16_bf16 v[114:129], v[166:169], v[174:177], v[114:129]
	global_load_lds_dwordx4 v[228:229], off
	v_lshl_add_u64 v[228:229], v[214:215], 0, s[24:25]
	s_add_i32 m0, s37, 0x2000
	v_mfma_f32_32x32x16_bf16 v[98:113], v[166:169], v[178:181], v[98:113]
	global_load_lds_dwordx4 v[228:229], off
	v_lshl_add_u64 v[228:229], v[214:215], 0, s[26:27]
	s_add_i32 m0, s37, 0x4000
	v_mfma_f32_32x32x16_bf16 v[82:97], v[166:169], v[182:185], v[82:97]
	global_load_lds_dwordx4 v[228:229], off
	v_lshl_add_u64 v[228:229], v[214:215], 0, s[38:39]
	s_add_i32 m0, s37, 0x6000
	v_mfma_f32_32x32x16_bf16 v[66:81], v[166:169], v[186:189], v[66:81]
	global_load_lds_dwordx4 v[228:229], off
	v_lshl_add_u64 v[228:229], v[226:227], 0, s[28:29]
	s_add_i32 m0, s37, 0x8000
	v_mfma_f32_32x32x16_bf16 v[50:65], v[170:173], v[174:177], v[50:65]
	global_load_lds_dwordx4 v[228:229], off
	v_lshl_add_u64 v[228:229], v[226:227], 0, s[24:25]
	s_add_i32 m0, s37, 0xa000
	v_mfma_f32_32x32x16_bf16 v[34:49], v[170:173], v[178:181], v[34:49]
	global_load_lds_dwordx4 v[228:229], off
	v_lshl_add_u64 v[228:229], v[226:227], 0, s[26:27]
	s_add_i32 m0, s37, 0xc000
	v_mfma_f32_32x32x16_bf16 v[18:33], v[170:173], v[182:185], v[18:33]
	global_load_lds_dwordx4 v[228:229], off
	v_lshl_add_u64 v[228:229], v[226:227], 0, s[38:39]
	s_add_i32 m0, s37, 0xe000
	v_mfma_f32_32x32x16_bf16 v[2:17], v[170:173], v[186:189], v[2:17]
	global_load_lds_dwordx4 v[228:229], off
	v_add3_u32 v166, s100, v140, v149
	v_add3_u32 v170, s100, v142, v150
	ds_read_b128 v[166:169], v166
	v_add3_u32 v174, s100, v143, v147
	ds_read_b128 v[170:173], v170
	v_add3_u32 v178, s100, v152, v148
	ds_read_b128 v[174:177], v174 offset:32768
	v_add3_u32 v182, s100, v153, v145
	ds_read_b128 v[178:181], v178 offset:32768
	v_add3_u32 v186, s100, v156, v146
	ds_read_b128 v[182:185], v182 offset:32768
	ds_read_b128 v[186:189], v186 offset:32768
	s_waitcnt lgkmcnt(6)
	v_mfma_f32_32x32x16_bf16 v[114:129], v[190:193], v[198:201], v[114:129]
	v_mfma_f32_32x32x16_bf16 v[98:113], v[190:193], v[202:205], v[98:113]
	v_mfma_f32_32x32x16_bf16 v[82:97], v[190:193], v[206:209], v[82:97]
	v_mfma_f32_32x32x16_bf16 v[66:81], v[190:193], v[210:213], v[66:81]
	v_mfma_f32_32x32x16_bf16 v[50:65], v[194:197], v[198:201], v[50:65]
	v_mfma_f32_32x32x16_bf16 v[34:49], v[194:197], v[202:205], v[34:49]
	v_mfma_f32_32x32x16_bf16 v[18:33], v[194:197], v[206:209], v[18:33]
	v_mfma_f32_32x32x16_bf16 v[2:17], v[194:197], v[210:213], v[2:17]
	v_add3_u32 v190, s100, v140, v138
	v_add3_u32 v194, s100, v142, v139
	ds_read_b128 v[190:193], v190
	v_add3_u32 v198, s100, v143, v136
	ds_read_b128 v[194:197], v194
	v_add3_u32 v202, s100, v152, v137
	ds_read_b128 v[198:201], v198 offset:32768
	v_add3_u32 v206, s100, v153, v134
	ds_read_b128 v[202:205], v202 offset:32768
	v_add3_u32 v210, s100, v156, v135
	ds_read_b128 v[206:209], v206 offset:32768
	ds_read_b128 v[210:213], v210 offset:32768
	s_waitcnt lgkmcnt(6)
	v_mfma_f32_32x32x16_bf16 v[114:129], v[166:169], v[174:177], v[114:129]
	v_mfma_f32_32x32x16_bf16 v[98:113], v[166:169], v[178:181], v[98:113]
	v_mfma_f32_32x32x16_bf16 v[82:97], v[166:169], v[182:185], v[82:97]
	v_mfma_f32_32x32x16_bf16 v[66:81], v[166:169], v[186:189], v[66:81]
	v_mfma_f32_32x32x16_bf16 v[50:65], v[170:173], v[174:177], v[50:65]
	v_mfma_f32_32x32x16_bf16 v[34:49], v[170:173], v[178:181], v[34:49]
	v_mfma_f32_32x32x16_bf16 v[18:33], v[170:173], v[182:185], v[18:33]
	v_mfma_f32_32x32x16_bf16 v[2:17], v[170:173], v[186:189], v[2:17]
	s_add_u32 s30, s30, 0x80
	s_addc_u32 s31, s31, 0
	s_add_i32 s7, s7, 0x10000
	s_waitcnt vmcnt(0) lgkmcnt(0)
	s_barrier
	v_add3_u32 v166, s42, v140, v141
	v_add3_u32 v170, s42, v142, v144
	ds_read_b128 v[166:169], v166
	v_add3_u32 v174, s42, v143, v151
	ds_read_b128 v[170:173], v170
	v_add3_u32 v178, s42, v152, v154
	ds_read_b128 v[174:177], v174 offset:32768
	v_add3_u32 v182, s42, v153, v155
	ds_read_b128 v[178:181], v178 offset:32768
	v_add3_u32 v186, s42, v156, v164
	ds_read_b128 v[182:185], v182 offset:32768
	ds_read_b128 v[186:189], v186 offset:32768
	v_mfma_f32_32x32x16_bf16 v[114:129], v[190:193], v[198:201], v[114:129]
	v_mfma_f32_32x32x16_bf16 v[98:113], v[190:193], v[202:205], v[98:113]
	v_mfma_f32_32x32x16_bf16 v[82:97], v[190:193], v[206:209], v[82:97]
	v_mfma_f32_32x32x16_bf16 v[66:81], v[190:193], v[210:213], v[66:81]
	v_mfma_f32_32x32x16_bf16 v[50:65], v[194:197], v[198:201], v[50:65]
	v_mfma_f32_32x32x16_bf16 v[34:49], v[194:197], v[202:205], v[34:49]
	v_mfma_f32_32x32x16_bf16 v[18:33], v[194:197], v[206:209], v[18:33]
	v_mfma_f32_32x32x16_bf16 v[2:17], v[194:197], v[210:213], v[2:17]
	s_cmpk_eq_i32 s30, 0x780
	s_cbranch_scc0 .LBB0_519
;     ...
;   for (int kt = 0; kt < nk; ++kt) {
;     char* cur = lds + (kt & 1) * STG; char* nxt = lds + ((kt + 1) & 1) * STG;
;     const bool more = kt + 1 < nk;
;     const bf16_t* An = Ag + (kt + 1) * BK; const bf16_t* Bn = Bg + (kt + 1) * BK;
;     if (!more) epi.pre(row0 + wm * 64, col0 + wn * (32 * NTW), lane, w, lds);
;     bf16x8 fa[2][2], fb[2][NTW];
; #pragma unroll
;     for (int mt = 0; mt < 2; ++mt) { int row = wm * 64 + mt * 32 + l31; fa[0][mt] = *(const bf16x8*)(cur + row * (BK * 2) + ((hh ^ swz<BK>(row)) << 4)); }
; #pragma unroll
;     for (int nt = 0; nt < NTW; ++nt) { int row = wn * (32 * NTW) + nt * 32 + l31; fb[0][nt] = *(const bf16x8*)(cur + ABYTES + row * (BK * 2) + ((hh ^ swz<BK>(row)) << 4)); }
; #pragma unroll
;     for (int kk = 0; kk < NKK; ++kk) {
;       if (kk + 1 < NKK) {
;         const int ch = (kk + 1) * 2 + hh;
; #pragma unroll
;         for (int mt = 0; mt < 2; ++mt) { int row = wm * 64 + mt * 32 + l31; fa[(kk + 1) & 1][mt] = *(const bf16x8*)(cur + row * (BK * 2) + ((ch ^ swz<BK>(row)) << 4)); }
; #pragma unroll
;         for (int nt = 0; nt < NTW; ++nt) { int row = wn * (32 * NTW) + nt * 32 + l31; fb[(kk + 1) & 1][nt] = *(const bf16x8*)(cur + ABYTES + row * (BK * 2) + ((ch ^ swz<BK>(row)) << 4)); }
;       }
;       if (more) {
; #pragma unroll
;         for (int q = 0; q < PPK; ++q) {
;           const int pi = kk * PPK + q;
;           if (pi < NPA) stage_piece<BM, BK>(An, lda, nxt, tid, pi, wv);
;           else if (pi < NP) stage_piece<BN, BK>(Bn, ldb, nxt + ABYTES, tid, pi - NPA, wv);
;         }
;       }
;       __builtin_amdgcn_s_setprio(1);
; #pragma unroll
;       for (int mt = 0; mt < 2; ++mt)
; #pragma unroll
;         for (int nt = 0; nt < NTW; ++nt) acc[mt][nt] = mfma(fa[kk & 1][mt], fb[kk & 1][nt], acc[mt][nt]);
;       __builtin_amdgcn_s_setprio(0);
;       __builtin_amdgcn_sched_barrier(0);
;     }
;     wait_vm0();
;     __syncthreads();
;   }
;   if (has_next) { const int tid3 = launder(threadIdx.x); stage_tile<BM, BK>(A + (size_t)row0n * lda, lda, lds, tid3); stage_tile<BN, BK>(Bt + (size_t)col0n * ldb, ldb, lds + ABYTES, tid3); }
; template <class Epi>
; DI void gemm_phase256(const bf16_t* A, int lda, const bf16_t* Bt, int K, int nN, char* lds, Epi& epi, int vb) {
;     ...
;   for (int t = vb; t < ntiles; t += gridDim.x) {
;     const int x = t & 7, L = t >> 3; const int pm = 8 * x + (L & 7), pn = L >> 3;
	s_waitcnt lgkmcnt(0)
	v_add_u32_e32 v0, 0x10000, v140
	v_add_u32_e32 v198, 0x10000, v142
	v_add_u32_e32 v130, v0, v141
	v_add_u32_e32 v140, v198, v144
	v_add_u32_e32 v199, 0x18000, v143
	v_add_u32_e32 v200, 0x18000, v152
	ds_read_b128 v[130:133], v130
	ds_read_b128 v[166:169], v140
	v_add_u32_e32 v140, v199, v151
	v_add_u32_e32 v144, v200, v154
	v_add_u32_e32 v201, 0x18000, v153
	ds_read_b128 v[140:143], v140
	ds_read_b128 v[170:173], v144
	v_add_u32_e32 v144, v201, v155
	v_add_u32_e32 v202, 0x18000, v156
	v_add_u32_e32 v151, v202, v164
	ds_read_b128 v[152:155], v144
	ds_read_b128 v[174:177], v151
	v_add_u32_e32 v144, v0, v161
	v_add_u32_e32 v151, v198, v163
	ds_read_b128 v[178:181], v144
	ds_read_b128 v[182:185], v151
	v_add_u32_e32 v144, v199, v159
	v_add_u32_e32 v151, v200, v160
	ds_read_b128 v[186:189], v144
	ds_read_b128 v[190:193], v151
	v_add_u32_e32 v144, v201, v157
	v_add_u32_e32 v151, v202, v158
	ds_read_b128 v[156:159], v144
	ds_read_b128 v[194:197], v151
	s_add_i32 s36, s36, s94
	s_cmpk_gt_i32 s36, 0x2ff
	s_cselect_b64 s[42:43], -1, 0
	s_cmpk_lt_i32 s36, 0x300
	s_setprio 1
	s_waitcnt lgkmcnt(9)
	v_mfma_f32_32x32x16_bf16 v[114:129], v[130:133], v[140:143], v[114:129]
	s_waitcnt lgkmcnt(8)
	v_mfma_f32_32x32x16_bf16 v[98:113], v[130:133], v[170:173], v[98:113]
	s_waitcnt lgkmcnt(7)
	v_mfma_f32_32x32x16_bf16 v[82:97], v[130:133], v[152:155], v[82:97]
	s_waitcnt lgkmcnt(6)
	v_mfma_f32_32x32x16_bf16 v[66:81], v[130:133], v[174:177], v[66:81]
	v_mfma_f32_32x32x16_bf16 v[50:65], v[166:169], v[140:143], v[50:65]
	v_mfma_f32_32x32x16_bf16 v[34:49], v[166:169], v[170:173], v[34:49]
	v_mfma_f32_32x32x16_bf16 v[18:33], v[166:169], v[152:155], v[18:33]
	v_mfma_f32_32x32x16_bf16 v[2:17], v[166:169], v[174:177], v[2:17]
	s_setprio 0
	v_add_u32_e32 v130, v0, v149
	v_add_u32_e32 v140, v198, v150
	v_add_u32_e32 v144, v199, v147
	ds_read_b128 v[130:133], v130
	ds_read_b128 v[140:143], v140
	v_add_u32_e32 v147, v200, v148
	ds_read_b128 v[148:151], v144
	ds_read_b128 v[152:155], v147
	v_add_u32_e32 v144, v201, v145
	v_add_u32_e32 v160, v202, v146
	ds_read_b128 v[144:147], v144
	ds_read_b128 v[166:169], v160
	s_setprio 1
	s_waitcnt lgkmcnt(9)
	v_mfma_f32_32x32x16_bf16 v[114:129], v[178:181], v[186:189], v[114:129]
	s_waitcnt lgkmcnt(8)
	v_mfma_f32_32x32x16_bf16 v[98:113], v[178:181], v[190:193], v[98:113]
	s_waitcnt lgkmcnt(7)
	v_mfma_f32_32x32x16_bf16 v[82:97], v[178:181], v[156:159], v[82:97]
	s_waitcnt lgkmcnt(6)
	v_mfma_f32_32x32x16_bf16 v[66:81], v[178:181], v[194:197], v[66:81]
	v_mfma_f32_32x32x16_bf16 v[50:65], v[182:185], v[186:189], v[50:65]
	v_mfma_f32_32x32x16_bf16 v[34:49], v[182:185], v[190:193], v[34:49]
	v_mfma_f32_32x32x16_bf16 v[18:33], v[182:185], v[156:159], v[18:33]
	v_mfma_f32_32x32x16_bf16 v[2:17], v[182:185], v[194:197], v[2:17]
	s_setprio 0
	v_add_u32_e32 v0, v0, v138
	v_add_u32_e32 v138, v198, v139
	ds_read_b128 v[156:159], v0
	ds_read_b128 v[170:173], v138
	v_add_u32_e32 v0, v199, v136
	v_add_u32_e32 v160, v200, v137
	ds_read_b128 v[136:139], v0
	ds_read_b128 v[174:177], v160
	v_add_u32_e32 v0, v201, v134
	v_add_u32_e32 v134, v202, v135
	ds_read_b128 v[178:181], v0
	ds_read_b128 v[182:185], v134
	s_setprio 1
	s_waitcnt lgkmcnt(9)
	v_mfma_f32_32x32x16_bf16 v[114:129], v[130:133], v[148:151], v[114:129]
	s_waitcnt lgkmcnt(8)
	v_mfma_f32_32x32x16_bf16 v[98:113], v[130:133], v[152:155], v[98:113]
	s_waitcnt lgkmcnt(7)
	v_mfma_f32_32x32x16_bf16 v[82:97], v[130:133], v[144:147], v[82:97]
	s_waitcnt lgkmcnt(6)
	v_mfma_f32_32x32x16_bf16 v[66:81], v[130:133], v[166:169], v[66:81]
	v_mfma_f32_32x32x16_bf16 v[50:65], v[140:143], v[148:151], v[50:65]
	v_mfma_f32_32x32x16_bf16 v[34:49], v[140:143], v[152:155], v[34:49]
	v_mfma_f32_32x32x16_bf16 v[18:33], v[140:143], v[144:147], v[18:33]
	v_mfma_f32_32x32x16_bf16 v[2:17], v[140:143], v[166:169], v[2:17]
	s_setprio 0
	s_setprio 1
	s_waitcnt lgkmcnt(3)
	v_mfma_f32_32x32x16_bf16 v[114:129], v[156:159], v[136:139], v[114:129]
	s_waitcnt lgkmcnt(2)
	v_mfma_f32_32x32x16_bf16 v[98:113], v[156:159], v[174:177], v[98:113]
	s_waitcnt lgkmcnt(1)
	v_mfma_f32_32x32x16_bf16 v[82:97], v[156:159], v[178:181], v[82:97]
	s_waitcnt lgkmcnt(0)
	v_mfma_f32_32x32x16_bf16 v[66:81], v[156:159], v[182:185], v[66:81]
	v_mfma_f32_32x32x16_bf16 v[50:65], v[170:173], v[136:139], v[50:65]
	v_mfma_f32_32x32x16_bf16 v[34:49], v[170:173], v[174:177], v[34:49]
	v_mfma_f32_32x32x16_bf16 v[18:33], v[170:173], v[178:181], v[18:33]
	v_mfma_f32_32x32x16_bf16 v[2:17], v[170:173], v[182:185], v[2:17]
	s_setprio 0
	s_waitcnt vmcnt(0)
	s_barrier
	s_cbranch_scc0 .LBB0_522
	v_mov_b32_e32 v132, v216
	s_lshl_b32 s3, s36, 3
	v_ashrrev_i32_e32 v0, 31, v132
	v_lshrrev_b32_e32 v130, 29, v0
	v_lshrrev_b32_e32 v0, 28, v0
	v_add_u32_e32 v0, v132, v0
	v_ashrrev_i32_e32 v0, 4, v0
	s_and_b32 s3, s3, 56
	s_bfe_u32 s7, s36, 0x30003
	v_lshrrev_b32_e32 v133, 29, v0
	s_or_b32 s3, s3, s7
	s_lshl_b32 s7, s36, 2
	v_add_u32_e32 v130, v132, v130
	v_add_u32_e32 v133, v0, v133
	s_and_b32 s30, s7, 0xffffff00
	s_lshl_b32 s3, s3, 19
	v_and_b32_e32 v131, 0xffffff8, v130
	v_and_b32_e32 v133, 0xffffff8, v133
	s_add_u32 s44, s12, s3
	v_sub_u32_e32 v131, v132, v131
	v_sub_u32_e32 v0, v0, v133
	v_lshlrev_b32_e32 v130, 8, v130
	v_readfirstlane_b32 s3, v132
	s_addc_u32 s45, s13, 0
	v_xor_b32_e32 v0, v0, v131
	v_and_b32_e32 v130, 0xfffff800, v130
	s_lshl_b32 s3, s3, 4
	v_lshl_add_u32 v0, v0, 4, v130
	s_and_b32 s3, s3, 0xfffffc00
	v_lshl_add_u64 v[130:131], s[44:45], 0, v[0:1]
	s_mov_b32 m0, s3
	v_lshl_add_u64 v[132:133], v[130:131], 0, s[58:59]
	global_load_lds_dwordx4 v0, s[44:45]
	s_add_i32 m0, s3, 0x2000
	s_ashr_i32 s31, s30, 31
	global_load_lds_dwordx4 v[132:133], off
	v_lshl_add_u64 v[132:133], v[130:131], 0, s[48:49]
	s_add_i32 m0, s3, 0x4000
	s_lshl_b64 s[30:31], s[30:31], 11
	global_load_lds_dwordx4 v[132:133], off
	s_add_i32 m0, s3, 0x6000
	s_add_u32 s30, s40, s30
	v_lshl_add_u64 v[130:131], v[130:131], 0, s[50:51]
	s_addc_u32 s31, s41, s31
	global_load_lds_dwordx4 v[130:131], off
	v_lshl_add_u64 v[130:131], s[30:31], 0, v[0:1]
	s_add_i32 m0, s3, 0x8000
	v_lshl_add_u64 v[132:133], v[130:131], 0, s[58:59]
	global_load_lds_dwordx4 v0, s[30:31]
	s_add_i32 m0, s3, 0xa000
	s_nop 0
	global_load_lds_dwordx4 v[132:133], off
	v_lshl_add_u64 v[132:133], v[130:131], 0, s[48:49]
	s_add_i32 m0, s3, 0xc000
	v_lshl_add_u64 v[130:131], v[130:131], 0, s[50:51]
	global_load_lds_dwordx4 v[132:133], off
	s_add_i32 m0, s3, 0xe000
	s_nop 0
	global_load_lds_dwordx4 v[130:131], off

; DI f32x16 mfma(bf16x8 a, bf16x8 b, f32x16 c) { return __builtin_amdgcn_mfma_f32_32x32x16_bf16(a, b, c, 0, 0, 0); }
; template <int BK> DI int swz(int row) { constexpr int CPR = BK / 8; return (row / (16 / CPR)) % CPR; }
; DI void wait_vm0() { asm volatile("s_waitcnt vmcnt(0)" ::: "memory"); }
;   DI void pre(int grow0, int gcol0, int lane, int w, char* lds) { xpass(0, grow0, gcol0, lane, w, lds); }
;     ...
;   for (int kt = 0; kt < nk; ++kt) {
;     char* cur = lds + (kt & 1) * STG; char* nxt = lds + ((kt + 1) & 1) * STG;
;     const bool more = kt + 1 < nk;
;     const bf16_t* An = Ag + (kt + 1) * BK; const bf16_t* Bn = Bg + (kt + 1) * BK;
;     if (!more) epi.pre(row0 + wm * 64, col0 + wn * (32 * NTW), lane, w, lds);
;     bf16x8 fa[2][2], fb[2][NTW];
; #pragma unroll
;     for (int mt = 0; mt < 2; ++mt) { int row = wm * 64 + mt * 32 + l31; fa[0][mt] = *(const bf16x8*)(cur + row * (BK * 2) + ((hh ^ swz<BK>(row)) << 4)); }
; #pragma unroll
;     for (int nt = 0; nt < NTW; ++nt) { int row = wn * (32 * NTW) + nt * 32 + l31; fb[0][nt] = *(const bf16x8*)(cur + ABYTES + row * (BK * 2) + ((hh ^ swz<BK>(row)) << 4)); }
; #pragma unroll
;     for (int kk = 0; kk < NKK; ++kk) {
;       if (kk + 1 < NKK) {
;         const int ch = (kk + 1) * 2 + hh;
; #pragma unroll
;         for (int mt = 0; mt < 2; ++mt) { int row = wm * 64 + mt * 32 + l31; fa[(kk + 1) & 1][mt] = *(const bf16x8*)(cur + row * (BK * 2) + ((ch ^ swz<BK>(row)) << 4)); }
; #pragma unroll
;         for (int nt = 0; nt < NTW; ++nt) { int row = wn * (32 * NTW) + nt * 32 + l31; fb[(kk + 1) & 1][nt] = *(const bf16x8*)(cur + ABYTES + row * (BK * 2) + ((ch ^ swz<BK>(row)) << 4)); }
;       }
;       if (more) {
; #pragma unroll
;         for (int q = 0; q < PPK; ++q) {
;           const int pi = kk * PPK + q;
;           if (pi < NPA) stage_piece<BM, BK>(An, lda, nxt, tid, pi, wv);
;           else if (pi < NP) stage_piece<BN, BK>(Bn, ldb, nxt + ABYTES, tid, pi - NPA, wv);
;         }
;       }
;       __builtin_amdgcn_s_setprio(1);
; #pragma unroll
;       for (int mt = 0; mt < 2; ++mt)
; #pragma unroll
;         for (int nt = 0; nt < NTW; ++nt) acc[mt][nt] = mfma(fa[kk & 1][mt], fb[kk & 1][nt], acc[mt][nt]);
;       __builtin_amdgcn_s_setprio(0);
;       __builtin_amdgcn_sched_barrier(0);
;     }
;     wait_vm0();
;     __syncthreads();
;   }
.LBB0_627:
	s_and_b32 s42, s35, 0x10000
	s_xor_b32 s100, s42, 0x10000
	s_add_i32 s41, s42, s34
	v_add3_u32 v190, s100, v136, v161
	v_add3_u32 v194, s100, v142, v163
	ds_read_b128 v[190:193], v190
	v_add3_u32 v198, s100, v143, v159
	ds_read_b128 v[194:197], v194
	v_add3_u32 v202, s100, v152, v160
	ds_read_b128 v[198:201], v198 offset:32768
	v_add3_u32 v206, s100, v153, v157
	ds_read_b128 v[202:205], v202 offset:32768
	v_add3_u32 v210, s100, v156, v158
	ds_read_b128 v[206:209], v206 offset:32768
	ds_read_b128 v[210:213], v210 offset:32768
	v_lshl_add_u64 v[214:215], v[130:131], 0, s[30:31]
	v_lshl_add_u64 v[226:227], v[132:133], 0, s[30:31]
	s_mov_b32 m0, s41
	v_lshl_add_u64 v[228:229], v[214:215], 0, s[28:29]
	s_waitcnt lgkmcnt(6)
	v_mfma_f32_32x32x16_bf16 v[114:129], v[166:169], v[174:177], v[114:129]
	global_load_lds_dwordx4 v[228:229], off
	v_lshl_add_u64 v[228:229], v[214:215], 0, s[24:25]
	s_add_i32 m0, s41, 0x2000
	v_mfma_f32_32x32x16_bf16 v[98:113], v[166:169], v[178:181], v[98:113]
	global_load_lds_dwordx4 v[228:229], off
	v_lshl_add_u64 v[228:229], v[214:215], 0, s[26:27]
	s_add_i32 m0, s41, 0x4000
	v_mfma_f32_32x32x16_bf16 v[82:97], v[166:169], v[182:185], v[82:97]
	global_load_lds_dwordx4 v[228:229], off
	v_lshl_add_u64 v[228:229], v[214:215], 0, s[38:39]
	s_add_i32 m0, s41, 0x6000
	v_mfma_f32_32x32x16_bf16 v[66:81], v[166:169], v[186:189], v[66:81]
	global_load_lds_dwordx4 v[228:229], off
	v_lshl_add_u64 v[228:229], v[226:227], 0, s[28:29]
	s_add_i32 m0, s41, 0x8000
	v_mfma_f32_32x32x16_bf16 v[50:65], v[170:173], v[174:177], v[50:65]
	global_load_lds_dwordx4 v[228:229], off
	v_lshl_add_u64 v[228:229], v[226:227], 0, s[24:25]
	s_add_i32 m0, s41, 0xa000
	v_mfma_f32_32x32x16_bf16 v[34:49], v[170:173], v[178:181], v[34:49]
	global_load_lds_dwordx4 v[228:229], off
	v_lshl_add_u64 v[228:229], v[226:227], 0, s[26:27]
	s_add_i32 m0, s41, 0xc000
	v_mfma_f32_32x32x16_bf16 v[18:33], v[170:173], v[182:185], v[18:33]
	global_load_lds_dwordx4 v[228:229], off
	v_lshl_add_u64 v[228:229], v[226:227], 0, s[38:39]
	s_add_i32 m0, s41, 0xe000
	v_mfma_f32_32x32x16_bf16 v[2:17], v[170:173], v[186:189], v[2:17]
	global_load_lds_dwordx4 v[228:229], off
	v_add3_u32 v166, s100, v136, v149
	v_add3_u32 v170, s100, v142, v150
	ds_read_b128 v[166:169], v166
	v_add3_u32 v174, s100, v143, v147
	ds_read_b128 v[170:173], v170
	v_add3_u32 v178, s100, v152, v148
	ds_read_b128 v[174:177], v174 offset:32768
	v_add3_u32 v182, s100, v153, v145
	ds_read_b128 v[178:181], v178 offset:32768
	v_add3_u32 v186, s100, v156, v146
	ds_read_b128 v[182:185], v182 offset:32768
	ds_read_b128 v[186:189], v186 offset:32768
	s_waitcnt lgkmcnt(6)
	v_mfma_f32_32x32x16_bf16 v[114:129], v[190:193], v[198:201], v[114:129]
	v_mfma_f32_32x32x16_bf16 v[98:113], v[190:193], v[202:205], v[98:113]
	v_mfma_f32_32x32x16_bf16 v[82:97], v[190:193], v[206:209], v[82:97]
	v_mfma_f32_32x32x16_bf16 v[66:81], v[190:193], v[210:213], v[66:81]
	v_mfma_f32_32x32x16_bf16 v[50:65], v[194:197], v[198:201], v[50:65]
	v_mfma_f32_32x32x16_bf16 v[34:49], v[194:197], v[202:205], v[34:49]
	v_mfma_f32_32x32x16_bf16 v[18:33], v[194:197], v[206:209], v[18:33]
	v_mfma_f32_32x32x16_bf16 v[2:17], v[194:197], v[210:213], v[2:17]
	v_add3_u32 v190, s100, v136, v139
	v_add3_u32 v194, s100, v142, v140
	ds_read_b128 v[190:193], v190
	v_add3_u32 v198, s100, v143, v137
	ds_read_b128 v[194:197], v194
	v_add3_u32 v202, s100, v152, v138
	ds_read_b128 v[198:201], v198 offset:32768
	v_add3_u32 v206, s100, v153, v134
	ds_read_b128 v[202:205], v202 offset:32768
	v_add3_u32 v210, s100, v156, v135
	ds_read_b128 v[206:209], v206 offset:32768
	ds_read_b128 v[210:213], v210 offset:32768
	s_waitcnt lgkmcnt(6)
	v_mfma_f32_32x32x16_bf16 v[114:129], v[166:169], v[174:177], v[114:129]
	v_mfma_f32_32x32x16_bf16 v[98:113], v[166:169], v[178:181], v[98:113]
	v_mfma_f32_32x32x16_bf16 v[82:97], v[166:169], v[182:185], v[82:97]
	v_mfma_f32_32x32x16_bf16 v[66:81], v[166:169], v[186:189], v[66:81]
	v_mfma_f32_32x32x16_bf16 v[50:65], v[170:173], v[174:177], v[50:65]
	v_mfma_f32_32x32x16_bf16 v[34:49], v[170:173], v[178:181], v[34:49]
	v_mfma_f32_32x32x16_bf16 v[18:33], v[170:173], v[182:185], v[18:33]
	v_mfma_f32_32x32x16_bf16 v[2:17], v[170:173], v[186:189], v[2:17]
	s_add_u32 s30, s30, 0x80
	s_addc_u32 s31, s31, 0
	s_add_i32 s35, s35, 0x10000
	s_waitcnt vmcnt(0) lgkmcnt(0)
	s_barrier
	v_add3_u32 v166, s42, v136, v141
	v_add3_u32 v170, s42, v142, v144
	ds_read_b128 v[166:169], v166
	v_add3_u32 v174, s42, v143, v151
	ds_read_b128 v[170:173], v170
	v_add3_u32 v178, s42, v152, v154
	ds_read_b128 v[174:177], v174 offset:32768
	v_add3_u32 v182, s42, v153, v155
	ds_read_b128 v[178:181], v178 offset:32768
	v_add3_u32 v186, s42, v156, v164
	ds_read_b128 v[182:185], v182 offset:32768
	ds_read_b128 v[186:189], v186 offset:32768
	v_mfma_f32_32x32x16_bf16 v[114:129], v[190:193], v[198:201], v[114:129]
	v_mfma_f32_32x32x16_bf16 v[98:113], v[190:193], v[202:205], v[98:113]
	v_mfma_f32_32x32x16_bf16 v[82:97], v[190:193], v[206:209], v[82:97]
	v_mfma_f32_32x32x16_bf16 v[66:81], v[190:193], v[210:213], v[66:81]
	v_mfma_f32_32x32x16_bf16 v[50:65], v[194:197], v[198:201], v[50:65]
	v_mfma_f32_32x32x16_bf16 v[34:49], v[194:197], v[202:205], v[34:49]
	v_mfma_f32_32x32x16_bf16 v[18:33], v[194:197], v[206:209], v[18:33]
	v_mfma_f32_32x32x16_bf16 v[2:17], v[194:197], v[210:213], v[2:17]
	s_cmpk_lg_i32 s30, 0x780
	s_cbranch_scc1 .LBB0_627
;     ...
;   for (int kt = 0; kt < nk; ++kt) {
;     char* cur = lds + (kt & 1) * STG; char* nxt = lds + ((kt + 1) & 1) * STG;
;     const bool more = kt + 1 < nk;
;     const bf16_t* An = Ag + (kt + 1) * BK; const bf16_t* Bn = Bg + (kt + 1) * BK;
;     if (!more) epi.pre(row0 + wm * 64, col0 + wn * (32 * NTW), lane, w, lds);
;     bf16x8 fa[2][2], fb[2][NTW];
; #pragma unroll
;     for (int mt = 0; mt < 2; ++mt) { int row = wm * 64 + mt * 32 + l31; fa[0][mt] = *(const bf16x8*)(cur + row * (BK * 2) + ((hh ^ swz<BK>(row)) << 4)); }
; #pragma unroll
;     for (int nt = 0; nt < NTW; ++nt) { int row = wn * (32 * NTW) + nt * 32 + l31; fb[0][nt] = *(const bf16x8*)(cur + ABYTES + row * (BK * 2) + ((hh ^ swz<BK>(row)) << 4)); }
; #pragma unroll
;     for (int kk = 0; kk < NKK; ++kk) {
;       if (kk + 1 < NKK) {
;         const int ch = (kk + 1) * 2 + hh;
; #pragma unroll
;         for (int mt = 0; mt < 2; ++mt) { int row = wm * 64 + mt * 32 + l31; fa[(kk + 1) & 1][mt] = *(const bf16x8*)(cur + row * (BK * 2) + ((ch ^ swz<BK>(row)) << 4)); }
; #pragma unroll
;         for (int nt = 0; nt < NTW; ++nt) { int row = wn * (32 * NTW) + nt * 32 + l31; fb[(kk + 1) & 1][nt] = *(const bf16x8*)(cur + ABYTES + row * (BK * 2) + ((ch ^ swz<BK>(row)) << 4)); }
;       }
;       if (more) {
; #pragma unroll
;         for (int q = 0; q < PPK; ++q) {
;           const int pi = kk * PPK + q;
;           if (pi < NPA) stage_piece<BM, BK>(An, lda, nxt, tid, pi, wv);
;           else if (pi < NP) stage_piece<BN, BK>(Bn, ldb, nxt + ABYTES, tid, pi - NPA, wv);
;         }
;       }
;       __builtin_amdgcn_s_setprio(1);
; #pragma unroll
;       for (int mt = 0; mt < 2; ++mt)
; #pragma unroll
;         for (int nt = 0; nt < NTW; ++nt) acc[mt][nt] = mfma(fa[kk & 1][mt], fb[kk & 1][nt], acc[mt][nt]);
;       __builtin_amdgcn_s_setprio(0);
;       __builtin_amdgcn_sched_barrier(0);
;     }
;     wait_vm0();
;     __syncthreads();
;   }
;   if (has_next) { const int tid3 = launder(threadIdx.x); stage_tile<BM, BK>(A + (size_t)row0n * lda, lda, lds, tid3); stage_tile<BN, BK>(Bt + (size_t)col0n * ldb, ldb, lds + ABYTES, tid3); }
;   { const int tid2 = launder(threadIdx.x); epi(acc, row0 + (((tid2 >> 6) % WM) * 64), col0 + (((tid2 >> 6) / WM) * (32 * NTW)), tid2 & 63, tid2 >> 6, lds); }
;   DI void operator()(f32x16 (&acc)[2][4], int grow0, int gcol0, int lane, int w, char* lds) {
	s_waitcnt lgkmcnt(0)
	v_add_u32_e32 v0, 0x10000, v136
	v_add_u32_e32 v136, 0x10000, v142
	v_add_u32_e32 v130, v0, v141
	v_add_u32_e32 v141, v136, v144
	ds_read_b128 v[130:133], v130
	ds_read_b128 v[166:169], v141
	v_add_u32_e32 v141, 0x18000, v143
	v_add_u32_e32 v142, v141, v151
	v_add_u32_e32 v202, 0x18000, v152
	v_add_u32_e32 v203, 0x18000, v153
	v_add_u32_e32 v143, v202, v154
	ds_read_b128 v[170:173], v142
	ds_read_b128 v[174:177], v143
	v_add_u32_e32 v142, v203, v155
	v_add_u32_e32 v204, 0x18000, v156
	v_add_u32_e32 v143, v204, v164
	ds_read_b128 v[152:155], v142
	ds_read_b128 v[178:181], v143
	v_add_u32_e32 v142, v0, v161
	v_add_u32_e32 v143, v136, v163
	ds_read_b128 v[182:185], v142
	ds_read_b128 v[186:189], v143
	v_add_u32_e32 v142, v141, v159
	v_add_u32_e32 v143, v202, v160
	ds_read_b128 v[190:193], v142
	ds_read_b128 v[194:197], v143
	v_add_u32_e32 v142, v203, v157
	v_add_u32_e32 v143, v204, v158
	ds_read_b128 v[156:159], v142
	ds_read_b128 v[198:201], v143
	s_lshl_b64 s[30:31], s[6:7], 22
	s_setprio 1
	s_waitcnt lgkmcnt(9)
	v_mfma_f32_32x32x16_bf16 v[114:129], v[130:133], v[170:173], v[114:129]
	s_waitcnt lgkmcnt(8)
	v_mfma_f32_32x32x16_bf16 v[98:113], v[130:133], v[174:177], v[98:113]
	s_waitcnt lgkmcnt(7)
	v_mfma_f32_32x32x16_bf16 v[82:97], v[130:133], v[152:155], v[82:97]
	s_waitcnt lgkmcnt(6)
	v_mfma_f32_32x32x16_bf16 v[66:81], v[130:133], v[178:181], v[66:81]
	v_mfma_f32_32x32x16_bf16 v[50:65], v[166:169], v[170:173], v[50:65]
	v_mfma_f32_32x32x16_bf16 v[34:49], v[166:169], v[174:177], v[34:49]
	v_mfma_f32_32x32x16_bf16 v[18:33], v[166:169], v[152:155], v[18:33]
	v_mfma_f32_32x32x16_bf16 v[2:17], v[166:169], v[178:181], v[2:17]
	s_setprio 0
	v_add_u32_e32 v130, v0, v149
	v_add_u32_e32 v142, v136, v150
	ds_read_b128 v[130:133], v130
	ds_read_b128 v[150:153], v142
	v_add_u32_e32 v142, v141, v147
	v_add_u32_e32 v143, v202, v148
	ds_read_b128 v[166:169], v142
	ds_read_b128 v[170:173], v143
	v_add_u32_e32 v142, v203, v145
	v_add_u32_e32 v146, v204, v146
	ds_read_b128 v[142:145], v142
	ds_read_b128 v[146:149], v146
	s_setprio 1
	s_waitcnt lgkmcnt(9)
	v_mfma_f32_32x32x16_bf16 v[114:129], v[182:185], v[190:193], v[114:129]
	s_waitcnt lgkmcnt(8)
	v_mfma_f32_32x32x16_bf16 v[98:113], v[182:185], v[194:197], v[98:113]
	s_waitcnt lgkmcnt(7)
	v_mfma_f32_32x32x16_bf16 v[82:97], v[182:185], v[156:159], v[82:97]
	s_waitcnt lgkmcnt(6)
	v_mfma_f32_32x32x16_bf16 v[66:81], v[182:185], v[198:201], v[66:81]
	v_mfma_f32_32x32x16_bf16 v[50:65], v[186:189], v[190:193], v[50:65]
	v_mfma_f32_32x32x16_bf16 v[34:49], v[186:189], v[194:197], v[34:49]
	v_mfma_f32_32x32x16_bf16 v[18:33], v[186:189], v[156:159], v[18:33]
	v_mfma_f32_32x32x16_bf16 v[2:17], v[186:189], v[198:201], v[2:17]
	s_setprio 0
	v_add_u32_e32 v0, v0, v139
	v_add_u32_e32 v136, v136, v140
	ds_read_b128 v[154:157], v0
	ds_read_b128 v[158:161], v136
	v_add_u32_e32 v0, v141, v137
	v_add_u32_e32 v140, v202, v138
	ds_read_b128 v[136:139], v0
	ds_read_b128 v[174:177], v140
	v_add_u32_e32 v0, v203, v134
	v_add_u32_e32 v134, v204, v135
	ds_read_b128 v[178:181], v0
	ds_read_b128 v[182:185], v134
	s_setprio 1
	s_waitcnt lgkmcnt(9)
	v_mfma_f32_32x32x16_bf16 v[114:129], v[130:133], v[166:169], v[114:129]
	s_waitcnt lgkmcnt(8)
	v_mfma_f32_32x32x16_bf16 v[98:113], v[130:133], v[170:173], v[98:113]
	s_waitcnt lgkmcnt(7)
	v_mfma_f32_32x32x16_bf16 v[82:97], v[130:133], v[142:145], v[82:97]
	s_waitcnt lgkmcnt(6)
	v_mfma_f32_32x32x16_bf16 v[66:81], v[130:133], v[146:149], v[66:81]
	v_mfma_f32_32x32x16_bf16 v[50:65], v[150:153], v[166:169], v[50:65]
	v_mfma_f32_32x32x16_bf16 v[34:49], v[150:153], v[170:173], v[34:49]
	v_mfma_f32_32x32x16_bf16 v[18:33], v[150:153], v[142:145], v[18:33]
	v_mfma_f32_32x32x16_bf16 v[2:17], v[150:153], v[146:149], v[2:17]
	s_setprio 0
	s_setprio 1
	s_waitcnt lgkmcnt(3)
	v_mfma_f32_32x32x16_bf16 v[114:129], v[154:157], v[136:139], v[114:129]
	s_waitcnt lgkmcnt(2)
	v_mfma_f32_32x32x16_bf16 v[98:113], v[154:157], v[174:177], v[98:113]
	s_waitcnt lgkmcnt(1)
	v_mfma_f32_32x32x16_bf16 v[82:97], v[154:157], v[178:181], v[82:97]
	s_waitcnt lgkmcnt(0)
	v_mfma_f32_32x32x16_bf16 v[66:81], v[154:157], v[182:185], v[66:81]
	v_mfma_f32_32x32x16_bf16 v[50:65], v[158:161], v[136:139], v[50:65]
	v_mfma_f32_32x32x16_bf16 v[34:49], v[158:161], v[174:177], v[34:49]
	v_mfma_f32_32x32x16_bf16 v[18:33], v[158:161], v[178:181], v[18:33]
	v_mfma_f32_32x32x16_bf16 v[2:17], v[158:161], v[182:185], v[2:17]
	s_setprio 0
	v_mov_b32_e32 v135, v216
	s_waitcnt vmcnt(0)
	s_barrier
	s_nop 0
	v_ashrrev_i32_e32 v134, 6, v135
	v_lshrrev_b32_e32 v0, 30, v134
	v_add_u32_e32 v0, v134, v0
	v_ashrrev_i32_e32 v130, 2, v0
	v_mul_i32_i24_e32 v0, 4, v130
	v_sub_u32_e32 v0, v134, v0
	v_lshlrev_b32_e32 v136, 6, v0
	v_lshl_add_u32 v132, v130, 7, s3
	v_add_u32_e32 v0, s2, v136
	v_and_b32_e32 v131, 31, v135
	v_bfe_u32 v133, v135, 5, 1
	v_cmp_lt_i32_e32 vcc, s57, v132
	s_and_saveexec_b64 s[2:3], vcc
	s_xor_b64 s[6:7], exec, s[2:3]
	s_cbranch_execz .LBB0_630
; DI unsigned pack2(float lo, float hi) { f32x2 v = {lo, hi}; bf2_t r = __builtin_convertvector(v, bf2_t); return __builtin_bit_cast(unsigned, r); }
; DI void tr_put(char* stg, int erow, const f32x16& v, int hh, float mul) {
; #pragma unroll
;   for (int qd = 0; qd < 4; ++qd) {
;     u32x2 pk; pk.x = pack2(v[4 * qd] * mul, v[4 * qd + 1] * mul); pk.y = pack2(v[4 * qd + 2] * mul, v[4 * qd + 3] * mul);
;     *(u32x2*)(stg + erow * 64 + (8 * qd + 4 * hh) * 2) = pk;
;   }
; }
; template <int R>
; DI void tr_flush(const char* stg, int row0, bf16_t* g, size_t grs, int lane) {
;   const int r0 = lane >> 2, ch = lane & 3;
; #pragma unroll
;   for (int it = 0; it < R / 16; ++it) {
;     const int r = it * 16 + r0;
;     u32x4 v = *(const u32x4*)(stg + (row0 + r) * 64 + ch * 16);
;     *(u32x4*)((char*)(g + (size_t)r * grs) + ch * 16) = v;
;   }
; }
;   DI void operator()(f32x16 (&acc)[2][4], int grow0, int gcol0, int lane, int w, char* lds) {
;     ...
;       const int cin = gcol0 - 1024, h = cin >> 8, b = grow0 >> 8, m0 = grow0 & 255;
;       char* stg = tr_stage(lds, w);
; #pragma unroll
;       for (int mt = 0; mt < 2; ++mt) {
; #pragma unroll
;         for (int nt = 0; nt < 4; ++nt) tr_put(stg, nt * 32 + l31, acc[mt][nt], hh, 1.f);
;         tr_flush<128>(stg, 0, Vxt + ((size_t)(b * 4 + h) * 256 + (cin & 255)) * 256 + m0 + mt * 32, 256, lane);
;       }
	v_add_u32_e32 v132, 0xfffffc00, v132
	v_lshl_add_u32 v134, v134, 13, v224
	v_lshlrev_b32_e32 v131, 6, v131
	v_lshlrev_b32_e32 v133, 3, v133
	v_ashrrev_i32_e32 v0, 6, v0
	v_lshrrev_b32_e32 v132, 8, v132
	v_or3_b32 v131, v134, v131, v133
	v_and_b32_e32 v0, -4, v0
	v_cvt_pk_bf16_f32 v66, v66, v67
	v_cvt_pk_bf16_f32 v67, v68, v69
	v_add_u32_e32 v132, v132, v0
	ds_write_b64 v131, v[66:67] offset:6144
	v_cvt_pk_bf16_f32 v66, v70, v71
	v_cvt_pk_bf16_f32 v67, v72, v73
	v_and_b32_e32 v135, 63, v135
	s_add_u32 s34, s74, s30
	v_ashrrev_i32_e32 v133, 31, v132
	v_cvt_pk_bf16_f32 v114, v114, v115
	v_cvt_pk_bf16_f32 v115, v116, v117
	ds_write_b64 v131, v[66:67] offset:6160
	v_cvt_pk_bf16_f32 v66, v74, v75
	v_cvt_pk_bf16_f32 v67, v76, v77
	s_addc_u32 s35, s75, s31
	v_lshlrev_b64 v[132:133], 17, v[132:133]
	v_lshlrev_b32_e32 v0, 4, v135
	ds_write_b64 v131, v[114:115]
	v_cvt_pk_bf16_f32 v114, v118, v119
	v_cvt_pk_bf16_f32 v115, v120, v121
	ds_write_b64 v131, v[66:67] offset:6176
	v_cvt_pk_bf16_f32 v66, v78, v79
	v_cvt_pk_bf16_f32 v67, v80, v81
	v_lshlrev_b32_e32 v68, 16, v130
	v_and_b32_e32 v136, 0xc0, v136
	v_lshrrev_b32_e32 v137, 2, v135
	v_and_b32_e32 v0, 48, v0
	ds_write_b64 v131, v[114:115] offset:16
	v_cvt_pk_bf16_f32 v114, v122, v123
	v_cvt_pk_bf16_f32 v115, v124, v125
	ds_write_b64 v131, v[66:67] offset:6192
	v_lshl_add_u64 v[66:67], s[34:35], 0, v[132:133]
	v_and_b32_e32 v68, 0x10000, v68
	v_mov_b32_e32 v69, v1
	v_or_b32_e32 v134, v134, v0
	v_or_b32_e32 v138, 16, v137
	ds_write_b64 v131, v[114:115] offset:32
	v_cvt_pk_bf16_f32 v114, v126, v127
	v_cvt_pk_bf16_f32 v115, v128, v129
	v_lshl_add_u64 v[66:67], v[66:67], 0, v[68:69]
	v_lshlrev_b32_e32 v68, 1, v136
	v_lshl_or_b32 v139, v138, 6, v134
	ds_write_b64 v131, v[114:115] offset:48
	v_lshl_add_u64 v[70:71], v[66:67], 0, v[68:69]
	v_cvt_pk_bf16_f32 v98, v98, v99
	v_cvt_pk_bf16_f32 v99, v100, v101
	v_lshl_add_u64 v[74:75], v[70:71], 0, v[0:1]
	ds_read_b128 v[70:73], v139
	ds_write_b64 v131, v[98:99] offset:2048
	v_cvt_pk_bf16_f32 v98, v102, v103
	v_cvt_pk_bf16_f32 v99, v104, v105
	ds_write_b64 v131, v[98:99] offset:2064
	v_cvt_pk_bf16_f32 v98, v106, v107
	v_cvt_pk_bf16_f32 v99, v108, v109
	v_lshlrev_b32_e32 v0, 9, v137
	v_or_b32_e32 v142, 48, v137
	ds_write_b64 v131, v[98:99] offset:2080
	v_cvt_pk_bf16_f32 v98, v110, v111
	v_cvt_pk_bf16_f32 v99, v112, v113
	v_lshl_add_u64 v[76:77], v[74:75], 0, v[0:1]
	v_lshlrev_b32_e32 v0, 9, v138
	v_lshl_or_b32 v143, v142, 6, v134
	ds_write_b64 v131, v[98:99] offset:2096
	v_lshl_add_u64 v[78:79], v[74:75], 0, v[0:1]
	v_cvt_pk_bf16_f32 v82, v82, v83
	v_cvt_pk_bf16_f32 v83, v84, v85
	s_waitcnt lgkmcnt(4)
	global_store_dwordx4 v[78:79], v[70:73], off
	ds_read_b128 v[70:73], v143
	v_or_b32_e32 v140, 32, v137
	ds_write_b64 v131, v[82:83] offset:4096
	v_cvt_pk_bf16_f32 v82, v86, v87
	v_cvt_pk_bf16_f32 v83, v88, v89
	ds_write_b64 v131, v[82:83] offset:4112
	v_cvt_pk_bf16_f32 v82, v90, v91
	v_cvt_pk_bf16_f32 v83, v92, v93
	v_lshlrev_b32_e32 v0, 9, v140
	v_or_b32_e32 v146, 0x50, v137
	ds_write_b64 v131, v[82:83] offset:4128
	v_cvt_pk_bf16_f32 v82, v94, v95
	v_cvt_pk_bf16_f32 v83, v96, v97
	v_lshl_add_u64 v[80:81], v[74:75], 0, v[0:1]
	v_lshlrev_b32_e32 v0, 9, v142
	v_lshl_or_b32 v135, v137, 6, v134
	v_lshl_or_b32 v147, v146, 6, v134
	ds_write_b64 v131, v[82:83] offset:4144
	v_lshl_add_u64 v[82:83], v[74:75], 0, v[0:1]
	ds_read_b128 v[66:69], v135
	s_waitcnt lgkmcnt(5)
	global_store_dwordx4 v[82:83], v[70:73], off
	ds_read_b128 v[70:73], v147
	v_or_b32_e32 v144, 64, v137
	v_lshlrev_b32_e32 v0, 9, v144
	v_or_b32_e32 v148, 0x60, v137
	v_or_b32_e32 v150, 0x70, v137
	v_lshl_add_u64 v[84:85], v[74:75], 0, v[0:1]
	v_lshlrev_b32_e32 v0, 9, v146
	v_lshl_or_b32 v141, v140, 6, v134
	v_lshl_or_b32 v145, v144, 6, v134
	v_lshl_or_b32 v149, v148, 6, v134
	v_lshl_or_b32 v134, v150, 6, v134
	v_lshl_add_u64 v[86:87], v[74:75], 0, v[0:1]
	s_waitcnt lgkmcnt(0)
	global_store_dwordx4 v[86:87], v[70:73], off
	ds_read_b128 v[70:73], v134
	global_store_dwordx4 v[76:77], v[66:69], off
	ds_read_b128 v[66:69], v141
	v_cvt_pk_bf16_f32 v50, v50, v51
	v_cvt_pk_bf16_f32 v51, v52, v53
	v_cvt_pk_bf16_f32 v34, v34, v35
	v_cvt_pk_bf16_f32 v35, v36, v37
	s_waitcnt lgkmcnt(0)
	global_store_dwordx4 v[80:81], v[66:69], off
	ds_read_b128 v[66:69], v145
	v_cvt_pk_bf16_f32 v18, v18, v19
	v_cvt_pk_bf16_f32 v19, v20, v21
	v_lshlrev_b32_e32 v0, 9, v148
	ds_write_b64 v131, v[50:51]
	s_waitcnt lgkmcnt(1)
	global_store_dwordx4 v[84:85], v[66:69], off
	ds_read_b128 v[66:69], v149
	v_cvt_pk_bf16_f32 v50, v54, v55
	v_cvt_pk_bf16_f32 v51, v56, v57
	ds_write_b64 v131, v[34:35] offset:2048
	v_cvt_pk_bf16_f32 v34, v38, v39
	v_cvt_pk_bf16_f32 v35, v40, v41
	ds_write_b64 v131, v[18:19] offset:4096
	v_cvt_pk_bf16_f32 v18, v22, v23
	v_cvt_pk_bf16_f32 v19, v24, v25
	v_cvt_pk_bf16_f32 v2, v2, v3
	v_cvt_pk_bf16_f32 v3, v4, v5
	v_lshl_add_u64 v[88:89], v[74:75], 0, v[0:1]
	v_lshlrev_b32_e32 v0, 9, v150
	ds_write_b64 v131, v[50:51] offset:16
	v_cvt_pk_bf16_f32 v50, v58, v59
	v_cvt_pk_bf16_f32 v51, v60, v61
	ds_write_b64 v131, v[34:35] offset:2064
	v_cvt_pk_bf16_f32 v34, v42, v43
	v_cvt_pk_bf16_f32 v35, v44, v45
	ds_write_b64 v131, v[18:19] offset:4112
	v_cvt_pk_bf16_f32 v18, v26, v27
	v_cvt_pk_bf16_f32 v19, v28, v29
	ds_write_b64 v131, v[2:3] offset:6144
	v_cvt_pk_bf16_f32 v2, v6, v7
	v_cvt_pk_bf16_f32 v3, v8, v9
	s_waitcnt lgkmcnt(6)
	global_store_dwordx4 v[88:89], v[66:69], off
	ds_write_b64 v131, v[50:51] offset:32
	v_cvt_pk_bf16_f32 v50, v62, v63
	v_lshl_add_u64 v[66:67], v[74:75], 0, v[0:1]
	v_cvt_pk_bf16_f32 v51, v64, v65
	ds_write_b64 v131, v[34:35] offset:2080
	v_cvt_pk_bf16_f32 v34, v46, v47
	v_cvt_pk_bf16_f32 v35, v48, v49
	ds_write_b64 v131, v[18:19] offset:4128
	v_cvt_pk_bf16_f32 v18, v30, v31
	v_cvt_pk_bf16_f32 v19, v32, v33
	ds_write_b64 v131, v[2:3] offset:6160
	v_cvt_pk_bf16_f32 v2, v10, v11
	v_cvt_pk_bf16_f32 v3, v12, v13
	global_store_dwordx4 v[66:67], v[70:73], off
	ds_write_b64 v131, v[50:51] offset:48
	ds_write_b64 v131, v[34:35] offset:2096
	ds_write_b64 v131, v[18:19] offset:4144
	ds_write_b64 v131, v[2:3] offset:6176
	ds_read_b128 v[2:5], v135
	ds_read_b128 v[6:9], v139
	ds_read_b128 v[10:13], v141
	v_cvt_pk_bf16_f32 v14, v14, v15
	v_cvt_pk_bf16_f32 v15, v16, v17
	ds_write_b64 v131, v[14:15] offset:6192
	s_waitcnt lgkmcnt(3)
	global_store_dwordx4 v[76:77], v[2:5], off offset:64
	s_waitcnt lgkmcnt(2)
	global_store_dwordx4 v[78:79], v[6:9], off offset:64
	s_waitcnt lgkmcnt(1)
	global_store_dwordx4 v[80:81], v[10:13], off offset:64
	ds_read_b128 v[2:5], v143
	ds_read_b128 v[6:9], v145
	ds_read_b128 v[10:13], v147
	ds_read_b128 v[14:17], v149
	ds_read_b128 v[18:21], v134
	s_waitcnt lgkmcnt(4)
	global_store_dwordx4 v[82:83], v[2:5], off offset:64
	s_waitcnt lgkmcnt(3)
	global_store_dwordx4 v[84:85], v[6:9], off offset:64
	s_waitcnt lgkmcnt(2)
	global_store_dwordx4 v[86:87], v[10:13], off offset:64
	s_waitcnt lgkmcnt(1)
	global_store_dwordx4 v[88:89], v[14:17], off offset:64
	s_waitcnt lgkmcnt(0)
	global_store_dwordx4 v[66:67], v[18:21], off offset:64
